# GEMM K-loops: K=2 late pre-MFMA barrier + removed redundant s_waitcnt lgkmcnt(0) and the mid-block s_setprio 0/1 pair in every MFMA block
# speedup vs baseline: 1.0044x; 1.0044x over previous
.LBB0_408:
	ds_read_b128 v[34:37], v196
	ds_read_b128 v[38:41], v196 offset:1024
	ds_read_b128 v[42:45], v196 offset:2048
	ds_read_b128 v[46:49], v196 offset:3072
	ds_read_b128 v[146:149], v197
	ds_read_b128 v[150:153], v197 offset:1024
	ds_read_b128 v[184:187], v197 offset:2048
	ds_read_b128 v[188:191], v197 offset:3072
	s_add_i32 s11, s6, 2
	s_add_u32 s12, s4, 0x80
	s_addc_u32 s7, s5, 0
	s_cmp_eq_u32 s27, s6
	s_cselect_b32 s6, s54, s12
	s_cselect_b32 s7, s55, s7
	s_cselect_b32 s13, s61, s9
	s_cselect_b32 s12, s60, s8
	v_lshl_add_u64 v[192:193], s[4:5], 0, v[174:175]
	s_add_i32 m0, s88, 0xc000
	ds_read_b128 v[200:203], v198
	ds_read_b128 v[204:207], v198 offset:1024
	ds_read_b128 v[208:211], v198 offset:2048
	ds_read_b128 v[212:215], v198 offset:3072
	ds_read_b128 v[216:219], v198 offset:4096
	ds_read_b128 v[220:223], v198 offset:5120
	ds_read_b128 v[224:227], v198 offset:6144
	ds_read_b128 v[228:231], v198 offset:7168
	global_load_lds_dwordx4 v[192:193], off
	v_lshl_add_u64 v[192:193], s[4:5], 0, v[176:177]
	s_add_i32 m0, s88, 0xe000
	s_nop 0
	global_load_lds_dwordx4 v[192:193], off
	s_waitcnt vmcnt(8)
	s_waitcnt lgkmcnt(0)
	s_setprio 1
	v_mfma_f32_16x16x32_bf16 v[142:145], v[34:37], v[200:203], v[142:145]
	v_mfma_f32_16x16x32_bf16 v[138:141], v[42:45], v[200:203], v[138:141]
	s_barrier
	v_mfma_f32_16x16x32_bf16 v[126:129], v[34:37], v[208:211], v[126:129]
	v_mfma_f32_16x16x32_bf16 v[122:125], v[42:45], v[208:211], v[122:125]
	v_mfma_f32_16x16x32_bf16 v[110:113], v[34:37], v[216:219], v[110:113]
	v_mfma_f32_16x16x32_bf16 v[106:109], v[42:45], v[216:219], v[106:109]
	v_mfma_f32_16x16x32_bf16 v[94:97], v[34:37], v[224:227], v[94:97]
	v_mfma_f32_16x16x32_bf16 v[90:93], v[42:45], v[224:227], v[90:93]
	v_mfma_f32_16x16x32_bf16 v[142:145], v[38:41], v[204:207], v[142:145]
	v_mfma_f32_16x16x32_bf16 v[138:141], v[46:49], v[204:207], v[138:141]
	v_mfma_f32_16x16x32_bf16 v[126:129], v[38:41], v[212:215], v[126:129]
	v_mfma_f32_16x16x32_bf16 v[122:125], v[46:49], v[212:215], v[122:125]
	v_mfma_f32_16x16x32_bf16 v[110:113], v[38:41], v[220:223], v[110:113]
	v_mfma_f32_16x16x32_bf16 v[106:109], v[46:49], v[220:223], v[106:109]
	v_mfma_f32_16x16x32_bf16 v[94:97], v[38:41], v[228:231], v[94:97]
	v_mfma_f32_16x16x32_bf16 v[90:93], v[46:49], v[228:231], v[90:93]
	v_mfma_f32_16x16x32_bf16 v[134:137], v[146:149], v[200:203], v[134:137]
	v_mfma_f32_16x16x32_bf16 v[130:133], v[184:187], v[200:203], v[130:133]
	v_mfma_f32_16x16x32_bf16 v[118:121], v[146:149], v[208:211], v[118:121]
	v_mfma_f32_16x16x32_bf16 v[114:117], v[184:187], v[208:211], v[114:117]
	v_mfma_f32_16x16x32_bf16 v[102:105], v[146:149], v[216:219], v[102:105]
	v_mfma_f32_16x16x32_bf16 v[98:101], v[184:187], v[216:219], v[98:101]
	v_mfma_f32_16x16x32_bf16 v[86:89], v[146:149], v[224:227], v[86:89]
	v_mfma_f32_16x16x32_bf16 v[82:85], v[184:187], v[224:227], v[82:85]
	v_mfma_f32_16x16x32_bf16 v[134:137], v[150:153], v[204:207], v[134:137]
	v_mfma_f32_16x16x32_bf16 v[130:133], v[188:191], v[204:207], v[130:133]
	v_mfma_f32_16x16x32_bf16 v[118:121], v[150:153], v[212:215], v[118:121]
	v_mfma_f32_16x16x32_bf16 v[114:117], v[188:191], v[212:215], v[114:117]
	v_mfma_f32_16x16x32_bf16 v[102:105], v[150:153], v[220:223], v[102:105]
	v_mfma_f32_16x16x32_bf16 v[98:101], v[188:191], v[220:223], v[98:101]
	v_mfma_f32_16x16x32_bf16 v[86:89], v[150:153], v[228:231], v[86:89]
	v_mfma_f32_16x16x32_bf16 v[82:85], v[188:191], v[228:231], v[82:85]
	s_setprio 0
	s_barrier
	s_add_i32 s24, s84, s81
	v_lshl_add_u64 v[192:193], s[12:13], 0, v[156:157]
	s_mov_b32 m0, s24
	ds_read_b128 v[200:203], v198 offset:16384
	ds_read_b128 v[204:207], v198 offset:17408
	ds_read_b128 v[208:211], v198 offset:18432
	ds_read_b128 v[212:215], v198 offset:19456
	ds_read_b128 v[216:219], v198 offset:20480
	ds_read_b128 v[220:223], v198 offset:21504
	ds_read_b128 v[224:227], v198 offset:22528
	ds_read_b128 v[228:231], v198 offset:23552
	global_load_lds_dwordx4 v[192:193], off
	s_add_i32 m0, s24, 0x2000
	v_lshl_add_u64 v[232:233], s[12:13], 0, v[160:161]
	s_add_u32 s12, s12, s20
	s_addc_u32 s13, s13, s21
	s_add_i32 s24, s85, s81
	global_load_lds_dwordx4 v[232:233], off
	v_lshl_add_u64 v[234:235], s[12:13], 0, v[156:157]
	s_mov_b32 m0, s24
	v_lshl_add_u64 v[236:237], s[12:13], 0, v[160:161]
	global_load_lds_dwordx4 v[234:235], off
	s_add_i32 m0, s24, 0x2000
	v_lshl_add_u64 v[238:239], s[6:7], 0, v[154:155]
	global_load_lds_dwordx4 v[236:237], off
	s_mov_b32 m0, s88
	v_lshl_add_u64 v[240:241], s[6:7], 0, v[158:159]
	global_load_lds_dwordx4 v[238:239], off
	s_mov_b32 m0, s90
	s_nop 0
	global_load_lds_dwordx4 v[240:241], off
	s_waitcnt vmcnt(8)
	s_waitcnt lgkmcnt(0)
	s_setprio 1
	v_mfma_f32_16x16x32_bf16 v[78:81], v[34:37], v[200:203], v[78:81]
	v_mfma_f32_16x16x32_bf16 v[74:77], v[42:45], v[200:203], v[74:77]
	s_barrier
	v_mfma_f32_16x16x32_bf16 v[62:65], v[34:37], v[208:211], v[62:65]
	v_mfma_f32_16x16x32_bf16 v[58:61], v[42:45], v[208:211], v[58:61]
	v_mfma_f32_16x16x32_bf16 v[30:33], v[34:37], v[216:219], v[30:33]
	v_mfma_f32_16x16x32_bf16 v[26:29], v[42:45], v[216:219], v[26:29]
	v_mfma_f32_16x16x32_bf16 v[14:17], v[34:37], v[224:227], v[14:17]
	v_mfma_f32_16x16x32_bf16 v[10:13], v[42:45], v[224:227], v[10:13]
	v_mfma_f32_16x16x32_bf16 v[78:81], v[38:41], v[204:207], v[78:81]
	v_mfma_f32_16x16x32_bf16 v[74:77], v[46:49], v[204:207], v[74:77]
	v_mfma_f32_16x16x32_bf16 v[62:65], v[38:41], v[212:215], v[62:65]
	v_mfma_f32_16x16x32_bf16 v[58:61], v[46:49], v[212:215], v[58:61]
	v_mfma_f32_16x16x32_bf16 v[30:33], v[38:41], v[220:223], v[30:33]
	v_mfma_f32_16x16x32_bf16 v[26:29], v[46:49], v[220:223], v[26:29]
	v_mfma_f32_16x16x32_bf16 v[14:17], v[38:41], v[228:231], v[14:17]
	v_mfma_f32_16x16x32_bf16 v[10:13], v[46:49], v[228:231], v[10:13]
	v_mfma_f32_16x16x32_bf16 v[22:25], v[146:149], v[216:219], v[22:25]
	v_mfma_f32_16x16x32_bf16 v[18:21], v[184:187], v[216:219], v[18:21]
	v_mfma_f32_16x16x32_bf16 v[6:9], v[146:149], v[224:227], v[6:9]
	v_mfma_f32_16x16x32_bf16 v[2:5], v[184:187], v[224:227], v[2:5]
	v_mfma_f32_16x16x32_bf16 v[34:37], v[146:149], v[200:203], v[70:73]
	v_mfma_f32_16x16x32_bf16 v[38:41], v[184:187], v[200:203], v[66:69]
	v_mfma_f32_16x16x32_bf16 v[42:45], v[146:149], v[208:211], v[54:57]
	v_mfma_f32_16x16x32_bf16 v[46:49], v[184:187], v[208:211], v[50:53]
	v_mfma_f32_16x16x32_bf16 v[22:25], v[150:153], v[220:223], v[22:25]
	v_mfma_f32_16x16x32_bf16 v[18:21], v[188:191], v[220:223], v[18:21]
	v_mfma_f32_16x16x32_bf16 v[6:9], v[150:153], v[228:231], v[6:9]
	v_mfma_f32_16x16x32_bf16 v[2:5], v[188:191], v[228:231], v[2:5]
	v_mfma_f32_16x16x32_bf16 v[34:37], v[150:153], v[204:207], v[34:37]
	v_mfma_f32_16x16x32_bf16 v[38:41], v[188:191], v[204:207], v[38:41]
	v_mfma_f32_16x16x32_bf16 v[42:45], v[150:153], v[212:215], v[42:45]
	v_mfma_f32_16x16x32_bf16 v[46:49], v[188:191], v[212:215], v[46:49]
	s_setprio 0
	s_barrier
	s_add_i32 s12, 0, 0x18000
	s_add_i32 s13, 0, 0x1c000
	v_add_u32_e32 v70, s12, v194
	v_add_u32_e32 v162, s13, v194
	ds_read_b128 v[50:53], v70
	ds_read_b128 v[54:57], v70 offset:1024
	ds_read_b128 v[66:69], v70 offset:2048
	ds_read_b128 v[70:73], v70 offset:3072
	ds_read_b128 v[146:149], v162
	ds_read_b128 v[150:153], v162 offset:1024
	ds_read_b128 v[184:187], v162 offset:2048
	ds_read_b128 v[188:191], v162 offset:3072
	s_add_u32 s6, s6, s20
	s_addc_u32 s7, s7, s21
	s_mov_b32 m0, s91
	v_lshl_add_u64 v[242:243], s[6:7], 0, v[154:155]
	ds_read_b128 v[200:203], v198 offset:32768
	ds_read_b128 v[204:207], v198 offset:33792
	ds_read_b128 v[208:211], v198 offset:34816
	ds_read_b128 v[212:215], v198 offset:35840
	ds_read_b128 v[216:219], v198 offset:36864
	ds_read_b128 v[220:223], v198 offset:37888
	ds_read_b128 v[224:227], v198 offset:38912
	ds_read_b128 v[228:231], v198 offset:39936
	global_load_lds_dwordx4 v[242:243], off
	v_lshl_add_u64 v[242:243], s[6:7], 0, v[158:159]
	s_mov_b32 m0, s95
	s_nop 0
	global_load_lds_dwordx4 v[242:243], off
	s_waitcnt vmcnt(8)
	s_waitcnt lgkmcnt(0)
	s_setprio 1
	v_mfma_f32_16x16x32_bf16 v[142:145], v[50:53], v[200:203], v[142:145]
	v_mfma_f32_16x16x32_bf16 v[138:141], v[66:69], v[200:203], v[138:141]
	s_barrier
	v_mfma_f32_16x16x32_bf16 v[126:129], v[50:53], v[208:211], v[126:129]
	v_mfma_f32_16x16x32_bf16 v[122:125], v[66:69], v[208:211], v[122:125]
	v_mfma_f32_16x16x32_bf16 v[110:113], v[50:53], v[216:219], v[110:113]
	v_mfma_f32_16x16x32_bf16 v[106:109], v[66:69], v[216:219], v[106:109]
	v_mfma_f32_16x16x32_bf16 v[94:97], v[50:53], v[224:227], v[94:97]
	v_mfma_f32_16x16x32_bf16 v[90:93], v[66:69], v[224:227], v[90:93]
	v_mfma_f32_16x16x32_bf16 v[142:145], v[54:57], v[204:207], v[142:145]
	v_mfma_f32_16x16x32_bf16 v[138:141], v[70:73], v[204:207], v[138:141]
	v_mfma_f32_16x16x32_bf16 v[126:129], v[54:57], v[212:215], v[126:129]
	v_mfma_f32_16x16x32_bf16 v[122:125], v[70:73], v[212:215], v[122:125]
	v_mfma_f32_16x16x32_bf16 v[110:113], v[54:57], v[220:223], v[110:113]
	v_mfma_f32_16x16x32_bf16 v[106:109], v[70:73], v[220:223], v[106:109]
	v_mfma_f32_16x16x32_bf16 v[94:97], v[54:57], v[228:231], v[94:97]
	v_mfma_f32_16x16x32_bf16 v[90:93], v[70:73], v[228:231], v[90:93]
	v_mfma_f32_16x16x32_bf16 v[134:137], v[146:149], v[200:203], v[134:137]
	v_mfma_f32_16x16x32_bf16 v[130:133], v[184:187], v[200:203], v[130:133]
	v_mfma_f32_16x16x32_bf16 v[118:121], v[146:149], v[208:211], v[118:121]
	v_mfma_f32_16x16x32_bf16 v[114:117], v[184:187], v[208:211], v[114:117]
	v_mfma_f32_16x16x32_bf16 v[102:105], v[146:149], v[216:219], v[102:105]
	v_mfma_f32_16x16x32_bf16 v[98:101], v[184:187], v[216:219], v[98:101]
	v_mfma_f32_16x16x32_bf16 v[86:89], v[146:149], v[224:227], v[86:89]
	v_mfma_f32_16x16x32_bf16 v[82:85], v[184:187], v[224:227], v[82:85]
	v_mfma_f32_16x16x32_bf16 v[134:137], v[150:153], v[204:207], v[134:137]
	v_mfma_f32_16x16x32_bf16 v[130:133], v[188:191], v[204:207], v[130:133]
	v_mfma_f32_16x16x32_bf16 v[118:121], v[150:153], v[212:215], v[118:121]
	v_mfma_f32_16x16x32_bf16 v[114:117], v[188:191], v[212:215], v[114:117]
	v_mfma_f32_16x16x32_bf16 v[102:105], v[150:153], v[220:223], v[102:105]
	v_mfma_f32_16x16x32_bf16 v[98:101], v[188:191], v[220:223], v[98:101]
	v_mfma_f32_16x16x32_bf16 v[86:89], v[150:153], v[228:231], v[86:89]
	v_mfma_f32_16x16x32_bf16 v[82:85], v[188:191], v[228:231], v[82:85]
	s_setprio 0
	s_barrier
	s_add_i32 s6, s12, s81
	v_lshl_add_u64 v[192:193], v[192:193], 0, s[44:45]
	s_mov_b32 m0, s6
	ds_read_b128 v[200:203], v198 offset:49152
	ds_read_b128 v[204:207], v198 offset:50176
	ds_read_b128 v[208:211], v198 offset:51200
	ds_read_b128 v[212:215], v198 offset:52224
	ds_read_b128 v[216:219], v198 offset:53248
	ds_read_b128 v[220:223], v198 offset:54272
	ds_read_b128 v[224:227], v198 offset:55296
	ds_read_b128 v[228:231], v198 offset:56320
	global_load_lds_dwordx4 v[192:193], off
	v_lshl_add_u64 v[192:193], v[232:233], 0, s[44:45]
	s_add_i32 m0, s6, 0x2000
	s_add_i32 s6, s13, s81
	global_load_lds_dwordx4 v[192:193], off
	v_lshl_add_u64 v[192:193], v[234:235], 0, s[44:45]
	s_mov_b32 m0, s6
	s_nop 0
	global_load_lds_dwordx4 v[192:193], off
	v_lshl_add_u64 v[192:193], v[236:237], 0, s[44:45]
	s_add_i32 m0, s6, 0x2000
	s_nop 0
	global_load_lds_dwordx4 v[192:193], off
	v_lshl_add_u64 v[192:193], v[238:239], 0, s[44:45]
	s_mov_b32 m0, s17
	s_nop 0
	global_load_lds_dwordx4 v[192:193], off
	v_lshl_add_u64 v[192:193], v[240:241], 0, s[44:45]
	s_mov_b32 m0, s94
	s_nop 0
	global_load_lds_dwordx4 v[192:193], off
	s_waitcnt vmcnt(8)
	s_waitcnt lgkmcnt(0)
	s_setprio 1
	v_mfma_f32_16x16x32_bf16 v[78:81], v[50:53], v[200:203], v[78:81]
	v_mfma_f32_16x16x32_bf16 v[74:77], v[66:69], v[200:203], v[74:77]
	s_barrier
	v_mfma_f32_16x16x32_bf16 v[62:65], v[50:53], v[208:211], v[62:65]
	v_mfma_f32_16x16x32_bf16 v[58:61], v[66:69], v[208:211], v[58:61]
	v_mfma_f32_16x16x32_bf16 v[30:33], v[50:53], v[216:219], v[30:33]
	v_mfma_f32_16x16x32_bf16 v[26:29], v[66:69], v[216:219], v[26:29]
	v_mfma_f32_16x16x32_bf16 v[14:17], v[50:53], v[224:227], v[14:17]
	v_mfma_f32_16x16x32_bf16 v[10:13], v[66:69], v[224:227], v[10:13]
	v_mfma_f32_16x16x32_bf16 v[78:81], v[54:57], v[204:207], v[78:81]
	v_mfma_f32_16x16x32_bf16 v[74:77], v[70:73], v[204:207], v[74:77]
	v_mfma_f32_16x16x32_bf16 v[62:65], v[54:57], v[212:215], v[62:65]
	v_mfma_f32_16x16x32_bf16 v[58:61], v[70:73], v[212:215], v[58:61]
	v_mfma_f32_16x16x32_bf16 v[30:33], v[54:57], v[220:223], v[30:33]
	v_mfma_f32_16x16x32_bf16 v[26:29], v[70:73], v[220:223], v[26:29]
	v_mfma_f32_16x16x32_bf16 v[14:17], v[54:57], v[228:231], v[14:17]
	v_mfma_f32_16x16x32_bf16 v[10:13], v[70:73], v[228:231], v[10:13]
	v_mfma_f32_16x16x32_bf16 v[34:37], v[146:149], v[200:203], v[34:37]
	v_mfma_f32_16x16x32_bf16 v[70:73], v[150:153], v[204:207], v[34:37]
	v_mfma_f32_16x16x32_bf16 v[34:37], v[184:187], v[200:203], v[38:41]
	v_mfma_f32_16x16x32_bf16 v[66:69], v[188:191], v[204:207], v[34:37]
	v_mfma_f32_16x16x32_bf16 v[34:37], v[146:149], v[208:211], v[42:45]
	v_mfma_f32_16x16x32_bf16 v[54:57], v[150:153], v[212:215], v[34:37]
	v_mfma_f32_16x16x32_bf16 v[34:37], v[184:187], v[208:211], v[46:49]
	v_mfma_f32_16x16x32_bf16 v[22:25], v[146:149], v[216:219], v[22:25]
	v_mfma_f32_16x16x32_bf16 v[18:21], v[184:187], v[216:219], v[18:21]
	v_mfma_f32_16x16x32_bf16 v[6:9], v[146:149], v[224:227], v[6:9]
	v_mfma_f32_16x16x32_bf16 v[2:5], v[184:187], v[224:227], v[2:5]
	v_mfma_f32_16x16x32_bf16 v[50:53], v[188:191], v[212:215], v[34:37]
	v_mfma_f32_16x16x32_bf16 v[22:25], v[150:153], v[220:223], v[22:25]
	v_mfma_f32_16x16x32_bf16 v[18:21], v[188:191], v[220:223], v[18:21]
	v_mfma_f32_16x16x32_bf16 v[6:9], v[150:153], v[228:231], v[6:9]
	v_mfma_f32_16x16x32_bf16 v[2:5], v[188:191], v[228:231], v[2:5]
	s_setprio 0
	s_barrier
	s_add_u32 s4, s4, 0x100
	s_addc_u32 s5, s5, 0
	s_add_u32 s8, s8, 0x100
	s_addc_u32 s9, s9, 0
	s_cmp_ge_i32 s11, s26
	s_mov_b32 s6, s11
	s_cbranch_scc0 .LBB0_408

.LBB0_895:
	v_add_u32_e32 v158, s84, v227
	v_add_u32_e32 v174, s85, v227
	ds_read_b128 v[146:149], v158
	ds_read_b128 v[150:153], v158 offset:1024
	ds_read_b128 v[154:157], v158 offset:2048
	ds_read_b128 v[158:161], v158 offset:3072
	ds_read_b128 v[162:165], v174
	ds_read_b128 v[166:169], v174 offset:1024
	ds_read_b128 v[170:173], v174 offset:2048
	ds_read_b128 v[174:177], v174 offset:3072
	s_add_i32 s16, s50, 2
	s_add_u32 s17, s46, 0x80
	s_addc_u32 s51, s47, 0
	s_cmp_eq_u32 s81, s50
	s_cselect_b32 s50, s4, s17
	s_cselect_b32 s51, s5, s51
	s_cselect_b32 s55, s45, vcc_hi
	s_cselect_b32 s54, s44, vcc_lo
	v_lshl_add_u64 v[210:211], s[46:47], 0, v[138:139]
	s_add_i32 m0, s63, 0xc000
	ds_read_b128 v[178:181], v229
	ds_read_b128 v[182:185], v229 offset:1024
	ds_read_b128 v[186:189], v229 offset:2048
	ds_read_b128 v[190:193], v229 offset:3072
	ds_read_b128 v[194:197], v229 offset:4096
	ds_read_b128 v[198:201], v229 offset:5120
	ds_read_b128 v[202:205], v229 offset:6144
	ds_read_b128 v[206:209], v229 offset:7168
	global_load_lds_dwordx4 v[210:211], off
	v_lshl_add_u64 v[210:211], s[46:47], 0, v[140:141]
	s_add_i32 m0, s63, 0xe000
	s_nop 0
	global_load_lds_dwordx4 v[210:211], off
	s_waitcnt vmcnt(8)
	s_waitcnt lgkmcnt(0)
	s_setprio 1
	v_mfma_i32_16x16x64_i8 v[126:129], v[146:149], v[178:181], v[126:129]
	v_mfma_i32_16x16x64_i8 v[122:125], v[154:157], v[178:181], v[122:125]
	s_barrier
	v_mfma_i32_16x16x64_i8 v[118:121], v[146:149], v[186:189], v[118:121]
	v_mfma_i32_16x16x64_i8 v[114:117], v[154:157], v[186:189], v[114:117]
	v_mfma_i32_16x16x64_i8 v[106:109], v[146:149], v[194:197], v[106:109]
	v_mfma_i32_16x16x64_i8 v[98:101], v[154:157], v[194:197], v[98:101]
	v_mfma_i32_16x16x64_i8 v[90:93], v[146:149], v[202:205], v[90:93]
	v_mfma_i32_16x16x64_i8 v[82:85], v[154:157], v[202:205], v[82:85]
	v_mfma_i32_16x16x64_i8 v[126:129], v[150:153], v[182:185], v[126:129]
	v_mfma_i32_16x16x64_i8 v[122:125], v[158:161], v[182:185], v[122:125]
	v_mfma_i32_16x16x64_i8 v[118:121], v[150:153], v[190:193], v[118:121]
	v_mfma_i32_16x16x64_i8 v[114:117], v[158:161], v[190:193], v[114:117]
	v_mfma_i32_16x16x64_i8 v[106:109], v[150:153], v[198:201], v[106:109]
	v_mfma_i32_16x16x64_i8 v[98:101], v[158:161], v[198:201], v[98:101]
	v_mfma_i32_16x16x64_i8 v[90:93], v[150:153], v[206:209], v[90:93]
	v_mfma_i32_16x16x64_i8 v[82:85], v[158:161], v[206:209], v[82:85]
	v_mfma_i32_16x16x64_i8 v[110:113], v[162:165], v[178:181], v[110:113]
	v_mfma_i32_16x16x64_i8 v[102:105], v[170:173], v[178:181], v[102:105]
	v_mfma_i32_16x16x64_i8 v[94:97], v[162:165], v[186:189], v[94:97]
	v_mfma_i32_16x16x64_i8 v[86:89], v[170:173], v[186:189], v[86:89]
	v_mfma_i32_16x16x64_i8 v[78:81], v[162:165], v[194:197], v[78:81]
	v_mfma_i32_16x16x64_i8 v[74:77], v[170:173], v[194:197], v[74:77]
	v_mfma_i32_16x16x64_i8 v[70:73], v[162:165], v[202:205], v[70:73]
	v_mfma_i32_16x16x64_i8 v[66:69], v[170:173], v[202:205], v[66:69]
	v_mfma_i32_16x16x64_i8 v[110:113], v[166:169], v[182:185], v[110:113]
	v_mfma_i32_16x16x64_i8 v[102:105], v[174:177], v[182:185], v[102:105]
	v_mfma_i32_16x16x64_i8 v[94:97], v[166:169], v[190:193], v[94:97]
	v_mfma_i32_16x16x64_i8 v[86:89], v[174:177], v[190:193], v[86:89]
	v_mfma_i32_16x16x64_i8 v[78:81], v[166:169], v[198:201], v[78:81]
	v_mfma_i32_16x16x64_i8 v[74:77], v[174:177], v[198:201], v[74:77]
	v_mfma_i32_16x16x64_i8 v[70:73], v[166:169], v[206:209], v[70:73]
	v_mfma_i32_16x16x64_i8 v[66:69], v[174:177], v[206:209], v[66:69]
	s_setprio 0
	s_barrier
	s_add_i32 s17, s84, s62
	v_lshl_add_u64 v[210:211], s[54:55], 0, v[132:133]
	s_mov_b32 m0, s17
	ds_read_b128 v[178:181], v229 offset:16384
	ds_read_b128 v[182:185], v229 offset:17408
	ds_read_b128 v[186:189], v229 offset:18432
	ds_read_b128 v[190:193], v229 offset:19456
	ds_read_b128 v[194:197], v229 offset:20480
	ds_read_b128 v[198:201], v229 offset:21504
	ds_read_b128 v[202:205], v229 offset:22528
	ds_read_b128 v[206:209], v229 offset:23552
	global_load_lds_dwordx4 v[210:211], off
	s_add_i32 m0, s17, 0x2000
	v_lshl_add_u64 v[212:213], s[54:55], 0, v[136:137]
	s_add_u32 s54, s54, s8
	s_addc_u32 s55, s55, s9
	s_add_i32 s17, s85, s62
	global_load_lds_dwordx4 v[212:213], off
	v_lshl_add_u64 v[214:215], s[54:55], 0, v[132:133]
	s_mov_b32 m0, s17
	v_lshl_add_u64 v[216:217], s[54:55], 0, v[136:137]
	global_load_lds_dwordx4 v[214:215], off
	s_add_i32 m0, s17, 0x2000
	v_lshl_add_u64 v[218:219], s[50:51], 0, v[130:131]
	global_load_lds_dwordx4 v[216:217], off
	s_mov_b32 m0, s63
	v_lshl_add_u64 v[220:221], s[50:51], 0, v[134:135]
	global_load_lds_dwordx4 v[218:219], off
	s_mov_b32 m0, s64
	s_nop 0
	global_load_lds_dwordx4 v[220:221], off
	s_waitcnt vmcnt(8)
	s_waitcnt lgkmcnt(0)
	s_setprio 1
	v_mfma_i32_16x16x64_i8 v[62:65], v[146:149], v[178:181], v[62:65]
	v_mfma_i32_16x16x64_i8 v[58:61], v[154:157], v[178:181], v[58:61]
	s_barrier
	v_mfma_i32_16x16x64_i8 v[54:57], v[146:149], v[186:189], v[54:57]
	v_mfma_i32_16x16x64_i8 v[50:53], v[154:157], v[186:189], v[50:53]
	v_mfma_i32_16x16x64_i8 v[42:45], v[146:149], v[194:197], v[42:45]
	v_mfma_i32_16x16x64_i8 v[34:37], v[154:157], v[194:197], v[34:37]
	v_mfma_i32_16x16x64_i8 v[26:29], v[146:149], v[202:205], v[26:29]
	v_mfma_i32_16x16x64_i8 v[18:21], v[154:157], v[202:205], v[18:21]
	v_mfma_i32_16x16x64_i8 v[62:65], v[150:153], v[182:185], v[62:65]
	v_mfma_i32_16x16x64_i8 v[58:61], v[158:161], v[182:185], v[58:61]
	v_mfma_i32_16x16x64_i8 v[54:57], v[150:153], v[190:193], v[54:57]
	v_mfma_i32_16x16x64_i8 v[50:53], v[158:161], v[190:193], v[50:53]
	v_mfma_i32_16x16x64_i8 v[42:45], v[150:153], v[198:201], v[42:45]
	v_mfma_i32_16x16x64_i8 v[34:37], v[158:161], v[198:201], v[34:37]
	v_mfma_i32_16x16x64_i8 v[26:29], v[150:153], v[206:209], v[26:29]
	v_mfma_i32_16x16x64_i8 v[18:21], v[158:161], v[206:209], v[18:21]
	v_mfma_i32_16x16x64_i8 v[46:49], v[162:165], v[178:181], v[46:49]
	v_mfma_i32_16x16x64_i8 v[38:41], v[170:173], v[178:181], v[38:41]
	v_mfma_i32_16x16x64_i8 v[30:33], v[162:165], v[186:189], v[30:33]
	v_mfma_i32_16x16x64_i8 v[22:25], v[170:173], v[186:189], v[22:25]
	v_mfma_i32_16x16x64_i8 v[14:17], v[162:165], v[194:197], v[14:17]
	v_mfma_i32_16x16x64_i8 v[10:13], v[170:173], v[194:197], v[10:13]
	v_mfma_i32_16x16x64_i8 v[6:9], v[162:165], v[202:205], v[6:9]
	v_mfma_i32_16x16x64_i8 v[2:5], v[170:173], v[202:205], v[2:5]
	v_mfma_i32_16x16x64_i8 v[46:49], v[166:169], v[182:185], v[46:49]
	v_mfma_i32_16x16x64_i8 v[38:41], v[174:177], v[182:185], v[38:41]
	v_mfma_i32_16x16x64_i8 v[30:33], v[166:169], v[190:193], v[30:33]
	v_mfma_i32_16x16x64_i8 v[22:25], v[174:177], v[190:193], v[22:25]
	v_mfma_i32_16x16x64_i8 v[14:17], v[166:169], v[198:201], v[14:17]
	v_mfma_i32_16x16x64_i8 v[10:13], v[174:177], v[198:201], v[10:13]
	v_mfma_i32_16x16x64_i8 v[6:9], v[166:169], v[206:209], v[6:9]
	v_mfma_i32_16x16x64_i8 v[2:5], v[174:177], v[206:209], v[2:5]
	s_setprio 0
	s_barrier
	s_add_i32 s17, 0, 0x18000
	s_add_i32 s54, 0, 0x1c000
	v_add_u32_e32 v158, s17, v227
	v_add_u32_e32 v174, s54, v227
	ds_read_b128 v[146:149], v158
	ds_read_b128 v[150:153], v158 offset:1024
	ds_read_b128 v[154:157], v158 offset:2048
	ds_read_b128 v[158:161], v158 offset:3072
	ds_read_b128 v[162:165], v174
	ds_read_b128 v[166:169], v174 offset:1024
	ds_read_b128 v[170:173], v174 offset:2048
	ds_read_b128 v[174:177], v174 offset:3072
	s_add_u32 s50, s50, s8
	s_addc_u32 s51, s51, s9
	s_mov_b32 m0, s65
	v_lshl_add_u64 v[222:223], s[50:51], 0, v[130:131]
	ds_read_b128 v[178:181], v229 offset:32768
	ds_read_b128 v[182:185], v229 offset:33792
	ds_read_b128 v[186:189], v229 offset:34816
	ds_read_b128 v[190:193], v229 offset:35840
	ds_read_b128 v[194:197], v229 offset:36864
	ds_read_b128 v[198:201], v229 offset:37888
	ds_read_b128 v[202:205], v229 offset:38912
	ds_read_b128 v[206:209], v229 offset:39936
	global_load_lds_dwordx4 v[222:223], off
	v_lshl_add_u64 v[222:223], s[50:51], 0, v[134:135]
	s_mov_b32 m0, s86
	s_nop 0
	global_load_lds_dwordx4 v[222:223], off
	s_waitcnt vmcnt(8)
	s_waitcnt lgkmcnt(0)
	s_setprio 1
	v_mfma_i32_16x16x64_i8 v[126:129], v[146:149], v[178:181], v[126:129]
	v_mfma_i32_16x16x64_i8 v[122:125], v[154:157], v[178:181], v[122:125]
	s_barrier
	v_mfma_i32_16x16x64_i8 v[118:121], v[146:149], v[186:189], v[118:121]
	v_mfma_i32_16x16x64_i8 v[114:117], v[154:157], v[186:189], v[114:117]
	v_mfma_i32_16x16x64_i8 v[106:109], v[146:149], v[194:197], v[106:109]
	v_mfma_i32_16x16x64_i8 v[98:101], v[154:157], v[194:197], v[98:101]
	v_mfma_i32_16x16x64_i8 v[90:93], v[146:149], v[202:205], v[90:93]
	v_mfma_i32_16x16x64_i8 v[82:85], v[154:157], v[202:205], v[82:85]
	v_mfma_i32_16x16x64_i8 v[126:129], v[150:153], v[182:185], v[126:129]
	v_mfma_i32_16x16x64_i8 v[122:125], v[158:161], v[182:185], v[122:125]
	v_mfma_i32_16x16x64_i8 v[118:121], v[150:153], v[190:193], v[118:121]
	v_mfma_i32_16x16x64_i8 v[114:117], v[158:161], v[190:193], v[114:117]
	v_mfma_i32_16x16x64_i8 v[106:109], v[150:153], v[198:201], v[106:109]
	v_mfma_i32_16x16x64_i8 v[98:101], v[158:161], v[198:201], v[98:101]
	v_mfma_i32_16x16x64_i8 v[90:93], v[150:153], v[206:209], v[90:93]
	v_mfma_i32_16x16x64_i8 v[82:85], v[158:161], v[206:209], v[82:85]
	v_mfma_i32_16x16x64_i8 v[110:113], v[162:165], v[178:181], v[110:113]
	v_mfma_i32_16x16x64_i8 v[102:105], v[170:173], v[178:181], v[102:105]
	v_mfma_i32_16x16x64_i8 v[94:97], v[162:165], v[186:189], v[94:97]
	v_mfma_i32_16x16x64_i8 v[86:89], v[170:173], v[186:189], v[86:89]
	v_mfma_i32_16x16x64_i8 v[78:81], v[162:165], v[194:197], v[78:81]
	v_mfma_i32_16x16x64_i8 v[74:77], v[170:173], v[194:197], v[74:77]
	v_mfma_i32_16x16x64_i8 v[70:73], v[162:165], v[202:205], v[70:73]
	v_mfma_i32_16x16x64_i8 v[66:69], v[170:173], v[202:205], v[66:69]
	v_mfma_i32_16x16x64_i8 v[110:113], v[166:169], v[182:185], v[110:113]
	v_mfma_i32_16x16x64_i8 v[102:105], v[174:177], v[182:185], v[102:105]
	v_mfma_i32_16x16x64_i8 v[94:97], v[166:169], v[190:193], v[94:97]
	v_mfma_i32_16x16x64_i8 v[86:89], v[174:177], v[190:193], v[86:89]
	v_mfma_i32_16x16x64_i8 v[78:81], v[166:169], v[198:201], v[78:81]
	v_mfma_i32_16x16x64_i8 v[74:77], v[174:177], v[198:201], v[74:77]
	v_mfma_i32_16x16x64_i8 v[70:73], v[166:169], v[206:209], v[70:73]
	v_mfma_i32_16x16x64_i8 v[66:69], v[174:177], v[206:209], v[66:69]
	s_setprio 0
	s_barrier
	s_add_i32 s17, s17, s62
	v_lshl_add_u64 v[210:211], v[210:211], 0, s[36:37]
	s_mov_b32 m0, s17
	ds_read_b128 v[178:181], v229 offset:49152
	ds_read_b128 v[182:185], v229 offset:50176
	ds_read_b128 v[186:189], v229 offset:51200
	ds_read_b128 v[190:193], v229 offset:52224
	ds_read_b128 v[194:197], v229 offset:53248
	ds_read_b128 v[198:201], v229 offset:54272
	ds_read_b128 v[202:205], v229 offset:55296
	ds_read_b128 v[206:209], v229 offset:56320
	global_load_lds_dwordx4 v[210:211], off
	v_lshl_add_u64 v[210:211], v[212:213], 0, s[36:37]
	s_add_i32 m0, s17, 0x2000
	s_add_i32 s17, s54, s62
	global_load_lds_dwordx4 v[210:211], off
	v_lshl_add_u64 v[210:211], v[214:215], 0, s[36:37]
	s_mov_b32 m0, s17
	s_nop 0
	global_load_lds_dwordx4 v[210:211], off
	v_lshl_add_u64 v[210:211], v[216:217], 0, s[36:37]
	s_add_i32 m0, s17, 0x2000
	s_nop 0
	global_load_lds_dwordx4 v[210:211], off
	v_lshl_add_u64 v[210:211], v[218:219], 0, s[36:37]
	s_mov_b32 m0, s95
	s_nop 0
	global_load_lds_dwordx4 v[210:211], off
	v_lshl_add_u64 v[210:211], v[220:221], 0, s[36:37]
	s_mov_b32 m0, s80
	s_nop 0
	global_load_lds_dwordx4 v[210:211], off
	s_waitcnt vmcnt(8)
	s_waitcnt lgkmcnt(0)
	s_setprio 1
	v_mfma_i32_16x16x64_i8 v[62:65], v[146:149], v[178:181], v[62:65]
	v_mfma_i32_16x16x64_i8 v[58:61], v[154:157], v[178:181], v[58:61]
	s_barrier
	v_mfma_i32_16x16x64_i8 v[54:57], v[146:149], v[186:189], v[54:57]
	v_mfma_i32_16x16x64_i8 v[50:53], v[154:157], v[186:189], v[50:53]
	v_mfma_i32_16x16x64_i8 v[42:45], v[146:149], v[194:197], v[42:45]
	v_mfma_i32_16x16x64_i8 v[34:37], v[154:157], v[194:197], v[34:37]
	v_mfma_i32_16x16x64_i8 v[26:29], v[146:149], v[202:205], v[26:29]
	v_mfma_i32_16x16x64_i8 v[18:21], v[154:157], v[202:205], v[18:21]
	v_mfma_i32_16x16x64_i8 v[62:65], v[150:153], v[182:185], v[62:65]
	v_mfma_i32_16x16x64_i8 v[58:61], v[158:161], v[182:185], v[58:61]
	v_mfma_i32_16x16x64_i8 v[54:57], v[150:153], v[190:193], v[54:57]
	v_mfma_i32_16x16x64_i8 v[50:53], v[158:161], v[190:193], v[50:53]
	v_mfma_i32_16x16x64_i8 v[42:45], v[150:153], v[198:201], v[42:45]
	v_mfma_i32_16x16x64_i8 v[34:37], v[158:161], v[198:201], v[34:37]
	v_mfma_i32_16x16x64_i8 v[26:29], v[150:153], v[206:209], v[26:29]
	v_mfma_i32_16x16x64_i8 v[18:21], v[158:161], v[206:209], v[18:21]
	v_mfma_i32_16x16x64_i8 v[46:49], v[162:165], v[178:181], v[46:49]
	v_mfma_i32_16x16x64_i8 v[38:41], v[170:173], v[178:181], v[38:41]
	v_mfma_i32_16x16x64_i8 v[30:33], v[162:165], v[186:189], v[30:33]
	v_mfma_i32_16x16x64_i8 v[22:25], v[170:173], v[186:189], v[22:25]
	v_mfma_i32_16x16x64_i8 v[14:17], v[162:165], v[194:197], v[14:17]
	v_mfma_i32_16x16x64_i8 v[10:13], v[170:173], v[194:197], v[10:13]
	v_mfma_i32_16x16x64_i8 v[6:9], v[162:165], v[202:205], v[6:9]
	v_mfma_i32_16x16x64_i8 v[2:5], v[170:173], v[202:205], v[2:5]
	v_mfma_i32_16x16x64_i8 v[46:49], v[166:169], v[182:185], v[46:49]
	v_mfma_i32_16x16x64_i8 v[38:41], v[174:177], v[182:185], v[38:41]
	v_mfma_i32_16x16x64_i8 v[30:33], v[166:169], v[190:193], v[30:33]
	v_mfma_i32_16x16x64_i8 v[22:25], v[174:177], v[190:193], v[22:25]
	v_mfma_i32_16x16x64_i8 v[14:17], v[166:169], v[198:201], v[14:17]
	v_mfma_i32_16x16x64_i8 v[10:13], v[174:177], v[198:201], v[10:13]
	v_mfma_i32_16x16x64_i8 v[6:9], v[166:169], v[206:209], v[6:9]
	v_mfma_i32_16x16x64_i8 v[2:5], v[174:177], v[206:209], v[2:5]
	s_setprio 0
	s_barrier
	s_add_u32 s46, s46, 0x100
	s_addc_u32 s47, s47, 0
	s_add_u32 vcc_lo, vcc_lo, 0x100
	s_addc_u32 vcc_hi, vcc_hi, 0
	s_cmp_ge_i32 s16, s90
	s_mov_b32 s50, s16
	s_cbranch_scc0 .LBB0_895
	v_cvt_f32_i32_e32 v220, v126
	v_cvt_f32_i32_e32 v221, v127
	v_cvt_f32_i32_e32 v218, v128
	v_cvt_f32_i32_e32 v219, v129
	v_cvt_f32_i32_e32 v224, v122
	v_cvt_f32_i32_e32 v225, v123
	v_cvt_f32_i32_e32 v222, v124
	v_cvt_f32_i32_e32 v223, v125
	v_cvt_f32_i32_e32 v212, v110
	v_cvt_f32_i32_e32 v213, v111
	v_cvt_f32_i32_e32 v210, v112
	v_cvt_f32_i32_e32 v211, v113
	v_cvt_f32_i32_e32 v216, v102
	v_cvt_f32_i32_e32 v217, v103
	v_cvt_f32_i32_e32 v214, v104
	v_cvt_f32_i32_e32 v215, v105
	v_cvt_f32_i32_e32 v204, v118
	v_cvt_f32_i32_e32 v205, v119
	v_cvt_f32_i32_e32 v202, v120
	v_cvt_f32_i32_e32 v203, v121
	v_cvt_f32_i32_e32 v208, v114
	v_cvt_f32_i32_e32 v209, v115
	v_cvt_f32_i32_e32 v206, v116
	v_cvt_f32_i32_e32 v207, v117
	v_cvt_f32_i32_e32 v198, v94
	v_cvt_f32_i32_e32 v199, v95
	v_cvt_f32_i32_e32 v194, v96
	v_cvt_f32_i32_e32 v195, v97
	v_cvt_f32_i32_e32 v200, v86
	v_cvt_f32_i32_e32 v201, v87
	v_cvt_f32_i32_e32 v196, v88
	v_cvt_f32_i32_e32 v197, v89
	v_cvt_f32_i32_e32 v188, v106
	v_cvt_f32_i32_e32 v189, v107
	v_cvt_f32_i32_e32 v186, v108
	v_cvt_f32_i32_e32 v187, v109
	v_cvt_f32_i32_e32 v192, v98
	v_cvt_f32_i32_e32 v193, v99
	v_cvt_f32_i32_e32 v190, v100
	v_cvt_f32_i32_e32 v191, v101
	v_cvt_f32_i32_e32 v182, v78
	v_cvt_f32_i32_e32 v183, v79
	v_cvt_f32_i32_e32 v178, v80
	v_cvt_f32_i32_e32 v179, v81
	v_cvt_f32_i32_e32 v184, v74
	v_cvt_f32_i32_e32 v185, v75
	v_cvt_f32_i32_e32 v180, v76
	v_cvt_f32_i32_e32 v181, v77
	v_cvt_f32_i32_e32 v170, v90
	v_cvt_f32_i32_e32 v171, v91
	v_cvt_f32_i32_e32 v168, v92
	v_cvt_f32_i32_e32 v169, v93
	v_cvt_f32_i32_e32 v174, v82
	v_cvt_f32_i32_e32 v175, v83
	v_cvt_f32_i32_e32 v172, v84
	v_cvt_f32_i32_e32 v173, v85
	v_cvt_f32_i32_e32 v164, v70
	v_cvt_f32_i32_e32 v165, v71
	v_cvt_f32_i32_e32 v160, v72
	v_cvt_f32_i32_e32 v161, v73
	v_cvt_f32_i32_e32 v166, v66
	v_cvt_f32_i32_e32 v167, v67
	v_cvt_f32_i32_e32 v162, v68
	v_cvt_f32_i32_e32 v163, v69
	v_cvt_f32_i32_e32 v154, v62
	v_cvt_f32_i32_e32 v155, v63
	v_cvt_f32_i32_e32 v152, v64
	v_cvt_f32_i32_e32 v153, v65
	v_cvt_f32_i32_e32 v158, v58
	v_cvt_f32_i32_e32 v159, v59
	v_cvt_f32_i32_e32 v156, v60
	v_cvt_f32_i32_e32 v157, v61
	v_cvt_f32_i32_e32 v148, v46
	v_cvt_f32_i32_e32 v149, v47
	v_cvt_f32_i32_e32 v128, v48
	v_cvt_f32_i32_e32 v129, v49
	v_cvt_f32_i32_e32 v150, v38
	v_cvt_f32_i32_e32 v151, v39
	v_cvt_f32_i32_e32 v146, v40
	v_cvt_f32_i32_e32 v147, v41
	v_cvt_f32_i32_e32 v122, v54
	v_cvt_f32_i32_e32 v123, v55
	v_cvt_f32_i32_e32 v120, v56
	v_cvt_f32_i32_e32 v121, v57
	v_cvt_f32_i32_e32 v126, v50
	v_cvt_f32_i32_e32 v127, v51
	v_cvt_f32_i32_e32 v124, v52
	v_cvt_f32_i32_e32 v125, v53
	v_cvt_f32_i32_e32 v114, v30
	v_cvt_f32_i32_e32 v115, v31
	v_cvt_f32_i32_e32 v110, v32
	v_cvt_f32_i32_e32 v111, v33
	v_cvt_f32_i32_e32 v116, v22
	v_cvt_f32_i32_e32 v117, v23
	v_cvt_f32_i32_e32 v112, v24
	v_cvt_f32_i32_e32 v113, v25
	v_cvt_f32_i32_e32 v102, v42
	v_cvt_f32_i32_e32 v103, v43
	v_cvt_f32_i32_e32 v100, v44
	v_cvt_f32_i32_e32 v101, v45
	v_cvt_f32_i32_e32 v106, v34
	v_cvt_f32_i32_e32 v107, v35
	v_cvt_f32_i32_e32 v104, v36
	v_cvt_f32_i32_e32 v105, v37
	v_cvt_f32_i32_e32 v96, v14
	v_cvt_f32_i32_e32 v97, v15
	v_cvt_f32_i32_e32 v92, v16
	v_cvt_f32_i32_e32 v93, v17
	v_cvt_f32_i32_e32 v98, v10
	v_cvt_f32_i32_e32 v99, v11
	v_cvt_f32_i32_e32 v94, v12
	v_cvt_f32_i32_e32 v95, v13
	v_cvt_f32_i32_e32 v52, v26
	v_cvt_f32_i32_e32 v53, v27
	v_cvt_f32_i32_e32 v50, v28
	v_cvt_f32_i32_e32 v51, v29
	v_cvt_f32_i32_e32 v56, v18
	v_cvt_f32_i32_e32 v57, v19
	v_cvt_f32_i32_e32 v54, v20
	v_cvt_f32_i32_e32 v55, v21
	v_cvt_f32_i32_e32 v46, v6
	v_cvt_f32_i32_e32 v47, v7
	v_cvt_f32_i32_e32 v42, v8
	v_cvt_f32_i32_e32 v43, v9
	v_cvt_f32_i32_e32 v48, v2
	v_cvt_f32_i32_e32 v49, v3
	v_cvt_f32_i32_e32 v44, v4
	v_cvt_f32_i32_e32 v45, v5

.LBB0_1087:
	v_add_u32_e32 v138, s80, v188
	ds_read_b128 v[148:151], v138
	ds_read_b128 v[152:155], v138 offset:1024
	ds_read_b128 v[156:159], v138 offset:2048
	ds_read_b128 v[160:163], v138 offset:3072
	v_add_u32_e32 v138, s81, v188
	ds_read_b128 v[164:167], v138
	ds_read_b128 v[168:171], v138 offset:1024
	ds_read_b128 v[172:175], v138 offset:2048
	ds_read_b128 v[176:179], v138 offset:3072
	s_add_i32 s84, s34, 2
	s_add_u32 s85, s30, 0x80
	s_addc_u32 s35, s31, 0
	s_cmp_eq_u32 s64, s34
	s_cselect_b32 s34, s2, s85
	s_cselect_b32 s35, s3, s35
	s_cselect_b32 s87, s29, s39
	s_cselect_b32 s86, s28, s38
	v_lshl_add_u64 v[184:185], s[30:31], 0, v[140:141]
	s_add_i32 m0, s50, 0xc000
	ds_read_b128 v[180:183], v189
	ds_read_b128 v[190:193], v189 offset:1024
	ds_read_b128 v[194:197], v189 offset:2048
	ds_read_b128 v[198:201], v189 offset:3072
	ds_read_b128 v[202:205], v189 offset:4096
	ds_read_b128 v[206:209], v189 offset:5120
	ds_read_b128 v[210:213], v189 offset:6144
	ds_read_b128 v[214:217], v189 offset:7168
	global_load_lds_dwordx4 v[184:185], off
	v_lshl_add_u64 v[184:185], s[30:31], 0, v[142:143]
	s_add_i32 m0, s50, 0xe000
	s_nop 0
	global_load_lds_dwordx4 v[184:185], off
	s_waitcnt vmcnt(8)
	s_waitcnt lgkmcnt(0)
	s_setprio 1
	v_mfma_i32_16x16x64_i8 v[126:129], v[148:151], v[180:183], v[126:129]
	v_mfma_i32_16x16x64_i8 v[122:125], v[156:159], v[180:183], v[122:125]
	s_barrier
	v_mfma_i32_16x16x64_i8 v[118:121], v[148:151], v[194:197], v[118:121]
	v_mfma_i32_16x16x64_i8 v[114:117], v[156:159], v[194:197], v[114:117]
	v_mfma_i32_16x16x64_i8 v[106:109], v[148:151], v[202:205], v[106:109]
	v_mfma_i32_16x16x64_i8 v[98:101], v[156:159], v[202:205], v[98:101]
	v_mfma_i32_16x16x64_i8 v[90:93], v[148:151], v[210:213], v[90:93]
	v_mfma_i32_16x16x64_i8 v[82:85], v[156:159], v[210:213], v[82:85]
	v_mfma_i32_16x16x64_i8 v[126:129], v[152:155], v[190:193], v[126:129]
	v_mfma_i32_16x16x64_i8 v[122:125], v[160:163], v[190:193], v[122:125]
	v_mfma_i32_16x16x64_i8 v[118:121], v[152:155], v[198:201], v[118:121]
	v_mfma_i32_16x16x64_i8 v[114:117], v[160:163], v[198:201], v[114:117]
	v_mfma_i32_16x16x64_i8 v[106:109], v[152:155], v[206:209], v[106:109]
	v_mfma_i32_16x16x64_i8 v[98:101], v[160:163], v[206:209], v[98:101]
	v_mfma_i32_16x16x64_i8 v[90:93], v[152:155], v[214:217], v[90:93]
	v_mfma_i32_16x16x64_i8 v[82:85], v[160:163], v[214:217], v[82:85]
	v_mfma_i32_16x16x64_i8 v[110:113], v[164:167], v[180:183], v[110:113]
	v_mfma_i32_16x16x64_i8 v[102:105], v[172:175], v[180:183], v[102:105]
	v_mfma_i32_16x16x64_i8 v[94:97], v[164:167], v[194:197], v[94:97]
	v_mfma_i32_16x16x64_i8 v[86:89], v[172:175], v[194:197], v[86:89]
	v_mfma_i32_16x16x64_i8 v[78:81], v[164:167], v[202:205], v[78:81]
	v_mfma_i32_16x16x64_i8 v[74:77], v[172:175], v[202:205], v[74:77]
	v_mfma_i32_16x16x64_i8 v[70:73], v[164:167], v[210:213], v[70:73]
	v_mfma_i32_16x16x64_i8 v[66:69], v[172:175], v[210:213], v[66:69]
	v_mfma_i32_16x16x64_i8 v[110:113], v[168:171], v[190:193], v[110:113]
	v_mfma_i32_16x16x64_i8 v[102:105], v[176:179], v[190:193], v[102:105]
	v_mfma_i32_16x16x64_i8 v[94:97], v[168:171], v[198:201], v[94:97]
	v_mfma_i32_16x16x64_i8 v[86:89], v[176:179], v[198:201], v[86:89]
	v_mfma_i32_16x16x64_i8 v[78:81], v[168:171], v[206:209], v[78:81]
	v_mfma_i32_16x16x64_i8 v[74:77], v[176:179], v[206:209], v[74:77]
	v_mfma_i32_16x16x64_i8 v[70:73], v[168:171], v[214:217], v[70:73]
	v_mfma_i32_16x16x64_i8 v[66:69], v[176:179], v[214:217], v[66:69]
	s_setprio 0
	s_barrier
	s_add_i32 s85, s80, s47
	v_lshl_add_u64 v[184:185], s[86:87], 0, v[132:133]
	s_mov_b32 m0, s85
	ds_read_b128 v[180:183], v189 offset:16384
	ds_read_b128 v[190:193], v189 offset:17408
	ds_read_b128 v[194:197], v189 offset:18432
	ds_read_b128 v[198:201], v189 offset:19456
	ds_read_b128 v[202:205], v189 offset:20480
	ds_read_b128 v[206:209], v189 offset:21504
	ds_read_b128 v[210:213], v189 offset:22528
	ds_read_b128 v[214:217], v189 offset:23552
	global_load_lds_dwordx4 v[184:185], off
	s_add_i32 m0, s85, 0x2000
	v_lshl_add_u64 v[218:219], s[86:87], 0, v[136:137]
	s_add_u32 s86, s86, s6
	s_addc_u32 s87, s87, s7
	s_add_i32 s85, s81, s47
	global_load_lds_dwordx4 v[218:219], off
	v_lshl_add_u64 v[220:221], s[86:87], 0, v[132:133]
	s_mov_b32 m0, s85
	v_lshl_add_u64 v[222:223], s[86:87], 0, v[136:137]
	global_load_lds_dwordx4 v[220:221], off
	s_add_i32 m0, s85, 0x2000
	v_lshl_add_u64 v[224:225], s[34:35], 0, v[130:131]
	global_load_lds_dwordx4 v[222:223], off
	s_mov_b32 m0, s50
	v_lshl_add_u64 v[226:227], s[34:35], 0, v[134:135]
	global_load_lds_dwordx4 v[224:225], off
	s_mov_b32 m0, s51
	s_nop 0
	global_load_lds_dwordx4 v[226:227], off
	s_waitcnt vmcnt(8)
	s_waitcnt lgkmcnt(0)
	s_setprio 1
	v_mfma_i32_16x16x64_i8 v[62:65], v[148:151], v[180:183], v[62:65]
	v_mfma_i32_16x16x64_i8 v[58:61], v[156:159], v[180:183], v[58:61]
	s_barrier
	v_mfma_i32_16x16x64_i8 v[54:57], v[148:151], v[194:197], v[54:57]
	v_mfma_i32_16x16x64_i8 v[50:53], v[156:159], v[194:197], v[50:53]
	v_mfma_i32_16x16x64_i8 v[42:45], v[148:151], v[202:205], v[42:45]
	v_mfma_i32_16x16x64_i8 v[34:37], v[156:159], v[202:205], v[34:37]
	v_mfma_i32_16x16x64_i8 v[26:29], v[148:151], v[210:213], v[26:29]
	v_mfma_i32_16x16x64_i8 v[18:21], v[156:159], v[210:213], v[18:21]
	v_mfma_i32_16x16x64_i8 v[62:65], v[152:155], v[190:193], v[62:65]
	v_mfma_i32_16x16x64_i8 v[58:61], v[160:163], v[190:193], v[58:61]
	v_mfma_i32_16x16x64_i8 v[54:57], v[152:155], v[198:201], v[54:57]
	v_mfma_i32_16x16x64_i8 v[50:53], v[160:163], v[198:201], v[50:53]
	v_mfma_i32_16x16x64_i8 v[42:45], v[152:155], v[206:209], v[42:45]
	v_mfma_i32_16x16x64_i8 v[34:37], v[160:163], v[206:209], v[34:37]
	v_mfma_i32_16x16x64_i8 v[26:29], v[152:155], v[214:217], v[26:29]
	v_mfma_i32_16x16x64_i8 v[18:21], v[160:163], v[214:217], v[18:21]
	v_mfma_i32_16x16x64_i8 v[46:49], v[164:167], v[180:183], v[46:49]
	v_mfma_i32_16x16x64_i8 v[38:41], v[172:175], v[180:183], v[38:41]
	v_mfma_i32_16x16x64_i8 v[30:33], v[164:167], v[194:197], v[30:33]
	v_mfma_i32_16x16x64_i8 v[22:25], v[172:175], v[194:197], v[22:25]
	v_mfma_i32_16x16x64_i8 v[14:17], v[164:167], v[202:205], v[14:17]
	v_mfma_i32_16x16x64_i8 v[10:13], v[172:175], v[202:205], v[10:13]
	v_mfma_i32_16x16x64_i8 v[6:9], v[164:167], v[210:213], v[6:9]
	v_mfma_i32_16x16x64_i8 v[2:5], v[172:175], v[210:213], v[2:5]
	v_mfma_i32_16x16x64_i8 v[46:49], v[168:171], v[190:193], v[46:49]
	v_mfma_i32_16x16x64_i8 v[38:41], v[176:179], v[190:193], v[38:41]
	v_mfma_i32_16x16x64_i8 v[30:33], v[168:171], v[198:201], v[30:33]
	v_mfma_i32_16x16x64_i8 v[22:25], v[176:179], v[198:201], v[22:25]
	v_mfma_i32_16x16x64_i8 v[14:17], v[168:171], v[206:209], v[14:17]
	v_mfma_i32_16x16x64_i8 v[10:13], v[176:179], v[206:209], v[10:13]
	v_mfma_i32_16x16x64_i8 v[6:9], v[168:171], v[214:217], v[6:9]
	v_mfma_i32_16x16x64_i8 v[2:5], v[176:179], v[214:217], v[2:5]
	s_setprio 0
	s_barrier
	s_add_i32 s85, 0, 0x18000
	v_add_u32_e32 v138, s85, v188
	s_add_i32 s86, 0, 0x1c000
	ds_read_b128 v[148:151], v138
	ds_read_b128 v[152:155], v138 offset:1024
	ds_read_b128 v[156:159], v138 offset:2048
	ds_read_b128 v[160:163], v138 offset:3072
	v_add_u32_e32 v138, s86, v188
	ds_read_b128 v[164:167], v138
	ds_read_b128 v[168:171], v138 offset:1024
	ds_read_b128 v[172:175], v138 offset:2048
	ds_read_b128 v[176:179], v138 offset:3072
	s_add_u32 s34, s34, s6
	s_addc_u32 s35, s35, s7
	s_mov_b32 m0, s54
	v_lshl_add_u64 v[228:229], s[34:35], 0, v[130:131]
	ds_read_b128 v[180:183], v189 offset:32768
	ds_read_b128 v[190:193], v189 offset:33792
	ds_read_b128 v[194:197], v189 offset:34816
	ds_read_b128 v[198:201], v189 offset:35840
	ds_read_b128 v[202:205], v189 offset:36864
	ds_read_b128 v[206:209], v189 offset:37888
	ds_read_b128 v[210:213], v189 offset:38912
	ds_read_b128 v[214:217], v189 offset:39936
	global_load_lds_dwordx4 v[228:229], off
	v_lshl_add_u64 v[228:229], s[34:35], 0, v[134:135]
	s_mov_b32 m0, s55
	s_nop 0
	global_load_lds_dwordx4 v[228:229], off
	s_waitcnt vmcnt(8)
	s_waitcnt lgkmcnt(0)
	s_setprio 1
	v_mfma_i32_16x16x64_i8 v[126:129], v[148:151], v[180:183], v[126:129]
	v_mfma_i32_16x16x64_i8 v[122:125], v[156:159], v[180:183], v[122:125]
	s_barrier
	v_mfma_i32_16x16x64_i8 v[118:121], v[148:151], v[194:197], v[118:121]
	v_mfma_i32_16x16x64_i8 v[114:117], v[156:159], v[194:197], v[114:117]
	v_mfma_i32_16x16x64_i8 v[106:109], v[148:151], v[202:205], v[106:109]
	v_mfma_i32_16x16x64_i8 v[98:101], v[156:159], v[202:205], v[98:101]
	v_mfma_i32_16x16x64_i8 v[90:93], v[148:151], v[210:213], v[90:93]
	v_mfma_i32_16x16x64_i8 v[82:85], v[156:159], v[210:213], v[82:85]
	v_mfma_i32_16x16x64_i8 v[126:129], v[152:155], v[190:193], v[126:129]
	v_mfma_i32_16x16x64_i8 v[122:125], v[160:163], v[190:193], v[122:125]
	v_mfma_i32_16x16x64_i8 v[118:121], v[152:155], v[198:201], v[118:121]
	v_mfma_i32_16x16x64_i8 v[114:117], v[160:163], v[198:201], v[114:117]
	v_mfma_i32_16x16x64_i8 v[106:109], v[152:155], v[206:209], v[106:109]
	v_mfma_i32_16x16x64_i8 v[98:101], v[160:163], v[206:209], v[98:101]
	v_mfma_i32_16x16x64_i8 v[90:93], v[152:155], v[214:217], v[90:93]
	v_mfma_i32_16x16x64_i8 v[82:85], v[160:163], v[214:217], v[82:85]
	v_mfma_i32_16x16x64_i8 v[110:113], v[164:167], v[180:183], v[110:113]
	v_mfma_i32_16x16x64_i8 v[102:105], v[172:175], v[180:183], v[102:105]
	v_mfma_i32_16x16x64_i8 v[94:97], v[164:167], v[194:197], v[94:97]
	v_mfma_i32_16x16x64_i8 v[86:89], v[172:175], v[194:197], v[86:89]
	v_mfma_i32_16x16x64_i8 v[78:81], v[164:167], v[202:205], v[78:81]
	v_mfma_i32_16x16x64_i8 v[74:77], v[172:175], v[202:205], v[74:77]
	v_mfma_i32_16x16x64_i8 v[70:73], v[164:167], v[210:213], v[70:73]
	v_mfma_i32_16x16x64_i8 v[66:69], v[172:175], v[210:213], v[66:69]
	v_mfma_i32_16x16x64_i8 v[110:113], v[168:171], v[190:193], v[110:113]
	v_mfma_i32_16x16x64_i8 v[102:105], v[176:179], v[190:193], v[102:105]
	v_mfma_i32_16x16x64_i8 v[94:97], v[168:171], v[198:201], v[94:97]
	v_mfma_i32_16x16x64_i8 v[86:89], v[176:179], v[198:201], v[86:89]
	v_mfma_i32_16x16x64_i8 v[78:81], v[168:171], v[206:209], v[78:81]
	v_mfma_i32_16x16x64_i8 v[74:77], v[176:179], v[206:209], v[74:77]
	v_mfma_i32_16x16x64_i8 v[70:73], v[168:171], v[214:217], v[70:73]
	v_mfma_i32_16x16x64_i8 v[66:69], v[176:179], v[214:217], v[66:69]
	s_setprio 0
	s_barrier
	s_add_i32 s34, s85, s47
	v_lshl_add_u64 v[184:185], v[184:185], 0, s[22:23]
	s_mov_b32 m0, s34
	ds_read_b128 v[180:183], v189 offset:49152
	ds_read_b128 v[190:193], v189 offset:50176
	ds_read_b128 v[194:197], v189 offset:51200
	ds_read_b128 v[198:201], v189 offset:52224
	ds_read_b128 v[202:205], v189 offset:53248
	ds_read_b128 v[206:209], v189 offset:54272
	ds_read_b128 v[210:213], v189 offset:55296
	ds_read_b128 v[214:217], v189 offset:56320
	global_load_lds_dwordx4 v[184:185], off
	v_lshl_add_u64 v[184:185], v[218:219], 0, s[22:23]
	s_add_i32 m0, s34, 0x2000
	s_add_i32 s34, s86, s47
	global_load_lds_dwordx4 v[184:185], off
	v_lshl_add_u64 v[184:185], v[220:221], 0, s[22:23]
	s_mov_b32 m0, s34
	s_nop 0
	global_load_lds_dwordx4 v[184:185], off
	v_lshl_add_u64 v[184:185], v[222:223], 0, s[22:23]
	s_add_i32 m0, s34, 0x2000
	s_nop 0
	global_load_lds_dwordx4 v[184:185], off
	v_lshl_add_u64 v[184:185], v[224:225], 0, s[22:23]
	s_mov_b32 m0, s59
	s_nop 0
	global_load_lds_dwordx4 v[184:185], off
	v_lshl_add_u64 v[184:185], v[226:227], 0, s[22:23]
	s_mov_b32 m0, s60
	s_nop 0
	global_load_lds_dwordx4 v[184:185], off
	s_waitcnt vmcnt(8)
	s_waitcnt lgkmcnt(0)
	s_setprio 1
	v_mfma_i32_16x16x64_i8 v[62:65], v[148:151], v[180:183], v[62:65]
	v_mfma_i32_16x16x64_i8 v[58:61], v[156:159], v[180:183], v[58:61]
	s_barrier
	v_mfma_i32_16x16x64_i8 v[54:57], v[148:151], v[194:197], v[54:57]
	v_mfma_i32_16x16x64_i8 v[50:53], v[156:159], v[194:197], v[50:53]
	v_mfma_i32_16x16x64_i8 v[42:45], v[148:151], v[202:205], v[42:45]
	v_mfma_i32_16x16x64_i8 v[34:37], v[156:159], v[202:205], v[34:37]
	v_mfma_i32_16x16x64_i8 v[26:29], v[148:151], v[210:213], v[26:29]
	v_mfma_i32_16x16x64_i8 v[18:21], v[156:159], v[210:213], v[18:21]
	v_mfma_i32_16x16x64_i8 v[62:65], v[152:155], v[190:193], v[62:65]
	v_mfma_i32_16x16x64_i8 v[58:61], v[160:163], v[190:193], v[58:61]
	v_mfma_i32_16x16x64_i8 v[54:57], v[152:155], v[198:201], v[54:57]
	v_mfma_i32_16x16x64_i8 v[50:53], v[160:163], v[198:201], v[50:53]
	v_mfma_i32_16x16x64_i8 v[42:45], v[152:155], v[206:209], v[42:45]
	v_mfma_i32_16x16x64_i8 v[34:37], v[160:163], v[206:209], v[34:37]
	v_mfma_i32_16x16x64_i8 v[26:29], v[152:155], v[214:217], v[26:29]
	v_mfma_i32_16x16x64_i8 v[18:21], v[160:163], v[214:217], v[18:21]
	v_mfma_i32_16x16x64_i8 v[46:49], v[164:167], v[180:183], v[46:49]
	v_mfma_i32_16x16x64_i8 v[38:41], v[172:175], v[180:183], v[38:41]
	v_mfma_i32_16x16x64_i8 v[30:33], v[164:167], v[194:197], v[30:33]
	v_mfma_i32_16x16x64_i8 v[22:25], v[172:175], v[194:197], v[22:25]
	v_mfma_i32_16x16x64_i8 v[14:17], v[164:167], v[202:205], v[14:17]
	v_mfma_i32_16x16x64_i8 v[10:13], v[172:175], v[202:205], v[10:13]
	v_mfma_i32_16x16x64_i8 v[6:9], v[164:167], v[210:213], v[6:9]
	v_mfma_i32_16x16x64_i8 v[2:5], v[172:175], v[210:213], v[2:5]
	v_mfma_i32_16x16x64_i8 v[46:49], v[168:171], v[190:193], v[46:49]
	v_mfma_i32_16x16x64_i8 v[38:41], v[176:179], v[190:193], v[38:41]
	v_mfma_i32_16x16x64_i8 v[30:33], v[168:171], v[198:201], v[30:33]
	v_mfma_i32_16x16x64_i8 v[22:25], v[176:179], v[198:201], v[22:25]
	v_mfma_i32_16x16x64_i8 v[14:17], v[168:171], v[206:209], v[14:17]
	v_mfma_i32_16x16x64_i8 v[10:13], v[176:179], v[206:209], v[10:13]
	v_mfma_i32_16x16x64_i8 v[6:9], v[168:171], v[214:217], v[6:9]
	v_mfma_i32_16x16x64_i8 v[2:5], v[176:179], v[214:217], v[2:5]
	s_setprio 0
	s_barrier
	s_add_u32 s30, s30, 0x100
	s_addc_u32 s31, s31, 0
	s_add_u32 s38, s38, 0x100
	s_addc_u32 s39, s39, 0
	s_cmp_ge_i32 s84, s61
	s_mov_b32 s34, s84
	s_cbranch_scc0 .LBB0_1087
	v_cvt_f32_i32_e32 v172, v126
	v_cvt_f32_i32_e32 v173, v127
	v_cvt_f32_i32_e32 v170, v128
	v_cvt_f32_i32_e32 v171, v129
	v_cvt_f32_i32_e32 v174, v122
	v_cvt_f32_i32_e32 v175, v123
	v_cvt_f32_i32_e32 v176, v124
	v_cvt_f32_i32_e32 v177, v125
	v_cvt_f32_i32_e32 v180, v110
	v_cvt_f32_i32_e32 v181, v111
	v_cvt_f32_i32_e32 v182, v112
	v_cvt_f32_i32_e32 v183, v113
	v_cvt_f32_i32_e32 v178, v102
	v_cvt_f32_i32_e32 v179, v103
	v_cvt_f32_i32_e32 v184, v104
	v_cvt_f32_i32_e32 v185, v105
	v_cvt_f32_i32_e32 v152, v118
	v_cvt_f32_i32_e32 v153, v119
	v_cvt_f32_i32_e32 v154, v120
	v_cvt_f32_i32_e32 v155, v121
	v_cvt_f32_i32_e32 v156, v114
	v_cvt_f32_i32_e32 v157, v115
	v_cvt_f32_i32_e32 v158, v116
	v_cvt_f32_i32_e32 v159, v117
	v_cvt_f32_i32_e32 v160, v94
	v_cvt_f32_i32_e32 v161, v95
	v_cvt_f32_i32_e32 v162, v96
	v_cvt_f32_i32_e32 v163, v97
	v_cvt_f32_i32_e32 v164, v86
	v_cvt_f32_i32_e32 v165, v87
	v_cvt_f32_i32_e32 v166, v88
	v_cvt_f32_i32_e32 v167, v89
	v_cvt_f32_i32_e32 v118, v106
	v_cvt_f32_i32_e32 v119, v107
	v_cvt_f32_i32_e32 v120, v108
	v_cvt_f32_i32_e32 v121, v109
	v_cvt_f32_i32_e32 v122, v98
	v_cvt_f32_i32_e32 v123, v99
	v_cvt_f32_i32_e32 v124, v100
	v_cvt_f32_i32_e32 v125, v101
	v_cvt_f32_i32_e32 v126, v78
	v_cvt_f32_i32_e32 v127, v79
	v_cvt_f32_i32_e32 v128, v80
	v_cvt_f32_i32_e32 v129, v81
	v_cvt_f32_i32_e32 v148, v74
	v_cvt_f32_i32_e32 v149, v75
	v_cvt_f32_i32_e32 v150, v76
	v_cvt_f32_i32_e32 v151, v77
	v_cvt_f32_i32_e32 v102, v90
	v_cvt_f32_i32_e32 v103, v91
	v_cvt_f32_i32_e32 v104, v92
	v_cvt_f32_i32_e32 v105, v93
	v_cvt_f32_i32_e32 v106, v82
	v_cvt_f32_i32_e32 v107, v83
	v_cvt_f32_i32_e32 v108, v84
	v_cvt_f32_i32_e32 v109, v85
	v_cvt_f32_i32_e32 v110, v70
	v_cvt_f32_i32_e32 v111, v71
	v_cvt_f32_i32_e32 v112, v72
	v_cvt_f32_i32_e32 v113, v73
	v_cvt_f32_i32_e32 v114, v66
	v_cvt_f32_i32_e32 v115, v67
	v_cvt_f32_i32_e32 v116, v68
	v_cvt_f32_i32_e32 v117, v69
	v_cvt_f32_i32_e32 v82, v62
	v_cvt_f32_i32_e32 v83, v63
	v_cvt_f32_i32_e32 v84, v64
	v_cvt_f32_i32_e32 v85, v65
	v_cvt_f32_i32_e32 v86, v58
	v_cvt_f32_i32_e32 v87, v59
	v_cvt_f32_i32_e32 v88, v60
	v_cvt_f32_i32_e32 v89, v61
	v_cvt_f32_i32_e32 v92, v46
	v_cvt_f32_i32_e32 v93, v47
	v_cvt_f32_i32_e32 v94, v48
	v_cvt_f32_i32_e32 v95, v49
	v_cvt_f32_i32_e32 v96, v38
	v_cvt_f32_i32_e32 v97, v39
	v_cvt_f32_i32_e32 v98, v40
	v_cvt_f32_i32_e32 v99, v41
	v_cvt_f32_i32_e32 v66, v54
	v_cvt_f32_i32_e32 v67, v55
	v_cvt_f32_i32_e32 v68, v56
	v_cvt_f32_i32_e32 v69, v57
	v_cvt_f32_i32_e32 v70, v50
	v_cvt_f32_i32_e32 v71, v51
	v_cvt_f32_i32_e32 v72, v52
	v_cvt_f32_i32_e32 v73, v53
	v_cvt_f32_i32_e32 v74, v30
	v_cvt_f32_i32_e32 v75, v31
	v_cvt_f32_i32_e32 v76, v32
	v_cvt_f32_i32_e32 v77, v33
	v_cvt_f32_i32_e32 v78, v22
	v_cvt_f32_i32_e32 v79, v23
	v_cvt_f32_i32_e32 v80, v24
	v_cvt_f32_i32_e32 v81, v25
	v_cvt_f32_i32_e32 v50, v42
	v_cvt_f32_i32_e32 v51, v43
	v_cvt_f32_i32_e32 v52, v44
	v_cvt_f32_i32_e32 v53, v45
	v_cvt_f32_i32_e32 v54, v34
	v_cvt_f32_i32_e32 v55, v35
	v_cvt_f32_i32_e32 v56, v36
	v_cvt_f32_i32_e32 v57, v37
	v_cvt_f32_i32_e32 v58, v14
	v_cvt_f32_i32_e32 v59, v15
	v_cvt_f32_i32_e32 v60, v16
	v_cvt_f32_i32_e32 v61, v17
	v_cvt_f32_i32_e32 v62, v10
	v_cvt_f32_i32_e32 v63, v11
	v_cvt_f32_i32_e32 v64, v12
	v_cvt_f32_i32_e32 v65, v13
	v_cvt_f32_i32_e32 v34, v26
	v_cvt_f32_i32_e32 v35, v27
	v_cvt_f32_i32_e32 v36, v28
	v_cvt_f32_i32_e32 v37, v29
	v_cvt_f32_i32_e32 v38, v18
	v_cvt_f32_i32_e32 v39, v19
	v_cvt_f32_i32_e32 v40, v20
	v_cvt_f32_i32_e32 v41, v21
	v_cvt_f32_i32_e32 v42, v6
	v_cvt_f32_i32_e32 v43, v7
	v_cvt_f32_i32_e32 v44, v8
	v_cvt_f32_i32_e32 v45, v9
	v_cvt_f32_i32_e32 v46, v2
	v_cvt_f32_i32_e32 v47, v3
	v_cvt_f32_i32_e32 v48, v4
	v_cvt_f32_i32_e32 v49, v5

.LBB0_1170:
	s_waitcnt lgkmcnt(0)
	ds_read_b128 v[114:117], v209
	ds_read_b128 v[118:121], v209 offset:1024
	ds_read_b128 v[122:125], v209 offset:2048
	ds_read_b128 v[126:129], v209 offset:3072
	ds_read_b128 v[146:149], v210
	ds_read_b128 v[150:153], v210 offset:1024
	ds_read_b128 v[154:157], v210 offset:2048
	ds_read_b128 v[158:161], v210 offset:3072
	s_add_i32 s92, s42, 2
	s_add_u32 s43, s38, 0x4000
	s_addc_u32 s44, s39, 0
	s_cmp_eq_u32 s81, s42
	s_cselect_b32 s45, s5, s44
	s_cselect_b32 s44, s4, s43
	s_cselect_b32 s94, s36, s90
	s_cselect_b32 s95, s37, s91
	s_add_u32 s42, s44, 0x8000
	s_addc_u32 s43, s45, 0
	v_lshl_add_u64 v[218:219], s[38:39], 0, v[170:171]
	s_add_i32 m0, s55, 0xc000
	ds_read_b128 v[178:181], v211
	ds_read_b128 v[182:185], v211 offset:1024
	ds_read_b128 v[186:189], v211 offset:2048
	ds_read_b128 v[190:193], v211 offset:3072
	ds_read_b128 v[194:197], v211 offset:4096
	ds_read_b128 v[198:201], v211 offset:5120
	ds_read_b128 v[202:205], v211 offset:6144
	ds_read_b128 v[214:217], v211 offset:7168
	global_load_lds_dwordx4 v[218:219], off
	v_lshl_add_u64 v[218:219], s[38:39], 0, v[172:173]
	s_add_i32 m0, s55, 0xe000
	s_nop 0
	global_load_lds_dwordx4 v[218:219], off
	s_waitcnt vmcnt(8)
	s_waitcnt lgkmcnt(0)
	s_setprio 1
	v_mfma_f32_16x16x32_bf16 v[142:145], v[114:117], v[178:181], v[142:145]
	v_mfma_f32_16x16x32_bf16 v[138:141], v[122:125], v[178:181], v[138:141]
	s_barrier
	v_mfma_f32_16x16x32_bf16 v[110:113], v[114:117], v[186:189], v[110:113]
	v_mfma_f32_16x16x32_bf16 v[106:109], v[122:125], v[186:189], v[106:109]
	v_mfma_f32_16x16x32_bf16 v[94:97], v[114:117], v[194:197], v[94:97]
	v_mfma_f32_16x16x32_bf16 v[90:93], v[122:125], v[194:197], v[90:93]
	v_mfma_f32_16x16x32_bf16 v[78:81], v[114:117], v[202:205], v[78:81]
	v_mfma_f32_16x16x32_bf16 v[74:77], v[122:125], v[202:205], v[74:77]
	v_mfma_f32_16x16x32_bf16 v[142:145], v[118:121], v[182:185], v[142:145]
	v_mfma_f32_16x16x32_bf16 v[138:141], v[126:129], v[182:185], v[138:141]
	v_mfma_f32_16x16x32_bf16 v[110:113], v[118:121], v[190:193], v[110:113]
	v_mfma_f32_16x16x32_bf16 v[106:109], v[126:129], v[190:193], v[106:109]
	v_mfma_f32_16x16x32_bf16 v[94:97], v[118:121], v[198:201], v[94:97]
	v_mfma_f32_16x16x32_bf16 v[90:93], v[126:129], v[198:201], v[90:93]
	v_mfma_f32_16x16x32_bf16 v[78:81], v[118:121], v[214:217], v[78:81]
	v_mfma_f32_16x16x32_bf16 v[74:77], v[126:129], v[214:217], v[74:77]
	v_mfma_f32_16x16x32_bf16 v[134:137], v[146:149], v[178:181], v[134:137]
	v_mfma_f32_16x16x32_bf16 v[130:133], v[154:157], v[178:181], v[130:133]
	v_mfma_f32_16x16x32_bf16 v[102:105], v[146:149], v[186:189], v[102:105]
	v_mfma_f32_16x16x32_bf16 v[98:101], v[154:157], v[186:189], v[98:101]
	v_mfma_f32_16x16x32_bf16 v[86:89], v[146:149], v[194:197], v[86:89]
	v_mfma_f32_16x16x32_bf16 v[82:85], v[154:157], v[194:197], v[82:85]
	v_mfma_f32_16x16x32_bf16 v[70:73], v[146:149], v[202:205], v[70:73]
	v_mfma_f32_16x16x32_bf16 v[66:69], v[154:157], v[202:205], v[66:69]
	v_mfma_f32_16x16x32_bf16 v[134:137], v[150:153], v[182:185], v[134:137]
	v_mfma_f32_16x16x32_bf16 v[130:133], v[158:161], v[182:185], v[130:133]
	v_mfma_f32_16x16x32_bf16 v[102:105], v[150:153], v[190:193], v[102:105]
	v_mfma_f32_16x16x32_bf16 v[98:101], v[158:161], v[190:193], v[98:101]
	v_mfma_f32_16x16x32_bf16 v[86:89], v[150:153], v[198:201], v[86:89]
	v_mfma_f32_16x16x32_bf16 v[82:85], v[158:161], v[198:201], v[82:85]
	v_mfma_f32_16x16x32_bf16 v[70:73], v[150:153], v[214:217], v[70:73]
	v_mfma_f32_16x16x32_bf16 v[66:69], v[158:161], v[214:217], v[66:69]
	s_setprio 0
	s_barrier
	s_add_i32 s93, s84, s54
	v_lshl_add_u64 v[218:219], s[94:95], 0, v[164:165]
	s_mov_b32 m0, s93
	ds_read_b128 v[178:181], v211 offset:16384
	ds_read_b128 v[182:185], v211 offset:17408
	ds_read_b128 v[186:189], v211 offset:18432
	ds_read_b128 v[190:193], v211 offset:19456
	ds_read_b128 v[194:197], v211 offset:20480
	ds_read_b128 v[198:201], v211 offset:21504
	ds_read_b128 v[202:205], v211 offset:22528
	ds_read_b128 v[214:217], v211 offset:23552
	global_load_lds_dwordx4 v[218:219], off
	s_add_i32 m0, s93, 0x2000
	v_lshl_add_u64 v[220:221], s[94:95], 0, v[168:169]
	s_add_u32 s94, s94, s8
	s_addc_u32 s95, s95, s9
	s_add_i32 s93, s85, s54
	global_load_lds_dwordx4 v[220:221], off
	v_lshl_add_u64 v[222:223], s[94:95], 0, v[164:165]
	s_mov_b32 m0, s93
	v_lshl_add_u64 v[224:225], s[94:95], 0, v[168:169]
	global_load_lds_dwordx4 v[222:223], off
	s_add_i32 m0, s93, 0x2000
	v_lshl_add_u64 v[226:227], s[44:45], 0, v[162:163]
	global_load_lds_dwordx4 v[224:225], off
	s_mov_b32 m0, s55
	s_nop 0
	global_load_lds_dwordx4 v[226:227], off
	v_lshl_add_u64 v[226:227], s[44:45], 0, v[166:167]
	s_mov_b32 m0, s56
	s_nop 0
	global_load_lds_dwordx4 v[226:227], off
	s_waitcnt vmcnt(8)
	s_waitcnt lgkmcnt(0)
	s_setprio 1
	v_mfma_f32_16x16x32_bf16 v[62:65], v[114:117], v[178:181], v[62:65]
	v_mfma_f32_16x16x32_bf16 v[58:61], v[122:125], v[178:181], v[58:61]
	s_barrier
	v_mfma_f32_16x16x32_bf16 v[46:49], v[114:117], v[186:189], v[46:49]
	v_mfma_f32_16x16x32_bf16 v[42:45], v[122:125], v[186:189], v[42:45]
	v_mfma_f32_16x16x32_bf16 v[30:33], v[114:117], v[194:197], v[30:33]
	v_mfma_f32_16x16x32_bf16 v[26:29], v[122:125], v[194:197], v[26:29]
	v_mfma_f32_16x16x32_bf16 v[14:17], v[114:117], v[202:205], v[14:17]
	v_mfma_f32_16x16x32_bf16 v[10:13], v[122:125], v[202:205], v[10:13]
	v_mfma_f32_16x16x32_bf16 v[62:65], v[118:121], v[182:185], v[62:65]
	v_mfma_f32_16x16x32_bf16 v[58:61], v[126:129], v[182:185], v[58:61]
	v_mfma_f32_16x16x32_bf16 v[46:49], v[118:121], v[190:193], v[46:49]
	v_mfma_f32_16x16x32_bf16 v[42:45], v[126:129], v[190:193], v[42:45]
	v_mfma_f32_16x16x32_bf16 v[30:33], v[118:121], v[198:201], v[30:33]
	v_mfma_f32_16x16x32_bf16 v[26:29], v[126:129], v[198:201], v[26:29]
	v_mfma_f32_16x16x32_bf16 v[14:17], v[118:121], v[214:217], v[14:17]
	v_mfma_f32_16x16x32_bf16 v[10:13], v[126:129], v[214:217], v[10:13]
	v_mfma_f32_16x16x32_bf16 v[54:57], v[146:149], v[178:181], v[54:57]
	v_mfma_f32_16x16x32_bf16 v[50:53], v[154:157], v[178:181], v[50:53]
	v_mfma_f32_16x16x32_bf16 v[38:41], v[146:149], v[186:189], v[38:41]
	v_mfma_f32_16x16x32_bf16 v[34:37], v[154:157], v[186:189], v[34:37]
	v_mfma_f32_16x16x32_bf16 v[22:25], v[146:149], v[194:197], v[22:25]
	v_mfma_f32_16x16x32_bf16 v[18:21], v[154:157], v[194:197], v[18:21]
	v_mfma_f32_16x16x32_bf16 v[6:9], v[146:149], v[202:205], v[6:9]
	v_mfma_f32_16x16x32_bf16 v[2:5], v[154:157], v[202:205], v[2:5]
	v_mfma_f32_16x16x32_bf16 v[54:57], v[150:153], v[182:185], v[54:57]
	v_mfma_f32_16x16x32_bf16 v[50:53], v[158:161], v[182:185], v[50:53]
	v_mfma_f32_16x16x32_bf16 v[38:41], v[150:153], v[190:193], v[38:41]
	v_mfma_f32_16x16x32_bf16 v[34:37], v[158:161], v[190:193], v[34:37]
	v_mfma_f32_16x16x32_bf16 v[22:25], v[150:153], v[198:201], v[22:25]
	v_mfma_f32_16x16x32_bf16 v[18:21], v[158:161], v[198:201], v[18:21]
	v_mfma_f32_16x16x32_bf16 v[6:9], v[150:153], v[214:217], v[6:9]
	v_mfma_f32_16x16x32_bf16 v[2:5], v[158:161], v[214:217], v[2:5]
	s_setprio 0
	s_barrier
	s_add_i32 s93, 0, 0x18000
	s_add_i32 s94, 0, 0x1c000
	v_add_u32_e32 v126, s93, v207
	v_add_u32_e32 v158, s94, v207
	ds_read_b128 v[114:117], v126
	ds_read_b128 v[118:121], v126 offset:1024
	ds_read_b128 v[122:125], v126 offset:2048
	ds_read_b128 v[126:129], v126 offset:3072
	ds_read_b128 v[146:149], v158
	ds_read_b128 v[150:153], v158 offset:1024
	ds_read_b128 v[154:157], v158 offset:2048
	ds_read_b128 v[158:161], v158 offset:3072
	s_add_u32 s44, s44, 0x4000
	s_addc_u32 s45, s45, 0
	s_mov_b32 m0, s57
	v_lshl_add_u64 v[226:227], s[44:45], 0, v[162:163]
	ds_read_b128 v[178:181], v211 offset:32768
	ds_read_b128 v[182:185], v211 offset:33792
	ds_read_b128 v[186:189], v211 offset:34816
	ds_read_b128 v[190:193], v211 offset:35840
	ds_read_b128 v[194:197], v211 offset:36864
	ds_read_b128 v[198:201], v211 offset:37888
	ds_read_b128 v[202:205], v211 offset:38912
	ds_read_b128 v[214:217], v211 offset:39936
	global_load_lds_dwordx4 v[226:227], off
	v_lshl_add_u64 v[226:227], s[44:45], 0, v[166:167]
	s_mov_b32 m0, s58
	s_nop 0
	global_load_lds_dwordx4 v[226:227], off
	s_waitcnt vmcnt(8)
	s_waitcnt lgkmcnt(0)
	s_setprio 1
	v_mfma_f32_16x16x32_bf16 v[142:145], v[114:117], v[178:181], v[142:145]
	v_mfma_f32_16x16x32_bf16 v[138:141], v[122:125], v[178:181], v[138:141]
	s_barrier
	v_mfma_f32_16x16x32_bf16 v[110:113], v[114:117], v[186:189], v[110:113]
	v_mfma_f32_16x16x32_bf16 v[106:109], v[122:125], v[186:189], v[106:109]
	v_mfma_f32_16x16x32_bf16 v[94:97], v[114:117], v[194:197], v[94:97]
	v_mfma_f32_16x16x32_bf16 v[90:93], v[122:125], v[194:197], v[90:93]
	v_mfma_f32_16x16x32_bf16 v[78:81], v[114:117], v[202:205], v[78:81]
	v_mfma_f32_16x16x32_bf16 v[74:77], v[122:125], v[202:205], v[74:77]
	v_mfma_f32_16x16x32_bf16 v[142:145], v[118:121], v[182:185], v[142:145]
	v_mfma_f32_16x16x32_bf16 v[138:141], v[126:129], v[182:185], v[138:141]
	v_mfma_f32_16x16x32_bf16 v[110:113], v[118:121], v[190:193], v[110:113]
	v_mfma_f32_16x16x32_bf16 v[106:109], v[126:129], v[190:193], v[106:109]
	v_mfma_f32_16x16x32_bf16 v[94:97], v[118:121], v[198:201], v[94:97]
	v_mfma_f32_16x16x32_bf16 v[90:93], v[126:129], v[198:201], v[90:93]
	v_mfma_f32_16x16x32_bf16 v[78:81], v[118:121], v[214:217], v[78:81]
	v_mfma_f32_16x16x32_bf16 v[74:77], v[126:129], v[214:217], v[74:77]
	v_mfma_f32_16x16x32_bf16 v[134:137], v[146:149], v[178:181], v[134:137]
	v_mfma_f32_16x16x32_bf16 v[130:133], v[154:157], v[178:181], v[130:133]
	v_mfma_f32_16x16x32_bf16 v[102:105], v[146:149], v[186:189], v[102:105]
	v_mfma_f32_16x16x32_bf16 v[98:101], v[154:157], v[186:189], v[98:101]
	v_mfma_f32_16x16x32_bf16 v[86:89], v[146:149], v[194:197], v[86:89]
	v_mfma_f32_16x16x32_bf16 v[82:85], v[154:157], v[194:197], v[82:85]
	v_mfma_f32_16x16x32_bf16 v[70:73], v[146:149], v[202:205], v[70:73]
	v_mfma_f32_16x16x32_bf16 v[66:69], v[154:157], v[202:205], v[66:69]
	v_mfma_f32_16x16x32_bf16 v[134:137], v[150:153], v[182:185], v[134:137]
	v_mfma_f32_16x16x32_bf16 v[130:133], v[158:161], v[182:185], v[130:133]
	v_mfma_f32_16x16x32_bf16 v[102:105], v[150:153], v[190:193], v[102:105]
	v_mfma_f32_16x16x32_bf16 v[98:101], v[158:161], v[190:193], v[98:101]
	v_mfma_f32_16x16x32_bf16 v[86:89], v[150:153], v[198:201], v[86:89]
	v_mfma_f32_16x16x32_bf16 v[82:85], v[158:161], v[198:201], v[82:85]
	v_mfma_f32_16x16x32_bf16 v[70:73], v[150:153], v[214:217], v[70:73]
	v_mfma_f32_16x16x32_bf16 v[66:69], v[158:161], v[214:217], v[66:69]
	s_setprio 0
	s_barrier
	s_add_i32 s44, s93, s54
	v_lshl_add_u64 v[218:219], v[218:219], 0, s[28:29]
	s_mov_b32 m0, s44
	ds_read_b128 v[178:181], v211 offset:49152
	ds_read_b128 v[182:185], v211 offset:50176
	ds_read_b128 v[186:189], v211 offset:51200
	ds_read_b128 v[190:193], v211 offset:52224
	ds_read_b128 v[194:197], v211 offset:53248
	ds_read_b128 v[198:201], v211 offset:54272
	ds_read_b128 v[202:205], v211 offset:55296
	ds_read_b128 v[214:217], v211 offset:56320
	global_load_lds_dwordx4 v[218:219], off
	v_lshl_add_u64 v[218:219], v[220:221], 0, s[28:29]
	s_add_i32 m0, s44, 0x2000
	s_add_i32 s44, s94, s54
	global_load_lds_dwordx4 v[218:219], off
	v_lshl_add_u64 v[218:219], v[222:223], 0, s[28:29]
	s_mov_b32 m0, s44
	s_nop 0
	global_load_lds_dwordx4 v[218:219], off
	v_lshl_add_u64 v[218:219], v[224:225], 0, s[28:29]
	s_add_i32 m0, s44, 0x2000
	s_nop 0
	global_load_lds_dwordx4 v[218:219], off
	v_lshl_add_u64 v[218:219], s[42:43], 0, v[162:163]
	s_mov_b32 m0, s65
	s_nop 0
	global_load_lds_dwordx4 v[218:219], off
	v_lshl_add_u64 v[218:219], s[42:43], 0, v[166:167]
	s_mov_b32 m0, s80
	s_nop 0
	global_load_lds_dwordx4 v[218:219], off
	s_waitcnt vmcnt(8)
	s_waitcnt lgkmcnt(0)
	s_setprio 1
	v_mfma_f32_16x16x32_bf16 v[62:65], v[114:117], v[178:181], v[62:65]
	v_mfma_f32_16x16x32_bf16 v[58:61], v[122:125], v[178:181], v[58:61]
	s_barrier
	v_mfma_f32_16x16x32_bf16 v[46:49], v[114:117], v[186:189], v[46:49]
	v_mfma_f32_16x16x32_bf16 v[42:45], v[122:125], v[186:189], v[42:45]
	v_mfma_f32_16x16x32_bf16 v[30:33], v[114:117], v[194:197], v[30:33]
	v_mfma_f32_16x16x32_bf16 v[26:29], v[122:125], v[194:197], v[26:29]
	v_mfma_f32_16x16x32_bf16 v[14:17], v[114:117], v[202:205], v[14:17]
	v_mfma_f32_16x16x32_bf16 v[10:13], v[122:125], v[202:205], v[10:13]
	v_mfma_f32_16x16x32_bf16 v[62:65], v[118:121], v[182:185], v[62:65]
	v_mfma_f32_16x16x32_bf16 v[58:61], v[126:129], v[182:185], v[58:61]
	v_mfma_f32_16x16x32_bf16 v[46:49], v[118:121], v[190:193], v[46:49]
	v_mfma_f32_16x16x32_bf16 v[42:45], v[126:129], v[190:193], v[42:45]
	v_mfma_f32_16x16x32_bf16 v[30:33], v[118:121], v[198:201], v[30:33]
	v_mfma_f32_16x16x32_bf16 v[26:29], v[126:129], v[198:201], v[26:29]
	v_mfma_f32_16x16x32_bf16 v[14:17], v[118:121], v[214:217], v[14:17]
	v_mfma_f32_16x16x32_bf16 v[10:13], v[126:129], v[214:217], v[10:13]
	v_mfma_f32_16x16x32_bf16 v[54:57], v[146:149], v[178:181], v[54:57]
	v_mfma_f32_16x16x32_bf16 v[50:53], v[154:157], v[178:181], v[50:53]
	v_mfma_f32_16x16x32_bf16 v[38:41], v[146:149], v[186:189], v[38:41]
	v_mfma_f32_16x16x32_bf16 v[34:37], v[154:157], v[186:189], v[34:37]
	v_mfma_f32_16x16x32_bf16 v[22:25], v[146:149], v[194:197], v[22:25]
	v_mfma_f32_16x16x32_bf16 v[18:21], v[154:157], v[194:197], v[18:21]
	v_mfma_f32_16x16x32_bf16 v[6:9], v[146:149], v[202:205], v[6:9]
	v_mfma_f32_16x16x32_bf16 v[2:5], v[154:157], v[202:205], v[2:5]
	v_mfma_f32_16x16x32_bf16 v[54:57], v[150:153], v[182:185], v[54:57]
	v_mfma_f32_16x16x32_bf16 v[50:53], v[158:161], v[182:185], v[50:53]
	v_mfma_f32_16x16x32_bf16 v[38:41], v[150:153], v[190:193], v[38:41]
	v_mfma_f32_16x16x32_bf16 v[34:37], v[158:161], v[190:193], v[34:37]
	v_mfma_f32_16x16x32_bf16 v[22:25], v[150:153], v[198:201], v[22:25]
	v_mfma_f32_16x16x32_bf16 v[18:21], v[158:161], v[198:201], v[18:21]
	v_mfma_f32_16x16x32_bf16 v[6:9], v[150:153], v[214:217], v[6:9]
	v_mfma_f32_16x16x32_bf16 v[2:5], v[158:161], v[214:217], v[2:5]
	s_setprio 0
	s_barrier
	s_add_u32 s90, s90, 0x100
	s_addc_u32 s91, s91, 0
	s_add_u32 s38, s38, 0x10000
	s_addc_u32 s39, s39, 0
	s_cmp_ge_i32 s92, s64
	s_mov_b32 s42, s92
	s_cbranch_scc0 .LBB0_1170

.LBB0_1276:
	ds_read_b128 v[114:117], v171
	ds_read_b128 v[118:121], v171 offset:1024
	ds_read_b128 v[122:125], v171 offset:2048
	ds_read_b128 v[130:133], v171 offset:3072
	ds_read_b128 v[162:165], v172
	ds_read_b128 v[176:179], v172 offset:1024
	ds_read_b128 v[180:183], v172 offset:2048
	ds_read_b128 v[184:187], v172 offset:3072
	s_add_i32 s82, s30, 2
	s_add_u32 s83, s2, 0x80
	s_addc_u32 s31, s3, 0
	s_cmp_eq_u32 s58, s30
	s_cselect_b32 s30, s26, s83
	s_cselect_b32 s31, s27, s31
	s_cselect_b32 s85, s29, s35
	s_cselect_b32 s84, s28, s34
	v_lshl_add_u64 v[220:221], s[2:3], 0, v[154:155]
	s_add_i32 m0, s44, 0xc000
	ds_read_b128 v[188:191], v173
	ds_read_b128 v[192:195], v173 offset:1024
	ds_read_b128 v[196:199], v173 offset:2048
	ds_read_b128 v[200:203], v173 offset:3072
	ds_read_b128 v[204:207], v173 offset:4096
	ds_read_b128 v[208:211], v173 offset:5120
	ds_read_b128 v[212:215], v173 offset:6144
	ds_read_b128 v[216:219], v173 offset:7168
	global_load_lds_dwordx4 v[220:221], off
	v_lshl_add_u64 v[220:221], s[2:3], 0, v[156:157]
	s_add_i32 m0, s44, 0xe000
	s_nop 0
	global_load_lds_dwordx4 v[220:221], off
	s_waitcnt vmcnt(8)
	s_waitcnt lgkmcnt(0)
	s_setprio 1
	v_mfma_f32_16x16x32_bf16 v[142:145], v[114:117], v[188:191], v[142:145]
	v_mfma_f32_16x16x32_bf16 v[138:141], v[122:125], v[188:191], v[138:141]
	s_barrier
	v_mfma_f32_16x16x32_bf16 v[110:113], v[114:117], v[196:199], v[110:113]
	v_mfma_f32_16x16x32_bf16 v[106:109], v[122:125], v[196:199], v[106:109]
	v_mfma_f32_16x16x32_bf16 v[94:97], v[114:117], v[204:207], v[94:97]
	v_mfma_f32_16x16x32_bf16 v[90:93], v[122:125], v[204:207], v[90:93]
	v_mfma_f32_16x16x32_bf16 v[78:81], v[114:117], v[212:215], v[78:81]
	v_mfma_f32_16x16x32_bf16 v[74:77], v[122:125], v[212:215], v[74:77]
	v_mfma_f32_16x16x32_bf16 v[142:145], v[118:121], v[192:195], v[142:145]
	v_mfma_f32_16x16x32_bf16 v[138:141], v[130:133], v[192:195], v[138:141]
	v_mfma_f32_16x16x32_bf16 v[110:113], v[118:121], v[200:203], v[110:113]
	v_mfma_f32_16x16x32_bf16 v[106:109], v[130:133], v[200:203], v[106:109]
	v_mfma_f32_16x16x32_bf16 v[94:97], v[118:121], v[208:211], v[94:97]
	v_mfma_f32_16x16x32_bf16 v[90:93], v[130:133], v[208:211], v[90:93]
	v_mfma_f32_16x16x32_bf16 v[78:81], v[118:121], v[216:219], v[78:81]
	v_mfma_f32_16x16x32_bf16 v[74:77], v[130:133], v[216:219], v[74:77]
	v_mfma_f32_16x16x32_bf16 v[134:137], v[162:165], v[188:191], v[134:137]
	v_mfma_f32_16x16x32_bf16 v[126:129], v[180:183], v[188:191], v[126:129]
	v_mfma_f32_16x16x32_bf16 v[102:105], v[162:165], v[196:199], v[102:105]
	v_mfma_f32_16x16x32_bf16 v[98:101], v[180:183], v[196:199], v[98:101]
	v_mfma_f32_16x16x32_bf16 v[86:89], v[162:165], v[204:207], v[86:89]
	v_mfma_f32_16x16x32_bf16 v[82:85], v[180:183], v[204:207], v[82:85]
	v_mfma_f32_16x16x32_bf16 v[70:73], v[162:165], v[212:215], v[70:73]
	v_mfma_f32_16x16x32_bf16 v[66:69], v[180:183], v[212:215], v[66:69]
	v_mfma_f32_16x16x32_bf16 v[134:137], v[176:179], v[192:195], v[134:137]
	v_mfma_f32_16x16x32_bf16 v[126:129], v[184:187], v[192:195], v[126:129]
	v_mfma_f32_16x16x32_bf16 v[102:105], v[176:179], v[200:203], v[102:105]
	v_mfma_f32_16x16x32_bf16 v[98:101], v[184:187], v[200:203], v[98:101]
	v_mfma_f32_16x16x32_bf16 v[86:89], v[176:179], v[208:211], v[86:89]
	v_mfma_f32_16x16x32_bf16 v[82:85], v[184:187], v[208:211], v[82:85]
	v_mfma_f32_16x16x32_bf16 v[70:73], v[176:179], v[216:219], v[70:73]
	v_mfma_f32_16x16x32_bf16 v[66:69], v[184:187], v[216:219], v[66:69]
	s_setprio 0
	s_barrier
	s_add_i32 s83, s61, s37
	v_lshl_add_u64 v[220:221], s[84:85], 0, v[148:149]
	s_mov_b32 m0, s83
	ds_read_b128 v[188:191], v173 offset:16384
	ds_read_b128 v[192:195], v173 offset:17408
	ds_read_b128 v[196:199], v173 offset:18432
	ds_read_b128 v[200:203], v173 offset:19456
	ds_read_b128 v[204:207], v173 offset:20480
	ds_read_b128 v[208:211], v173 offset:21504
	ds_read_b128 v[212:215], v173 offset:22528
	ds_read_b128 v[216:219], v173 offset:23552
	global_load_lds_dwordx4 v[220:221], off
	s_add_i32 m0, s83, 0x2000
	v_lshl_add_u64 v[222:223], s[84:85], 0, v[152:153]
	s_add_u32 s84, s84, s6
	s_addc_u32 s85, s85, s7
	s_add_i32 s83, s62, s37
	global_load_lds_dwordx4 v[222:223], off
	v_lshl_add_u64 v[224:225], s[84:85], 0, v[148:149]
	s_mov_b32 m0, s83
	v_lshl_add_u64 v[226:227], s[84:85], 0, v[152:153]
	global_load_lds_dwordx4 v[224:225], off
	s_add_i32 m0, s83, 0x2000
	v_lshl_add_u64 v[228:229], s[30:31], 0, v[146:147]
	global_load_lds_dwordx4 v[226:227], off
	s_mov_b32 m0, s44
	v_lshl_add_u64 v[230:231], s[30:31], 0, v[150:151]
	global_load_lds_dwordx4 v[228:229], off
	s_mov_b32 m0, s45
	s_nop 0
	global_load_lds_dwordx4 v[230:231], off
	s_waitcnt vmcnt(8)
	s_waitcnt lgkmcnt(0)
	s_setprio 1
	v_mfma_f32_16x16x32_bf16 v[62:65], v[114:117], v[188:191], v[62:65]
	v_mfma_f32_16x16x32_bf16 v[58:61], v[122:125], v[188:191], v[58:61]
	s_barrier
	v_mfma_f32_16x16x32_bf16 v[46:49], v[114:117], v[196:199], v[46:49]
	v_mfma_f32_16x16x32_bf16 v[42:45], v[122:125], v[196:199], v[42:45]
	v_mfma_f32_16x16x32_bf16 v[30:33], v[114:117], v[204:207], v[30:33]
	v_mfma_f32_16x16x32_bf16 v[26:29], v[122:125], v[204:207], v[26:29]
	v_mfma_f32_16x16x32_bf16 v[14:17], v[114:117], v[212:215], v[14:17]
	v_mfma_f32_16x16x32_bf16 v[10:13], v[122:125], v[212:215], v[10:13]
	v_mfma_f32_16x16x32_bf16 v[62:65], v[118:121], v[192:195], v[62:65]
	v_mfma_f32_16x16x32_bf16 v[58:61], v[130:133], v[192:195], v[58:61]
	v_mfma_f32_16x16x32_bf16 v[46:49], v[118:121], v[200:203], v[46:49]
	v_mfma_f32_16x16x32_bf16 v[42:45], v[130:133], v[200:203], v[42:45]
	v_mfma_f32_16x16x32_bf16 v[30:33], v[118:121], v[208:211], v[30:33]
	v_mfma_f32_16x16x32_bf16 v[26:29], v[130:133], v[208:211], v[26:29]
	v_mfma_f32_16x16x32_bf16 v[14:17], v[118:121], v[216:219], v[14:17]
	v_mfma_f32_16x16x32_bf16 v[10:13], v[130:133], v[216:219], v[10:13]
	v_mfma_f32_16x16x32_bf16 v[54:57], v[162:165], v[188:191], v[54:57]
	v_mfma_f32_16x16x32_bf16 v[50:53], v[180:183], v[188:191], v[50:53]
	v_mfma_f32_16x16x32_bf16 v[38:41], v[162:165], v[196:199], v[38:41]
	v_mfma_f32_16x16x32_bf16 v[34:37], v[180:183], v[196:199], v[34:37]
	v_mfma_f32_16x16x32_bf16 v[22:25], v[162:165], v[204:207], v[22:25]
	v_mfma_f32_16x16x32_bf16 v[18:21], v[180:183], v[204:207], v[18:21]
	v_mfma_f32_16x16x32_bf16 v[6:9], v[162:165], v[212:215], v[6:9]
	v_mfma_f32_16x16x32_bf16 v[2:5], v[180:183], v[212:215], v[2:5]
	v_mfma_f32_16x16x32_bf16 v[54:57], v[176:179], v[192:195], v[54:57]
	v_mfma_f32_16x16x32_bf16 v[50:53], v[184:187], v[192:195], v[50:53]
	v_mfma_f32_16x16x32_bf16 v[38:41], v[176:179], v[200:203], v[38:41]
	v_mfma_f32_16x16x32_bf16 v[34:37], v[184:187], v[200:203], v[34:37]
	v_mfma_f32_16x16x32_bf16 v[22:25], v[176:179], v[208:211], v[22:25]
	v_mfma_f32_16x16x32_bf16 v[18:21], v[184:187], v[208:211], v[18:21]
	v_mfma_f32_16x16x32_bf16 v[6:9], v[176:179], v[216:219], v[6:9]
	v_mfma_f32_16x16x32_bf16 v[2:5], v[184:187], v[216:219], v[2:5]
	s_setprio 0
	s_barrier
	s_add_i32 s83, 0, 0x18000
	s_add_i32 s84, 0, 0x1c000
	v_add_u32_e32 v130, s83, v168
	v_add_u32_e32 v166, s84, v168
	ds_read_b128 v[114:117], v130
	ds_read_b128 v[118:121], v130 offset:1024
	ds_read_b128 v[122:125], v130 offset:2048
	ds_read_b128 v[130:133], v130 offset:3072
	ds_read_b128 v[162:165], v166
	ds_read_b128 v[176:179], v166 offset:1024
	ds_read_b128 v[180:183], v166 offset:2048
	ds_read_b128 v[184:187], v166 offset:3072
	s_add_u32 s30, s30, s6
	s_addc_u32 s31, s31, s7
	s_mov_b32 m0, s46
	v_lshl_add_u64 v[232:233], s[30:31], 0, v[146:147]
	ds_read_b128 v[188:191], v173 offset:32768
	ds_read_b128 v[192:195], v173 offset:33792
	ds_read_b128 v[196:199], v173 offset:34816
	ds_read_b128 v[200:203], v173 offset:35840
	ds_read_b128 v[204:207], v173 offset:36864
	ds_read_b128 v[208:211], v173 offset:37888
	ds_read_b128 v[212:215], v173 offset:38912
	ds_read_b128 v[216:219], v173 offset:39936
	global_load_lds_dwordx4 v[232:233], off
	v_lshl_add_u64 v[232:233], s[30:31], 0, v[150:151]
	s_mov_b32 m0, s47
	s_nop 0
	global_load_lds_dwordx4 v[232:233], off
	s_waitcnt vmcnt(8)
	s_waitcnt lgkmcnt(0)
	s_setprio 1
	v_mfma_f32_16x16x32_bf16 v[142:145], v[114:117], v[188:191], v[142:145]
	v_mfma_f32_16x16x32_bf16 v[138:141], v[122:125], v[188:191], v[138:141]
	s_barrier
	v_mfma_f32_16x16x32_bf16 v[110:113], v[114:117], v[196:199], v[110:113]
	v_mfma_f32_16x16x32_bf16 v[106:109], v[122:125], v[196:199], v[106:109]
	v_mfma_f32_16x16x32_bf16 v[94:97], v[114:117], v[204:207], v[94:97]
	v_mfma_f32_16x16x32_bf16 v[90:93], v[122:125], v[204:207], v[90:93]
	v_mfma_f32_16x16x32_bf16 v[78:81], v[114:117], v[212:215], v[78:81]
	v_mfma_f32_16x16x32_bf16 v[74:77], v[122:125], v[212:215], v[74:77]
	v_mfma_f32_16x16x32_bf16 v[142:145], v[118:121], v[192:195], v[142:145]
	v_mfma_f32_16x16x32_bf16 v[138:141], v[130:133], v[192:195], v[138:141]
	v_mfma_f32_16x16x32_bf16 v[110:113], v[118:121], v[200:203], v[110:113]
	v_mfma_f32_16x16x32_bf16 v[106:109], v[130:133], v[200:203], v[106:109]
	v_mfma_f32_16x16x32_bf16 v[94:97], v[118:121], v[208:211], v[94:97]
	v_mfma_f32_16x16x32_bf16 v[90:93], v[130:133], v[208:211], v[90:93]
	v_mfma_f32_16x16x32_bf16 v[78:81], v[118:121], v[216:219], v[78:81]
	v_mfma_f32_16x16x32_bf16 v[74:77], v[130:133], v[216:219], v[74:77]
	v_mfma_f32_16x16x32_bf16 v[134:137], v[162:165], v[188:191], v[134:137]
	v_mfma_f32_16x16x32_bf16 v[126:129], v[180:183], v[188:191], v[126:129]
	v_mfma_f32_16x16x32_bf16 v[102:105], v[162:165], v[196:199], v[102:105]
	v_mfma_f32_16x16x32_bf16 v[98:101], v[180:183], v[196:199], v[98:101]
	v_mfma_f32_16x16x32_bf16 v[86:89], v[162:165], v[204:207], v[86:89]
	v_mfma_f32_16x16x32_bf16 v[82:85], v[180:183], v[204:207], v[82:85]
	v_mfma_f32_16x16x32_bf16 v[70:73], v[162:165], v[212:215], v[70:73]
	v_mfma_f32_16x16x32_bf16 v[66:69], v[180:183], v[212:215], v[66:69]
	v_mfma_f32_16x16x32_bf16 v[134:137], v[176:179], v[192:195], v[134:137]
	v_mfma_f32_16x16x32_bf16 v[126:129], v[184:187], v[192:195], v[126:129]
	v_mfma_f32_16x16x32_bf16 v[102:105], v[176:179], v[200:203], v[102:105]
	v_mfma_f32_16x16x32_bf16 v[98:101], v[184:187], v[200:203], v[98:101]
	v_mfma_f32_16x16x32_bf16 v[86:89], v[176:179], v[208:211], v[86:89]
	v_mfma_f32_16x16x32_bf16 v[82:85], v[184:187], v[208:211], v[82:85]
	v_mfma_f32_16x16x32_bf16 v[70:73], v[176:179], v[216:219], v[70:73]
	v_mfma_f32_16x16x32_bf16 v[66:69], v[184:187], v[216:219], v[66:69]
	s_setprio 0
	s_barrier
	s_add_i32 s30, s83, s37
	v_lshl_add_u64 v[220:221], v[220:221], 0, s[20:21]
	s_mov_b32 m0, s30
	ds_read_b128 v[188:191], v173 offset:49152
	ds_read_b128 v[192:195], v173 offset:50176
	ds_read_b128 v[196:199], v173 offset:51200
	ds_read_b128 v[200:203], v173 offset:52224
	ds_read_b128 v[204:207], v173 offset:53248
	ds_read_b128 v[208:211], v173 offset:54272
	ds_read_b128 v[212:215], v173 offset:55296
	ds_read_b128 v[216:219], v173 offset:56320
	global_load_lds_dwordx4 v[220:221], off
	v_lshl_add_u64 v[220:221], v[222:223], 0, s[20:21]
	s_add_i32 m0, s30, 0x2000
	s_add_i32 s30, s84, s37
	global_load_lds_dwordx4 v[220:221], off
	v_lshl_add_u64 v[220:221], v[224:225], 0, s[20:21]
	s_mov_b32 m0, s30
	s_nop 0
	global_load_lds_dwordx4 v[220:221], off
	v_lshl_add_u64 v[220:221], v[226:227], 0, s[20:21]
	s_add_i32 m0, s30, 0x2000
	s_nop 0
	global_load_lds_dwordx4 v[220:221], off
	v_lshl_add_u64 v[220:221], v[228:229], 0, s[20:21]
	s_mov_b32 m0, s55
	s_nop 0
	global_load_lds_dwordx4 v[220:221], off
	v_lshl_add_u64 v[220:221], v[230:231], 0, s[20:21]
	s_mov_b32 m0, s56
	s_nop 0
	global_load_lds_dwordx4 v[220:221], off
	s_waitcnt vmcnt(8)
	s_waitcnt lgkmcnt(0)
	s_setprio 1
	v_mfma_f32_16x16x32_bf16 v[62:65], v[114:117], v[188:191], v[62:65]
	v_mfma_f32_16x16x32_bf16 v[58:61], v[122:125], v[188:191], v[58:61]
	s_barrier
	v_mfma_f32_16x16x32_bf16 v[46:49], v[114:117], v[196:199], v[46:49]
	v_mfma_f32_16x16x32_bf16 v[42:45], v[122:125], v[196:199], v[42:45]
	v_mfma_f32_16x16x32_bf16 v[30:33], v[114:117], v[204:207], v[30:33]
	v_mfma_f32_16x16x32_bf16 v[26:29], v[122:125], v[204:207], v[26:29]
	v_mfma_f32_16x16x32_bf16 v[14:17], v[114:117], v[212:215], v[14:17]
	v_mfma_f32_16x16x32_bf16 v[10:13], v[122:125], v[212:215], v[10:13]
	v_mfma_f32_16x16x32_bf16 v[62:65], v[118:121], v[192:195], v[62:65]
	v_mfma_f32_16x16x32_bf16 v[58:61], v[130:133], v[192:195], v[58:61]
	v_mfma_f32_16x16x32_bf16 v[46:49], v[118:121], v[200:203], v[46:49]
	v_mfma_f32_16x16x32_bf16 v[42:45], v[130:133], v[200:203], v[42:45]
	v_mfma_f32_16x16x32_bf16 v[30:33], v[118:121], v[208:211], v[30:33]
	v_mfma_f32_16x16x32_bf16 v[26:29], v[130:133], v[208:211], v[26:29]
	v_mfma_f32_16x16x32_bf16 v[14:17], v[118:121], v[216:219], v[14:17]
	v_mfma_f32_16x16x32_bf16 v[10:13], v[130:133], v[216:219], v[10:13]
	v_mfma_f32_16x16x32_bf16 v[54:57], v[162:165], v[188:191], v[54:57]
	v_mfma_f32_16x16x32_bf16 v[50:53], v[180:183], v[188:191], v[50:53]
	v_mfma_f32_16x16x32_bf16 v[38:41], v[162:165], v[196:199], v[38:41]
	v_mfma_f32_16x16x32_bf16 v[34:37], v[180:183], v[196:199], v[34:37]
	v_mfma_f32_16x16x32_bf16 v[22:25], v[162:165], v[204:207], v[22:25]
	v_mfma_f32_16x16x32_bf16 v[18:21], v[180:183], v[204:207], v[18:21]
	v_mfma_f32_16x16x32_bf16 v[6:9], v[162:165], v[212:215], v[6:9]
	v_mfma_f32_16x16x32_bf16 v[2:5], v[180:183], v[212:215], v[2:5]
	v_mfma_f32_16x16x32_bf16 v[54:57], v[176:179], v[192:195], v[54:57]
	v_mfma_f32_16x16x32_bf16 v[50:53], v[184:187], v[192:195], v[50:53]
	v_mfma_f32_16x16x32_bf16 v[38:41], v[176:179], v[200:203], v[38:41]
	v_mfma_f32_16x16x32_bf16 v[34:37], v[184:187], v[200:203], v[34:37]
	v_mfma_f32_16x16x32_bf16 v[22:25], v[176:179], v[208:211], v[22:25]
	v_mfma_f32_16x16x32_bf16 v[18:21], v[184:187], v[208:211], v[18:21]
	v_mfma_f32_16x16x32_bf16 v[6:9], v[176:179], v[216:219], v[6:9]
	v_mfma_f32_16x16x32_bf16 v[2:5], v[184:187], v[216:219], v[2:5]
	s_setprio 0
	s_barrier
	s_add_u32 s2, s2, 0x100
	s_addc_u32 s3, s3, 0
	s_add_u32 s34, s34, 0x100
	s_addc_u32 s35, s35, 0
	s_cmp_ge_i32 s82, s57
	s_mov_b32 s30, s82
	s_cbranch_scc0 .LBB0_1276

.LBB0_1461:
	ds_read_b128 v[148:151], v168
	ds_read_b128 v[172:175], v168 offset:1024
	ds_read_b128 v[176:179], v168 offset:2048
	ds_read_b128 v[180:183], v168 offset:3072
	ds_read_b128 v[184:187], v169
	ds_read_b128 v[188:191], v169 offset:1024
	ds_read_b128 v[192:195], v169 offset:2048
	ds_read_b128 v[196:199], v169 offset:3072
	s_add_i32 s67, s26, 2
	s_add_u32 s68, s24, 0x80
	s_addc_u32 s27, s25, 0
	s_cmp_eq_u32 s50, s26
	s_cselect_b32 s26, s2, s68
	s_cselect_b32 s27, s3, s27
	s_cselect_b32 s69, s23, s66
	s_cselect_b32 s68, s22, s65
	v_lshl_add_u64 v[232:233], s[24:25], 0, v[140:141]
	s_add_i32 m0, s37, 0xc000
	ds_read_b128 v[200:203], v170
	ds_read_b128 v[204:207], v170 offset:1024
	ds_read_b128 v[208:211], v170 offset:2048
	ds_read_b128 v[212:215], v170 offset:3072
	ds_read_b128 v[216:219], v170 offset:4096
	ds_read_b128 v[220:223], v170 offset:5120
	ds_read_b128 v[224:227], v170 offset:6144
	ds_read_b128 v[228:231], v170 offset:7168
	global_load_lds_dwordx4 v[232:233], off
	v_lshl_add_u64 v[232:233], s[24:25], 0, v[142:143]
	s_add_i32 m0, s37, 0xe000
	s_nop 0
	global_load_lds_dwordx4 v[232:233], off
	s_waitcnt vmcnt(8)
	s_waitcnt lgkmcnt(0)
	s_setprio 1
	v_mfma_f32_16x16x32_bf16 v[128:131], v[148:151], v[200:203], v[128:131]
	v_mfma_f32_16x16x32_bf16 v[124:127], v[176:179], v[200:203], v[124:127]
	s_barrier
	v_mfma_f32_16x16x32_bf16 v[120:123], v[148:151], v[208:211], v[120:123]
	v_mfma_f32_16x16x32_bf16 v[116:119], v[176:179], v[208:211], v[116:119]
	v_mfma_f32_16x16x32_bf16 v[112:115], v[148:151], v[216:219], v[112:115]
	v_mfma_f32_16x16x32_bf16 v[108:111], v[176:179], v[216:219], v[108:111]
	v_mfma_f32_16x16x32_bf16 v[104:107], v[148:151], v[224:227], v[104:107]
	v_mfma_f32_16x16x32_bf16 v[100:103], v[176:179], v[224:227], v[100:103]
	v_mfma_f32_16x16x32_bf16 v[128:131], v[172:175], v[204:207], v[128:131]
	v_mfma_f32_16x16x32_bf16 v[124:127], v[180:183], v[204:207], v[124:127]
	v_mfma_f32_16x16x32_bf16 v[120:123], v[172:175], v[212:215], v[120:123]
	v_mfma_f32_16x16x32_bf16 v[116:119], v[180:183], v[212:215], v[116:119]
	v_mfma_f32_16x16x32_bf16 v[112:115], v[172:175], v[220:223], v[112:115]
	v_mfma_f32_16x16x32_bf16 v[108:111], v[180:183], v[220:223], v[108:111]
	v_mfma_f32_16x16x32_bf16 v[104:107], v[172:175], v[228:231], v[104:107]
	v_mfma_f32_16x16x32_bf16 v[100:103], v[180:183], v[228:231], v[100:103]
	v_mfma_f32_16x16x32_bf16 v[64:67], v[184:187], v[200:203], v[64:67]
	v_mfma_f32_16x16x32_bf16 v[60:63], v[192:195], v[200:203], v[60:63]
	v_mfma_f32_16x16x32_bf16 v[56:59], v[184:187], v[208:211], v[56:59]
	v_mfma_f32_16x16x32_bf16 v[52:55], v[192:195], v[208:211], v[52:55]
	v_mfma_f32_16x16x32_bf16 v[48:51], v[184:187], v[216:219], v[48:51]
	v_mfma_f32_16x16x32_bf16 v[44:47], v[192:195], v[216:219], v[44:47]
	v_mfma_f32_16x16x32_bf16 v[40:43], v[184:187], v[224:227], v[40:43]
	v_mfma_f32_16x16x32_bf16 v[36:39], v[192:195], v[224:227], v[36:39]
	v_mfma_f32_16x16x32_bf16 v[64:67], v[188:191], v[204:207], v[64:67]
	v_mfma_f32_16x16x32_bf16 v[60:63], v[196:199], v[204:207], v[60:63]
	v_mfma_f32_16x16x32_bf16 v[56:59], v[188:191], v[212:215], v[56:59]
	v_mfma_f32_16x16x32_bf16 v[52:55], v[196:199], v[212:215], v[52:55]
	v_mfma_f32_16x16x32_bf16 v[48:51], v[188:191], v[220:223], v[48:51]
	v_mfma_f32_16x16x32_bf16 v[44:47], v[196:199], v[220:223], v[44:47]
	v_mfma_f32_16x16x32_bf16 v[40:43], v[188:191], v[228:231], v[40:43]
	v_mfma_f32_16x16x32_bf16 v[36:39], v[196:199], v[228:231], v[36:39]
	s_setprio 0
	s_barrier
	s_add_i32 s80, s57, s36
	v_lshl_add_u64 v[232:233], s[68:69], 0, v[134:135]
	s_mov_b32 m0, s80
	ds_read_b128 v[200:203], v170 offset:16384
	ds_read_b128 v[204:207], v170 offset:17408
	ds_read_b128 v[208:211], v170 offset:18432
	ds_read_b128 v[212:215], v170 offset:19456
	ds_read_b128 v[216:219], v170 offset:20480
	ds_read_b128 v[220:223], v170 offset:21504
	ds_read_b128 v[224:227], v170 offset:22528
	ds_read_b128 v[228:231], v170 offset:23552
	global_load_lds_dwordx4 v[232:233], off
	s_add_i32 m0, s80, 0x2000
	v_lshl_add_u64 v[234:235], s[68:69], 0, v[138:139]
	s_add_u32 s68, s68, s6
	s_addc_u32 s69, s69, s7
	s_add_i32 s80, s58, s36
	global_load_lds_dwordx4 v[234:235], off
	v_lshl_add_u64 v[236:237], s[68:69], 0, v[134:135]
	s_mov_b32 m0, s80
	v_lshl_add_u64 v[238:239], s[68:69], 0, v[138:139]
	global_load_lds_dwordx4 v[236:237], off
	s_add_i32 m0, s80, 0x2000
	v_lshl_add_u64 v[240:241], s[26:27], 0, v[132:133]
	global_load_lds_dwordx4 v[238:239], off
	s_mov_b32 m0, s37
	v_lshl_add_u64 v[242:243], s[26:27], 0, v[136:137]
	global_load_lds_dwordx4 v[240:241], off
	s_mov_b32 m0, s38
	s_nop 0
	global_load_lds_dwordx4 v[242:243], off
	s_waitcnt vmcnt(8)
	s_waitcnt lgkmcnt(0)
	s_setprio 1
	v_mfma_f32_16x16x32_bf16 v[96:99], v[148:151], v[200:203], v[96:99]
	v_mfma_f32_16x16x32_bf16 v[92:95], v[176:179], v[200:203], v[92:95]
	s_barrier
	v_mfma_f32_16x16x32_bf16 v[88:91], v[148:151], v[208:211], v[88:91]
	v_mfma_f32_16x16x32_bf16 v[84:87], v[176:179], v[208:211], v[84:87]
	v_mfma_f32_16x16x32_bf16 v[80:83], v[148:151], v[216:219], v[80:83]
	v_mfma_f32_16x16x32_bf16 v[76:79], v[176:179], v[216:219], v[76:79]
	v_mfma_f32_16x16x32_bf16 v[72:75], v[148:151], v[224:227], v[72:75]
	v_mfma_f32_16x16x32_bf16 v[68:71], v[176:179], v[224:227], v[68:71]
	v_mfma_f32_16x16x32_bf16 v[96:99], v[172:175], v[204:207], v[96:99]
	v_mfma_f32_16x16x32_bf16 v[92:95], v[180:183], v[204:207], v[92:95]
	v_mfma_f32_16x16x32_bf16 v[88:91], v[172:175], v[212:215], v[88:91]
	v_mfma_f32_16x16x32_bf16 v[84:87], v[180:183], v[212:215], v[84:87]
	v_mfma_f32_16x16x32_bf16 v[80:83], v[172:175], v[220:223], v[80:83]
	v_mfma_f32_16x16x32_bf16 v[76:79], v[180:183], v[220:223], v[76:79]
	v_mfma_f32_16x16x32_bf16 v[72:75], v[172:175], v[228:231], v[72:75]
	v_mfma_f32_16x16x32_bf16 v[68:71], v[180:183], v[228:231], v[68:71]
	v_mfma_f32_16x16x32_bf16 v[32:35], v[184:187], v[200:203], v[32:35]
	v_mfma_f32_16x16x32_bf16 v[28:31], v[192:195], v[200:203], v[28:31]
	v_mfma_f32_16x16x32_bf16 v[24:27], v[184:187], v[208:211], v[24:27]
	v_mfma_f32_16x16x32_bf16 v[20:23], v[192:195], v[208:211], v[20:23]
	v_mfma_f32_16x16x32_bf16 v[16:19], v[184:187], v[216:219], v[16:19]
	v_mfma_f32_16x16x32_bf16 v[12:15], v[192:195], v[216:219], v[12:15]
	v_mfma_f32_16x16x32_bf16 v[8:11], v[184:187], v[224:227], v[8:11]
	v_mfma_f32_16x16x32_bf16 v[4:7], v[192:195], v[224:227], v[4:7]
	v_mfma_f32_16x16x32_bf16 v[32:35], v[188:191], v[204:207], v[32:35]
	v_mfma_f32_16x16x32_bf16 v[28:31], v[196:199], v[204:207], v[28:31]
	v_mfma_f32_16x16x32_bf16 v[24:27], v[188:191], v[212:215], v[24:27]
	v_mfma_f32_16x16x32_bf16 v[20:23], v[196:199], v[212:215], v[20:23]
	v_mfma_f32_16x16x32_bf16 v[16:19], v[188:191], v[220:223], v[16:19]
	v_mfma_f32_16x16x32_bf16 v[12:15], v[196:199], v[220:223], v[12:15]
	v_mfma_f32_16x16x32_bf16 v[8:11], v[188:191], v[228:231], v[8:11]
	v_mfma_f32_16x16x32_bf16 v[4:7], v[196:199], v[228:231], v[4:7]
	s_setprio 0
	s_barrier
	s_add_i32 s68, 0, 0x18000
	v_add_u32_e32 v3, s68, v166
	s_add_i32 s69, 0, 0x1c000
	ds_read_b128 v[148:151], v3
	ds_read_b128 v[172:175], v3 offset:1024
	ds_read_b128 v[176:179], v3 offset:2048
	ds_read_b128 v[180:183], v3 offset:3072
	v_add_u32_e32 v3, s69, v166
	ds_read_b128 v[184:187], v3
	ds_read_b128 v[188:191], v3 offset:1024
	ds_read_b128 v[192:195], v3 offset:2048
	ds_read_b128 v[196:199], v3 offset:3072
	s_add_u32 s26, s26, s6
	s_addc_u32 s27, s27, s7
	s_mov_b32 m0, s39
	v_lshl_add_u64 v[244:245], s[26:27], 0, v[132:133]
	ds_read_b128 v[200:203], v170 offset:32768
	ds_read_b128 v[204:207], v170 offset:33792
	ds_read_b128 v[208:211], v170 offset:34816
	ds_read_b128 v[212:215], v170 offset:35840
	ds_read_b128 v[216:219], v170 offset:36864
	ds_read_b128 v[220:223], v170 offset:37888
	ds_read_b128 v[224:227], v170 offset:38912
	ds_read_b128 v[228:231], v170 offset:39936
	global_load_lds_dwordx4 v[244:245], off
	v_lshl_add_u64 v[244:245], s[26:27], 0, v[136:137]
	s_mov_b32 m0, s42
	s_nop 0
	global_load_lds_dwordx4 v[244:245], off
	s_waitcnt vmcnt(8)
	s_waitcnt lgkmcnt(0)
	s_setprio 1
	v_mfma_f32_16x16x32_bf16 v[128:131], v[148:151], v[200:203], v[128:131]
	v_mfma_f32_16x16x32_bf16 v[124:127], v[176:179], v[200:203], v[124:127]
	s_barrier
	v_mfma_f32_16x16x32_bf16 v[120:123], v[148:151], v[208:211], v[120:123]
	v_mfma_f32_16x16x32_bf16 v[116:119], v[176:179], v[208:211], v[116:119]
	v_mfma_f32_16x16x32_bf16 v[112:115], v[148:151], v[216:219], v[112:115]
	v_mfma_f32_16x16x32_bf16 v[108:111], v[176:179], v[216:219], v[108:111]
	v_mfma_f32_16x16x32_bf16 v[104:107], v[148:151], v[224:227], v[104:107]
	v_mfma_f32_16x16x32_bf16 v[100:103], v[176:179], v[224:227], v[100:103]
	v_mfma_f32_16x16x32_bf16 v[128:131], v[172:175], v[204:207], v[128:131]
	v_mfma_f32_16x16x32_bf16 v[124:127], v[180:183], v[204:207], v[124:127]
	v_mfma_f32_16x16x32_bf16 v[120:123], v[172:175], v[212:215], v[120:123]
	v_mfma_f32_16x16x32_bf16 v[116:119], v[180:183], v[212:215], v[116:119]
	v_mfma_f32_16x16x32_bf16 v[112:115], v[172:175], v[220:223], v[112:115]
	v_mfma_f32_16x16x32_bf16 v[108:111], v[180:183], v[220:223], v[108:111]
	v_mfma_f32_16x16x32_bf16 v[104:107], v[172:175], v[228:231], v[104:107]
	v_mfma_f32_16x16x32_bf16 v[100:103], v[180:183], v[228:231], v[100:103]
	v_mfma_f32_16x16x32_bf16 v[64:67], v[184:187], v[200:203], v[64:67]
	v_mfma_f32_16x16x32_bf16 v[60:63], v[192:195], v[200:203], v[60:63]
	v_mfma_f32_16x16x32_bf16 v[56:59], v[184:187], v[208:211], v[56:59]
	v_mfma_f32_16x16x32_bf16 v[52:55], v[192:195], v[208:211], v[52:55]
	v_mfma_f32_16x16x32_bf16 v[48:51], v[184:187], v[216:219], v[48:51]
	v_mfma_f32_16x16x32_bf16 v[44:47], v[192:195], v[216:219], v[44:47]
	v_mfma_f32_16x16x32_bf16 v[40:43], v[184:187], v[224:227], v[40:43]
	v_mfma_f32_16x16x32_bf16 v[36:39], v[192:195], v[224:227], v[36:39]
	v_mfma_f32_16x16x32_bf16 v[64:67], v[188:191], v[204:207], v[64:67]
	v_mfma_f32_16x16x32_bf16 v[60:63], v[196:199], v[204:207], v[60:63]
	v_mfma_f32_16x16x32_bf16 v[56:59], v[188:191], v[212:215], v[56:59]
	v_mfma_f32_16x16x32_bf16 v[52:55], v[196:199], v[212:215], v[52:55]
	v_mfma_f32_16x16x32_bf16 v[48:51], v[188:191], v[220:223], v[48:51]
	v_mfma_f32_16x16x32_bf16 v[44:47], v[196:199], v[220:223], v[44:47]
	v_mfma_f32_16x16x32_bf16 v[40:43], v[188:191], v[228:231], v[40:43]
	v_mfma_f32_16x16x32_bf16 v[36:39], v[196:199], v[228:231], v[36:39]
	s_setprio 0
	s_barrier
	s_add_i32 s26, s68, s36
	v_lshl_add_u64 v[232:233], v[232:233], 0, s[16:17]
	s_mov_b32 m0, s26
	ds_read_b128 v[200:203], v170 offset:49152
	ds_read_b128 v[204:207], v170 offset:50176
	ds_read_b128 v[208:211], v170 offset:51200
	ds_read_b128 v[212:215], v170 offset:52224
	ds_read_b128 v[216:219], v170 offset:53248
	ds_read_b128 v[220:223], v170 offset:54272
	ds_read_b128 v[224:227], v170 offset:55296
	ds_read_b128 v[228:231], v170 offset:56320
	global_load_lds_dwordx4 v[232:233], off
	v_lshl_add_u64 v[232:233], v[234:235], 0, s[16:17]
	s_add_i32 m0, s26, 0x2000
	s_add_i32 s26, s69, s36
	global_load_lds_dwordx4 v[232:233], off
	v_lshl_add_u64 v[232:233], v[236:237], 0, s[16:17]
	s_mov_b32 m0, s26
	s_nop 0
	global_load_lds_dwordx4 v[232:233], off
	v_lshl_add_u64 v[232:233], v[238:239], 0, s[16:17]
	s_add_i32 m0, s26, 0x2000
	s_nop 0
	global_load_lds_dwordx4 v[232:233], off
	v_lshl_add_u64 v[232:233], v[240:241], 0, s[16:17]
	s_mov_b32 m0, s44
	s_nop 0
	global_load_lds_dwordx4 v[232:233], off
	v_lshl_add_u64 v[232:233], v[242:243], 0, s[16:17]
	s_mov_b32 m0, s45
	s_nop 0
	global_load_lds_dwordx4 v[232:233], off
	s_waitcnt vmcnt(8)
	s_waitcnt lgkmcnt(0)
	s_setprio 1
	v_mfma_f32_16x16x32_bf16 v[96:99], v[148:151], v[200:203], v[96:99]
	v_mfma_f32_16x16x32_bf16 v[92:95], v[176:179], v[200:203], v[92:95]
	s_barrier
	v_mfma_f32_16x16x32_bf16 v[88:91], v[148:151], v[208:211], v[88:91]
	v_mfma_f32_16x16x32_bf16 v[84:87], v[176:179], v[208:211], v[84:87]
	v_mfma_f32_16x16x32_bf16 v[80:83], v[148:151], v[216:219], v[80:83]
	v_mfma_f32_16x16x32_bf16 v[76:79], v[176:179], v[216:219], v[76:79]
	v_mfma_f32_16x16x32_bf16 v[72:75], v[148:151], v[224:227], v[72:75]
	v_mfma_f32_16x16x32_bf16 v[68:71], v[176:179], v[224:227], v[68:71]
	v_mfma_f32_16x16x32_bf16 v[96:99], v[172:175], v[204:207], v[96:99]
	v_mfma_f32_16x16x32_bf16 v[92:95], v[180:183], v[204:207], v[92:95]
	v_mfma_f32_16x16x32_bf16 v[88:91], v[172:175], v[212:215], v[88:91]
	v_mfma_f32_16x16x32_bf16 v[84:87], v[180:183], v[212:215], v[84:87]
	v_mfma_f32_16x16x32_bf16 v[80:83], v[172:175], v[220:223], v[80:83]
	v_mfma_f32_16x16x32_bf16 v[76:79], v[180:183], v[220:223], v[76:79]
	v_mfma_f32_16x16x32_bf16 v[72:75], v[172:175], v[228:231], v[72:75]
	v_mfma_f32_16x16x32_bf16 v[68:71], v[180:183], v[228:231], v[68:71]
	v_mfma_f32_16x16x32_bf16 v[32:35], v[184:187], v[200:203], v[32:35]
	v_mfma_f32_16x16x32_bf16 v[28:31], v[192:195], v[200:203], v[28:31]
	v_mfma_f32_16x16x32_bf16 v[24:27], v[184:187], v[208:211], v[24:27]
	v_mfma_f32_16x16x32_bf16 v[20:23], v[192:195], v[208:211], v[20:23]
	v_mfma_f32_16x16x32_bf16 v[16:19], v[184:187], v[216:219], v[16:19]
	v_mfma_f32_16x16x32_bf16 v[12:15], v[192:195], v[216:219], v[12:15]
	v_mfma_f32_16x16x32_bf16 v[8:11], v[184:187], v[224:227], v[8:11]
	v_mfma_f32_16x16x32_bf16 v[4:7], v[192:195], v[224:227], v[4:7]
	v_mfma_f32_16x16x32_bf16 v[32:35], v[188:191], v[204:207], v[32:35]
	v_mfma_f32_16x16x32_bf16 v[28:31], v[196:199], v[204:207], v[28:31]
	v_mfma_f32_16x16x32_bf16 v[24:27], v[188:191], v[212:215], v[24:27]
	v_mfma_f32_16x16x32_bf16 v[20:23], v[196:199], v[212:215], v[20:23]
	v_mfma_f32_16x16x32_bf16 v[16:19], v[188:191], v[220:223], v[16:19]
	v_mfma_f32_16x16x32_bf16 v[12:15], v[196:199], v[220:223], v[12:15]
	v_mfma_f32_16x16x32_bf16 v[8:11], v[188:191], v[228:231], v[8:11]
	v_mfma_f32_16x16x32_bf16 v[4:7], v[196:199], v[228:231], v[4:7]
	s_setprio 0
	s_barrier
	s_add_u32 s24, s24, 0x100
	s_addc_u32 s25, s25, 0
	s_add_u32 s65, s65, 0x100
	s_addc_u32 s66, s66, 0
	s_cmp_ge_i32 s67, s46
	s_mov_b32 s26, s67
	s_cbranch_scc0 .LBB0_1461

.LBB0_1514:
	ds_read_b128 v[152:155], v149
	ds_read_b128 v[156:159], v149 offset:1024
	ds_read_b128 v[160:163], v149 offset:2048
	ds_read_b128 v[164:167], v149 offset:3072
	ds_read_b128 v[168:171], v150
	ds_read_b128 v[172:175], v150 offset:1024
	ds_read_b128 v[176:179], v150 offset:2048
	ds_read_b128 v[180:183], v150 offset:3072
	s_add_i32 s69, s36, 2
	s_add_u32 s80, s34, 0x80
	s_addc_u32 s37, s35, 0
	s_cmp_eq_u32 s59, s36
	s_cselect_b32 s36, s2, s80
	s_cselect_b32 s37, s3, s37
	s_cselect_b32 s81, s31, s68
	s_cselect_b32 s80, s30, s67
	v_lshl_add_u64 v[216:217], s[34:35], 0, v[138:139]
	s_add_i32 m0, s47, 0xc000
	ds_read_b128 v[184:187], v151
	ds_read_b128 v[188:191], v151 offset:1024
	ds_read_b128 v[192:195], v151 offset:2048
	ds_read_b128 v[196:199], v151 offset:3072
	ds_read_b128 v[200:203], v151 offset:4096
	ds_read_b128 v[204:207], v151 offset:5120
	ds_read_b128 v[208:211], v151 offset:6144
	ds_read_b128 v[212:215], v151 offset:7168
	global_load_lds_dwordx4 v[216:217], off
	v_lshl_add_u64 v[216:217], s[34:35], 0, v[140:141]
	s_add_i32 m0, s47, 0xe000
	s_nop 0
	global_load_lds_dwordx4 v[216:217], off
	s_waitcnt vmcnt(8)
	s_waitcnt lgkmcnt(0)
	s_setprio 1
	v_mfma_f32_16x16x32_bf16 v[122:125], v[152:155], v[184:187], v[122:125]
	v_mfma_f32_16x16x32_bf16 v[126:129], v[160:163], v[184:187], v[126:129]
	s_barrier
	v_mfma_f32_16x16x32_bf16 v[110:113], v[152:155], v[192:195], v[110:113]
	v_mfma_f32_16x16x32_bf16 v[106:109], v[160:163], v[192:195], v[106:109]
	v_mfma_f32_16x16x32_bf16 v[94:97], v[152:155], v[200:203], v[94:97]
	v_mfma_f32_16x16x32_bf16 v[90:93], v[160:163], v[200:203], v[90:93]
	v_mfma_f32_16x16x32_bf16 v[78:81], v[152:155], v[208:211], v[78:81]
	v_mfma_f32_16x16x32_bf16 v[74:77], v[160:163], v[208:211], v[74:77]
	v_mfma_f32_16x16x32_bf16 v[122:125], v[156:159], v[188:191], v[122:125]
	v_mfma_f32_16x16x32_bf16 v[126:129], v[164:167], v[188:191], v[126:129]
	v_mfma_f32_16x16x32_bf16 v[110:113], v[156:159], v[196:199], v[110:113]
	v_mfma_f32_16x16x32_bf16 v[106:109], v[164:167], v[196:199], v[106:109]
	v_mfma_f32_16x16x32_bf16 v[94:97], v[156:159], v[204:207], v[94:97]
	v_mfma_f32_16x16x32_bf16 v[90:93], v[164:167], v[204:207], v[90:93]
	v_mfma_f32_16x16x32_bf16 v[78:81], v[156:159], v[212:215], v[78:81]
	v_mfma_f32_16x16x32_bf16 v[74:77], v[164:167], v[212:215], v[74:77]
	v_mfma_f32_16x16x32_bf16 v[118:121], v[168:171], v[184:187], v[118:121]
	v_mfma_f32_16x16x32_bf16 v[114:117], v[176:179], v[184:187], v[114:117]
	v_mfma_f32_16x16x32_bf16 v[102:105], v[168:171], v[192:195], v[102:105]
	v_mfma_f32_16x16x32_bf16 v[98:101], v[176:179], v[192:195], v[98:101]
	v_mfma_f32_16x16x32_bf16 v[86:89], v[168:171], v[200:203], v[86:89]
	v_mfma_f32_16x16x32_bf16 v[82:85], v[176:179], v[200:203], v[82:85]
	v_mfma_f32_16x16x32_bf16 v[70:73], v[168:171], v[208:211], v[70:73]
	v_mfma_f32_16x16x32_bf16 v[66:69], v[176:179], v[208:211], v[66:69]
	v_mfma_f32_16x16x32_bf16 v[118:121], v[172:175], v[188:191], v[118:121]
	v_mfma_f32_16x16x32_bf16 v[114:117], v[180:183], v[188:191], v[114:117]
	v_mfma_f32_16x16x32_bf16 v[102:105], v[172:175], v[196:199], v[102:105]
	v_mfma_f32_16x16x32_bf16 v[98:101], v[180:183], v[196:199], v[98:101]
	v_mfma_f32_16x16x32_bf16 v[86:89], v[172:175], v[204:207], v[86:89]
	v_mfma_f32_16x16x32_bf16 v[82:85], v[180:183], v[204:207], v[82:85]
	v_mfma_f32_16x16x32_bf16 v[70:73], v[172:175], v[212:215], v[70:73]
	v_mfma_f32_16x16x32_bf16 v[66:69], v[180:183], v[212:215], v[66:69]
	s_setprio 0
	s_barrier
	s_add_i32 s82, s61, s44
	v_lshl_add_u64 v[216:217], s[80:81], 0, v[134:135]
	s_mov_b32 m0, s82
	ds_read_b128 v[184:187], v151 offset:16384
	ds_read_b128 v[188:191], v151 offset:17408
	ds_read_b128 v[192:195], v151 offset:18432
	ds_read_b128 v[196:199], v151 offset:19456
	ds_read_b128 v[200:203], v151 offset:20480
	ds_read_b128 v[204:207], v151 offset:21504
	ds_read_b128 v[208:211], v151 offset:22528
	ds_read_b128 v[212:215], v151 offset:23552
	global_load_lds_dwordx4 v[216:217], off
	s_add_i32 m0, s82, 0x2000
	v_lshl_add_u64 v[218:219], s[80:81], 0, v[130:131]
	s_add_u32 s80, s80, s6
	s_addc_u32 s81, s81, s7
	s_add_i32 s82, s62, s44
	global_load_lds_dwordx4 v[218:219], off
	v_lshl_add_u64 v[220:221], s[80:81], 0, v[134:135]
	s_mov_b32 m0, s82
	v_lshl_add_u64 v[222:223], s[80:81], 0, v[130:131]
	global_load_lds_dwordx4 v[220:221], off
	s_add_i32 m0, s82, 0x2000
	v_lshl_add_u64 v[224:225], s[36:37], 0, v[136:137]
	global_load_lds_dwordx4 v[222:223], off
	s_mov_b32 m0, s47
	v_lshl_add_u64 v[226:227], s[36:37], 0, v[132:133]
	global_load_lds_dwordx4 v[224:225], off
	s_mov_b32 m0, s50
	s_nop 0
	global_load_lds_dwordx4 v[226:227], off
	s_waitcnt vmcnt(8)
	s_waitcnt lgkmcnt(0)
	s_setprio 1
	v_mfma_f32_16x16x32_bf16 v[62:65], v[152:155], v[184:187], v[62:65]
	v_mfma_f32_16x16x32_bf16 v[58:61], v[160:163], v[184:187], v[58:61]
	s_barrier
	v_mfma_f32_16x16x32_bf16 v[46:49], v[152:155], v[192:195], v[46:49]
	v_mfma_f32_16x16x32_bf16 v[42:45], v[160:163], v[192:195], v[42:45]
	v_mfma_f32_16x16x32_bf16 v[30:33], v[152:155], v[200:203], v[30:33]
	v_mfma_f32_16x16x32_bf16 v[26:29], v[160:163], v[200:203], v[26:29]
	v_mfma_f32_16x16x32_bf16 v[14:17], v[152:155], v[208:211], v[14:17]
	v_mfma_f32_16x16x32_bf16 v[10:13], v[160:163], v[208:211], v[10:13]
	v_mfma_f32_16x16x32_bf16 v[62:65], v[156:159], v[188:191], v[62:65]
	v_mfma_f32_16x16x32_bf16 v[58:61], v[164:167], v[188:191], v[58:61]
	v_mfma_f32_16x16x32_bf16 v[46:49], v[156:159], v[196:199], v[46:49]
	v_mfma_f32_16x16x32_bf16 v[42:45], v[164:167], v[196:199], v[42:45]
	v_mfma_f32_16x16x32_bf16 v[30:33], v[156:159], v[204:207], v[30:33]
	v_mfma_f32_16x16x32_bf16 v[26:29], v[164:167], v[204:207], v[26:29]
	v_mfma_f32_16x16x32_bf16 v[14:17], v[156:159], v[212:215], v[14:17]
	v_mfma_f32_16x16x32_bf16 v[10:13], v[164:167], v[212:215], v[10:13]
	v_mfma_f32_16x16x32_bf16 v[54:57], v[168:171], v[184:187], v[54:57]
	v_mfma_f32_16x16x32_bf16 v[50:53], v[176:179], v[184:187], v[50:53]
	v_mfma_f32_16x16x32_bf16 v[38:41], v[168:171], v[192:195], v[38:41]
	v_mfma_f32_16x16x32_bf16 v[34:37], v[176:179], v[192:195], v[34:37]
	v_mfma_f32_16x16x32_bf16 v[22:25], v[168:171], v[200:203], v[22:25]
	v_mfma_f32_16x16x32_bf16 v[18:21], v[176:179], v[200:203], v[18:21]
	v_mfma_f32_16x16x32_bf16 v[6:9], v[168:171], v[208:211], v[6:9]
	v_mfma_f32_16x16x32_bf16 v[2:5], v[176:179], v[208:211], v[2:5]
	v_mfma_f32_16x16x32_bf16 v[54:57], v[172:175], v[188:191], v[54:57]
	v_mfma_f32_16x16x32_bf16 v[50:53], v[180:183], v[188:191], v[50:53]
	v_mfma_f32_16x16x32_bf16 v[38:41], v[172:175], v[196:199], v[38:41]
	v_mfma_f32_16x16x32_bf16 v[34:37], v[180:183], v[196:199], v[34:37]
	v_mfma_f32_16x16x32_bf16 v[22:25], v[172:175], v[204:207], v[22:25]
	v_mfma_f32_16x16x32_bf16 v[18:21], v[180:183], v[204:207], v[18:21]
	v_mfma_f32_16x16x32_bf16 v[6:9], v[172:175], v[212:215], v[6:9]
	v_mfma_f32_16x16x32_bf16 v[2:5], v[180:183], v[212:215], v[2:5]
	s_setprio 0
	s_barrier
	s_add_i32 s80, 0, 0x18000
	s_add_i32 s81, 0, 0x1c000
	v_add_u32_e32 v164, s80, v147
	v_add_u32_e32 v180, s81, v147
	ds_read_b128 v[152:155], v164
	ds_read_b128 v[156:159], v164 offset:1024
	ds_read_b128 v[160:163], v164 offset:2048
	ds_read_b128 v[164:167], v164 offset:3072
	ds_read_b128 v[168:171], v180
	ds_read_b128 v[172:175], v180 offset:1024
	ds_read_b128 v[176:179], v180 offset:2048
	ds_read_b128 v[180:183], v180 offset:3072
	s_add_u32 s36, s36, s6
	s_addc_u32 s37, s37, s7
	s_mov_b32 m0, s51
	v_lshl_add_u64 v[228:229], s[36:37], 0, v[136:137]
	ds_read_b128 v[184:187], v151 offset:32768
	ds_read_b128 v[188:191], v151 offset:33792
	ds_read_b128 v[192:195], v151 offset:34816
	ds_read_b128 v[196:199], v151 offset:35840
	ds_read_b128 v[200:203], v151 offset:36864
	ds_read_b128 v[204:207], v151 offset:37888
	ds_read_b128 v[208:211], v151 offset:38912
	ds_read_b128 v[212:215], v151 offset:39936
	global_load_lds_dwordx4 v[228:229], off
	v_lshl_add_u64 v[228:229], s[36:37], 0, v[132:133]
	s_mov_b32 m0, s54
	s_nop 0
	global_load_lds_dwordx4 v[228:229], off
	s_waitcnt vmcnt(8)
	s_waitcnt lgkmcnt(0)
	s_setprio 1
	v_mfma_f32_16x16x32_bf16 v[122:125], v[152:155], v[184:187], v[122:125]
	v_mfma_f32_16x16x32_bf16 v[126:129], v[160:163], v[184:187], v[126:129]
	s_barrier
	v_mfma_f32_16x16x32_bf16 v[110:113], v[152:155], v[192:195], v[110:113]
	v_mfma_f32_16x16x32_bf16 v[106:109], v[160:163], v[192:195], v[106:109]
	v_mfma_f32_16x16x32_bf16 v[94:97], v[152:155], v[200:203], v[94:97]
	v_mfma_f32_16x16x32_bf16 v[90:93], v[160:163], v[200:203], v[90:93]
	v_mfma_f32_16x16x32_bf16 v[78:81], v[152:155], v[208:211], v[78:81]
	v_mfma_f32_16x16x32_bf16 v[74:77], v[160:163], v[208:211], v[74:77]
	v_mfma_f32_16x16x32_bf16 v[122:125], v[156:159], v[188:191], v[122:125]
	v_mfma_f32_16x16x32_bf16 v[126:129], v[164:167], v[188:191], v[126:129]
	v_mfma_f32_16x16x32_bf16 v[110:113], v[156:159], v[196:199], v[110:113]
	v_mfma_f32_16x16x32_bf16 v[106:109], v[164:167], v[196:199], v[106:109]
	v_mfma_f32_16x16x32_bf16 v[94:97], v[156:159], v[204:207], v[94:97]
	v_mfma_f32_16x16x32_bf16 v[90:93], v[164:167], v[204:207], v[90:93]
	v_mfma_f32_16x16x32_bf16 v[78:81], v[156:159], v[212:215], v[78:81]
	v_mfma_f32_16x16x32_bf16 v[74:77], v[164:167], v[212:215], v[74:77]
	v_mfma_f32_16x16x32_bf16 v[118:121], v[168:171], v[184:187], v[118:121]
	v_mfma_f32_16x16x32_bf16 v[114:117], v[176:179], v[184:187], v[114:117]
	v_mfma_f32_16x16x32_bf16 v[102:105], v[168:171], v[192:195], v[102:105]
	v_mfma_f32_16x16x32_bf16 v[98:101], v[176:179], v[192:195], v[98:101]
	v_mfma_f32_16x16x32_bf16 v[86:89], v[168:171], v[200:203], v[86:89]
	v_mfma_f32_16x16x32_bf16 v[82:85], v[176:179], v[200:203], v[82:85]
	v_mfma_f32_16x16x32_bf16 v[70:73], v[168:171], v[208:211], v[70:73]
	v_mfma_f32_16x16x32_bf16 v[66:69], v[176:179], v[208:211], v[66:69]
	v_mfma_f32_16x16x32_bf16 v[118:121], v[172:175], v[188:191], v[118:121]
	v_mfma_f32_16x16x32_bf16 v[114:117], v[180:183], v[188:191], v[114:117]
	v_mfma_f32_16x16x32_bf16 v[102:105], v[172:175], v[196:199], v[102:105]
	v_mfma_f32_16x16x32_bf16 v[98:101], v[180:183], v[196:199], v[98:101]
	v_mfma_f32_16x16x32_bf16 v[86:89], v[172:175], v[204:207], v[86:89]
	v_mfma_f32_16x16x32_bf16 v[82:85], v[180:183], v[204:207], v[82:85]
	v_mfma_f32_16x16x32_bf16 v[70:73], v[172:175], v[212:215], v[70:73]
	v_mfma_f32_16x16x32_bf16 v[66:69], v[180:183], v[212:215], v[66:69]
	s_setprio 0
	s_barrier
	s_add_i32 s36, s80, s44
	v_lshl_add_u64 v[216:217], v[216:217], 0, s[16:17]
	s_mov_b32 m0, s36
	ds_read_b128 v[184:187], v151 offset:49152
	ds_read_b128 v[188:191], v151 offset:50176
	ds_read_b128 v[192:195], v151 offset:51200
	ds_read_b128 v[196:199], v151 offset:52224
	ds_read_b128 v[200:203], v151 offset:53248
	ds_read_b128 v[204:207], v151 offset:54272
	ds_read_b128 v[208:211], v151 offset:55296
	ds_read_b128 v[212:215], v151 offset:56320
	global_load_lds_dwordx4 v[216:217], off
	v_lshl_add_u64 v[216:217], v[218:219], 0, s[16:17]
	s_add_i32 m0, s36, 0x2000
	s_add_i32 s36, s81, s44
	global_load_lds_dwordx4 v[216:217], off
	v_lshl_add_u64 v[216:217], v[220:221], 0, s[16:17]
	s_mov_b32 m0, s36
	s_nop 0
	global_load_lds_dwordx4 v[216:217], off
	v_lshl_add_u64 v[216:217], v[222:223], 0, s[16:17]
	s_add_i32 m0, s36, 0x2000
	s_nop 0
	global_load_lds_dwordx4 v[216:217], off
	v_lshl_add_u64 v[216:217], v[224:225], 0, s[16:17]
	s_mov_b32 m0, s56
	s_nop 0
	global_load_lds_dwordx4 v[216:217], off
	v_lshl_add_u64 v[216:217], v[226:227], 0, s[16:17]
	s_mov_b32 m0, s57
	s_nop 0
	global_load_lds_dwordx4 v[216:217], off
	s_waitcnt vmcnt(8)
	s_waitcnt lgkmcnt(0)
	s_setprio 1
	v_mfma_f32_16x16x32_bf16 v[62:65], v[152:155], v[184:187], v[62:65]
	v_mfma_f32_16x16x32_bf16 v[58:61], v[160:163], v[184:187], v[58:61]
	s_barrier
	v_mfma_f32_16x16x32_bf16 v[46:49], v[152:155], v[192:195], v[46:49]
	v_mfma_f32_16x16x32_bf16 v[42:45], v[160:163], v[192:195], v[42:45]
	v_mfma_f32_16x16x32_bf16 v[30:33], v[152:155], v[200:203], v[30:33]
	v_mfma_f32_16x16x32_bf16 v[26:29], v[160:163], v[200:203], v[26:29]
	v_mfma_f32_16x16x32_bf16 v[14:17], v[152:155], v[208:211], v[14:17]
	v_mfma_f32_16x16x32_bf16 v[10:13], v[160:163], v[208:211], v[10:13]
	v_mfma_f32_16x16x32_bf16 v[62:65], v[156:159], v[188:191], v[62:65]
	v_mfma_f32_16x16x32_bf16 v[58:61], v[164:167], v[188:191], v[58:61]
	v_mfma_f32_16x16x32_bf16 v[46:49], v[156:159], v[196:199], v[46:49]
	v_mfma_f32_16x16x32_bf16 v[42:45], v[164:167], v[196:199], v[42:45]
	v_mfma_f32_16x16x32_bf16 v[30:33], v[156:159], v[204:207], v[30:33]
	v_mfma_f32_16x16x32_bf16 v[26:29], v[164:167], v[204:207], v[26:29]
	v_mfma_f32_16x16x32_bf16 v[14:17], v[156:159], v[212:215], v[14:17]
	v_mfma_f32_16x16x32_bf16 v[10:13], v[164:167], v[212:215], v[10:13]
	v_mfma_f32_16x16x32_bf16 v[54:57], v[168:171], v[184:187], v[54:57]
	v_mfma_f32_16x16x32_bf16 v[50:53], v[176:179], v[184:187], v[50:53]
	v_mfma_f32_16x16x32_bf16 v[38:41], v[168:171], v[192:195], v[38:41]
	v_mfma_f32_16x16x32_bf16 v[34:37], v[176:179], v[192:195], v[34:37]
	v_mfma_f32_16x16x32_bf16 v[22:25], v[168:171], v[200:203], v[22:25]
	v_mfma_f32_16x16x32_bf16 v[18:21], v[176:179], v[200:203], v[18:21]
	v_mfma_f32_16x16x32_bf16 v[6:9], v[168:171], v[208:211], v[6:9]
	v_mfma_f32_16x16x32_bf16 v[2:5], v[176:179], v[208:211], v[2:5]
	v_mfma_f32_16x16x32_bf16 v[54:57], v[172:175], v[188:191], v[54:57]
	v_mfma_f32_16x16x32_bf16 v[50:53], v[180:183], v[188:191], v[50:53]
	v_mfma_f32_16x16x32_bf16 v[38:41], v[172:175], v[196:199], v[38:41]
	v_mfma_f32_16x16x32_bf16 v[34:37], v[180:183], v[196:199], v[34:37]
	v_mfma_f32_16x16x32_bf16 v[22:25], v[172:175], v[204:207], v[22:25]
	v_mfma_f32_16x16x32_bf16 v[18:21], v[180:183], v[204:207], v[18:21]
	v_mfma_f32_16x16x32_bf16 v[6:9], v[172:175], v[212:215], v[6:9]
	v_mfma_f32_16x16x32_bf16 v[2:5], v[180:183], v[212:215], v[2:5]
	s_setprio 0
	s_barrier
	s_add_u32 s34, s34, 0x100
	s_addc_u32 s35, s35, 0
	s_add_u32 s67, s67, 0x100
	s_addc_u32 s68, s68, 0
	s_cmp_ge_i32 s69, s58
	s_mov_b32 s36, s69
	s_cbranch_scc0 .LBB0_1514

.LBB0_1754:
	v_add_u32_e32 v158, s80, v229
	v_add_u32_e32 v174, s81, v229
	ds_read_b128 v[146:149], v158
	ds_read_b128 v[150:153], v158 offset:1024
	ds_read_b128 v[154:157], v158 offset:2048
	ds_read_b128 v[158:161], v158 offset:3072
	ds_read_b128 v[162:165], v174
	ds_read_b128 v[166:169], v174 offset:1024
	ds_read_b128 v[170:173], v174 offset:2048
	ds_read_b128 v[174:177], v174 offset:3072
	s_add_i32 s88, s44, 2
	s_add_u32 s89, s42, 0x80
	s_addc_u32 s45, s43, 0
	s_cmp_eq_u32 s67, s44
	s_cselect_b32 s44, s4, s89
	s_cselect_b32 s45, s5, s45
	s_cselect_b32 s91, s39, s87
	s_cselect_b32 s90, s38, s86
	v_lshl_add_u64 v[210:211], s[42:43], 0, v[138:139]
	s_add_i32 m0, s55, 0xc000
	ds_read_b128 v[178:181], v231
	ds_read_b128 v[182:185], v231 offset:1024
	ds_read_b128 v[186:189], v231 offset:2048
	ds_read_b128 v[190:193], v231 offset:3072
	ds_read_b128 v[194:197], v231 offset:4096
	ds_read_b128 v[198:201], v231 offset:5120
	ds_read_b128 v[202:205], v231 offset:6144
	ds_read_b128 v[206:209], v231 offset:7168
	global_load_lds_dwordx4 v[210:211], off
	v_lshl_add_u64 v[210:211], s[42:43], 0, v[140:141]
	s_add_i32 m0, s55, 0xe000
	s_nop 0
	global_load_lds_dwordx4 v[210:211], off
	s_waitcnt vmcnt(8)
	s_waitcnt lgkmcnt(0)
	s_setprio 1
	v_mfma_i32_16x16x64_i8 v[126:129], v[146:149], v[178:181], v[126:129]
	v_mfma_i32_16x16x64_i8 v[122:125], v[154:157], v[178:181], v[122:125]
	s_barrier
	v_mfma_i32_16x16x64_i8 v[118:121], v[146:149], v[186:189], v[118:121]
	v_mfma_i32_16x16x64_i8 v[114:117], v[154:157], v[186:189], v[114:117]
	v_mfma_i32_16x16x64_i8 v[106:109], v[146:149], v[194:197], v[106:109]
	v_mfma_i32_16x16x64_i8 v[98:101], v[154:157], v[194:197], v[98:101]
	v_mfma_i32_16x16x64_i8 v[90:93], v[146:149], v[202:205], v[90:93]
	v_mfma_i32_16x16x64_i8 v[82:85], v[154:157], v[202:205], v[82:85]
	v_mfma_i32_16x16x64_i8 v[126:129], v[150:153], v[182:185], v[126:129]
	v_mfma_i32_16x16x64_i8 v[122:125], v[158:161], v[182:185], v[122:125]
	v_mfma_i32_16x16x64_i8 v[118:121], v[150:153], v[190:193], v[118:121]
	v_mfma_i32_16x16x64_i8 v[114:117], v[158:161], v[190:193], v[114:117]
	v_mfma_i32_16x16x64_i8 v[106:109], v[150:153], v[198:201], v[106:109]
	v_mfma_i32_16x16x64_i8 v[98:101], v[158:161], v[198:201], v[98:101]
	v_mfma_i32_16x16x64_i8 v[90:93], v[150:153], v[206:209], v[90:93]
	v_mfma_i32_16x16x64_i8 v[82:85], v[158:161], v[206:209], v[82:85]
	v_mfma_i32_16x16x64_i8 v[110:113], v[162:165], v[178:181], v[110:113]
	v_mfma_i32_16x16x64_i8 v[102:105], v[170:173], v[178:181], v[102:105]
	v_mfma_i32_16x16x64_i8 v[94:97], v[162:165], v[186:189], v[94:97]
	v_mfma_i32_16x16x64_i8 v[86:89], v[170:173], v[186:189], v[86:89]
	v_mfma_i32_16x16x64_i8 v[78:81], v[162:165], v[194:197], v[78:81]
	v_mfma_i32_16x16x64_i8 v[74:77], v[170:173], v[194:197], v[74:77]
	v_mfma_i32_16x16x64_i8 v[70:73], v[162:165], v[202:205], v[70:73]
	v_mfma_i32_16x16x64_i8 v[66:69], v[170:173], v[202:205], v[66:69]
	v_mfma_i32_16x16x64_i8 v[110:113], v[166:169], v[182:185], v[110:113]
	v_mfma_i32_16x16x64_i8 v[102:105], v[174:177], v[182:185], v[102:105]
	v_mfma_i32_16x16x64_i8 v[94:97], v[166:169], v[190:193], v[94:97]
	v_mfma_i32_16x16x64_i8 v[86:89], v[174:177], v[190:193], v[86:89]
	v_mfma_i32_16x16x64_i8 v[78:81], v[166:169], v[198:201], v[78:81]
	v_mfma_i32_16x16x64_i8 v[74:77], v[174:177], v[198:201], v[74:77]
	v_mfma_i32_16x16x64_i8 v[70:73], v[166:169], v[206:209], v[70:73]
	v_mfma_i32_16x16x64_i8 v[66:69], v[174:177], v[206:209], v[66:69]
	s_setprio 0
	s_barrier
	s_add_i32 s89, s80, s54
	v_lshl_add_u64 v[210:211], s[90:91], 0, v[132:133]
	s_mov_b32 m0, s89
	ds_read_b128 v[178:181], v231 offset:16384
	ds_read_b128 v[182:185], v231 offset:17408
	ds_read_b128 v[186:189], v231 offset:18432
	ds_read_b128 v[190:193], v231 offset:19456
	ds_read_b128 v[194:197], v231 offset:20480
	ds_read_b128 v[198:201], v231 offset:21504
	ds_read_b128 v[202:205], v231 offset:22528
	ds_read_b128 v[206:209], v231 offset:23552
	global_load_lds_dwordx4 v[210:211], off
	s_add_i32 m0, s89, 0x2000
	v_lshl_add_u64 v[212:213], s[90:91], 0, v[136:137]
	s_add_u32 s90, s90, s8
	s_addc_u32 s91, s91, s9
	s_add_i32 s89, s81, s54
	global_load_lds_dwordx4 v[212:213], off
	v_lshl_add_u64 v[214:215], s[90:91], 0, v[132:133]
	s_mov_b32 m0, s89
	v_lshl_add_u64 v[216:217], s[90:91], 0, v[136:137]
	global_load_lds_dwordx4 v[214:215], off
	s_add_i32 m0, s89, 0x2000
	v_lshl_add_u64 v[218:219], s[44:45], 0, v[130:131]
	global_load_lds_dwordx4 v[216:217], off
	s_mov_b32 m0, s55
	v_lshl_add_u64 v[220:221], s[44:45], 0, v[134:135]
	global_load_lds_dwordx4 v[218:219], off
	s_mov_b32 m0, s56
	s_nop 0
	global_load_lds_dwordx4 v[220:221], off
	s_waitcnt vmcnt(8)
	s_waitcnt lgkmcnt(0)
	s_setprio 1
	v_mfma_i32_16x16x64_i8 v[62:65], v[146:149], v[178:181], v[62:65]
	v_mfma_i32_16x16x64_i8 v[58:61], v[154:157], v[178:181], v[58:61]
	s_barrier
	v_mfma_i32_16x16x64_i8 v[54:57], v[146:149], v[186:189], v[54:57]
	v_mfma_i32_16x16x64_i8 v[50:53], v[154:157], v[186:189], v[50:53]
	v_mfma_i32_16x16x64_i8 v[42:45], v[146:149], v[194:197], v[42:45]
	v_mfma_i32_16x16x64_i8 v[34:37], v[154:157], v[194:197], v[34:37]
	v_mfma_i32_16x16x64_i8 v[26:29], v[146:149], v[202:205], v[26:29]
	v_mfma_i32_16x16x64_i8 v[18:21], v[154:157], v[202:205], v[18:21]
	v_mfma_i32_16x16x64_i8 v[62:65], v[150:153], v[182:185], v[62:65]
	v_mfma_i32_16x16x64_i8 v[58:61], v[158:161], v[182:185], v[58:61]
	v_mfma_i32_16x16x64_i8 v[54:57], v[150:153], v[190:193], v[54:57]
	v_mfma_i32_16x16x64_i8 v[50:53], v[158:161], v[190:193], v[50:53]
	v_mfma_i32_16x16x64_i8 v[42:45], v[150:153], v[198:201], v[42:45]
	v_mfma_i32_16x16x64_i8 v[34:37], v[158:161], v[198:201], v[34:37]
	v_mfma_i32_16x16x64_i8 v[26:29], v[150:153], v[206:209], v[26:29]
	v_mfma_i32_16x16x64_i8 v[18:21], v[158:161], v[206:209], v[18:21]
	v_mfma_i32_16x16x64_i8 v[46:49], v[162:165], v[178:181], v[46:49]
	v_mfma_i32_16x16x64_i8 v[38:41], v[170:173], v[178:181], v[38:41]
	v_mfma_i32_16x16x64_i8 v[30:33], v[162:165], v[186:189], v[30:33]
	v_mfma_i32_16x16x64_i8 v[22:25], v[170:173], v[186:189], v[22:25]
	v_mfma_i32_16x16x64_i8 v[14:17], v[162:165], v[194:197], v[14:17]
	v_mfma_i32_16x16x64_i8 v[10:13], v[170:173], v[194:197], v[10:13]
	v_mfma_i32_16x16x64_i8 v[6:9], v[162:165], v[202:205], v[6:9]
	v_mfma_i32_16x16x64_i8 v[2:5], v[170:173], v[202:205], v[2:5]
	v_mfma_i32_16x16x64_i8 v[46:49], v[166:169], v[182:185], v[46:49]
	v_mfma_i32_16x16x64_i8 v[38:41], v[174:177], v[182:185], v[38:41]
	v_mfma_i32_16x16x64_i8 v[30:33], v[166:169], v[190:193], v[30:33]
	v_mfma_i32_16x16x64_i8 v[22:25], v[174:177], v[190:193], v[22:25]
	v_mfma_i32_16x16x64_i8 v[14:17], v[166:169], v[198:201], v[14:17]
	v_mfma_i32_16x16x64_i8 v[10:13], v[174:177], v[198:201], v[10:13]
	v_mfma_i32_16x16x64_i8 v[6:9], v[166:169], v[206:209], v[6:9]
	v_mfma_i32_16x16x64_i8 v[2:5], v[174:177], v[206:209], v[2:5]
	s_setprio 0
	s_barrier
	s_add_i32 s89, 0, 0x18000
	s_add_i32 s90, 0, 0x1c000
	v_add_u32_e32 v158, s89, v229
	v_add_u32_e32 v174, s90, v229
	ds_read_b128 v[146:149], v158
	ds_read_b128 v[150:153], v158 offset:1024
	ds_read_b128 v[154:157], v158 offset:2048
	ds_read_b128 v[158:161], v158 offset:3072
	ds_read_b128 v[162:165], v174
	ds_read_b128 v[166:169], v174 offset:1024
	ds_read_b128 v[170:173], v174 offset:2048
	ds_read_b128 v[174:177], v174 offset:3072
	s_add_u32 s44, s44, s8
	s_addc_u32 s45, s45, s9
	s_mov_b32 m0, s57
	v_lshl_add_u64 v[222:223], s[44:45], 0, v[130:131]
	ds_read_b128 v[178:181], v231 offset:32768
	ds_read_b128 v[182:185], v231 offset:33792
	ds_read_b128 v[186:189], v231 offset:34816
	ds_read_b128 v[190:193], v231 offset:35840
	ds_read_b128 v[194:197], v231 offset:36864
	ds_read_b128 v[198:201], v231 offset:37888
	ds_read_b128 v[202:205], v231 offset:38912
	ds_read_b128 v[206:209], v231 offset:39936
	global_load_lds_dwordx4 v[222:223], off
	v_lshl_add_u64 v[222:223], s[44:45], 0, v[134:135]
	s_mov_b32 m0, s58
	s_nop 0
	global_load_lds_dwordx4 v[222:223], off
	s_waitcnt vmcnt(8)
	s_waitcnt lgkmcnt(0)
	s_setprio 1
	v_mfma_i32_16x16x64_i8 v[126:129], v[146:149], v[178:181], v[126:129]
	v_mfma_i32_16x16x64_i8 v[122:125], v[154:157], v[178:181], v[122:125]
	s_barrier
	v_mfma_i32_16x16x64_i8 v[118:121], v[146:149], v[186:189], v[118:121]
	v_mfma_i32_16x16x64_i8 v[114:117], v[154:157], v[186:189], v[114:117]
	v_mfma_i32_16x16x64_i8 v[106:109], v[146:149], v[194:197], v[106:109]
	v_mfma_i32_16x16x64_i8 v[98:101], v[154:157], v[194:197], v[98:101]
	v_mfma_i32_16x16x64_i8 v[90:93], v[146:149], v[202:205], v[90:93]
	v_mfma_i32_16x16x64_i8 v[82:85], v[154:157], v[202:205], v[82:85]
	v_mfma_i32_16x16x64_i8 v[126:129], v[150:153], v[182:185], v[126:129]
	v_mfma_i32_16x16x64_i8 v[122:125], v[158:161], v[182:185], v[122:125]
	v_mfma_i32_16x16x64_i8 v[118:121], v[150:153], v[190:193], v[118:121]
	v_mfma_i32_16x16x64_i8 v[114:117], v[158:161], v[190:193], v[114:117]
	v_mfma_i32_16x16x64_i8 v[106:109], v[150:153], v[198:201], v[106:109]
	v_mfma_i32_16x16x64_i8 v[98:101], v[158:161], v[198:201], v[98:101]
	v_mfma_i32_16x16x64_i8 v[90:93], v[150:153], v[206:209], v[90:93]
	v_mfma_i32_16x16x64_i8 v[82:85], v[158:161], v[206:209], v[82:85]
	v_mfma_i32_16x16x64_i8 v[110:113], v[162:165], v[178:181], v[110:113]
	v_mfma_i32_16x16x64_i8 v[102:105], v[170:173], v[178:181], v[102:105]
	v_mfma_i32_16x16x64_i8 v[94:97], v[162:165], v[186:189], v[94:97]
	v_mfma_i32_16x16x64_i8 v[86:89], v[170:173], v[186:189], v[86:89]
	v_mfma_i32_16x16x64_i8 v[78:81], v[162:165], v[194:197], v[78:81]
	v_mfma_i32_16x16x64_i8 v[74:77], v[170:173], v[194:197], v[74:77]
	v_mfma_i32_16x16x64_i8 v[70:73], v[162:165], v[202:205], v[70:73]
	v_mfma_i32_16x16x64_i8 v[66:69], v[170:173], v[202:205], v[66:69]
	v_mfma_i32_16x16x64_i8 v[110:113], v[166:169], v[182:185], v[110:113]
	v_mfma_i32_16x16x64_i8 v[102:105], v[174:177], v[182:185], v[102:105]
	v_mfma_i32_16x16x64_i8 v[94:97], v[166:169], v[190:193], v[94:97]
	v_mfma_i32_16x16x64_i8 v[86:89], v[174:177], v[190:193], v[86:89]
	v_mfma_i32_16x16x64_i8 v[78:81], v[166:169], v[198:201], v[78:81]
	v_mfma_i32_16x16x64_i8 v[74:77], v[174:177], v[198:201], v[74:77]
	v_mfma_i32_16x16x64_i8 v[70:73], v[166:169], v[206:209], v[70:73]
	v_mfma_i32_16x16x64_i8 v[66:69], v[174:177], v[206:209], v[66:69]
	s_setprio 0
	s_barrier
	s_add_i32 s44, s89, s54
	v_lshl_add_u64 v[210:211], v[210:211], 0, s[30:31]
	s_mov_b32 m0, s44
	ds_read_b128 v[178:181], v231 offset:49152
	ds_read_b128 v[182:185], v231 offset:50176
	ds_read_b128 v[186:189], v231 offset:51200
	ds_read_b128 v[190:193], v231 offset:52224
	ds_read_b128 v[194:197], v231 offset:53248
	ds_read_b128 v[198:201], v231 offset:54272
	ds_read_b128 v[202:205], v231 offset:55296
	ds_read_b128 v[206:209], v231 offset:56320
	global_load_lds_dwordx4 v[210:211], off
	v_lshl_add_u64 v[210:211], v[212:213], 0, s[30:31]
	s_add_i32 m0, s44, 0x2000
	s_add_i32 s44, s90, s54
	global_load_lds_dwordx4 v[210:211], off
	v_lshl_add_u64 v[210:211], v[214:215], 0, s[30:31]
	s_mov_b32 m0, s44
	s_nop 0
	global_load_lds_dwordx4 v[210:211], off
	v_lshl_add_u64 v[210:211], v[216:217], 0, s[30:31]
	s_add_i32 m0, s44, 0x2000
	s_nop 0
	global_load_lds_dwordx4 v[210:211], off
	v_lshl_add_u64 v[210:211], v[218:219], 0, s[30:31]
	s_mov_b32 m0, s63
	s_nop 0
	global_load_lds_dwordx4 v[210:211], off
	v_lshl_add_u64 v[210:211], v[220:221], 0, s[30:31]
	s_mov_b32 m0, s64
	s_nop 0
	global_load_lds_dwordx4 v[210:211], off
	s_waitcnt vmcnt(8)
	s_waitcnt lgkmcnt(0)
	s_setprio 1
	v_mfma_i32_16x16x64_i8 v[62:65], v[146:149], v[178:181], v[62:65]
	v_mfma_i32_16x16x64_i8 v[58:61], v[154:157], v[178:181], v[58:61]
	s_barrier
	v_mfma_i32_16x16x64_i8 v[54:57], v[146:149], v[186:189], v[54:57]
	v_mfma_i32_16x16x64_i8 v[50:53], v[154:157], v[186:189], v[50:53]
	v_mfma_i32_16x16x64_i8 v[42:45], v[146:149], v[194:197], v[42:45]
	v_mfma_i32_16x16x64_i8 v[34:37], v[154:157], v[194:197], v[34:37]
	v_mfma_i32_16x16x64_i8 v[26:29], v[146:149], v[202:205], v[26:29]
	v_mfma_i32_16x16x64_i8 v[18:21], v[154:157], v[202:205], v[18:21]
	v_mfma_i32_16x16x64_i8 v[62:65], v[150:153], v[182:185], v[62:65]
	v_mfma_i32_16x16x64_i8 v[58:61], v[158:161], v[182:185], v[58:61]
	v_mfma_i32_16x16x64_i8 v[54:57], v[150:153], v[190:193], v[54:57]
	v_mfma_i32_16x16x64_i8 v[50:53], v[158:161], v[190:193], v[50:53]
	v_mfma_i32_16x16x64_i8 v[42:45], v[150:153], v[198:201], v[42:45]
	v_mfma_i32_16x16x64_i8 v[34:37], v[158:161], v[198:201], v[34:37]
	v_mfma_i32_16x16x64_i8 v[26:29], v[150:153], v[206:209], v[26:29]
	v_mfma_i32_16x16x64_i8 v[18:21], v[158:161], v[206:209], v[18:21]
	v_mfma_i32_16x16x64_i8 v[46:49], v[162:165], v[178:181], v[46:49]
	v_mfma_i32_16x16x64_i8 v[38:41], v[170:173], v[178:181], v[38:41]
	v_mfma_i32_16x16x64_i8 v[30:33], v[162:165], v[186:189], v[30:33]
	v_mfma_i32_16x16x64_i8 v[22:25], v[170:173], v[186:189], v[22:25]
	v_mfma_i32_16x16x64_i8 v[14:17], v[162:165], v[194:197], v[14:17]
	v_mfma_i32_16x16x64_i8 v[10:13], v[170:173], v[194:197], v[10:13]
	v_mfma_i32_16x16x64_i8 v[6:9], v[162:165], v[202:205], v[6:9]
	v_mfma_i32_16x16x64_i8 v[2:5], v[170:173], v[202:205], v[2:5]
	v_mfma_i32_16x16x64_i8 v[46:49], v[166:169], v[182:185], v[46:49]
	v_mfma_i32_16x16x64_i8 v[38:41], v[174:177], v[182:185], v[38:41]
	v_mfma_i32_16x16x64_i8 v[30:33], v[166:169], v[190:193], v[30:33]
	v_mfma_i32_16x16x64_i8 v[22:25], v[174:177], v[190:193], v[22:25]
	v_mfma_i32_16x16x64_i8 v[14:17], v[166:169], v[198:201], v[14:17]
	v_mfma_i32_16x16x64_i8 v[10:13], v[174:177], v[198:201], v[10:13]
	v_mfma_i32_16x16x64_i8 v[6:9], v[166:169], v[206:209], v[6:9]
	v_mfma_i32_16x16x64_i8 v[2:5], v[174:177], v[206:209], v[2:5]
	s_setprio 0
	s_barrier
	s_add_u32 s42, s42, 0x100
	s_addc_u32 s43, s43, 0
	s_add_u32 s86, s86, 0x100
	s_addc_u32 s87, s87, 0
	s_cmp_ge_i32 s88, s66
	s_mov_b32 s44, s88
	s_cbranch_scc0 .LBB0_1754
	v_cvt_f32_i32_e32 v214, v126
	v_cvt_f32_i32_e32 v215, v127
	v_cvt_f32_i32_e32 v212, v128
	v_cvt_f32_i32_e32 v213, v129
	v_cvt_f32_i32_e32 v218, v122
	v_cvt_f32_i32_e32 v219, v123
	v_cvt_f32_i32_e32 v216, v124
	v_cvt_f32_i32_e32 v217, v125
	v_cvt_f32_i32_e32 v222, v110
	v_cvt_f32_i32_e32 v223, v111
	v_cvt_f32_i32_e32 v220, v112
	v_cvt_f32_i32_e32 v221, v113
	v_cvt_f32_i32_e32 v226, v102
	v_cvt_f32_i32_e32 v227, v103
	v_cvt_f32_i32_e32 v224, v104
	v_cvt_f32_i32_e32 v225, v105
	v_cvt_f32_i32_e32 v194, v118
	v_cvt_f32_i32_e32 v195, v119
	v_cvt_f32_i32_e32 v192, v120
	v_cvt_f32_i32_e32 v193, v121
	v_cvt_f32_i32_e32 v200, v114
	v_cvt_f32_i32_e32 v201, v115
	v_cvt_f32_i32_e32 v198, v116
	v_cvt_f32_i32_e32 v199, v117
	v_cvt_f32_i32_e32 v206, v94
	v_cvt_f32_i32_e32 v207, v95
	v_cvt_f32_i32_e32 v202, v96
	v_cvt_f32_i32_e32 v203, v97
	v_cvt_f32_i32_e32 v208, v86
	v_cvt_f32_i32_e32 v209, v87
	v_cvt_f32_i32_e32 v204, v88
	v_cvt_f32_i32_e32 v205, v89
	v_cvt_f32_i32_e32 v178, v106
	v_cvt_f32_i32_e32 v179, v107
	v_cvt_f32_i32_e32 v176, v108
	v_cvt_f32_i32_e32 v177, v109
	v_cvt_f32_i32_e32 v182, v98
	v_cvt_f32_i32_e32 v183, v99
	v_cvt_f32_i32_e32 v180, v100
	v_cvt_f32_i32_e32 v181, v101
	v_cvt_f32_i32_e32 v188, v78
	v_cvt_f32_i32_e32 v189, v79
	v_cvt_f32_i32_e32 v184, v80
	v_cvt_f32_i32_e32 v185, v81
	v_cvt_f32_i32_e32 v190, v74
	v_cvt_f32_i32_e32 v191, v75
	v_cvt_f32_i32_e32 v186, v76
	v_cvt_f32_i32_e32 v187, v77
	v_cvt_f32_i32_e32 v162, v90
	v_cvt_f32_i32_e32 v163, v91
	v_cvt_f32_i32_e32 v160, v92
	v_cvt_f32_i32_e32 v161, v93
	v_cvt_f32_i32_e32 v166, v82
	v_cvt_f32_i32_e32 v167, v83
	v_cvt_f32_i32_e32 v164, v84
	v_cvt_f32_i32_e32 v165, v85
	v_cvt_f32_i32_e32 v172, v70
	v_cvt_f32_i32_e32 v173, v71
	v_cvt_f32_i32_e32 v168, v72
	v_cvt_f32_i32_e32 v169, v73
	v_cvt_f32_i32_e32 v174, v66
	v_cvt_f32_i32_e32 v175, v67
	v_cvt_f32_i32_e32 v170, v68
	v_cvt_f32_i32_e32 v171, v69
	v_cvt_f32_i32_e32 v146, v62
	v_cvt_f32_i32_e32 v147, v63
	v_cvt_f32_i32_e32 v128, v64
	v_cvt_f32_i32_e32 v129, v65
	v_cvt_f32_i32_e32 v150, v58
	v_cvt_f32_i32_e32 v151, v59
	v_cvt_f32_i32_e32 v148, v60
	v_cvt_f32_i32_e32 v149, v61
	v_cvt_f32_i32_e32 v156, v46
	v_cvt_f32_i32_e32 v157, v47
	v_cvt_f32_i32_e32 v152, v48
	v_cvt_f32_i32_e32 v153, v49
	v_cvt_f32_i32_e32 v158, v38
	v_cvt_f32_i32_e32 v159, v39
	v_cvt_f32_i32_e32 v154, v40
	v_cvt_f32_i32_e32 v155, v41
	v_cvt_f32_i32_e32 v114, v54
	v_cvt_f32_i32_e32 v115, v55
	v_cvt_f32_i32_e32 v112, v56
	v_cvt_f32_i32_e32 v113, v57
	v_cvt_f32_i32_e32 v118, v50
	v_cvt_f32_i32_e32 v119, v51
	v_cvt_f32_i32_e32 v116, v52
	v_cvt_f32_i32_e32 v117, v53
	v_cvt_f32_i32_e32 v124, v30
	v_cvt_f32_i32_e32 v125, v31
	v_cvt_f32_i32_e32 v120, v32
	v_cvt_f32_i32_e32 v121, v33
	v_cvt_f32_i32_e32 v126, v22
	v_cvt_f32_i32_e32 v127, v23
	v_cvt_f32_i32_e32 v122, v24
	v_cvt_f32_i32_e32 v123, v25
	v_cvt_f32_i32_e32 v64, v42
	v_cvt_f32_i32_e32 v65, v43
	v_cvt_f32_i32_e32 v62, v44
	v_cvt_f32_i32_e32 v63, v45
	v_cvt_f32_i32_e32 v68, v34
	v_cvt_f32_i32_e32 v69, v35
	v_cvt_f32_i32_e32 v66, v36
	v_cvt_f32_i32_e32 v67, v37
	v_cvt_f32_i32_e32 v74, v14
	v_cvt_f32_i32_e32 v75, v15
	v_cvt_f32_i32_e32 v70, v16
	v_cvt_f32_i32_e32 v71, v17
	v_cvt_f32_i32_e32 v76, v10
	v_cvt_f32_i32_e32 v77, v11
	v_cvt_f32_i32_e32 v72, v12
	v_cvt_f32_i32_e32 v73, v13
	v_cvt_f32_i32_e32 v48, v26
	v_cvt_f32_i32_e32 v49, v27
	v_cvt_f32_i32_e32 v46, v28
	v_cvt_f32_i32_e32 v47, v29
	v_cvt_f32_i32_e32 v52, v18
	v_cvt_f32_i32_e32 v53, v19
	v_cvt_f32_i32_e32 v50, v20
	v_cvt_f32_i32_e32 v51, v21
	v_cvt_f32_i32_e32 v58, v6
	v_cvt_f32_i32_e32 v59, v7
	v_cvt_f32_i32_e32 v54, v8
	v_cvt_f32_i32_e32 v55, v9
	v_cvt_f32_i32_e32 v60, v2
	v_cvt_f32_i32_e32 v61, v3
	v_cvt_f32_i32_e32 v56, v4
	v_cvt_f32_i32_e32 v57, v5

.LBB0_1939:
	v_add_u32_e32 v138, s62, v188
	ds_read_b128 v[148:151], v138
	ds_read_b128 v[152:155], v138 offset:1024
	ds_read_b128 v[156:159], v138 offset:2048
	ds_read_b128 v[160:163], v138 offset:3072
	v_add_u32_e32 v138, s63, v188
	ds_read_b128 v[164:167], v138
	ds_read_b128 v[168:171], v138 offset:1024
	ds_read_b128 v[172:175], v138 offset:2048
	ds_read_b128 v[176:179], v138 offset:3072
	s_add_i32 s66, s28, 2
	s_add_u32 s67, s26, 0x80
	s_addc_u32 s29, s27, 0
	s_cmp_eq_u32 s60, s28
	s_cselect_b32 s28, s2, s67
	s_cselect_b32 s29, s3, s29
	s_cselect_b32 s69, s25, s35
	s_cselect_b32 s68, s24, s34
	v_lshl_add_u64 v[184:185], s[26:27], 0, v[140:141]
	s_add_i32 m0, s44, 0xc000
	ds_read_b128 v[180:183], v189
	ds_read_b128 v[190:193], v189 offset:1024
	ds_read_b128 v[194:197], v189 offset:2048
	ds_read_b128 v[198:201], v189 offset:3072
	ds_read_b128 v[202:205], v189 offset:4096
	ds_read_b128 v[206:209], v189 offset:5120
	ds_read_b128 v[210:213], v189 offset:6144
	ds_read_b128 v[214:217], v189 offset:7168
	global_load_lds_dwordx4 v[184:185], off
	v_lshl_add_u64 v[184:185], s[26:27], 0, v[142:143]
	s_add_i32 m0, s44, 0xe000
	s_nop 0
	global_load_lds_dwordx4 v[184:185], off
	s_waitcnt vmcnt(8)
	s_waitcnt lgkmcnt(0)
	s_setprio 1
	v_mfma_i32_16x16x64_i8 v[126:129], v[148:151], v[180:183], v[126:129]
	v_mfma_i32_16x16x64_i8 v[122:125], v[156:159], v[180:183], v[122:125]
	s_barrier
	v_mfma_i32_16x16x64_i8 v[118:121], v[148:151], v[194:197], v[118:121]
	v_mfma_i32_16x16x64_i8 v[114:117], v[156:159], v[194:197], v[114:117]
	v_mfma_i32_16x16x64_i8 v[106:109], v[148:151], v[202:205], v[106:109]
	v_mfma_i32_16x16x64_i8 v[98:101], v[156:159], v[202:205], v[98:101]
	v_mfma_i32_16x16x64_i8 v[90:93], v[148:151], v[210:213], v[90:93]
	v_mfma_i32_16x16x64_i8 v[82:85], v[156:159], v[210:213], v[82:85]
	v_mfma_i32_16x16x64_i8 v[126:129], v[152:155], v[190:193], v[126:129]
	v_mfma_i32_16x16x64_i8 v[122:125], v[160:163], v[190:193], v[122:125]
	v_mfma_i32_16x16x64_i8 v[118:121], v[152:155], v[198:201], v[118:121]
	v_mfma_i32_16x16x64_i8 v[114:117], v[160:163], v[198:201], v[114:117]
	v_mfma_i32_16x16x64_i8 v[106:109], v[152:155], v[206:209], v[106:109]
	v_mfma_i32_16x16x64_i8 v[98:101], v[160:163], v[206:209], v[98:101]
	v_mfma_i32_16x16x64_i8 v[90:93], v[152:155], v[214:217], v[90:93]
	v_mfma_i32_16x16x64_i8 v[82:85], v[160:163], v[214:217], v[82:85]
	v_mfma_i32_16x16x64_i8 v[110:113], v[164:167], v[180:183], v[110:113]
	v_mfma_i32_16x16x64_i8 v[102:105], v[172:175], v[180:183], v[102:105]
	v_mfma_i32_16x16x64_i8 v[94:97], v[164:167], v[194:197], v[94:97]
	v_mfma_i32_16x16x64_i8 v[86:89], v[172:175], v[194:197], v[86:89]
	v_mfma_i32_16x16x64_i8 v[78:81], v[164:167], v[202:205], v[78:81]
	v_mfma_i32_16x16x64_i8 v[74:77], v[172:175], v[202:205], v[74:77]
	v_mfma_i32_16x16x64_i8 v[70:73], v[164:167], v[210:213], v[70:73]
	v_mfma_i32_16x16x64_i8 v[66:69], v[172:175], v[210:213], v[66:69]
	v_mfma_i32_16x16x64_i8 v[110:113], v[168:171], v[190:193], v[110:113]
	v_mfma_i32_16x16x64_i8 v[102:105], v[176:179], v[190:193], v[102:105]
	v_mfma_i32_16x16x64_i8 v[94:97], v[168:171], v[198:201], v[94:97]
	v_mfma_i32_16x16x64_i8 v[86:89], v[176:179], v[198:201], v[86:89]
	v_mfma_i32_16x16x64_i8 v[78:81], v[168:171], v[206:209], v[78:81]
	v_mfma_i32_16x16x64_i8 v[74:77], v[176:179], v[206:209], v[74:77]
	v_mfma_i32_16x16x64_i8 v[70:73], v[168:171], v[214:217], v[70:73]
	v_mfma_i32_16x16x64_i8 v[66:69], v[176:179], v[214:217], v[66:69]
	s_setprio 0
	s_barrier
	s_add_i32 s67, s62, s43
	v_lshl_add_u64 v[184:185], s[68:69], 0, v[132:133]
	s_mov_b32 m0, s67
	ds_read_b128 v[180:183], v189 offset:16384
	ds_read_b128 v[190:193], v189 offset:17408
	ds_read_b128 v[194:197], v189 offset:18432
	ds_read_b128 v[198:201], v189 offset:19456
	ds_read_b128 v[202:205], v189 offset:20480
	ds_read_b128 v[206:209], v189 offset:21504
	ds_read_b128 v[210:213], v189 offset:22528
	ds_read_b128 v[214:217], v189 offset:23552
	global_load_lds_dwordx4 v[184:185], off
	s_add_i32 m0, s67, 0x2000
	v_lshl_add_u64 v[218:219], s[68:69], 0, v[136:137]
	s_add_u32 s68, s68, s6
	s_addc_u32 s69, s69, s7
	s_add_i32 s67, s63, s43
	global_load_lds_dwordx4 v[218:219], off
	v_lshl_add_u64 v[220:221], s[68:69], 0, v[132:133]
	s_mov_b32 m0, s67
	v_lshl_add_u64 v[222:223], s[68:69], 0, v[136:137]
	global_load_lds_dwordx4 v[220:221], off
	s_add_i32 m0, s67, 0x2000
	v_lshl_add_u64 v[224:225], s[28:29], 0, v[130:131]
	global_load_lds_dwordx4 v[222:223], off
	s_mov_b32 m0, s44
	v_lshl_add_u64 v[226:227], s[28:29], 0, v[134:135]
	global_load_lds_dwordx4 v[224:225], off
	s_mov_b32 m0, s45
	s_nop 0
	global_load_lds_dwordx4 v[226:227], off
	s_waitcnt vmcnt(8)
	s_waitcnt lgkmcnt(0)
	s_setprio 1
	v_mfma_i32_16x16x64_i8 v[62:65], v[148:151], v[180:183], v[62:65]
	v_mfma_i32_16x16x64_i8 v[58:61], v[156:159], v[180:183], v[58:61]
	s_barrier
	v_mfma_i32_16x16x64_i8 v[54:57], v[148:151], v[194:197], v[54:57]
	v_mfma_i32_16x16x64_i8 v[50:53], v[156:159], v[194:197], v[50:53]
	v_mfma_i32_16x16x64_i8 v[42:45], v[148:151], v[202:205], v[42:45]
	v_mfma_i32_16x16x64_i8 v[34:37], v[156:159], v[202:205], v[34:37]
	v_mfma_i32_16x16x64_i8 v[26:29], v[148:151], v[210:213], v[26:29]
	v_mfma_i32_16x16x64_i8 v[18:21], v[156:159], v[210:213], v[18:21]
	v_mfma_i32_16x16x64_i8 v[62:65], v[152:155], v[190:193], v[62:65]
	v_mfma_i32_16x16x64_i8 v[58:61], v[160:163], v[190:193], v[58:61]
	v_mfma_i32_16x16x64_i8 v[54:57], v[152:155], v[198:201], v[54:57]
	v_mfma_i32_16x16x64_i8 v[50:53], v[160:163], v[198:201], v[50:53]
	v_mfma_i32_16x16x64_i8 v[42:45], v[152:155], v[206:209], v[42:45]
	v_mfma_i32_16x16x64_i8 v[34:37], v[160:163], v[206:209], v[34:37]
	v_mfma_i32_16x16x64_i8 v[26:29], v[152:155], v[214:217], v[26:29]
	v_mfma_i32_16x16x64_i8 v[18:21], v[160:163], v[214:217], v[18:21]
	v_mfma_i32_16x16x64_i8 v[46:49], v[164:167], v[180:183], v[46:49]
	v_mfma_i32_16x16x64_i8 v[38:41], v[172:175], v[180:183], v[38:41]
	v_mfma_i32_16x16x64_i8 v[30:33], v[164:167], v[194:197], v[30:33]
	v_mfma_i32_16x16x64_i8 v[22:25], v[172:175], v[194:197], v[22:25]
	v_mfma_i32_16x16x64_i8 v[14:17], v[164:167], v[202:205], v[14:17]
	v_mfma_i32_16x16x64_i8 v[10:13], v[172:175], v[202:205], v[10:13]
	v_mfma_i32_16x16x64_i8 v[6:9], v[164:167], v[210:213], v[6:9]
	v_mfma_i32_16x16x64_i8 v[2:5], v[172:175], v[210:213], v[2:5]
	v_mfma_i32_16x16x64_i8 v[46:49], v[168:171], v[190:193], v[46:49]
	v_mfma_i32_16x16x64_i8 v[38:41], v[176:179], v[190:193], v[38:41]
	v_mfma_i32_16x16x64_i8 v[30:33], v[168:171], v[198:201], v[30:33]
	v_mfma_i32_16x16x64_i8 v[22:25], v[176:179], v[198:201], v[22:25]
	v_mfma_i32_16x16x64_i8 v[14:17], v[168:171], v[206:209], v[14:17]
	v_mfma_i32_16x16x64_i8 v[10:13], v[176:179], v[206:209], v[10:13]
	v_mfma_i32_16x16x64_i8 v[6:9], v[168:171], v[214:217], v[6:9]
	v_mfma_i32_16x16x64_i8 v[2:5], v[176:179], v[214:217], v[2:5]
	s_setprio 0
	s_barrier
	s_add_i32 s67, 0, 0x18000
	v_add_u32_e32 v138, s67, v188
	s_add_i32 s68, 0, 0x1c000
	ds_read_b128 v[148:151], v138
	ds_read_b128 v[152:155], v138 offset:1024
	ds_read_b128 v[156:159], v138 offset:2048
	ds_read_b128 v[160:163], v138 offset:3072
	v_add_u32_e32 v138, s68, v188
	ds_read_b128 v[164:167], v138
	ds_read_b128 v[168:171], v138 offset:1024
	ds_read_b128 v[172:175], v138 offset:2048
	ds_read_b128 v[176:179], v138 offset:3072
	s_add_u32 s28, s28, s6
	s_addc_u32 s29, s29, s7
	s_mov_b32 m0, s46
	v_lshl_add_u64 v[228:229], s[28:29], 0, v[130:131]
	ds_read_b128 v[180:183], v189 offset:32768
	ds_read_b128 v[190:193], v189 offset:33792
	ds_read_b128 v[194:197], v189 offset:34816
	ds_read_b128 v[198:201], v189 offset:35840
	ds_read_b128 v[202:205], v189 offset:36864
	ds_read_b128 v[206:209], v189 offset:37888
	ds_read_b128 v[210:213], v189 offset:38912
	ds_read_b128 v[214:217], v189 offset:39936
	global_load_lds_dwordx4 v[228:229], off
	v_lshl_add_u64 v[228:229], s[28:29], 0, v[134:135]
	s_mov_b32 m0, s47
	s_nop 0
	global_load_lds_dwordx4 v[228:229], off
	s_waitcnt vmcnt(8)
	s_waitcnt lgkmcnt(0)
	s_setprio 1
	v_mfma_i32_16x16x64_i8 v[126:129], v[148:151], v[180:183], v[126:129]
	v_mfma_i32_16x16x64_i8 v[122:125], v[156:159], v[180:183], v[122:125]
	s_barrier
	v_mfma_i32_16x16x64_i8 v[118:121], v[148:151], v[194:197], v[118:121]
	v_mfma_i32_16x16x64_i8 v[114:117], v[156:159], v[194:197], v[114:117]
	v_mfma_i32_16x16x64_i8 v[106:109], v[148:151], v[202:205], v[106:109]
	v_mfma_i32_16x16x64_i8 v[98:101], v[156:159], v[202:205], v[98:101]
	v_mfma_i32_16x16x64_i8 v[90:93], v[148:151], v[210:213], v[90:93]
	v_mfma_i32_16x16x64_i8 v[82:85], v[156:159], v[210:213], v[82:85]
	v_mfma_i32_16x16x64_i8 v[126:129], v[152:155], v[190:193], v[126:129]
	v_mfma_i32_16x16x64_i8 v[122:125], v[160:163], v[190:193], v[122:125]
	v_mfma_i32_16x16x64_i8 v[118:121], v[152:155], v[198:201], v[118:121]
	v_mfma_i32_16x16x64_i8 v[114:117], v[160:163], v[198:201], v[114:117]
	v_mfma_i32_16x16x64_i8 v[106:109], v[152:155], v[206:209], v[106:109]
	v_mfma_i32_16x16x64_i8 v[98:101], v[160:163], v[206:209], v[98:101]
	v_mfma_i32_16x16x64_i8 v[90:93], v[152:155], v[214:217], v[90:93]
	v_mfma_i32_16x16x64_i8 v[82:85], v[160:163], v[214:217], v[82:85]
	v_mfma_i32_16x16x64_i8 v[110:113], v[164:167], v[180:183], v[110:113]
	v_mfma_i32_16x16x64_i8 v[102:105], v[172:175], v[180:183], v[102:105]
	v_mfma_i32_16x16x64_i8 v[94:97], v[164:167], v[194:197], v[94:97]
	v_mfma_i32_16x16x64_i8 v[86:89], v[172:175], v[194:197], v[86:89]
	v_mfma_i32_16x16x64_i8 v[78:81], v[164:167], v[202:205], v[78:81]
	v_mfma_i32_16x16x64_i8 v[74:77], v[172:175], v[202:205], v[74:77]
	v_mfma_i32_16x16x64_i8 v[70:73], v[164:167], v[210:213], v[70:73]
	v_mfma_i32_16x16x64_i8 v[66:69], v[172:175], v[210:213], v[66:69]
	v_mfma_i32_16x16x64_i8 v[110:113], v[168:171], v[190:193], v[110:113]
	v_mfma_i32_16x16x64_i8 v[102:105], v[176:179], v[190:193], v[102:105]
	v_mfma_i32_16x16x64_i8 v[94:97], v[168:171], v[198:201], v[94:97]
	v_mfma_i32_16x16x64_i8 v[86:89], v[176:179], v[198:201], v[86:89]
	v_mfma_i32_16x16x64_i8 v[78:81], v[168:171], v[206:209], v[78:81]
	v_mfma_i32_16x16x64_i8 v[74:77], v[176:179], v[206:209], v[74:77]
	v_mfma_i32_16x16x64_i8 v[70:73], v[168:171], v[214:217], v[70:73]
	v_mfma_i32_16x16x64_i8 v[66:69], v[176:179], v[214:217], v[66:69]
	s_setprio 0
	s_barrier
	s_add_i32 s28, s67, s43
	v_lshl_add_u64 v[184:185], v[184:185], 0, s[18:19]
	s_mov_b32 m0, s28
	ds_read_b128 v[180:183], v189 offset:49152
	ds_read_b128 v[190:193], v189 offset:50176
	ds_read_b128 v[194:197], v189 offset:51200
	ds_read_b128 v[198:201], v189 offset:52224
	ds_read_b128 v[202:205], v189 offset:53248
	ds_read_b128 v[206:209], v189 offset:54272
	ds_read_b128 v[210:213], v189 offset:55296
	ds_read_b128 v[214:217], v189 offset:56320
	global_load_lds_dwordx4 v[184:185], off
	v_lshl_add_u64 v[184:185], v[218:219], 0, s[18:19]
	s_add_i32 m0, s28, 0x2000
	s_add_i32 s28, s68, s43
	global_load_lds_dwordx4 v[184:185], off
	v_lshl_add_u64 v[184:185], v[220:221], 0, s[18:19]
	s_mov_b32 m0, s28
	s_nop 0
	global_load_lds_dwordx4 v[184:185], off
	v_lshl_add_u64 v[184:185], v[222:223], 0, s[18:19]
	s_add_i32 m0, s28, 0x2000
	s_nop 0
	global_load_lds_dwordx4 v[184:185], off
	v_lshl_add_u64 v[184:185], v[224:225], 0, s[18:19]
	s_mov_b32 m0, s55
	s_nop 0
	global_load_lds_dwordx4 v[184:185], off
	v_lshl_add_u64 v[184:185], v[226:227], 0, s[18:19]
	s_mov_b32 m0, s56
	s_nop 0
	global_load_lds_dwordx4 v[184:185], off
	s_waitcnt vmcnt(8)
	s_waitcnt lgkmcnt(0)
	s_setprio 1
	v_mfma_i32_16x16x64_i8 v[62:65], v[148:151], v[180:183], v[62:65]
	v_mfma_i32_16x16x64_i8 v[58:61], v[156:159], v[180:183], v[58:61]
	s_barrier
	v_mfma_i32_16x16x64_i8 v[54:57], v[148:151], v[194:197], v[54:57]
	v_mfma_i32_16x16x64_i8 v[50:53], v[156:159], v[194:197], v[50:53]
	v_mfma_i32_16x16x64_i8 v[42:45], v[148:151], v[202:205], v[42:45]
	v_mfma_i32_16x16x64_i8 v[34:37], v[156:159], v[202:205], v[34:37]
	v_mfma_i32_16x16x64_i8 v[26:29], v[148:151], v[210:213], v[26:29]
	v_mfma_i32_16x16x64_i8 v[18:21], v[156:159], v[210:213], v[18:21]
	v_mfma_i32_16x16x64_i8 v[62:65], v[152:155], v[190:193], v[62:65]
	v_mfma_i32_16x16x64_i8 v[58:61], v[160:163], v[190:193], v[58:61]
	v_mfma_i32_16x16x64_i8 v[54:57], v[152:155], v[198:201], v[54:57]
	v_mfma_i32_16x16x64_i8 v[50:53], v[160:163], v[198:201], v[50:53]
	v_mfma_i32_16x16x64_i8 v[42:45], v[152:155], v[206:209], v[42:45]
	v_mfma_i32_16x16x64_i8 v[34:37], v[160:163], v[206:209], v[34:37]
	v_mfma_i32_16x16x64_i8 v[26:29], v[152:155], v[214:217], v[26:29]
	v_mfma_i32_16x16x64_i8 v[18:21], v[160:163], v[214:217], v[18:21]
	v_mfma_i32_16x16x64_i8 v[46:49], v[164:167], v[180:183], v[46:49]
	v_mfma_i32_16x16x64_i8 v[38:41], v[172:175], v[180:183], v[38:41]
	v_mfma_i32_16x16x64_i8 v[30:33], v[164:167], v[194:197], v[30:33]
	v_mfma_i32_16x16x64_i8 v[22:25], v[172:175], v[194:197], v[22:25]
	v_mfma_i32_16x16x64_i8 v[14:17], v[164:167], v[202:205], v[14:17]
	v_mfma_i32_16x16x64_i8 v[10:13], v[172:175], v[202:205], v[10:13]
	v_mfma_i32_16x16x64_i8 v[6:9], v[164:167], v[210:213], v[6:9]
	v_mfma_i32_16x16x64_i8 v[2:5], v[172:175], v[210:213], v[2:5]
	v_mfma_i32_16x16x64_i8 v[46:49], v[168:171], v[190:193], v[46:49]
	v_mfma_i32_16x16x64_i8 v[38:41], v[176:179], v[190:193], v[38:41]
	v_mfma_i32_16x16x64_i8 v[30:33], v[168:171], v[198:201], v[30:33]
	v_mfma_i32_16x16x64_i8 v[22:25], v[176:179], v[198:201], v[22:25]
	v_mfma_i32_16x16x64_i8 v[14:17], v[168:171], v[206:209], v[14:17]
	v_mfma_i32_16x16x64_i8 v[10:13], v[176:179], v[206:209], v[10:13]
	v_mfma_i32_16x16x64_i8 v[6:9], v[168:171], v[214:217], v[6:9]
	v_mfma_i32_16x16x64_i8 v[2:5], v[176:179], v[214:217], v[2:5]
	s_setprio 0
	s_barrier
	s_add_u32 s26, s26, 0x100
	s_addc_u32 s27, s27, 0
	s_add_u32 s34, s34, 0x100
	s_addc_u32 s35, s35, 0
	s_cmp_ge_i32 s66, s57
	s_mov_b32 s28, s66
	s_cbranch_scc0 .LBB0_1939
	v_cvt_f32_i32_e32 v172, v126
	v_cvt_f32_i32_e32 v173, v127
	v_cvt_f32_i32_e32 v170, v128
	v_cvt_f32_i32_e32 v171, v129
	v_cvt_f32_i32_e32 v174, v122
	v_cvt_f32_i32_e32 v175, v123
	v_cvt_f32_i32_e32 v176, v124
	v_cvt_f32_i32_e32 v177, v125
	v_cvt_f32_i32_e32 v180, v110
	v_cvt_f32_i32_e32 v181, v111
	v_cvt_f32_i32_e32 v182, v112
	v_cvt_f32_i32_e32 v183, v113
	v_cvt_f32_i32_e32 v178, v102
	v_cvt_f32_i32_e32 v179, v103
	v_cvt_f32_i32_e32 v184, v104
	v_cvt_f32_i32_e32 v185, v105
	v_cvt_f32_i32_e32 v152, v118
	v_cvt_f32_i32_e32 v153, v119
	v_cvt_f32_i32_e32 v154, v120
	v_cvt_f32_i32_e32 v155, v121
	v_cvt_f32_i32_e32 v156, v114
	v_cvt_f32_i32_e32 v157, v115
	v_cvt_f32_i32_e32 v158, v116
	v_cvt_f32_i32_e32 v159, v117
	v_cvt_f32_i32_e32 v160, v94
	v_cvt_f32_i32_e32 v161, v95
	v_cvt_f32_i32_e32 v162, v96
	v_cvt_f32_i32_e32 v163, v97
	v_cvt_f32_i32_e32 v164, v86
	v_cvt_f32_i32_e32 v165, v87
	v_cvt_f32_i32_e32 v166, v88
	v_cvt_f32_i32_e32 v167, v89
	v_cvt_f32_i32_e32 v118, v106
	v_cvt_f32_i32_e32 v119, v107
	v_cvt_f32_i32_e32 v120, v108
	v_cvt_f32_i32_e32 v121, v109
	v_cvt_f32_i32_e32 v122, v98
	v_cvt_f32_i32_e32 v123, v99
	v_cvt_f32_i32_e32 v124, v100
	v_cvt_f32_i32_e32 v125, v101
	v_cvt_f32_i32_e32 v126, v78
	v_cvt_f32_i32_e32 v127, v79
	v_cvt_f32_i32_e32 v128, v80
	v_cvt_f32_i32_e32 v129, v81
	v_cvt_f32_i32_e32 v148, v74
	v_cvt_f32_i32_e32 v149, v75
	v_cvt_f32_i32_e32 v150, v76
	v_cvt_f32_i32_e32 v151, v77
	v_cvt_f32_i32_e32 v102, v90
	v_cvt_f32_i32_e32 v103, v91
	v_cvt_f32_i32_e32 v104, v92
	v_cvt_f32_i32_e32 v105, v93
	v_cvt_f32_i32_e32 v106, v82
	v_cvt_f32_i32_e32 v107, v83
	v_cvt_f32_i32_e32 v108, v84
	v_cvt_f32_i32_e32 v109, v85
	v_cvt_f32_i32_e32 v110, v70
	v_cvt_f32_i32_e32 v111, v71
	v_cvt_f32_i32_e32 v112, v72
	v_cvt_f32_i32_e32 v113, v73
	v_cvt_f32_i32_e32 v114, v66
	v_cvt_f32_i32_e32 v115, v67
	v_cvt_f32_i32_e32 v116, v68
	v_cvt_f32_i32_e32 v117, v69
	v_cvt_f32_i32_e32 v82, v62
	v_cvt_f32_i32_e32 v83, v63
	v_cvt_f32_i32_e32 v84, v64
	v_cvt_f32_i32_e32 v85, v65
	v_cvt_f32_i32_e32 v86, v58
	v_cvt_f32_i32_e32 v87, v59
	v_cvt_f32_i32_e32 v88, v60
	v_cvt_f32_i32_e32 v89, v61
	v_cvt_f32_i32_e32 v92, v46
	v_cvt_f32_i32_e32 v93, v47
	v_cvt_f32_i32_e32 v94, v48
	v_cvt_f32_i32_e32 v95, v49
	v_cvt_f32_i32_e32 v96, v38
	v_cvt_f32_i32_e32 v97, v39
	v_cvt_f32_i32_e32 v98, v40
	v_cvt_f32_i32_e32 v99, v41
	v_cvt_f32_i32_e32 v66, v54
	v_cvt_f32_i32_e32 v67, v55
	v_cvt_f32_i32_e32 v68, v56
	v_cvt_f32_i32_e32 v69, v57
	v_cvt_f32_i32_e32 v70, v50
	v_cvt_f32_i32_e32 v71, v51
	v_cvt_f32_i32_e32 v72, v52
	v_cvt_f32_i32_e32 v73, v53
	v_cvt_f32_i32_e32 v74, v30
	v_cvt_f32_i32_e32 v75, v31
	v_cvt_f32_i32_e32 v76, v32
	v_cvt_f32_i32_e32 v77, v33
	v_cvt_f32_i32_e32 v78, v22
	v_cvt_f32_i32_e32 v79, v23
	v_cvt_f32_i32_e32 v80, v24
	v_cvt_f32_i32_e32 v81, v25
	v_cvt_f32_i32_e32 v50, v42
	v_cvt_f32_i32_e32 v51, v43
	v_cvt_f32_i32_e32 v52, v44
	v_cvt_f32_i32_e32 v53, v45
	v_cvt_f32_i32_e32 v54, v34
	v_cvt_f32_i32_e32 v55, v35
	v_cvt_f32_i32_e32 v56, v36
	v_cvt_f32_i32_e32 v57, v37
	v_cvt_f32_i32_e32 v58, v14
	v_cvt_f32_i32_e32 v59, v15
	v_cvt_f32_i32_e32 v60, v16
	v_cvt_f32_i32_e32 v61, v17
	v_cvt_f32_i32_e32 v62, v10
	v_cvt_f32_i32_e32 v63, v11
	v_cvt_f32_i32_e32 v64, v12
	v_cvt_f32_i32_e32 v65, v13
	v_cvt_f32_i32_e32 v34, v26
	v_cvt_f32_i32_e32 v35, v27
	v_cvt_f32_i32_e32 v36, v28
	v_cvt_f32_i32_e32 v37, v29
	v_cvt_f32_i32_e32 v38, v18
	v_cvt_f32_i32_e32 v39, v19
	v_cvt_f32_i32_e32 v40, v20
	v_cvt_f32_i32_e32 v41, v21
	v_cvt_f32_i32_e32 v42, v6
	v_cvt_f32_i32_e32 v43, v7
	v_cvt_f32_i32_e32 v44, v8
	v_cvt_f32_i32_e32 v45, v9
	v_cvt_f32_i32_e32 v46, v2
	v_cvt_f32_i32_e32 v47, v3
	v_cvt_f32_i32_e32 v48, v4
	v_cvt_f32_i32_e32 v49, v5

.LBB0_2022:
	ds_read_b128 v[114:117], v209
	ds_read_b128 v[118:121], v209 offset:1024
	ds_read_b128 v[122:125], v209 offset:2048
	ds_read_b128 v[126:129], v209 offset:3072
	ds_read_b128 v[146:149], v210
	ds_read_b128 v[150:153], v210 offset:1024
	ds_read_b128 v[154:157], v210 offset:2048
	ds_read_b128 v[158:161], v210 offset:3072
	s_add_i32 s84, s36, 2
	s_add_u32 s37, s34, 0x4000
	s_addc_u32 s38, s35, 0
	s_cmp_eq_u32 s63, s36
	s_cselect_b32 s39, s5, s38
	s_cselect_b32 s38, s4, s37
	s_cselect_b32 s86, s30, s82
	s_cselect_b32 s87, s31, s83
	s_add_u32 s36, s38, 0x8000
	s_addc_u32 s37, s39, 0
	v_lshl_add_u64 v[218:219], s[34:35], 0, v[170:171]
	s_add_i32 m0, s47, 0xc000
	ds_read_b128 v[178:181], v211
	ds_read_b128 v[182:185], v211 offset:1024
	ds_read_b128 v[186:189], v211 offset:2048
	ds_read_b128 v[190:193], v211 offset:3072
	ds_read_b128 v[194:197], v211 offset:4096
	ds_read_b128 v[198:201], v211 offset:5120
	ds_read_b128 v[202:205], v211 offset:6144
	ds_read_b128 v[214:217], v211 offset:7168
	global_load_lds_dwordx4 v[218:219], off
	v_lshl_add_u64 v[218:219], s[34:35], 0, v[172:173]
	s_add_i32 m0, s47, 0xe000
	s_nop 0
	global_load_lds_dwordx4 v[218:219], off
	s_waitcnt vmcnt(8)
	s_waitcnt lgkmcnt(0)
	s_setprio 1
	v_mfma_f32_16x16x32_bf16 v[142:145], v[114:117], v[178:181], v[142:145]
	v_mfma_f32_16x16x32_bf16 v[138:141], v[122:125], v[178:181], v[138:141]
	s_barrier
	v_mfma_f32_16x16x32_bf16 v[110:113], v[114:117], v[186:189], v[110:113]
	v_mfma_f32_16x16x32_bf16 v[106:109], v[122:125], v[186:189], v[106:109]
	v_mfma_f32_16x16x32_bf16 v[94:97], v[114:117], v[194:197], v[94:97]
	v_mfma_f32_16x16x32_bf16 v[90:93], v[122:125], v[194:197], v[90:93]
	v_mfma_f32_16x16x32_bf16 v[78:81], v[114:117], v[202:205], v[78:81]
	v_mfma_f32_16x16x32_bf16 v[74:77], v[122:125], v[202:205], v[74:77]
	v_mfma_f32_16x16x32_bf16 v[142:145], v[118:121], v[182:185], v[142:145]
	v_mfma_f32_16x16x32_bf16 v[138:141], v[126:129], v[182:185], v[138:141]
	v_mfma_f32_16x16x32_bf16 v[110:113], v[118:121], v[190:193], v[110:113]
	v_mfma_f32_16x16x32_bf16 v[106:109], v[126:129], v[190:193], v[106:109]
	v_mfma_f32_16x16x32_bf16 v[94:97], v[118:121], v[198:201], v[94:97]
	v_mfma_f32_16x16x32_bf16 v[90:93], v[126:129], v[198:201], v[90:93]
	v_mfma_f32_16x16x32_bf16 v[78:81], v[118:121], v[214:217], v[78:81]
	v_mfma_f32_16x16x32_bf16 v[74:77], v[126:129], v[214:217], v[74:77]
	v_mfma_f32_16x16x32_bf16 v[134:137], v[146:149], v[178:181], v[134:137]
	v_mfma_f32_16x16x32_bf16 v[130:133], v[154:157], v[178:181], v[130:133]
	v_mfma_f32_16x16x32_bf16 v[102:105], v[146:149], v[186:189], v[102:105]
	v_mfma_f32_16x16x32_bf16 v[98:101], v[154:157], v[186:189], v[98:101]
	v_mfma_f32_16x16x32_bf16 v[86:89], v[146:149], v[194:197], v[86:89]
	v_mfma_f32_16x16x32_bf16 v[82:85], v[154:157], v[194:197], v[82:85]
	v_mfma_f32_16x16x32_bf16 v[70:73], v[146:149], v[202:205], v[70:73]
	v_mfma_f32_16x16x32_bf16 v[66:69], v[154:157], v[202:205], v[66:69]
	v_mfma_f32_16x16x32_bf16 v[134:137], v[150:153], v[182:185], v[134:137]
	v_mfma_f32_16x16x32_bf16 v[130:133], v[158:161], v[182:185], v[130:133]
	v_mfma_f32_16x16x32_bf16 v[102:105], v[150:153], v[190:193], v[102:105]
	v_mfma_f32_16x16x32_bf16 v[98:101], v[158:161], v[190:193], v[98:101]
	v_mfma_f32_16x16x32_bf16 v[86:89], v[150:153], v[198:201], v[86:89]
	v_mfma_f32_16x16x32_bf16 v[82:85], v[158:161], v[198:201], v[82:85]
	v_mfma_f32_16x16x32_bf16 v[70:73], v[150:153], v[214:217], v[70:73]
	v_mfma_f32_16x16x32_bf16 v[66:69], v[158:161], v[214:217], v[66:69]
	s_setprio 0
	s_barrier
	s_add_i32 s85, s66, s46
	v_lshl_add_u64 v[218:219], s[86:87], 0, v[164:165]
	s_mov_b32 m0, s85
	ds_read_b128 v[178:181], v211 offset:16384
	ds_read_b128 v[182:185], v211 offset:17408
	ds_read_b128 v[186:189], v211 offset:18432
	ds_read_b128 v[190:193], v211 offset:19456
	ds_read_b128 v[194:197], v211 offset:20480
	ds_read_b128 v[198:201], v211 offset:21504
	ds_read_b128 v[202:205], v211 offset:22528
	ds_read_b128 v[214:217], v211 offset:23552
	global_load_lds_dwordx4 v[218:219], off
	s_add_i32 m0, s85, 0x2000
	v_lshl_add_u64 v[220:221], s[86:87], 0, v[168:169]
	s_add_u32 s86, s86, s8
	s_addc_u32 s87, s87, s9
	s_add_i32 s85, s67, s46
	global_load_lds_dwordx4 v[220:221], off
	v_lshl_add_u64 v[222:223], s[86:87], 0, v[164:165]
	s_mov_b32 m0, s85
	v_lshl_add_u64 v[224:225], s[86:87], 0, v[168:169]
	global_load_lds_dwordx4 v[222:223], off
	s_add_i32 m0, s85, 0x2000
	v_lshl_add_u64 v[226:227], s[38:39], 0, v[162:163]
	global_load_lds_dwordx4 v[224:225], off
	s_mov_b32 m0, s47
	s_nop 0
	global_load_lds_dwordx4 v[226:227], off
	v_lshl_add_u64 v[226:227], s[38:39], 0, v[166:167]
	s_mov_b32 m0, s50
	s_nop 0
	global_load_lds_dwordx4 v[226:227], off
	s_waitcnt vmcnt(8)
	s_waitcnt lgkmcnt(0)
	s_setprio 1
	v_mfma_f32_16x16x32_bf16 v[62:65], v[114:117], v[178:181], v[62:65]
	v_mfma_f32_16x16x32_bf16 v[58:61], v[122:125], v[178:181], v[58:61]
	s_barrier
	v_mfma_f32_16x16x32_bf16 v[46:49], v[114:117], v[186:189], v[46:49]
	v_mfma_f32_16x16x32_bf16 v[42:45], v[122:125], v[186:189], v[42:45]
	v_mfma_f32_16x16x32_bf16 v[30:33], v[114:117], v[194:197], v[30:33]
	v_mfma_f32_16x16x32_bf16 v[26:29], v[122:125], v[194:197], v[26:29]
	v_mfma_f32_16x16x32_bf16 v[14:17], v[114:117], v[202:205], v[14:17]
	v_mfma_f32_16x16x32_bf16 v[10:13], v[122:125], v[202:205], v[10:13]
	v_mfma_f32_16x16x32_bf16 v[62:65], v[118:121], v[182:185], v[62:65]
	v_mfma_f32_16x16x32_bf16 v[58:61], v[126:129], v[182:185], v[58:61]
	v_mfma_f32_16x16x32_bf16 v[46:49], v[118:121], v[190:193], v[46:49]
	v_mfma_f32_16x16x32_bf16 v[42:45], v[126:129], v[190:193], v[42:45]
	v_mfma_f32_16x16x32_bf16 v[30:33], v[118:121], v[198:201], v[30:33]
	v_mfma_f32_16x16x32_bf16 v[26:29], v[126:129], v[198:201], v[26:29]
	v_mfma_f32_16x16x32_bf16 v[14:17], v[118:121], v[214:217], v[14:17]
	v_mfma_f32_16x16x32_bf16 v[10:13], v[126:129], v[214:217], v[10:13]
	v_mfma_f32_16x16x32_bf16 v[54:57], v[146:149], v[178:181], v[54:57]
	v_mfma_f32_16x16x32_bf16 v[50:53], v[154:157], v[178:181], v[50:53]
	v_mfma_f32_16x16x32_bf16 v[38:41], v[146:149], v[186:189], v[38:41]
	v_mfma_f32_16x16x32_bf16 v[34:37], v[154:157], v[186:189], v[34:37]
	v_mfma_f32_16x16x32_bf16 v[22:25], v[146:149], v[194:197], v[22:25]
	v_mfma_f32_16x16x32_bf16 v[18:21], v[154:157], v[194:197], v[18:21]
	v_mfma_f32_16x16x32_bf16 v[6:9], v[146:149], v[202:205], v[6:9]
	v_mfma_f32_16x16x32_bf16 v[2:5], v[154:157], v[202:205], v[2:5]
	v_mfma_f32_16x16x32_bf16 v[54:57], v[150:153], v[182:185], v[54:57]
	v_mfma_f32_16x16x32_bf16 v[50:53], v[158:161], v[182:185], v[50:53]
	v_mfma_f32_16x16x32_bf16 v[38:41], v[150:153], v[190:193], v[38:41]
	v_mfma_f32_16x16x32_bf16 v[34:37], v[158:161], v[190:193], v[34:37]
	v_mfma_f32_16x16x32_bf16 v[22:25], v[150:153], v[198:201], v[22:25]
	v_mfma_f32_16x16x32_bf16 v[18:21], v[158:161], v[198:201], v[18:21]
	v_mfma_f32_16x16x32_bf16 v[6:9], v[150:153], v[214:217], v[6:9]
	v_mfma_f32_16x16x32_bf16 v[2:5], v[158:161], v[214:217], v[2:5]
	s_setprio 0
	s_barrier
	s_add_i32 s85, 0, 0x18000
	s_add_i32 s86, 0, 0x1c000
	v_add_u32_e32 v126, s85, v207
	v_add_u32_e32 v158, s86, v207
	ds_read_b128 v[114:117], v126
	ds_read_b128 v[118:121], v126 offset:1024
	ds_read_b128 v[122:125], v126 offset:2048
	ds_read_b128 v[126:129], v126 offset:3072
	ds_read_b128 v[146:149], v158
	ds_read_b128 v[150:153], v158 offset:1024
	ds_read_b128 v[154:157], v158 offset:2048
	ds_read_b128 v[158:161], v158 offset:3072
	s_add_u32 s38, s38, 0x4000
	s_addc_u32 s39, s39, 0
	s_mov_b32 m0, s51
	v_lshl_add_u64 v[226:227], s[38:39], 0, v[162:163]
	ds_read_b128 v[178:181], v211 offset:32768
	ds_read_b128 v[182:185], v211 offset:33792
	ds_read_b128 v[186:189], v211 offset:34816
	ds_read_b128 v[190:193], v211 offset:35840
	ds_read_b128 v[194:197], v211 offset:36864
	ds_read_b128 v[198:201], v211 offset:37888
	ds_read_b128 v[202:205], v211 offset:38912
	ds_read_b128 v[214:217], v211 offset:39936
	global_load_lds_dwordx4 v[226:227], off
	v_lshl_add_u64 v[226:227], s[38:39], 0, v[166:167]
	s_mov_b32 m0, s54
	s_nop 0
	global_load_lds_dwordx4 v[226:227], off
	s_waitcnt vmcnt(8)
	s_waitcnt lgkmcnt(0)
	s_setprio 1
	v_mfma_f32_16x16x32_bf16 v[142:145], v[114:117], v[178:181], v[142:145]
	v_mfma_f32_16x16x32_bf16 v[138:141], v[122:125], v[178:181], v[138:141]
	s_barrier
	v_mfma_f32_16x16x32_bf16 v[110:113], v[114:117], v[186:189], v[110:113]
	v_mfma_f32_16x16x32_bf16 v[106:109], v[122:125], v[186:189], v[106:109]
	v_mfma_f32_16x16x32_bf16 v[94:97], v[114:117], v[194:197], v[94:97]
	v_mfma_f32_16x16x32_bf16 v[90:93], v[122:125], v[194:197], v[90:93]
	v_mfma_f32_16x16x32_bf16 v[78:81], v[114:117], v[202:205], v[78:81]
	v_mfma_f32_16x16x32_bf16 v[74:77], v[122:125], v[202:205], v[74:77]
	v_mfma_f32_16x16x32_bf16 v[142:145], v[118:121], v[182:185], v[142:145]
	v_mfma_f32_16x16x32_bf16 v[138:141], v[126:129], v[182:185], v[138:141]
	v_mfma_f32_16x16x32_bf16 v[110:113], v[118:121], v[190:193], v[110:113]
	v_mfma_f32_16x16x32_bf16 v[106:109], v[126:129], v[190:193], v[106:109]
	v_mfma_f32_16x16x32_bf16 v[94:97], v[118:121], v[198:201], v[94:97]
	v_mfma_f32_16x16x32_bf16 v[90:93], v[126:129], v[198:201], v[90:93]
	v_mfma_f32_16x16x32_bf16 v[78:81], v[118:121], v[214:217], v[78:81]
	v_mfma_f32_16x16x32_bf16 v[74:77], v[126:129], v[214:217], v[74:77]
	v_mfma_f32_16x16x32_bf16 v[134:137], v[146:149], v[178:181], v[134:137]
	v_mfma_f32_16x16x32_bf16 v[130:133], v[154:157], v[178:181], v[130:133]
	v_mfma_f32_16x16x32_bf16 v[102:105], v[146:149], v[186:189], v[102:105]
	v_mfma_f32_16x16x32_bf16 v[98:101], v[154:157], v[186:189], v[98:101]
	v_mfma_f32_16x16x32_bf16 v[86:89], v[146:149], v[194:197], v[86:89]
	v_mfma_f32_16x16x32_bf16 v[82:85], v[154:157], v[194:197], v[82:85]
	v_mfma_f32_16x16x32_bf16 v[70:73], v[146:149], v[202:205], v[70:73]
	v_mfma_f32_16x16x32_bf16 v[66:69], v[154:157], v[202:205], v[66:69]
	v_mfma_f32_16x16x32_bf16 v[134:137], v[150:153], v[182:185], v[134:137]
	v_mfma_f32_16x16x32_bf16 v[130:133], v[158:161], v[182:185], v[130:133]
	v_mfma_f32_16x16x32_bf16 v[102:105], v[150:153], v[190:193], v[102:105]
	v_mfma_f32_16x16x32_bf16 v[98:101], v[158:161], v[190:193], v[98:101]
	v_mfma_f32_16x16x32_bf16 v[86:89], v[150:153], v[198:201], v[86:89]
	v_mfma_f32_16x16x32_bf16 v[82:85], v[158:161], v[198:201], v[82:85]
	v_mfma_f32_16x16x32_bf16 v[70:73], v[150:153], v[214:217], v[70:73]
	v_mfma_f32_16x16x32_bf16 v[66:69], v[158:161], v[214:217], v[66:69]
	s_setprio 0
	s_barrier
	s_add_i32 s38, s85, s46
	v_lshl_add_u64 v[218:219], v[218:219], 0, s[24:25]
	s_mov_b32 m0, s38
	ds_read_b128 v[178:181], v211 offset:49152
	ds_read_b128 v[182:185], v211 offset:50176
	ds_read_b128 v[186:189], v211 offset:51200
	ds_read_b128 v[190:193], v211 offset:52224
	ds_read_b128 v[194:197], v211 offset:53248
	ds_read_b128 v[198:201], v211 offset:54272
	ds_read_b128 v[202:205], v211 offset:55296
	ds_read_b128 v[214:217], v211 offset:56320
	global_load_lds_dwordx4 v[218:219], off
	v_lshl_add_u64 v[218:219], v[220:221], 0, s[24:25]
	s_add_i32 m0, s38, 0x2000
	s_add_i32 s38, s86, s46
	global_load_lds_dwordx4 v[218:219], off
	v_lshl_add_u64 v[218:219], v[222:223], 0, s[24:25]
	s_mov_b32 m0, s38
	s_nop 0
	global_load_lds_dwordx4 v[218:219], off
	v_lshl_add_u64 v[218:219], v[224:225], 0, s[24:25]
	s_add_i32 m0, s38, 0x2000
	s_nop 0
	global_load_lds_dwordx4 v[218:219], off
	v_lshl_add_u64 v[218:219], s[36:37], 0, v[162:163]
	s_mov_b32 m0, s61
	s_nop 0
	global_load_lds_dwordx4 v[218:219], off
	v_lshl_add_u64 v[218:219], s[36:37], 0, v[166:167]
	s_mov_b32 m0, s62
	s_nop 0
	global_load_lds_dwordx4 v[218:219], off
	s_waitcnt vmcnt(8)
	s_waitcnt lgkmcnt(0)
	s_setprio 1
	v_mfma_f32_16x16x32_bf16 v[62:65], v[114:117], v[178:181], v[62:65]
	v_mfma_f32_16x16x32_bf16 v[58:61], v[122:125], v[178:181], v[58:61]
	s_barrier
	v_mfma_f32_16x16x32_bf16 v[46:49], v[114:117], v[186:189], v[46:49]
	v_mfma_f32_16x16x32_bf16 v[42:45], v[122:125], v[186:189], v[42:45]
	v_mfma_f32_16x16x32_bf16 v[30:33], v[114:117], v[194:197], v[30:33]
	v_mfma_f32_16x16x32_bf16 v[26:29], v[122:125], v[194:197], v[26:29]
	v_mfma_f32_16x16x32_bf16 v[14:17], v[114:117], v[202:205], v[14:17]
	v_mfma_f32_16x16x32_bf16 v[10:13], v[122:125], v[202:205], v[10:13]
	v_mfma_f32_16x16x32_bf16 v[62:65], v[118:121], v[182:185], v[62:65]
	v_mfma_f32_16x16x32_bf16 v[58:61], v[126:129], v[182:185], v[58:61]
	v_mfma_f32_16x16x32_bf16 v[46:49], v[118:121], v[190:193], v[46:49]
	v_mfma_f32_16x16x32_bf16 v[42:45], v[126:129], v[190:193], v[42:45]
	v_mfma_f32_16x16x32_bf16 v[30:33], v[118:121], v[198:201], v[30:33]
	v_mfma_f32_16x16x32_bf16 v[26:29], v[126:129], v[198:201], v[26:29]
	v_mfma_f32_16x16x32_bf16 v[14:17], v[118:121], v[214:217], v[14:17]
	v_mfma_f32_16x16x32_bf16 v[10:13], v[126:129], v[214:217], v[10:13]
	v_mfma_f32_16x16x32_bf16 v[54:57], v[146:149], v[178:181], v[54:57]
	v_mfma_f32_16x16x32_bf16 v[50:53], v[154:157], v[178:181], v[50:53]
	v_mfma_f32_16x16x32_bf16 v[38:41], v[146:149], v[186:189], v[38:41]
	v_mfma_f32_16x16x32_bf16 v[34:37], v[154:157], v[186:189], v[34:37]
	v_mfma_f32_16x16x32_bf16 v[22:25], v[146:149], v[194:197], v[22:25]
	v_mfma_f32_16x16x32_bf16 v[18:21], v[154:157], v[194:197], v[18:21]
	v_mfma_f32_16x16x32_bf16 v[6:9], v[146:149], v[202:205], v[6:9]
	v_mfma_f32_16x16x32_bf16 v[2:5], v[154:157], v[202:205], v[2:5]
	v_mfma_f32_16x16x32_bf16 v[54:57], v[150:153], v[182:185], v[54:57]
	v_mfma_f32_16x16x32_bf16 v[50:53], v[158:161], v[182:185], v[50:53]
	v_mfma_f32_16x16x32_bf16 v[38:41], v[150:153], v[190:193], v[38:41]
	v_mfma_f32_16x16x32_bf16 v[34:37], v[158:161], v[190:193], v[34:37]
	v_mfma_f32_16x16x32_bf16 v[22:25], v[150:153], v[198:201], v[22:25]
	v_mfma_f32_16x16x32_bf16 v[18:21], v[158:161], v[198:201], v[18:21]
	v_mfma_f32_16x16x32_bf16 v[6:9], v[150:153], v[214:217], v[6:9]
	v_mfma_f32_16x16x32_bf16 v[2:5], v[158:161], v[214:217], v[2:5]
	s_setprio 0
	s_barrier
	s_add_u32 s82, s82, 0x100
	s_addc_u32 s83, s83, 0
	s_add_u32 s34, s34, 0x10000
	s_addc_u32 s35, s35, 0
	s_cmp_ge_i32 s84, s60
	s_mov_b32 s36, s84
	s_cbranch_scc0 .LBB0_2022

.LBB0_2116:
	ds_read_b128 v[34:37], v186
	ds_read_b128 v[38:41], v186 offset:1024
	ds_read_b128 v[50:53], v186 offset:2048
	ds_read_b128 v[54:57], v186 offset:3072
	ds_read_b128 v[168:171], v187
	ds_read_b128 v[172:175], v187 offset:1024
	ds_read_b128 v[176:179], v187 offset:2048
	ds_read_b128 v[192:195], v187 offset:3072
	s_add_i32 s47, s4, 2
	s_add_u32 s50, s2, 0x80
	s_addc_u32 s5, s3, 0
	s_cmp_eq_u32 s85, s4
	s_cselect_b32 s4, s42, s50
	s_cselect_b32 s5, s43, s5
	s_cselect_b32 s51, s45, s7
	s_cselect_b32 s50, s44, s6
	v_lshl_add_u64 v[228:229], s[2:3], 0, v[160:161]
	s_add_i32 m0, s65, 0xc000
	ds_read_b128 v[196:199], v188
	ds_read_b128 v[200:203], v188 offset:1024
	ds_read_b128 v[204:207], v188 offset:2048
	ds_read_b128 v[208:211], v188 offset:3072
	ds_read_b128 v[212:215], v188 offset:4096
	ds_read_b128 v[216:219], v188 offset:5120
	ds_read_b128 v[220:223], v188 offset:6144
	ds_read_b128 v[224:227], v188 offset:7168
	global_load_lds_dwordx4 v[228:229], off
	v_lshl_add_u64 v[228:229], s[2:3], 0, v[162:163]
	s_add_i32 m0, s65, 0xe000
	s_nop 0
	global_load_lds_dwordx4 v[228:229], off
	s_waitcnt vmcnt(8)
	s_waitcnt lgkmcnt(0)
	s_setprio 1
	v_mfma_f32_16x16x32_bf16 v[142:145], v[34:37], v[196:199], v[142:145]
	v_mfma_f32_16x16x32_bf16 v[138:141], v[50:53], v[196:199], v[138:141]
	s_barrier
	v_mfma_f32_16x16x32_bf16 v[126:129], v[34:37], v[204:207], v[126:129]
	v_mfma_f32_16x16x32_bf16 v[122:125], v[50:53], v[204:207], v[122:125]
	v_mfma_f32_16x16x32_bf16 v[110:113], v[34:37], v[212:215], v[110:113]
	v_mfma_f32_16x16x32_bf16 v[106:109], v[50:53], v[212:215], v[106:109]
	v_mfma_f32_16x16x32_bf16 v[94:97], v[34:37], v[220:223], v[94:97]
	v_mfma_f32_16x16x32_bf16 v[90:93], v[50:53], v[220:223], v[90:93]
	v_mfma_f32_16x16x32_bf16 v[142:145], v[38:41], v[200:203], v[142:145]
	v_mfma_f32_16x16x32_bf16 v[138:141], v[54:57], v[200:203], v[138:141]
	v_mfma_f32_16x16x32_bf16 v[126:129], v[38:41], v[208:211], v[126:129]
	v_mfma_f32_16x16x32_bf16 v[122:125], v[54:57], v[208:211], v[122:125]
	v_mfma_f32_16x16x32_bf16 v[110:113], v[38:41], v[216:219], v[110:113]
	v_mfma_f32_16x16x32_bf16 v[106:109], v[54:57], v[216:219], v[106:109]
	v_mfma_f32_16x16x32_bf16 v[94:97], v[38:41], v[224:227], v[94:97]
	v_mfma_f32_16x16x32_bf16 v[90:93], v[54:57], v[224:227], v[90:93]
	v_mfma_f32_16x16x32_bf16 v[134:137], v[168:171], v[196:199], v[134:137]
	v_mfma_f32_16x16x32_bf16 v[130:133], v[176:179], v[196:199], v[130:133]
	v_mfma_f32_16x16x32_bf16 v[118:121], v[168:171], v[204:207], v[118:121]
	v_mfma_f32_16x16x32_bf16 v[114:117], v[176:179], v[204:207], v[114:117]
	v_mfma_f32_16x16x32_bf16 v[102:105], v[168:171], v[212:215], v[102:105]
	v_mfma_f32_16x16x32_bf16 v[98:101], v[176:179], v[212:215], v[98:101]
	v_mfma_f32_16x16x32_bf16 v[86:89], v[168:171], v[220:223], v[86:89]
	v_mfma_f32_16x16x32_bf16 v[82:85], v[176:179], v[220:223], v[82:85]
	v_mfma_f32_16x16x32_bf16 v[134:137], v[172:175], v[200:203], v[134:137]
	v_mfma_f32_16x16x32_bf16 v[130:133], v[192:195], v[200:203], v[130:133]
	v_mfma_f32_16x16x32_bf16 v[118:121], v[172:175], v[208:211], v[118:121]
	v_mfma_f32_16x16x32_bf16 v[114:117], v[192:195], v[208:211], v[114:117]
	v_mfma_f32_16x16x32_bf16 v[102:105], v[172:175], v[216:219], v[102:105]
	v_mfma_f32_16x16x32_bf16 v[98:101], v[192:195], v[216:219], v[98:101]
	v_mfma_f32_16x16x32_bf16 v[86:89], v[172:175], v[224:227], v[86:89]
	v_mfma_f32_16x16x32_bf16 v[82:85], v[192:195], v[224:227], v[82:85]
	s_setprio 0
	s_barrier
	s_add_i32 s55, s88, s62
	v_lshl_add_u64 v[228:229], s[50:51], 0, v[148:149]
	s_mov_b32 m0, s55
	ds_read_b128 v[196:199], v188 offset:16384
	ds_read_b128 v[200:203], v188 offset:17408
	ds_read_b128 v[204:207], v188 offset:18432
	ds_read_b128 v[208:211], v188 offset:19456
	ds_read_b128 v[212:215], v188 offset:20480
	ds_read_b128 v[216:219], v188 offset:21504
	ds_read_b128 v[220:223], v188 offset:22528
	ds_read_b128 v[224:227], v188 offset:23552
	global_load_lds_dwordx4 v[228:229], off
	s_add_i32 m0, s55, 0x2000
	v_lshl_add_u64 v[230:231], s[50:51], 0, v[152:153]
	s_add_u32 s50, s50, s14
	s_addc_u32 s51, s51, s15
	s_add_i32 s55, s89, s62
	global_load_lds_dwordx4 v[230:231], off
	v_lshl_add_u64 v[232:233], s[50:51], 0, v[148:149]
	s_mov_b32 m0, s55
	v_lshl_add_u64 v[234:235], s[50:51], 0, v[152:153]
	global_load_lds_dwordx4 v[232:233], off
	s_add_i32 m0, s55, 0x2000
	v_lshl_add_u64 v[236:237], s[4:5], 0, v[146:147]
	global_load_lds_dwordx4 v[234:235], off
	s_mov_b32 m0, s65
	v_lshl_add_u64 v[238:239], s[4:5], 0, v[150:151]
	global_load_lds_dwordx4 v[236:237], off
	s_mov_b32 m0, s66
	s_nop 0
	global_load_lds_dwordx4 v[238:239], off
	s_waitcnt vmcnt(8)
	s_waitcnt lgkmcnt(0)
	s_setprio 1
	v_mfma_f32_16x16x32_bf16 v[78:81], v[34:37], v[196:199], v[78:81]
	v_mfma_f32_16x16x32_bf16 v[74:77], v[50:53], v[196:199], v[74:77]
	s_barrier
	v_mfma_f32_16x16x32_bf16 v[62:65], v[34:37], v[204:207], v[62:65]
	v_mfma_f32_16x16x32_bf16 v[58:61], v[50:53], v[204:207], v[58:61]
	v_mfma_f32_16x16x32_bf16 v[30:33], v[34:37], v[212:215], v[30:33]
	v_mfma_f32_16x16x32_bf16 v[26:29], v[50:53], v[212:215], v[26:29]
	v_mfma_f32_16x16x32_bf16 v[14:17], v[34:37], v[220:223], v[14:17]
	v_mfma_f32_16x16x32_bf16 v[10:13], v[50:53], v[220:223], v[10:13]
	v_mfma_f32_16x16x32_bf16 v[78:81], v[38:41], v[200:203], v[78:81]
	v_mfma_f32_16x16x32_bf16 v[74:77], v[54:57], v[200:203], v[74:77]
	v_mfma_f32_16x16x32_bf16 v[62:65], v[38:41], v[208:211], v[62:65]
	v_mfma_f32_16x16x32_bf16 v[58:61], v[54:57], v[208:211], v[58:61]
	v_mfma_f32_16x16x32_bf16 v[30:33], v[38:41], v[216:219], v[30:33]
	v_mfma_f32_16x16x32_bf16 v[26:29], v[54:57], v[216:219], v[26:29]
	v_mfma_f32_16x16x32_bf16 v[14:17], v[38:41], v[224:227], v[14:17]
	v_mfma_f32_16x16x32_bf16 v[10:13], v[54:57], v[224:227], v[10:13]
	v_mfma_f32_16x16x32_bf16 v[46:49], v[168:171], v[204:207], v[46:49]
	v_mfma_f32_16x16x32_bf16 v[42:45], v[176:179], v[204:207], v[42:45]
	v_mfma_f32_16x16x32_bf16 v[22:25], v[168:171], v[212:215], v[22:25]
	v_mfma_f32_16x16x32_bf16 v[18:21], v[176:179], v[212:215], v[18:21]
	v_mfma_f32_16x16x32_bf16 v[6:9], v[168:171], v[220:223], v[6:9]
	v_mfma_f32_16x16x32_bf16 v[2:5], v[176:179], v[220:223], v[2:5]
	v_mfma_f32_16x16x32_bf16 v[34:37], v[168:171], v[196:199], v[70:73]
	v_mfma_f32_16x16x32_bf16 v[38:41], v[176:179], v[196:199], v[66:69]
	v_mfma_f32_16x16x32_bf16 v[46:49], v[172:175], v[208:211], v[46:49]
	v_mfma_f32_16x16x32_bf16 v[42:45], v[192:195], v[208:211], v[42:45]
	v_mfma_f32_16x16x32_bf16 v[22:25], v[172:175], v[216:219], v[22:25]
	v_mfma_f32_16x16x32_bf16 v[18:21], v[192:195], v[216:219], v[18:21]
	v_mfma_f32_16x16x32_bf16 v[6:9], v[172:175], v[224:227], v[6:9]
	v_mfma_f32_16x16x32_bf16 v[2:5], v[192:195], v[224:227], v[2:5]
	v_mfma_f32_16x16x32_bf16 v[34:37], v[172:175], v[200:203], v[34:37]
	v_mfma_f32_16x16x32_bf16 v[38:41], v[192:195], v[200:203], v[38:41]
	s_setprio 0
	s_barrier
	s_add_i32 s50, 0, 0x18000
	s_add_i32 s51, 0, 0x1c000
	v_add_u32_e32 v70, s50, v184
	v_add_u32_e32 v154, s51, v184
	ds_read_b128 v[50:53], v70
	ds_read_b128 v[54:57], v70 offset:1024
	ds_read_b128 v[66:69], v70 offset:2048
	ds_read_b128 v[70:73], v70 offset:3072
	ds_read_b128 v[168:171], v154
	ds_read_b128 v[172:175], v154 offset:1024
	ds_read_b128 v[176:179], v154 offset:2048
	ds_read_b128 v[192:195], v154 offset:3072
	s_add_u32 s4, s4, s14
	s_addc_u32 s5, s5, s15
	s_mov_b32 m0, s67
	v_lshl_add_u64 v[240:241], s[4:5], 0, v[146:147]
	ds_read_b128 v[196:199], v188 offset:32768
	ds_read_b128 v[200:203], v188 offset:33792
	ds_read_b128 v[204:207], v188 offset:34816
	ds_read_b128 v[208:211], v188 offset:35840
	ds_read_b128 v[212:215], v188 offset:36864
	ds_read_b128 v[216:219], v188 offset:37888
	ds_read_b128 v[220:223], v188 offset:38912
	ds_read_b128 v[224:227], v188 offset:39936
	global_load_lds_dwordx4 v[240:241], off
	v_lshl_add_u64 v[240:241], s[4:5], 0, v[150:151]
	s_mov_b32 m0, s68
	s_nop 0
	global_load_lds_dwordx4 v[240:241], off
	s_waitcnt vmcnt(8)
	s_waitcnt lgkmcnt(0)
	s_setprio 1
	v_mfma_f32_16x16x32_bf16 v[142:145], v[50:53], v[196:199], v[142:145]
	v_mfma_f32_16x16x32_bf16 v[138:141], v[66:69], v[196:199], v[138:141]
	s_barrier
	v_mfma_f32_16x16x32_bf16 v[126:129], v[50:53], v[204:207], v[126:129]
	v_mfma_f32_16x16x32_bf16 v[122:125], v[66:69], v[204:207], v[122:125]
	v_mfma_f32_16x16x32_bf16 v[110:113], v[50:53], v[212:215], v[110:113]
	v_mfma_f32_16x16x32_bf16 v[106:109], v[66:69], v[212:215], v[106:109]
	v_mfma_f32_16x16x32_bf16 v[94:97], v[50:53], v[220:223], v[94:97]
	v_mfma_f32_16x16x32_bf16 v[90:93], v[66:69], v[220:223], v[90:93]
	v_mfma_f32_16x16x32_bf16 v[142:145], v[54:57], v[200:203], v[142:145]
	v_mfma_f32_16x16x32_bf16 v[138:141], v[70:73], v[200:203], v[138:141]
	v_mfma_f32_16x16x32_bf16 v[126:129], v[54:57], v[208:211], v[126:129]
	v_mfma_f32_16x16x32_bf16 v[122:125], v[70:73], v[208:211], v[122:125]
	v_mfma_f32_16x16x32_bf16 v[110:113], v[54:57], v[216:219], v[110:113]
	v_mfma_f32_16x16x32_bf16 v[106:109], v[70:73], v[216:219], v[106:109]
	v_mfma_f32_16x16x32_bf16 v[94:97], v[54:57], v[224:227], v[94:97]
	v_mfma_f32_16x16x32_bf16 v[90:93], v[70:73], v[224:227], v[90:93]
	v_mfma_f32_16x16x32_bf16 v[134:137], v[168:171], v[196:199], v[134:137]
	v_mfma_f32_16x16x32_bf16 v[130:133], v[176:179], v[196:199], v[130:133]
	v_mfma_f32_16x16x32_bf16 v[118:121], v[168:171], v[204:207], v[118:121]
	v_mfma_f32_16x16x32_bf16 v[114:117], v[176:179], v[204:207], v[114:117]
	v_mfma_f32_16x16x32_bf16 v[102:105], v[168:171], v[212:215], v[102:105]
	v_mfma_f32_16x16x32_bf16 v[98:101], v[176:179], v[212:215], v[98:101]
	v_mfma_f32_16x16x32_bf16 v[86:89], v[168:171], v[220:223], v[86:89]
	v_mfma_f32_16x16x32_bf16 v[82:85], v[176:179], v[220:223], v[82:85]
	v_mfma_f32_16x16x32_bf16 v[134:137], v[172:175], v[200:203], v[134:137]
	v_mfma_f32_16x16x32_bf16 v[130:133], v[192:195], v[200:203], v[130:133]
	v_mfma_f32_16x16x32_bf16 v[118:121], v[172:175], v[208:211], v[118:121]
	v_mfma_f32_16x16x32_bf16 v[114:117], v[192:195], v[208:211], v[114:117]
	v_mfma_f32_16x16x32_bf16 v[102:105], v[172:175], v[216:219], v[102:105]
	v_mfma_f32_16x16x32_bf16 v[98:101], v[192:195], v[216:219], v[98:101]
	v_mfma_f32_16x16x32_bf16 v[86:89], v[172:175], v[224:227], v[86:89]
	v_mfma_f32_16x16x32_bf16 v[82:85], v[192:195], v[224:227], v[82:85]
	s_setprio 0
	s_barrier
	s_add_i32 s4, s50, s62
	v_lshl_add_u64 v[228:229], v[228:229], 0, s[28:29]
	s_mov_b32 m0, s4
	ds_read_b128 v[196:199], v188 offset:49152
	ds_read_b128 v[200:203], v188 offset:50176
	ds_read_b128 v[204:207], v188 offset:51200
	ds_read_b128 v[208:211], v188 offset:52224
	ds_read_b128 v[212:215], v188 offset:53248
	ds_read_b128 v[216:219], v188 offset:54272
	ds_read_b128 v[220:223], v188 offset:55296
	ds_read_b128 v[224:227], v188 offset:56320
	global_load_lds_dwordx4 v[228:229], off
	v_lshl_add_u64 v[228:229], v[230:231], 0, s[28:29]
	s_add_i32 m0, s4, 0x2000
	s_add_i32 s4, s51, s62
	global_load_lds_dwordx4 v[228:229], off
	v_lshl_add_u64 v[228:229], v[232:233], 0, s[28:29]
	s_mov_b32 m0, s4
	s_nop 0
	global_load_lds_dwordx4 v[228:229], off
	v_lshl_add_u64 v[228:229], v[234:235], 0, s[28:29]
	s_add_i32 m0, s4, 0x2000
	s_nop 0
	global_load_lds_dwordx4 v[228:229], off
	v_lshl_add_u64 v[228:229], v[236:237], 0, s[28:29]
	s_mov_b32 m0, s82
	s_nop 0
	global_load_lds_dwordx4 v[228:229], off
	v_lshl_add_u64 v[228:229], v[238:239], 0, s[28:29]
	s_mov_b32 m0, s83
	s_nop 0
	global_load_lds_dwordx4 v[228:229], off
	s_waitcnt vmcnt(8)
	s_waitcnt lgkmcnt(0)
	s_setprio 1
	v_mfma_f32_16x16x32_bf16 v[78:81], v[50:53], v[196:199], v[78:81]
	v_mfma_f32_16x16x32_bf16 v[74:77], v[66:69], v[196:199], v[74:77]
	s_barrier
	v_mfma_f32_16x16x32_bf16 v[62:65], v[50:53], v[204:207], v[62:65]
	v_mfma_f32_16x16x32_bf16 v[58:61], v[66:69], v[204:207], v[58:61]
	v_mfma_f32_16x16x32_bf16 v[30:33], v[50:53], v[212:215], v[30:33]
	v_mfma_f32_16x16x32_bf16 v[26:29], v[66:69], v[212:215], v[26:29]
	v_mfma_f32_16x16x32_bf16 v[14:17], v[50:53], v[220:223], v[14:17]
	v_mfma_f32_16x16x32_bf16 v[10:13], v[66:69], v[220:223], v[10:13]
	v_mfma_f32_16x16x32_bf16 v[78:81], v[54:57], v[200:203], v[78:81]
	v_mfma_f32_16x16x32_bf16 v[74:77], v[70:73], v[200:203], v[74:77]
	v_mfma_f32_16x16x32_bf16 v[62:65], v[54:57], v[208:211], v[62:65]
	v_mfma_f32_16x16x32_bf16 v[58:61], v[70:73], v[208:211], v[58:61]
	v_mfma_f32_16x16x32_bf16 v[30:33], v[54:57], v[216:219], v[30:33]
	v_mfma_f32_16x16x32_bf16 v[26:29], v[70:73], v[216:219], v[26:29]
	v_mfma_f32_16x16x32_bf16 v[14:17], v[54:57], v[224:227], v[14:17]
	v_mfma_f32_16x16x32_bf16 v[10:13], v[70:73], v[224:227], v[10:13]
	v_mfma_f32_16x16x32_bf16 v[34:37], v[168:171], v[196:199], v[34:37]
	v_mfma_f32_16x16x32_bf16 v[70:73], v[172:175], v[200:203], v[34:37]
	v_mfma_f32_16x16x32_bf16 v[34:37], v[176:179], v[196:199], v[38:41]
	v_mfma_f32_16x16x32_bf16 v[66:69], v[192:195], v[200:203], v[34:37]
	v_mfma_f32_16x16x32_bf16 v[34:37], v[168:171], v[204:207], v[46:49]
	v_mfma_f32_16x16x32_bf16 v[46:49], v[172:175], v[208:211], v[34:37]
	v_mfma_f32_16x16x32_bf16 v[34:37], v[176:179], v[204:207], v[42:45]
	v_mfma_f32_16x16x32_bf16 v[22:25], v[168:171], v[212:215], v[22:25]
	v_mfma_f32_16x16x32_bf16 v[18:21], v[176:179], v[212:215], v[18:21]
	v_mfma_f32_16x16x32_bf16 v[6:9], v[168:171], v[220:223], v[6:9]
	v_mfma_f32_16x16x32_bf16 v[2:5], v[176:179], v[220:223], v[2:5]
	v_mfma_f32_16x16x32_bf16 v[42:45], v[192:195], v[208:211], v[34:37]
	v_mfma_f32_16x16x32_bf16 v[22:25], v[172:175], v[216:219], v[22:25]
	v_mfma_f32_16x16x32_bf16 v[18:21], v[192:195], v[216:219], v[18:21]
	v_mfma_f32_16x16x32_bf16 v[6:9], v[172:175], v[224:227], v[6:9]
	v_mfma_f32_16x16x32_bf16 v[2:5], v[192:195], v[224:227], v[2:5]
	s_setprio 0
	s_barrier
	s_add_u32 s2, s2, 0x100
	s_addc_u32 s3, s3, 0
	s_add_u32 s6, s6, 0x100
	s_addc_u32 s7, s7, 0
	s_cmp_ge_i32 s47, s84
	s_mov_b32 s4, s47
	s_cbranch_scc0 .LBB0_2116

.LBB0_2764:
	v_add_u32_e32 v158, s68, v229
	v_add_u32_e32 v174, s69, v229
	ds_read_b128 v[146:149], v158
	ds_read_b128 v[150:153], v158 offset:1024
	ds_read_b128 v[154:157], v158 offset:2048
	ds_read_b128 v[158:161], v158 offset:3072
	ds_read_b128 v[162:165], v174
	ds_read_b128 v[166:169], v174 offset:1024
	ds_read_b128 v[170:173], v174 offset:2048
	ds_read_b128 v[174:177], v174 offset:3072
	s_add_i32 s84, s42, 2
	s_add_u32 s85, s40, 0x80
	s_addc_u32 s43, s41, 0
	s_cmp_eq_u32 s65, s42
	s_cselect_b32 s42, s4, s85
	s_cselect_b32 s43, s5, s43
	s_cselect_b32 s87, s39, s83
	s_cselect_b32 s86, s38, s82
	v_lshl_add_u64 v[210:211], s[40:41], 0, v[138:139]
	s_add_i32 m0, s51, 0xc000
	ds_read_b128 v[178:181], v231
	ds_read_b128 v[182:185], v231 offset:1024
	ds_read_b128 v[186:189], v231 offset:2048
	ds_read_b128 v[190:193], v231 offset:3072
	ds_read_b128 v[194:197], v231 offset:4096
	ds_read_b128 v[198:201], v231 offset:5120
	ds_read_b128 v[202:205], v231 offset:6144
	ds_read_b128 v[206:209], v231 offset:7168
	global_load_lds_dwordx4 v[210:211], off
	v_lshl_add_u64 v[210:211], s[40:41], 0, v[140:141]
	s_add_i32 m0, s51, 0xe000
	s_nop 0
	global_load_lds_dwordx4 v[210:211], off
	s_waitcnt vmcnt(8)
	s_waitcnt lgkmcnt(0)
	s_setprio 1
	v_mfma_i32_16x16x64_i8 v[126:129], v[146:149], v[178:181], v[126:129]
	v_mfma_i32_16x16x64_i8 v[122:125], v[154:157], v[178:181], v[122:125]
	s_barrier
	v_mfma_i32_16x16x64_i8 v[118:121], v[146:149], v[186:189], v[118:121]
	v_mfma_i32_16x16x64_i8 v[114:117], v[154:157], v[186:189], v[114:117]
	v_mfma_i32_16x16x64_i8 v[106:109], v[146:149], v[194:197], v[106:109]
	v_mfma_i32_16x16x64_i8 v[98:101], v[154:157], v[194:197], v[98:101]
	v_mfma_i32_16x16x64_i8 v[90:93], v[146:149], v[202:205], v[90:93]
	v_mfma_i32_16x16x64_i8 v[82:85], v[154:157], v[202:205], v[82:85]
	v_mfma_i32_16x16x64_i8 v[126:129], v[150:153], v[182:185], v[126:129]
	v_mfma_i32_16x16x64_i8 v[122:125], v[158:161], v[182:185], v[122:125]
	v_mfma_i32_16x16x64_i8 v[118:121], v[150:153], v[190:193], v[118:121]
	v_mfma_i32_16x16x64_i8 v[114:117], v[158:161], v[190:193], v[114:117]
	v_mfma_i32_16x16x64_i8 v[106:109], v[150:153], v[198:201], v[106:109]
	v_mfma_i32_16x16x64_i8 v[98:101], v[158:161], v[198:201], v[98:101]
	v_mfma_i32_16x16x64_i8 v[90:93], v[150:153], v[206:209], v[90:93]
	v_mfma_i32_16x16x64_i8 v[82:85], v[158:161], v[206:209], v[82:85]
	v_mfma_i32_16x16x64_i8 v[110:113], v[162:165], v[178:181], v[110:113]
	v_mfma_i32_16x16x64_i8 v[102:105], v[170:173], v[178:181], v[102:105]
	v_mfma_i32_16x16x64_i8 v[94:97], v[162:165], v[186:189], v[94:97]
	v_mfma_i32_16x16x64_i8 v[86:89], v[170:173], v[186:189], v[86:89]
	v_mfma_i32_16x16x64_i8 v[78:81], v[162:165], v[194:197], v[78:81]
	v_mfma_i32_16x16x64_i8 v[74:77], v[170:173], v[194:197], v[74:77]
	v_mfma_i32_16x16x64_i8 v[70:73], v[162:165], v[202:205], v[70:73]
	v_mfma_i32_16x16x64_i8 v[66:69], v[170:173], v[202:205], v[66:69]
	v_mfma_i32_16x16x64_i8 v[110:113], v[166:169], v[182:185], v[110:113]
	v_mfma_i32_16x16x64_i8 v[102:105], v[174:177], v[182:185], v[102:105]
	v_mfma_i32_16x16x64_i8 v[94:97], v[166:169], v[190:193], v[94:97]
	v_mfma_i32_16x16x64_i8 v[86:89], v[174:177], v[190:193], v[86:89]
	v_mfma_i32_16x16x64_i8 v[78:81], v[166:169], v[198:201], v[78:81]
	v_mfma_i32_16x16x64_i8 v[74:77], v[174:177], v[198:201], v[74:77]
	v_mfma_i32_16x16x64_i8 v[70:73], v[166:169], v[206:209], v[70:73]
	v_mfma_i32_16x16x64_i8 v[66:69], v[174:177], v[206:209], v[66:69]
	s_setprio 0
	s_barrier
	s_add_i32 s85, s68, s50
	v_lshl_add_u64 v[210:211], s[86:87], 0, v[132:133]
	s_mov_b32 m0, s85
	ds_read_b128 v[178:181], v231 offset:16384
	ds_read_b128 v[182:185], v231 offset:17408
	ds_read_b128 v[186:189], v231 offset:18432
	ds_read_b128 v[190:193], v231 offset:19456
	ds_read_b128 v[194:197], v231 offset:20480
	ds_read_b128 v[198:201], v231 offset:21504
	ds_read_b128 v[202:205], v231 offset:22528
	ds_read_b128 v[206:209], v231 offset:23552
	global_load_lds_dwordx4 v[210:211], off
	s_add_i32 m0, s85, 0x2000
	v_lshl_add_u64 v[212:213], s[86:87], 0, v[136:137]
	s_add_u32 s86, s86, s8
	s_addc_u32 s87, s87, s9
	s_add_i32 s85, s69, s50
	global_load_lds_dwordx4 v[212:213], off
	v_lshl_add_u64 v[214:215], s[86:87], 0, v[132:133]
	s_mov_b32 m0, s85
	v_lshl_add_u64 v[216:217], s[86:87], 0, v[136:137]
	global_load_lds_dwordx4 v[214:215], off
	s_add_i32 m0, s85, 0x2000
	v_lshl_add_u64 v[218:219], s[42:43], 0, v[130:131]
	global_load_lds_dwordx4 v[216:217], off
	s_mov_b32 m0, s51
	v_lshl_add_u64 v[220:221], s[42:43], 0, v[134:135]
	global_load_lds_dwordx4 v[218:219], off
	s_mov_b32 m0, s54
	s_nop 0
	global_load_lds_dwordx4 v[220:221], off
	s_waitcnt vmcnt(8)
	s_waitcnt lgkmcnt(0)
	s_setprio 1
	v_mfma_i32_16x16x64_i8 v[62:65], v[146:149], v[178:181], v[62:65]
	v_mfma_i32_16x16x64_i8 v[58:61], v[154:157], v[178:181], v[58:61]
	s_barrier
	v_mfma_i32_16x16x64_i8 v[54:57], v[146:149], v[186:189], v[54:57]
	v_mfma_i32_16x16x64_i8 v[50:53], v[154:157], v[186:189], v[50:53]
	v_mfma_i32_16x16x64_i8 v[42:45], v[146:149], v[194:197], v[42:45]
	v_mfma_i32_16x16x64_i8 v[34:37], v[154:157], v[194:197], v[34:37]
	v_mfma_i32_16x16x64_i8 v[26:29], v[146:149], v[202:205], v[26:29]
	v_mfma_i32_16x16x64_i8 v[18:21], v[154:157], v[202:205], v[18:21]
	v_mfma_i32_16x16x64_i8 v[62:65], v[150:153], v[182:185], v[62:65]
	v_mfma_i32_16x16x64_i8 v[58:61], v[158:161], v[182:185], v[58:61]
	v_mfma_i32_16x16x64_i8 v[54:57], v[150:153], v[190:193], v[54:57]
	v_mfma_i32_16x16x64_i8 v[50:53], v[158:161], v[190:193], v[50:53]
	v_mfma_i32_16x16x64_i8 v[42:45], v[150:153], v[198:201], v[42:45]
	v_mfma_i32_16x16x64_i8 v[34:37], v[158:161], v[198:201], v[34:37]
	v_mfma_i32_16x16x64_i8 v[26:29], v[150:153], v[206:209], v[26:29]
	v_mfma_i32_16x16x64_i8 v[18:21], v[158:161], v[206:209], v[18:21]
	v_mfma_i32_16x16x64_i8 v[46:49], v[162:165], v[178:181], v[46:49]
	v_mfma_i32_16x16x64_i8 v[38:41], v[170:173], v[178:181], v[38:41]
	v_mfma_i32_16x16x64_i8 v[30:33], v[162:165], v[186:189], v[30:33]
	v_mfma_i32_16x16x64_i8 v[22:25], v[170:173], v[186:189], v[22:25]
	v_mfma_i32_16x16x64_i8 v[14:17], v[162:165], v[194:197], v[14:17]
	v_mfma_i32_16x16x64_i8 v[10:13], v[170:173], v[194:197], v[10:13]
	v_mfma_i32_16x16x64_i8 v[6:9], v[162:165], v[202:205], v[6:9]
	v_mfma_i32_16x16x64_i8 v[2:5], v[170:173], v[202:205], v[2:5]
	v_mfma_i32_16x16x64_i8 v[46:49], v[166:169], v[182:185], v[46:49]
	v_mfma_i32_16x16x64_i8 v[38:41], v[174:177], v[182:185], v[38:41]
	v_mfma_i32_16x16x64_i8 v[30:33], v[166:169], v[190:193], v[30:33]
	v_mfma_i32_16x16x64_i8 v[22:25], v[174:177], v[190:193], v[22:25]
	v_mfma_i32_16x16x64_i8 v[14:17], v[166:169], v[198:201], v[14:17]
	v_mfma_i32_16x16x64_i8 v[10:13], v[174:177], v[198:201], v[10:13]
	v_mfma_i32_16x16x64_i8 v[6:9], v[166:169], v[206:209], v[6:9]
	v_mfma_i32_16x16x64_i8 v[2:5], v[174:177], v[206:209], v[2:5]
	s_setprio 0
	s_barrier
	s_add_i32 s85, 0, 0x18000
	s_add_i32 s86, 0, 0x1c000
	v_add_u32_e32 v158, s85, v229
	v_add_u32_e32 v174, s86, v229
	ds_read_b128 v[146:149], v158
	ds_read_b128 v[150:153], v158 offset:1024
	ds_read_b128 v[154:157], v158 offset:2048
	ds_read_b128 v[158:161], v158 offset:3072
	ds_read_b128 v[162:165], v174
	ds_read_b128 v[166:169], v174 offset:1024
	ds_read_b128 v[170:173], v174 offset:2048
	ds_read_b128 v[174:177], v174 offset:3072
	s_add_u32 s42, s42, s8
	s_addc_u32 s43, s43, s9
	s_mov_b32 m0, s55
	v_lshl_add_u64 v[222:223], s[42:43], 0, v[130:131]
	ds_read_b128 v[178:181], v231 offset:32768
	ds_read_b128 v[182:185], v231 offset:33792
	ds_read_b128 v[186:189], v231 offset:34816
	ds_read_b128 v[190:193], v231 offset:35840
	ds_read_b128 v[194:197], v231 offset:36864
	ds_read_b128 v[198:201], v231 offset:37888
	ds_read_b128 v[202:205], v231 offset:38912
	ds_read_b128 v[206:209], v231 offset:39936
	global_load_lds_dwordx4 v[222:223], off
	v_lshl_add_u64 v[222:223], s[42:43], 0, v[134:135]
	s_mov_b32 m0, s56
	s_nop 0
	global_load_lds_dwordx4 v[222:223], off
	s_waitcnt vmcnt(8)
	s_waitcnt lgkmcnt(0)
	s_setprio 1
	v_mfma_i32_16x16x64_i8 v[126:129], v[146:149], v[178:181], v[126:129]
	v_mfma_i32_16x16x64_i8 v[122:125], v[154:157], v[178:181], v[122:125]
	s_barrier
	v_mfma_i32_16x16x64_i8 v[118:121], v[146:149], v[186:189], v[118:121]
	v_mfma_i32_16x16x64_i8 v[114:117], v[154:157], v[186:189], v[114:117]
	v_mfma_i32_16x16x64_i8 v[106:109], v[146:149], v[194:197], v[106:109]
	v_mfma_i32_16x16x64_i8 v[98:101], v[154:157], v[194:197], v[98:101]
	v_mfma_i32_16x16x64_i8 v[90:93], v[146:149], v[202:205], v[90:93]
	v_mfma_i32_16x16x64_i8 v[82:85], v[154:157], v[202:205], v[82:85]
	v_mfma_i32_16x16x64_i8 v[126:129], v[150:153], v[182:185], v[126:129]
	v_mfma_i32_16x16x64_i8 v[122:125], v[158:161], v[182:185], v[122:125]
	v_mfma_i32_16x16x64_i8 v[118:121], v[150:153], v[190:193], v[118:121]
	v_mfma_i32_16x16x64_i8 v[114:117], v[158:161], v[190:193], v[114:117]
	v_mfma_i32_16x16x64_i8 v[106:109], v[150:153], v[198:201], v[106:109]
	v_mfma_i32_16x16x64_i8 v[98:101], v[158:161], v[198:201], v[98:101]
	v_mfma_i32_16x16x64_i8 v[90:93], v[150:153], v[206:209], v[90:93]
	v_mfma_i32_16x16x64_i8 v[82:85], v[158:161], v[206:209], v[82:85]
	v_mfma_i32_16x16x64_i8 v[110:113], v[162:165], v[178:181], v[110:113]
	v_mfma_i32_16x16x64_i8 v[102:105], v[170:173], v[178:181], v[102:105]
	v_mfma_i32_16x16x64_i8 v[94:97], v[162:165], v[186:189], v[94:97]
	v_mfma_i32_16x16x64_i8 v[86:89], v[170:173], v[186:189], v[86:89]
	v_mfma_i32_16x16x64_i8 v[78:81], v[162:165], v[194:197], v[78:81]
	v_mfma_i32_16x16x64_i8 v[74:77], v[170:173], v[194:197], v[74:77]
	v_mfma_i32_16x16x64_i8 v[70:73], v[162:165], v[202:205], v[70:73]
	v_mfma_i32_16x16x64_i8 v[66:69], v[170:173], v[202:205], v[66:69]
	v_mfma_i32_16x16x64_i8 v[110:113], v[166:169], v[182:185], v[110:113]
	v_mfma_i32_16x16x64_i8 v[102:105], v[174:177], v[182:185], v[102:105]
	v_mfma_i32_16x16x64_i8 v[94:97], v[166:169], v[190:193], v[94:97]
	v_mfma_i32_16x16x64_i8 v[86:89], v[174:177], v[190:193], v[86:89]
	v_mfma_i32_16x16x64_i8 v[78:81], v[166:169], v[198:201], v[78:81]
	v_mfma_i32_16x16x64_i8 v[74:77], v[174:177], v[198:201], v[74:77]
	v_mfma_i32_16x16x64_i8 v[70:73], v[166:169], v[206:209], v[70:73]
	v_mfma_i32_16x16x64_i8 v[66:69], v[174:177], v[206:209], v[66:69]
	s_setprio 0
	s_barrier
	s_add_i32 s42, s85, s50
	v_lshl_add_u64 v[210:211], v[210:211], 0, s[30:31]
	s_mov_b32 m0, s42
	ds_read_b128 v[178:181], v231 offset:49152
	ds_read_b128 v[182:185], v231 offset:50176
	ds_read_b128 v[186:189], v231 offset:51200
	ds_read_b128 v[190:193], v231 offset:52224
	ds_read_b128 v[194:197], v231 offset:53248
	ds_read_b128 v[198:201], v231 offset:54272
	ds_read_b128 v[202:205], v231 offset:55296
	ds_read_b128 v[206:209], v231 offset:56320
	global_load_lds_dwordx4 v[210:211], off
	v_lshl_add_u64 v[210:211], v[212:213], 0, s[30:31]
	s_add_i32 m0, s42, 0x2000
	s_add_i32 s42, s86, s50
	global_load_lds_dwordx4 v[210:211], off
	v_lshl_add_u64 v[210:211], v[214:215], 0, s[30:31]
	s_mov_b32 m0, s42
	s_nop 0
	global_load_lds_dwordx4 v[210:211], off
	v_lshl_add_u64 v[210:211], v[216:217], 0, s[30:31]
	s_add_i32 m0, s42, 0x2000
	s_nop 0
	global_load_lds_dwordx4 v[210:211], off
	v_lshl_add_u64 v[210:211], v[218:219], 0, s[30:31]
	s_mov_b32 m0, s61
	s_nop 0
	global_load_lds_dwordx4 v[210:211], off
	v_lshl_add_u64 v[210:211], v[220:221], 0, s[30:31]
	s_mov_b32 m0, s62
	s_nop 0
	global_load_lds_dwordx4 v[210:211], off
	s_waitcnt vmcnt(8)
	s_waitcnt lgkmcnt(0)
	s_setprio 1
	v_mfma_i32_16x16x64_i8 v[62:65], v[146:149], v[178:181], v[62:65]
	v_mfma_i32_16x16x64_i8 v[58:61], v[154:157], v[178:181], v[58:61]
	s_barrier
	v_mfma_i32_16x16x64_i8 v[54:57], v[146:149], v[186:189], v[54:57]
	v_mfma_i32_16x16x64_i8 v[50:53], v[154:157], v[186:189], v[50:53]
	v_mfma_i32_16x16x64_i8 v[42:45], v[146:149], v[194:197], v[42:45]
	v_mfma_i32_16x16x64_i8 v[34:37], v[154:157], v[194:197], v[34:37]
	v_mfma_i32_16x16x64_i8 v[26:29], v[146:149], v[202:205], v[26:29]
	v_mfma_i32_16x16x64_i8 v[18:21], v[154:157], v[202:205], v[18:21]
	v_mfma_i32_16x16x64_i8 v[62:65], v[150:153], v[182:185], v[62:65]
	v_mfma_i32_16x16x64_i8 v[58:61], v[158:161], v[182:185], v[58:61]
	v_mfma_i32_16x16x64_i8 v[54:57], v[150:153], v[190:193], v[54:57]
	v_mfma_i32_16x16x64_i8 v[50:53], v[158:161], v[190:193], v[50:53]
	v_mfma_i32_16x16x64_i8 v[42:45], v[150:153], v[198:201], v[42:45]
	v_mfma_i32_16x16x64_i8 v[34:37], v[158:161], v[198:201], v[34:37]
	v_mfma_i32_16x16x64_i8 v[26:29], v[150:153], v[206:209], v[26:29]
	v_mfma_i32_16x16x64_i8 v[18:21], v[158:161], v[206:209], v[18:21]
	v_mfma_i32_16x16x64_i8 v[46:49], v[162:165], v[178:181], v[46:49]
	v_mfma_i32_16x16x64_i8 v[38:41], v[170:173], v[178:181], v[38:41]
	v_mfma_i32_16x16x64_i8 v[30:33], v[162:165], v[186:189], v[30:33]
	v_mfma_i32_16x16x64_i8 v[22:25], v[170:173], v[186:189], v[22:25]
	v_mfma_i32_16x16x64_i8 v[14:17], v[162:165], v[194:197], v[14:17]
	v_mfma_i32_16x16x64_i8 v[10:13], v[170:173], v[194:197], v[10:13]
	v_mfma_i32_16x16x64_i8 v[6:9], v[162:165], v[202:205], v[6:9]
	v_mfma_i32_16x16x64_i8 v[2:5], v[170:173], v[202:205], v[2:5]
	v_mfma_i32_16x16x64_i8 v[46:49], v[166:169], v[182:185], v[46:49]
	v_mfma_i32_16x16x64_i8 v[38:41], v[174:177], v[182:185], v[38:41]
	v_mfma_i32_16x16x64_i8 v[30:33], v[166:169], v[190:193], v[30:33]
	v_mfma_i32_16x16x64_i8 v[22:25], v[174:177], v[190:193], v[22:25]
	v_mfma_i32_16x16x64_i8 v[14:17], v[166:169], v[198:201], v[14:17]
	v_mfma_i32_16x16x64_i8 v[10:13], v[174:177], v[198:201], v[10:13]
	v_mfma_i32_16x16x64_i8 v[6:9], v[166:169], v[206:209], v[6:9]
	v_mfma_i32_16x16x64_i8 v[2:5], v[174:177], v[206:209], v[2:5]
	s_setprio 0
	s_barrier
	s_add_u32 s40, s40, 0x100
	s_addc_u32 s41, s41, 0
	s_add_u32 s82, s82, 0x100
	s_addc_u32 s83, s83, 0
	s_cmp_ge_i32 s84, s64
	s_mov_b32 s42, s84
	s_cbranch_scc0 .LBB0_2764
	v_cvt_f32_i32_e32 v214, v126
	v_cvt_f32_i32_e32 v215, v127
	v_cvt_f32_i32_e32 v212, v128
	v_cvt_f32_i32_e32 v213, v129
	v_cvt_f32_i32_e32 v218, v122
	v_cvt_f32_i32_e32 v219, v123
	v_cvt_f32_i32_e32 v216, v124
	v_cvt_f32_i32_e32 v217, v125
	v_cvt_f32_i32_e32 v222, v110
	v_cvt_f32_i32_e32 v223, v111
	v_cvt_f32_i32_e32 v220, v112
	v_cvt_f32_i32_e32 v221, v113
	v_cvt_f32_i32_e32 v226, v102
	v_cvt_f32_i32_e32 v227, v103
	v_cvt_f32_i32_e32 v224, v104
	v_cvt_f32_i32_e32 v225, v105
	v_cvt_f32_i32_e32 v194, v118
	v_cvt_f32_i32_e32 v195, v119
	v_cvt_f32_i32_e32 v192, v120
	v_cvt_f32_i32_e32 v193, v121
	v_cvt_f32_i32_e32 v200, v114
	v_cvt_f32_i32_e32 v201, v115
	v_cvt_f32_i32_e32 v198, v116
	v_cvt_f32_i32_e32 v199, v117
	v_cvt_f32_i32_e32 v206, v94
	v_cvt_f32_i32_e32 v207, v95
	v_cvt_f32_i32_e32 v202, v96
	v_cvt_f32_i32_e32 v203, v97
	v_cvt_f32_i32_e32 v208, v86
	v_cvt_f32_i32_e32 v209, v87
	v_cvt_f32_i32_e32 v204, v88
	v_cvt_f32_i32_e32 v205, v89
	v_cvt_f32_i32_e32 v178, v106
	v_cvt_f32_i32_e32 v179, v107
	v_cvt_f32_i32_e32 v176, v108
	v_cvt_f32_i32_e32 v177, v109
	v_cvt_f32_i32_e32 v182, v98
	v_cvt_f32_i32_e32 v183, v99
	v_cvt_f32_i32_e32 v180, v100
	v_cvt_f32_i32_e32 v181, v101
	v_cvt_f32_i32_e32 v188, v78
	v_cvt_f32_i32_e32 v189, v79
	v_cvt_f32_i32_e32 v184, v80
	v_cvt_f32_i32_e32 v185, v81
	v_cvt_f32_i32_e32 v190, v74
	v_cvt_f32_i32_e32 v191, v75
	v_cvt_f32_i32_e32 v186, v76
	v_cvt_f32_i32_e32 v187, v77
	v_cvt_f32_i32_e32 v162, v90
	v_cvt_f32_i32_e32 v163, v91
	v_cvt_f32_i32_e32 v160, v92
	v_cvt_f32_i32_e32 v161, v93
	v_cvt_f32_i32_e32 v166, v82
	v_cvt_f32_i32_e32 v167, v83
	v_cvt_f32_i32_e32 v164, v84
	v_cvt_f32_i32_e32 v165, v85
	v_cvt_f32_i32_e32 v172, v70
	v_cvt_f32_i32_e32 v173, v71
	v_cvt_f32_i32_e32 v168, v72
	v_cvt_f32_i32_e32 v169, v73
	v_cvt_f32_i32_e32 v174, v66
	v_cvt_f32_i32_e32 v175, v67
	v_cvt_f32_i32_e32 v170, v68
	v_cvt_f32_i32_e32 v171, v69
	v_cvt_f32_i32_e32 v146, v62
	v_cvt_f32_i32_e32 v147, v63
	v_cvt_f32_i32_e32 v128, v64
	v_cvt_f32_i32_e32 v129, v65
	v_cvt_f32_i32_e32 v150, v58
	v_cvt_f32_i32_e32 v151, v59
	v_cvt_f32_i32_e32 v148, v60
	v_cvt_f32_i32_e32 v149, v61
	v_cvt_f32_i32_e32 v156, v46
	v_cvt_f32_i32_e32 v157, v47
	v_cvt_f32_i32_e32 v152, v48
	v_cvt_f32_i32_e32 v153, v49
	v_cvt_f32_i32_e32 v158, v38
	v_cvt_f32_i32_e32 v159, v39
	v_cvt_f32_i32_e32 v154, v40
	v_cvt_f32_i32_e32 v155, v41
	v_cvt_f32_i32_e32 v114, v54
	v_cvt_f32_i32_e32 v115, v55
	v_cvt_f32_i32_e32 v112, v56
	v_cvt_f32_i32_e32 v113, v57
	v_cvt_f32_i32_e32 v118, v50
	v_cvt_f32_i32_e32 v119, v51
	v_cvt_f32_i32_e32 v116, v52
	v_cvt_f32_i32_e32 v117, v53
	v_cvt_f32_i32_e32 v124, v30
	v_cvt_f32_i32_e32 v125, v31
	v_cvt_f32_i32_e32 v120, v32
	v_cvt_f32_i32_e32 v121, v33
	v_cvt_f32_i32_e32 v126, v22
	v_cvt_f32_i32_e32 v127, v23
	v_cvt_f32_i32_e32 v122, v24
	v_cvt_f32_i32_e32 v123, v25
	v_cvt_f32_i32_e32 v64, v42
	v_cvt_f32_i32_e32 v65, v43
	v_cvt_f32_i32_e32 v62, v44
	v_cvt_f32_i32_e32 v63, v45
	v_cvt_f32_i32_e32 v68, v34
	v_cvt_f32_i32_e32 v69, v35
	v_cvt_f32_i32_e32 v66, v36
	v_cvt_f32_i32_e32 v67, v37
	v_cvt_f32_i32_e32 v74, v14
	v_cvt_f32_i32_e32 v75, v15
	v_cvt_f32_i32_e32 v70, v16
	v_cvt_f32_i32_e32 v71, v17
	v_cvt_f32_i32_e32 v76, v10
	v_cvt_f32_i32_e32 v77, v11
	v_cvt_f32_i32_e32 v72, v12
	v_cvt_f32_i32_e32 v73, v13
	v_cvt_f32_i32_e32 v48, v26
	v_cvt_f32_i32_e32 v49, v27
	v_cvt_f32_i32_e32 v46, v28
	v_cvt_f32_i32_e32 v47, v29
	v_cvt_f32_i32_e32 v52, v18
	v_cvt_f32_i32_e32 v53, v19
	v_cvt_f32_i32_e32 v50, v20
	v_cvt_f32_i32_e32 v51, v21
	v_cvt_f32_i32_e32 v58, v6
	v_cvt_f32_i32_e32 v59, v7
	v_cvt_f32_i32_e32 v54, v8
	v_cvt_f32_i32_e32 v55, v9
	v_cvt_f32_i32_e32 v60, v2
	v_cvt_f32_i32_e32 v61, v3
	v_cvt_f32_i32_e32 v56, v4
	v_cvt_f32_i32_e32 v57, v5

.LBB0_2949:
	v_add_u32_e32 v138, s60, v188
	ds_read_b128 v[148:151], v138
	ds_read_b128 v[152:155], v138 offset:1024
	ds_read_b128 v[156:159], v138 offset:2048
	ds_read_b128 v[160:163], v138 offset:3072
	v_add_u32_e32 v138, s61, v188
	ds_read_b128 v[164:167], v138
	ds_read_b128 v[168:171], v138 offset:1024
	ds_read_b128 v[172:175], v138 offset:2048
	ds_read_b128 v[176:179], v138 offset:3072
	s_add_i32 s64, s28, 2
	s_add_u32 s65, s26, 0x80
	s_addc_u32 s29, s27, 0
	s_cmp_eq_u32 s58, s28
	s_cselect_b32 s28, s2, s65
	s_cselect_b32 s29, s3, s29
	s_cselect_b32 s67, s25, s35
	s_cselect_b32 s66, s24, s34
	v_lshl_add_u64 v[184:185], s[26:27], 0, v[140:141]
	s_add_i32 m0, s42, 0xc000
	ds_read_b128 v[180:183], v189
	ds_read_b128 v[190:193], v189 offset:1024
	ds_read_b128 v[194:197], v189 offset:2048
	ds_read_b128 v[198:201], v189 offset:3072
	ds_read_b128 v[202:205], v189 offset:4096
	ds_read_b128 v[206:209], v189 offset:5120
	ds_read_b128 v[210:213], v189 offset:6144
	ds_read_b128 v[214:217], v189 offset:7168
	global_load_lds_dwordx4 v[184:185], off
	v_lshl_add_u64 v[184:185], s[26:27], 0, v[142:143]
	s_add_i32 m0, s42, 0xe000
	s_nop 0
	global_load_lds_dwordx4 v[184:185], off
	s_waitcnt vmcnt(8)
	s_waitcnt lgkmcnt(0)
	s_setprio 1
	v_mfma_i32_16x16x64_i8 v[126:129], v[148:151], v[180:183], v[126:129]
	v_mfma_i32_16x16x64_i8 v[122:125], v[156:159], v[180:183], v[122:125]
	s_barrier
	v_mfma_i32_16x16x64_i8 v[118:121], v[148:151], v[194:197], v[118:121]
	v_mfma_i32_16x16x64_i8 v[114:117], v[156:159], v[194:197], v[114:117]
	v_mfma_i32_16x16x64_i8 v[106:109], v[148:151], v[202:205], v[106:109]
	v_mfma_i32_16x16x64_i8 v[98:101], v[156:159], v[202:205], v[98:101]
	v_mfma_i32_16x16x64_i8 v[90:93], v[148:151], v[210:213], v[90:93]
	v_mfma_i32_16x16x64_i8 v[82:85], v[156:159], v[210:213], v[82:85]
	v_mfma_i32_16x16x64_i8 v[126:129], v[152:155], v[190:193], v[126:129]
	v_mfma_i32_16x16x64_i8 v[122:125], v[160:163], v[190:193], v[122:125]
	v_mfma_i32_16x16x64_i8 v[118:121], v[152:155], v[198:201], v[118:121]
	v_mfma_i32_16x16x64_i8 v[114:117], v[160:163], v[198:201], v[114:117]
	v_mfma_i32_16x16x64_i8 v[106:109], v[152:155], v[206:209], v[106:109]
	v_mfma_i32_16x16x64_i8 v[98:101], v[160:163], v[206:209], v[98:101]
	v_mfma_i32_16x16x64_i8 v[90:93], v[152:155], v[214:217], v[90:93]
	v_mfma_i32_16x16x64_i8 v[82:85], v[160:163], v[214:217], v[82:85]
	v_mfma_i32_16x16x64_i8 v[110:113], v[164:167], v[180:183], v[110:113]
	v_mfma_i32_16x16x64_i8 v[102:105], v[172:175], v[180:183], v[102:105]
	v_mfma_i32_16x16x64_i8 v[94:97], v[164:167], v[194:197], v[94:97]
	v_mfma_i32_16x16x64_i8 v[86:89], v[172:175], v[194:197], v[86:89]
	v_mfma_i32_16x16x64_i8 v[78:81], v[164:167], v[202:205], v[78:81]
	v_mfma_i32_16x16x64_i8 v[74:77], v[172:175], v[202:205], v[74:77]
	v_mfma_i32_16x16x64_i8 v[70:73], v[164:167], v[210:213], v[70:73]
	v_mfma_i32_16x16x64_i8 v[66:69], v[172:175], v[210:213], v[66:69]
	v_mfma_i32_16x16x64_i8 v[110:113], v[168:171], v[190:193], v[110:113]
	v_mfma_i32_16x16x64_i8 v[102:105], v[176:179], v[190:193], v[102:105]
	v_mfma_i32_16x16x64_i8 v[94:97], v[168:171], v[198:201], v[94:97]
	v_mfma_i32_16x16x64_i8 v[86:89], v[176:179], v[198:201], v[86:89]
	v_mfma_i32_16x16x64_i8 v[78:81], v[168:171], v[206:209], v[78:81]
	v_mfma_i32_16x16x64_i8 v[74:77], v[176:179], v[206:209], v[74:77]
	v_mfma_i32_16x16x64_i8 v[70:73], v[168:171], v[214:217], v[70:73]
	v_mfma_i32_16x16x64_i8 v[66:69], v[176:179], v[214:217], v[66:69]
	s_setprio 0
	s_barrier
	s_add_i32 s65, s60, s41
	v_lshl_add_u64 v[184:185], s[66:67], 0, v[132:133]
	s_mov_b32 m0, s65
	ds_read_b128 v[180:183], v189 offset:16384
	ds_read_b128 v[190:193], v189 offset:17408
	ds_read_b128 v[194:197], v189 offset:18432
	ds_read_b128 v[198:201], v189 offset:19456
	ds_read_b128 v[202:205], v189 offset:20480
	ds_read_b128 v[206:209], v189 offset:21504
	ds_read_b128 v[210:213], v189 offset:22528
	ds_read_b128 v[214:217], v189 offset:23552
	global_load_lds_dwordx4 v[184:185], off
	s_add_i32 m0, s65, 0x2000
	v_lshl_add_u64 v[218:219], s[66:67], 0, v[136:137]
	s_add_u32 s66, s66, s6
	s_addc_u32 s67, s67, s7
	s_add_i32 s65, s61, s41
	global_load_lds_dwordx4 v[218:219], off
	v_lshl_add_u64 v[220:221], s[66:67], 0, v[132:133]
	s_mov_b32 m0, s65
	v_lshl_add_u64 v[222:223], s[66:67], 0, v[136:137]
	global_load_lds_dwordx4 v[220:221], off
	s_add_i32 m0, s65, 0x2000
	v_lshl_add_u64 v[224:225], s[28:29], 0, v[130:131]
	global_load_lds_dwordx4 v[222:223], off
	s_mov_b32 m0, s42
	v_lshl_add_u64 v[226:227], s[28:29], 0, v[134:135]
	global_load_lds_dwordx4 v[224:225], off
	s_mov_b32 m0, s43
	s_nop 0
	global_load_lds_dwordx4 v[226:227], off
	s_waitcnt vmcnt(8)
	s_waitcnt lgkmcnt(0)
	s_setprio 1
	v_mfma_i32_16x16x64_i8 v[62:65], v[148:151], v[180:183], v[62:65]
	v_mfma_i32_16x16x64_i8 v[58:61], v[156:159], v[180:183], v[58:61]
	s_barrier
	v_mfma_i32_16x16x64_i8 v[54:57], v[148:151], v[194:197], v[54:57]
	v_mfma_i32_16x16x64_i8 v[50:53], v[156:159], v[194:197], v[50:53]
	v_mfma_i32_16x16x64_i8 v[42:45], v[148:151], v[202:205], v[42:45]
	v_mfma_i32_16x16x64_i8 v[34:37], v[156:159], v[202:205], v[34:37]
	v_mfma_i32_16x16x64_i8 v[26:29], v[148:151], v[210:213], v[26:29]
	v_mfma_i32_16x16x64_i8 v[18:21], v[156:159], v[210:213], v[18:21]
	v_mfma_i32_16x16x64_i8 v[62:65], v[152:155], v[190:193], v[62:65]
	v_mfma_i32_16x16x64_i8 v[58:61], v[160:163], v[190:193], v[58:61]
	v_mfma_i32_16x16x64_i8 v[54:57], v[152:155], v[198:201], v[54:57]
	v_mfma_i32_16x16x64_i8 v[50:53], v[160:163], v[198:201], v[50:53]
	v_mfma_i32_16x16x64_i8 v[42:45], v[152:155], v[206:209], v[42:45]
	v_mfma_i32_16x16x64_i8 v[34:37], v[160:163], v[206:209], v[34:37]
	v_mfma_i32_16x16x64_i8 v[26:29], v[152:155], v[214:217], v[26:29]
	v_mfma_i32_16x16x64_i8 v[18:21], v[160:163], v[214:217], v[18:21]
	v_mfma_i32_16x16x64_i8 v[46:49], v[164:167], v[180:183], v[46:49]
	v_mfma_i32_16x16x64_i8 v[38:41], v[172:175], v[180:183], v[38:41]
	v_mfma_i32_16x16x64_i8 v[30:33], v[164:167], v[194:197], v[30:33]
	v_mfma_i32_16x16x64_i8 v[22:25], v[172:175], v[194:197], v[22:25]
	v_mfma_i32_16x16x64_i8 v[14:17], v[164:167], v[202:205], v[14:17]
	v_mfma_i32_16x16x64_i8 v[10:13], v[172:175], v[202:205], v[10:13]
	v_mfma_i32_16x16x64_i8 v[6:9], v[164:167], v[210:213], v[6:9]
	v_mfma_i32_16x16x64_i8 v[2:5], v[172:175], v[210:213], v[2:5]
	v_mfma_i32_16x16x64_i8 v[46:49], v[168:171], v[190:193], v[46:49]
	v_mfma_i32_16x16x64_i8 v[38:41], v[176:179], v[190:193], v[38:41]
	v_mfma_i32_16x16x64_i8 v[30:33], v[168:171], v[198:201], v[30:33]
	v_mfma_i32_16x16x64_i8 v[22:25], v[176:179], v[198:201], v[22:25]
	v_mfma_i32_16x16x64_i8 v[14:17], v[168:171], v[206:209], v[14:17]
	v_mfma_i32_16x16x64_i8 v[10:13], v[176:179], v[206:209], v[10:13]
	v_mfma_i32_16x16x64_i8 v[6:9], v[168:171], v[214:217], v[6:9]
	v_mfma_i32_16x16x64_i8 v[2:5], v[176:179], v[214:217], v[2:5]
	s_setprio 0
	s_barrier
	s_add_i32 s65, 0, 0x18000
	v_add_u32_e32 v138, s65, v188
	s_add_i32 s66, 0, 0x1c000
	ds_read_b128 v[148:151], v138
	ds_read_b128 v[152:155], v138 offset:1024
	ds_read_b128 v[156:159], v138 offset:2048
	ds_read_b128 v[160:163], v138 offset:3072
	v_add_u32_e32 v138, s66, v188
	ds_read_b128 v[164:167], v138
	ds_read_b128 v[168:171], v138 offset:1024
	ds_read_b128 v[172:175], v138 offset:2048
	ds_read_b128 v[176:179], v138 offset:3072
	s_add_u32 s28, s28, s6
	s_addc_u32 s29, s29, s7
	s_mov_b32 m0, s44
	v_lshl_add_u64 v[228:229], s[28:29], 0, v[130:131]
	ds_read_b128 v[180:183], v189 offset:32768
	ds_read_b128 v[190:193], v189 offset:33792
	ds_read_b128 v[194:197], v189 offset:34816
	ds_read_b128 v[198:201], v189 offset:35840
	ds_read_b128 v[202:205], v189 offset:36864
	ds_read_b128 v[206:209], v189 offset:37888
	ds_read_b128 v[210:213], v189 offset:38912
	ds_read_b128 v[214:217], v189 offset:39936
	global_load_lds_dwordx4 v[228:229], off
	v_lshl_add_u64 v[228:229], s[28:29], 0, v[134:135]
	s_mov_b32 m0, s45
	s_nop 0
	global_load_lds_dwordx4 v[228:229], off
	s_waitcnt vmcnt(8)
	s_waitcnt lgkmcnt(0)
	s_setprio 1
	v_mfma_i32_16x16x64_i8 v[126:129], v[148:151], v[180:183], v[126:129]
	v_mfma_i32_16x16x64_i8 v[122:125], v[156:159], v[180:183], v[122:125]
	s_barrier
	v_mfma_i32_16x16x64_i8 v[118:121], v[148:151], v[194:197], v[118:121]
	v_mfma_i32_16x16x64_i8 v[114:117], v[156:159], v[194:197], v[114:117]
	v_mfma_i32_16x16x64_i8 v[106:109], v[148:151], v[202:205], v[106:109]
	v_mfma_i32_16x16x64_i8 v[98:101], v[156:159], v[202:205], v[98:101]
	v_mfma_i32_16x16x64_i8 v[90:93], v[148:151], v[210:213], v[90:93]
	v_mfma_i32_16x16x64_i8 v[82:85], v[156:159], v[210:213], v[82:85]
	v_mfma_i32_16x16x64_i8 v[126:129], v[152:155], v[190:193], v[126:129]
	v_mfma_i32_16x16x64_i8 v[122:125], v[160:163], v[190:193], v[122:125]
	v_mfma_i32_16x16x64_i8 v[118:121], v[152:155], v[198:201], v[118:121]
	v_mfma_i32_16x16x64_i8 v[114:117], v[160:163], v[198:201], v[114:117]
	v_mfma_i32_16x16x64_i8 v[106:109], v[152:155], v[206:209], v[106:109]
	v_mfma_i32_16x16x64_i8 v[98:101], v[160:163], v[206:209], v[98:101]
	v_mfma_i32_16x16x64_i8 v[90:93], v[152:155], v[214:217], v[90:93]
	v_mfma_i32_16x16x64_i8 v[82:85], v[160:163], v[214:217], v[82:85]
	v_mfma_i32_16x16x64_i8 v[110:113], v[164:167], v[180:183], v[110:113]
	v_mfma_i32_16x16x64_i8 v[102:105], v[172:175], v[180:183], v[102:105]
	v_mfma_i32_16x16x64_i8 v[94:97], v[164:167], v[194:197], v[94:97]
	v_mfma_i32_16x16x64_i8 v[86:89], v[172:175], v[194:197], v[86:89]
	v_mfma_i32_16x16x64_i8 v[78:81], v[164:167], v[202:205], v[78:81]
	v_mfma_i32_16x16x64_i8 v[74:77], v[172:175], v[202:205], v[74:77]
	v_mfma_i32_16x16x64_i8 v[70:73], v[164:167], v[210:213], v[70:73]
	v_mfma_i32_16x16x64_i8 v[66:69], v[172:175], v[210:213], v[66:69]
	v_mfma_i32_16x16x64_i8 v[110:113], v[168:171], v[190:193], v[110:113]
	v_mfma_i32_16x16x64_i8 v[102:105], v[176:179], v[190:193], v[102:105]
	v_mfma_i32_16x16x64_i8 v[94:97], v[168:171], v[198:201], v[94:97]
	v_mfma_i32_16x16x64_i8 v[86:89], v[176:179], v[198:201], v[86:89]
	v_mfma_i32_16x16x64_i8 v[78:81], v[168:171], v[206:209], v[78:81]
	v_mfma_i32_16x16x64_i8 v[74:77], v[176:179], v[206:209], v[74:77]
	v_mfma_i32_16x16x64_i8 v[70:73], v[168:171], v[214:217], v[70:73]
	v_mfma_i32_16x16x64_i8 v[66:69], v[176:179], v[214:217], v[66:69]
	s_setprio 0
	s_barrier
	s_add_i32 s28, s65, s41
	v_lshl_add_u64 v[184:185], v[184:185], 0, s[18:19]
	s_mov_b32 m0, s28
	ds_read_b128 v[180:183], v189 offset:49152
	ds_read_b128 v[190:193], v189 offset:50176
	ds_read_b128 v[194:197], v189 offset:51200
	ds_read_b128 v[198:201], v189 offset:52224
	ds_read_b128 v[202:205], v189 offset:53248
	ds_read_b128 v[206:209], v189 offset:54272
	ds_read_b128 v[210:213], v189 offset:55296
	ds_read_b128 v[214:217], v189 offset:56320
	global_load_lds_dwordx4 v[184:185], off
	v_lshl_add_u64 v[184:185], v[218:219], 0, s[18:19]
	s_add_i32 m0, s28, 0x2000
	s_add_i32 s28, s66, s41
	global_load_lds_dwordx4 v[184:185], off
	v_lshl_add_u64 v[184:185], v[220:221], 0, s[18:19]
	s_mov_b32 m0, s28
	s_nop 0
	global_load_lds_dwordx4 v[184:185], off
	v_lshl_add_u64 v[184:185], v[222:223], 0, s[18:19]
	s_add_i32 m0, s28, 0x2000
	s_nop 0
	global_load_lds_dwordx4 v[184:185], off
	v_lshl_add_u64 v[184:185], v[224:225], 0, s[18:19]
	s_mov_b32 m0, s51
	s_nop 0
	global_load_lds_dwordx4 v[184:185], off
	v_lshl_add_u64 v[184:185], v[226:227], 0, s[18:19]
	s_mov_b32 m0, s54
	s_nop 0
	global_load_lds_dwordx4 v[184:185], off
	s_waitcnt vmcnt(8)
	s_waitcnt lgkmcnt(0)
	s_setprio 1
	v_mfma_i32_16x16x64_i8 v[62:65], v[148:151], v[180:183], v[62:65]
	v_mfma_i32_16x16x64_i8 v[58:61], v[156:159], v[180:183], v[58:61]
	s_barrier
	v_mfma_i32_16x16x64_i8 v[54:57], v[148:151], v[194:197], v[54:57]
	v_mfma_i32_16x16x64_i8 v[50:53], v[156:159], v[194:197], v[50:53]
	v_mfma_i32_16x16x64_i8 v[42:45], v[148:151], v[202:205], v[42:45]
	v_mfma_i32_16x16x64_i8 v[34:37], v[156:159], v[202:205], v[34:37]
	v_mfma_i32_16x16x64_i8 v[26:29], v[148:151], v[210:213], v[26:29]
	v_mfma_i32_16x16x64_i8 v[18:21], v[156:159], v[210:213], v[18:21]
	v_mfma_i32_16x16x64_i8 v[62:65], v[152:155], v[190:193], v[62:65]
	v_mfma_i32_16x16x64_i8 v[58:61], v[160:163], v[190:193], v[58:61]
	v_mfma_i32_16x16x64_i8 v[54:57], v[152:155], v[198:201], v[54:57]
	v_mfma_i32_16x16x64_i8 v[50:53], v[160:163], v[198:201], v[50:53]
	v_mfma_i32_16x16x64_i8 v[42:45], v[152:155], v[206:209], v[42:45]
	v_mfma_i32_16x16x64_i8 v[34:37], v[160:163], v[206:209], v[34:37]
	v_mfma_i32_16x16x64_i8 v[26:29], v[152:155], v[214:217], v[26:29]
	v_mfma_i32_16x16x64_i8 v[18:21], v[160:163], v[214:217], v[18:21]
	v_mfma_i32_16x16x64_i8 v[46:49], v[164:167], v[180:183], v[46:49]
	v_mfma_i32_16x16x64_i8 v[38:41], v[172:175], v[180:183], v[38:41]
	v_mfma_i32_16x16x64_i8 v[30:33], v[164:167], v[194:197], v[30:33]
	v_mfma_i32_16x16x64_i8 v[22:25], v[172:175], v[194:197], v[22:25]
	v_mfma_i32_16x16x64_i8 v[14:17], v[164:167], v[202:205], v[14:17]
	v_mfma_i32_16x16x64_i8 v[10:13], v[172:175], v[202:205], v[10:13]
	v_mfma_i32_16x16x64_i8 v[6:9], v[164:167], v[210:213], v[6:9]
	v_mfma_i32_16x16x64_i8 v[2:5], v[172:175], v[210:213], v[2:5]
	v_mfma_i32_16x16x64_i8 v[46:49], v[168:171], v[190:193], v[46:49]
	v_mfma_i32_16x16x64_i8 v[38:41], v[176:179], v[190:193], v[38:41]
	v_mfma_i32_16x16x64_i8 v[30:33], v[168:171], v[198:201], v[30:33]
	v_mfma_i32_16x16x64_i8 v[22:25], v[176:179], v[198:201], v[22:25]
	v_mfma_i32_16x16x64_i8 v[14:17], v[168:171], v[206:209], v[14:17]
	v_mfma_i32_16x16x64_i8 v[10:13], v[176:179], v[206:209], v[10:13]
	v_mfma_i32_16x16x64_i8 v[6:9], v[168:171], v[214:217], v[6:9]
	v_mfma_i32_16x16x64_i8 v[2:5], v[176:179], v[214:217], v[2:5]
	s_setprio 0
	s_barrier
	s_add_u32 s26, s26, 0x100
	s_addc_u32 s27, s27, 0
	s_add_u32 s34, s34, 0x100
	s_addc_u32 s35, s35, 0
	s_cmp_ge_i32 s64, s55
	s_mov_b32 s28, s64
	s_cbranch_scc0 .LBB0_2949
	v_cvt_f32_i32_e32 v172, v126
	v_cvt_f32_i32_e32 v173, v127
	v_cvt_f32_i32_e32 v170, v128
	v_cvt_f32_i32_e32 v171, v129
	v_cvt_f32_i32_e32 v174, v122
	v_cvt_f32_i32_e32 v175, v123
	v_cvt_f32_i32_e32 v176, v124
	v_cvt_f32_i32_e32 v177, v125
	v_cvt_f32_i32_e32 v180, v110
	v_cvt_f32_i32_e32 v181, v111
	v_cvt_f32_i32_e32 v182, v112
	v_cvt_f32_i32_e32 v183, v113
	v_cvt_f32_i32_e32 v178, v102
	v_cvt_f32_i32_e32 v179, v103
	v_cvt_f32_i32_e32 v184, v104
	v_cvt_f32_i32_e32 v185, v105
	v_cvt_f32_i32_e32 v152, v118
	v_cvt_f32_i32_e32 v153, v119
	v_cvt_f32_i32_e32 v154, v120
	v_cvt_f32_i32_e32 v155, v121
	v_cvt_f32_i32_e32 v156, v114
	v_cvt_f32_i32_e32 v157, v115
	v_cvt_f32_i32_e32 v158, v116
	v_cvt_f32_i32_e32 v159, v117
	v_cvt_f32_i32_e32 v160, v94
	v_cvt_f32_i32_e32 v161, v95
	v_cvt_f32_i32_e32 v162, v96
	v_cvt_f32_i32_e32 v163, v97
	v_cvt_f32_i32_e32 v164, v86
	v_cvt_f32_i32_e32 v165, v87
	v_cvt_f32_i32_e32 v166, v88
	v_cvt_f32_i32_e32 v167, v89
	v_cvt_f32_i32_e32 v118, v106
	v_cvt_f32_i32_e32 v119, v107
	v_cvt_f32_i32_e32 v120, v108
	v_cvt_f32_i32_e32 v121, v109
	v_cvt_f32_i32_e32 v122, v98
	v_cvt_f32_i32_e32 v123, v99
	v_cvt_f32_i32_e32 v124, v100
	v_cvt_f32_i32_e32 v125, v101
	v_cvt_f32_i32_e32 v126, v78
	v_cvt_f32_i32_e32 v127, v79
	v_cvt_f32_i32_e32 v128, v80
	v_cvt_f32_i32_e32 v129, v81
	v_cvt_f32_i32_e32 v148, v74
	v_cvt_f32_i32_e32 v149, v75
	v_cvt_f32_i32_e32 v150, v76
	v_cvt_f32_i32_e32 v151, v77
	v_cvt_f32_i32_e32 v102, v90
	v_cvt_f32_i32_e32 v103, v91
	v_cvt_f32_i32_e32 v104, v92
	v_cvt_f32_i32_e32 v105, v93
	v_cvt_f32_i32_e32 v106, v82
	v_cvt_f32_i32_e32 v107, v83
	v_cvt_f32_i32_e32 v108, v84
	v_cvt_f32_i32_e32 v109, v85
	v_cvt_f32_i32_e32 v110, v70
	v_cvt_f32_i32_e32 v111, v71
	v_cvt_f32_i32_e32 v112, v72
	v_cvt_f32_i32_e32 v113, v73
	v_cvt_f32_i32_e32 v114, v66
	v_cvt_f32_i32_e32 v115, v67
	v_cvt_f32_i32_e32 v116, v68
	v_cvt_f32_i32_e32 v117, v69
	v_cvt_f32_i32_e32 v82, v62
	v_cvt_f32_i32_e32 v83, v63
	v_cvt_f32_i32_e32 v84, v64
	v_cvt_f32_i32_e32 v85, v65
	v_cvt_f32_i32_e32 v86, v58
	v_cvt_f32_i32_e32 v87, v59
	v_cvt_f32_i32_e32 v88, v60
	v_cvt_f32_i32_e32 v89, v61
	v_cvt_f32_i32_e32 v92, v46
	v_cvt_f32_i32_e32 v93, v47
	v_cvt_f32_i32_e32 v94, v48
	v_cvt_f32_i32_e32 v95, v49
	v_cvt_f32_i32_e32 v96, v38
	v_cvt_f32_i32_e32 v97, v39
	v_cvt_f32_i32_e32 v98, v40
	v_cvt_f32_i32_e32 v99, v41
	v_cvt_f32_i32_e32 v66, v54
	v_cvt_f32_i32_e32 v67, v55
	v_cvt_f32_i32_e32 v68, v56
	v_cvt_f32_i32_e32 v69, v57
	v_cvt_f32_i32_e32 v70, v50
	v_cvt_f32_i32_e32 v71, v51
	v_cvt_f32_i32_e32 v72, v52
	v_cvt_f32_i32_e32 v73, v53
	v_cvt_f32_i32_e32 v74, v30
	v_cvt_f32_i32_e32 v75, v31
	v_cvt_f32_i32_e32 v76, v32
	v_cvt_f32_i32_e32 v77, v33
	v_cvt_f32_i32_e32 v78, v22
	v_cvt_f32_i32_e32 v79, v23
	v_cvt_f32_i32_e32 v80, v24
	v_cvt_f32_i32_e32 v81, v25
	v_cvt_f32_i32_e32 v50, v42
	v_cvt_f32_i32_e32 v51, v43
	v_cvt_f32_i32_e32 v52, v44
	v_cvt_f32_i32_e32 v53, v45
	v_cvt_f32_i32_e32 v54, v34
	v_cvt_f32_i32_e32 v55, v35
	v_cvt_f32_i32_e32 v56, v36
	v_cvt_f32_i32_e32 v57, v37
	v_cvt_f32_i32_e32 v58, v14
	v_cvt_f32_i32_e32 v59, v15
	v_cvt_f32_i32_e32 v60, v16
	v_cvt_f32_i32_e32 v61, v17
	v_cvt_f32_i32_e32 v62, v10
	v_cvt_f32_i32_e32 v63, v11
	v_cvt_f32_i32_e32 v64, v12
	v_cvt_f32_i32_e32 v65, v13
	v_cvt_f32_i32_e32 v34, v26
	v_cvt_f32_i32_e32 v35, v27
	v_cvt_f32_i32_e32 v36, v28
	v_cvt_f32_i32_e32 v37, v29
	v_cvt_f32_i32_e32 v38, v18
	v_cvt_f32_i32_e32 v39, v19
	v_cvt_f32_i32_e32 v40, v20
	v_cvt_f32_i32_e32 v41, v21
	v_cvt_f32_i32_e32 v42, v6
	v_cvt_f32_i32_e32 v43, v7
	v_cvt_f32_i32_e32 v44, v8
	v_cvt_f32_i32_e32 v45, v9
	v_cvt_f32_i32_e32 v46, v2
	v_cvt_f32_i32_e32 v47, v3
	v_cvt_f32_i32_e32 v48, v4
	v_cvt_f32_i32_e32 v49, v5

.LBB0_3032:
	ds_read_b128 v[114:117], v209
	ds_read_b128 v[118:121], v209 offset:1024
	ds_read_b128 v[122:125], v209 offset:2048
	ds_read_b128 v[126:129], v209 offset:3072
	ds_read_b128 v[146:149], v210
	ds_read_b128 v[150:153], v210 offset:1024
	ds_read_b128 v[154:157], v210 offset:2048
	ds_read_b128 v[158:161], v210 offset:3072
	s_add_i32 s80, s36, 2
	s_add_u32 s37, s34, 0x4000
	s_addc_u32 s38, s35, 0
	s_cmp_eq_u32 s61, s36
	s_cselect_b32 s39, s5, s38
	s_cselect_b32 s38, s4, s37
	s_cselect_b32 s82, s30, s70
	s_cselect_b32 s83, s31, s71
	s_add_u32 s36, s38, 0x8000
	s_addc_u32 s37, s39, 0
	v_lshl_add_u64 v[218:219], s[34:35], 0, v[170:171]
	s_add_i32 m0, s45, 0xc000
	ds_read_b128 v[178:181], v211
	ds_read_b128 v[182:185], v211 offset:1024
	ds_read_b128 v[186:189], v211 offset:2048
	ds_read_b128 v[190:193], v211 offset:3072
	ds_read_b128 v[194:197], v211 offset:4096
	ds_read_b128 v[198:201], v211 offset:5120
	ds_read_b128 v[202:205], v211 offset:6144
	ds_read_b128 v[214:217], v211 offset:7168
	global_load_lds_dwordx4 v[218:219], off
	v_lshl_add_u64 v[218:219], s[34:35], 0, v[172:173]
	s_add_i32 m0, s45, 0xe000
	s_nop 0
	global_load_lds_dwordx4 v[218:219], off
	s_waitcnt vmcnt(8)
	s_waitcnt lgkmcnt(0)
	s_setprio 1
	v_mfma_f32_16x16x32_bf16 v[142:145], v[114:117], v[178:181], v[142:145]
	v_mfma_f32_16x16x32_bf16 v[138:141], v[122:125], v[178:181], v[138:141]
	s_barrier
	v_mfma_f32_16x16x32_bf16 v[110:113], v[114:117], v[186:189], v[110:113]
	v_mfma_f32_16x16x32_bf16 v[106:109], v[122:125], v[186:189], v[106:109]
	v_mfma_f32_16x16x32_bf16 v[94:97], v[114:117], v[194:197], v[94:97]
	v_mfma_f32_16x16x32_bf16 v[90:93], v[122:125], v[194:197], v[90:93]
	v_mfma_f32_16x16x32_bf16 v[78:81], v[114:117], v[202:205], v[78:81]
	v_mfma_f32_16x16x32_bf16 v[74:77], v[122:125], v[202:205], v[74:77]
	v_mfma_f32_16x16x32_bf16 v[142:145], v[118:121], v[182:185], v[142:145]
	v_mfma_f32_16x16x32_bf16 v[138:141], v[126:129], v[182:185], v[138:141]
	v_mfma_f32_16x16x32_bf16 v[110:113], v[118:121], v[190:193], v[110:113]
	v_mfma_f32_16x16x32_bf16 v[106:109], v[126:129], v[190:193], v[106:109]
	v_mfma_f32_16x16x32_bf16 v[94:97], v[118:121], v[198:201], v[94:97]
	v_mfma_f32_16x16x32_bf16 v[90:93], v[126:129], v[198:201], v[90:93]
	v_mfma_f32_16x16x32_bf16 v[78:81], v[118:121], v[214:217], v[78:81]
	v_mfma_f32_16x16x32_bf16 v[74:77], v[126:129], v[214:217], v[74:77]
	v_mfma_f32_16x16x32_bf16 v[134:137], v[146:149], v[178:181], v[134:137]
	v_mfma_f32_16x16x32_bf16 v[130:133], v[154:157], v[178:181], v[130:133]
	v_mfma_f32_16x16x32_bf16 v[102:105], v[146:149], v[186:189], v[102:105]
	v_mfma_f32_16x16x32_bf16 v[98:101], v[154:157], v[186:189], v[98:101]
	v_mfma_f32_16x16x32_bf16 v[86:89], v[146:149], v[194:197], v[86:89]
	v_mfma_f32_16x16x32_bf16 v[82:85], v[154:157], v[194:197], v[82:85]
	v_mfma_f32_16x16x32_bf16 v[70:73], v[146:149], v[202:205], v[70:73]
	v_mfma_f32_16x16x32_bf16 v[66:69], v[154:157], v[202:205], v[66:69]
	v_mfma_f32_16x16x32_bf16 v[134:137], v[150:153], v[182:185], v[134:137]
	v_mfma_f32_16x16x32_bf16 v[130:133], v[158:161], v[182:185], v[130:133]
	v_mfma_f32_16x16x32_bf16 v[102:105], v[150:153], v[190:193], v[102:105]
	v_mfma_f32_16x16x32_bf16 v[98:101], v[158:161], v[190:193], v[98:101]
	v_mfma_f32_16x16x32_bf16 v[86:89], v[150:153], v[198:201], v[86:89]
	v_mfma_f32_16x16x32_bf16 v[82:85], v[158:161], v[198:201], v[82:85]
	v_mfma_f32_16x16x32_bf16 v[70:73], v[150:153], v[214:217], v[70:73]
	v_mfma_f32_16x16x32_bf16 v[66:69], v[158:161], v[214:217], v[66:69]
	s_setprio 0
	s_barrier
	s_add_i32 s81, s64, s44
	v_lshl_add_u64 v[218:219], s[82:83], 0, v[164:165]
	s_mov_b32 m0, s81
	ds_read_b128 v[178:181], v211 offset:16384
	ds_read_b128 v[182:185], v211 offset:17408
	ds_read_b128 v[186:189], v211 offset:18432
	ds_read_b128 v[190:193], v211 offset:19456
	ds_read_b128 v[194:197], v211 offset:20480
	ds_read_b128 v[198:201], v211 offset:21504
	ds_read_b128 v[202:205], v211 offset:22528
	ds_read_b128 v[214:217], v211 offset:23552
	global_load_lds_dwordx4 v[218:219], off
	s_add_i32 m0, s81, 0x2000
	v_lshl_add_u64 v[220:221], s[82:83], 0, v[168:169]
	s_add_u32 s82, s82, s8
	s_addc_u32 s83, s83, s9
	s_add_i32 s81, s65, s44
	global_load_lds_dwordx4 v[220:221], off
	v_lshl_add_u64 v[222:223], s[82:83], 0, v[164:165]
	s_mov_b32 m0, s81
	v_lshl_add_u64 v[224:225], s[82:83], 0, v[168:169]
	global_load_lds_dwordx4 v[222:223], off
	s_add_i32 m0, s81, 0x2000
	v_lshl_add_u64 v[226:227], s[38:39], 0, v[162:163]
	global_load_lds_dwordx4 v[224:225], off
	s_mov_b32 m0, s45
	s_nop 0
	global_load_lds_dwordx4 v[226:227], off
	v_lshl_add_u64 v[226:227], s[38:39], 0, v[166:167]
	s_mov_b32 m0, s46
	s_nop 0
	global_load_lds_dwordx4 v[226:227], off
	s_waitcnt vmcnt(8)
	s_waitcnt lgkmcnt(0)
	s_setprio 1
	v_mfma_f32_16x16x32_bf16 v[62:65], v[114:117], v[178:181], v[62:65]
	v_mfma_f32_16x16x32_bf16 v[58:61], v[122:125], v[178:181], v[58:61]
	s_barrier
	v_mfma_f32_16x16x32_bf16 v[46:49], v[114:117], v[186:189], v[46:49]
	v_mfma_f32_16x16x32_bf16 v[42:45], v[122:125], v[186:189], v[42:45]
	v_mfma_f32_16x16x32_bf16 v[30:33], v[114:117], v[194:197], v[30:33]
	v_mfma_f32_16x16x32_bf16 v[26:29], v[122:125], v[194:197], v[26:29]
	v_mfma_f32_16x16x32_bf16 v[14:17], v[114:117], v[202:205], v[14:17]
	v_mfma_f32_16x16x32_bf16 v[10:13], v[122:125], v[202:205], v[10:13]
	v_mfma_f32_16x16x32_bf16 v[62:65], v[118:121], v[182:185], v[62:65]
	v_mfma_f32_16x16x32_bf16 v[58:61], v[126:129], v[182:185], v[58:61]
	v_mfma_f32_16x16x32_bf16 v[46:49], v[118:121], v[190:193], v[46:49]
	v_mfma_f32_16x16x32_bf16 v[42:45], v[126:129], v[190:193], v[42:45]
	v_mfma_f32_16x16x32_bf16 v[30:33], v[118:121], v[198:201], v[30:33]
	v_mfma_f32_16x16x32_bf16 v[26:29], v[126:129], v[198:201], v[26:29]
	v_mfma_f32_16x16x32_bf16 v[14:17], v[118:121], v[214:217], v[14:17]
	v_mfma_f32_16x16x32_bf16 v[10:13], v[126:129], v[214:217], v[10:13]
	v_mfma_f32_16x16x32_bf16 v[54:57], v[146:149], v[178:181], v[54:57]
	v_mfma_f32_16x16x32_bf16 v[50:53], v[154:157], v[178:181], v[50:53]
	v_mfma_f32_16x16x32_bf16 v[38:41], v[146:149], v[186:189], v[38:41]
	v_mfma_f32_16x16x32_bf16 v[34:37], v[154:157], v[186:189], v[34:37]
	v_mfma_f32_16x16x32_bf16 v[22:25], v[146:149], v[194:197], v[22:25]
	v_mfma_f32_16x16x32_bf16 v[18:21], v[154:157], v[194:197], v[18:21]
	v_mfma_f32_16x16x32_bf16 v[6:9], v[146:149], v[202:205], v[6:9]
	v_mfma_f32_16x16x32_bf16 v[2:5], v[154:157], v[202:205], v[2:5]
	v_mfma_f32_16x16x32_bf16 v[54:57], v[150:153], v[182:185], v[54:57]
	v_mfma_f32_16x16x32_bf16 v[50:53], v[158:161], v[182:185], v[50:53]
	v_mfma_f32_16x16x32_bf16 v[38:41], v[150:153], v[190:193], v[38:41]
	v_mfma_f32_16x16x32_bf16 v[34:37], v[158:161], v[190:193], v[34:37]
	v_mfma_f32_16x16x32_bf16 v[22:25], v[150:153], v[198:201], v[22:25]
	v_mfma_f32_16x16x32_bf16 v[18:21], v[158:161], v[198:201], v[18:21]
	v_mfma_f32_16x16x32_bf16 v[6:9], v[150:153], v[214:217], v[6:9]
	v_mfma_f32_16x16x32_bf16 v[2:5], v[158:161], v[214:217], v[2:5]
	s_setprio 0
	s_barrier
	s_add_i32 s81, 0, 0x18000
	s_add_i32 s82, 0, 0x1c000
	v_add_u32_e32 v126, s81, v207
	v_add_u32_e32 v158, s82, v207
	ds_read_b128 v[114:117], v126
	ds_read_b128 v[118:121], v126 offset:1024
	ds_read_b128 v[122:125], v126 offset:2048
	ds_read_b128 v[126:129], v126 offset:3072
	ds_read_b128 v[146:149], v158
	ds_read_b128 v[150:153], v158 offset:1024
	ds_read_b128 v[154:157], v158 offset:2048
	ds_read_b128 v[158:161], v158 offset:3072
	s_add_u32 s38, s38, 0x4000
	s_addc_u32 s39, s39, 0
	s_mov_b32 m0, s47
	v_lshl_add_u64 v[226:227], s[38:39], 0, v[162:163]
	ds_read_b128 v[178:181], v211 offset:32768
	ds_read_b128 v[182:185], v211 offset:33792
	ds_read_b128 v[186:189], v211 offset:34816
	ds_read_b128 v[190:193], v211 offset:35840
	ds_read_b128 v[194:197], v211 offset:36864
	ds_read_b128 v[198:201], v211 offset:37888
	ds_read_b128 v[202:205], v211 offset:38912
	ds_read_b128 v[214:217], v211 offset:39936
	global_load_lds_dwordx4 v[226:227], off
	v_lshl_add_u64 v[226:227], s[38:39], 0, v[166:167]
	s_mov_b32 m0, s50
	s_nop 0
	global_load_lds_dwordx4 v[226:227], off
	s_waitcnt vmcnt(8)
	s_waitcnt lgkmcnt(0)
	s_setprio 1
	v_mfma_f32_16x16x32_bf16 v[142:145], v[114:117], v[178:181], v[142:145]
	v_mfma_f32_16x16x32_bf16 v[138:141], v[122:125], v[178:181], v[138:141]
	s_barrier
	v_mfma_f32_16x16x32_bf16 v[110:113], v[114:117], v[186:189], v[110:113]
	v_mfma_f32_16x16x32_bf16 v[106:109], v[122:125], v[186:189], v[106:109]
	v_mfma_f32_16x16x32_bf16 v[94:97], v[114:117], v[194:197], v[94:97]
	v_mfma_f32_16x16x32_bf16 v[90:93], v[122:125], v[194:197], v[90:93]
	v_mfma_f32_16x16x32_bf16 v[78:81], v[114:117], v[202:205], v[78:81]
	v_mfma_f32_16x16x32_bf16 v[74:77], v[122:125], v[202:205], v[74:77]
	v_mfma_f32_16x16x32_bf16 v[142:145], v[118:121], v[182:185], v[142:145]
	v_mfma_f32_16x16x32_bf16 v[138:141], v[126:129], v[182:185], v[138:141]
	v_mfma_f32_16x16x32_bf16 v[110:113], v[118:121], v[190:193], v[110:113]
	v_mfma_f32_16x16x32_bf16 v[106:109], v[126:129], v[190:193], v[106:109]
	v_mfma_f32_16x16x32_bf16 v[94:97], v[118:121], v[198:201], v[94:97]
	v_mfma_f32_16x16x32_bf16 v[90:93], v[126:129], v[198:201], v[90:93]
	v_mfma_f32_16x16x32_bf16 v[78:81], v[118:121], v[214:217], v[78:81]
	v_mfma_f32_16x16x32_bf16 v[74:77], v[126:129], v[214:217], v[74:77]
	v_mfma_f32_16x16x32_bf16 v[134:137], v[146:149], v[178:181], v[134:137]
	v_mfma_f32_16x16x32_bf16 v[130:133], v[154:157], v[178:181], v[130:133]
	v_mfma_f32_16x16x32_bf16 v[102:105], v[146:149], v[186:189], v[102:105]
	v_mfma_f32_16x16x32_bf16 v[98:101], v[154:157], v[186:189], v[98:101]
	v_mfma_f32_16x16x32_bf16 v[86:89], v[146:149], v[194:197], v[86:89]
	v_mfma_f32_16x16x32_bf16 v[82:85], v[154:157], v[194:197], v[82:85]
	v_mfma_f32_16x16x32_bf16 v[70:73], v[146:149], v[202:205], v[70:73]
	v_mfma_f32_16x16x32_bf16 v[66:69], v[154:157], v[202:205], v[66:69]
	v_mfma_f32_16x16x32_bf16 v[134:137], v[150:153], v[182:185], v[134:137]
	v_mfma_f32_16x16x32_bf16 v[130:133], v[158:161], v[182:185], v[130:133]
	v_mfma_f32_16x16x32_bf16 v[102:105], v[150:153], v[190:193], v[102:105]
	v_mfma_f32_16x16x32_bf16 v[98:101], v[158:161], v[190:193], v[98:101]
	v_mfma_f32_16x16x32_bf16 v[86:89], v[150:153], v[198:201], v[86:89]
	v_mfma_f32_16x16x32_bf16 v[82:85], v[158:161], v[198:201], v[82:85]
	v_mfma_f32_16x16x32_bf16 v[70:73], v[150:153], v[214:217], v[70:73]
	v_mfma_f32_16x16x32_bf16 v[66:69], v[158:161], v[214:217], v[66:69]
	s_setprio 0
	s_barrier
	s_add_i32 s38, s81, s44
	v_lshl_add_u64 v[218:219], v[218:219], 0, s[24:25]
	s_mov_b32 m0, s38
	ds_read_b128 v[178:181], v211 offset:49152
	ds_read_b128 v[182:185], v211 offset:50176
	ds_read_b128 v[186:189], v211 offset:51200
	ds_read_b128 v[190:193], v211 offset:52224
	ds_read_b128 v[194:197], v211 offset:53248
	ds_read_b128 v[198:201], v211 offset:54272
	ds_read_b128 v[202:205], v211 offset:55296
	ds_read_b128 v[214:217], v211 offset:56320
	global_load_lds_dwordx4 v[218:219], off
	v_lshl_add_u64 v[218:219], v[220:221], 0, s[24:25]
	s_add_i32 m0, s38, 0x2000
	s_add_i32 s38, s82, s44
	global_load_lds_dwordx4 v[218:219], off
	v_lshl_add_u64 v[218:219], v[222:223], 0, s[24:25]
	s_mov_b32 m0, s38
	s_nop 0
	global_load_lds_dwordx4 v[218:219], off
	v_lshl_add_u64 v[218:219], v[224:225], 0, s[24:25]
	s_add_i32 m0, s38, 0x2000
	s_nop 0
	global_load_lds_dwordx4 v[218:219], off
	v_lshl_add_u64 v[218:219], s[36:37], 0, v[162:163]
	s_mov_b32 m0, s59
	s_nop 0
	global_load_lds_dwordx4 v[218:219], off
	v_lshl_add_u64 v[218:219], s[36:37], 0, v[166:167]
	s_mov_b32 m0, s60
	s_nop 0
	global_load_lds_dwordx4 v[218:219], off
	s_waitcnt vmcnt(8)
	s_waitcnt lgkmcnt(0)
	s_setprio 1
	v_mfma_f32_16x16x32_bf16 v[62:65], v[114:117], v[178:181], v[62:65]
	v_mfma_f32_16x16x32_bf16 v[58:61], v[122:125], v[178:181], v[58:61]
	s_barrier
	v_mfma_f32_16x16x32_bf16 v[46:49], v[114:117], v[186:189], v[46:49]
	v_mfma_f32_16x16x32_bf16 v[42:45], v[122:125], v[186:189], v[42:45]
	v_mfma_f32_16x16x32_bf16 v[30:33], v[114:117], v[194:197], v[30:33]
	v_mfma_f32_16x16x32_bf16 v[26:29], v[122:125], v[194:197], v[26:29]
	v_mfma_f32_16x16x32_bf16 v[14:17], v[114:117], v[202:205], v[14:17]
	v_mfma_f32_16x16x32_bf16 v[10:13], v[122:125], v[202:205], v[10:13]
	v_mfma_f32_16x16x32_bf16 v[62:65], v[118:121], v[182:185], v[62:65]
	v_mfma_f32_16x16x32_bf16 v[58:61], v[126:129], v[182:185], v[58:61]
	v_mfma_f32_16x16x32_bf16 v[46:49], v[118:121], v[190:193], v[46:49]
	v_mfma_f32_16x16x32_bf16 v[42:45], v[126:129], v[190:193], v[42:45]
	v_mfma_f32_16x16x32_bf16 v[30:33], v[118:121], v[198:201], v[30:33]
	v_mfma_f32_16x16x32_bf16 v[26:29], v[126:129], v[198:201], v[26:29]
	v_mfma_f32_16x16x32_bf16 v[14:17], v[118:121], v[214:217], v[14:17]
	v_mfma_f32_16x16x32_bf16 v[10:13], v[126:129], v[214:217], v[10:13]
	v_mfma_f32_16x16x32_bf16 v[54:57], v[146:149], v[178:181], v[54:57]
	v_mfma_f32_16x16x32_bf16 v[50:53], v[154:157], v[178:181], v[50:53]
	v_mfma_f32_16x16x32_bf16 v[38:41], v[146:149], v[186:189], v[38:41]
	v_mfma_f32_16x16x32_bf16 v[34:37], v[154:157], v[186:189], v[34:37]
	v_mfma_f32_16x16x32_bf16 v[22:25], v[146:149], v[194:197], v[22:25]
	v_mfma_f32_16x16x32_bf16 v[18:21], v[154:157], v[194:197], v[18:21]
	v_mfma_f32_16x16x32_bf16 v[6:9], v[146:149], v[202:205], v[6:9]
	v_mfma_f32_16x16x32_bf16 v[2:5], v[154:157], v[202:205], v[2:5]
	v_mfma_f32_16x16x32_bf16 v[54:57], v[150:153], v[182:185], v[54:57]
	v_mfma_f32_16x16x32_bf16 v[50:53], v[158:161], v[182:185], v[50:53]
	v_mfma_f32_16x16x32_bf16 v[38:41], v[150:153], v[190:193], v[38:41]
	v_mfma_f32_16x16x32_bf16 v[34:37], v[158:161], v[190:193], v[34:37]
	v_mfma_f32_16x16x32_bf16 v[22:25], v[150:153], v[198:201], v[22:25]
	v_mfma_f32_16x16x32_bf16 v[18:21], v[158:161], v[198:201], v[18:21]
	v_mfma_f32_16x16x32_bf16 v[6:9], v[150:153], v[214:217], v[6:9]
	v_mfma_f32_16x16x32_bf16 v[2:5], v[158:161], v[214:217], v[2:5]
	s_setprio 0
	s_barrier
	s_add_u32 s70, s70, 0x100
	s_addc_u32 s71, s71, 0
	s_add_u32 s34, s34, 0x10000
	s_addc_u32 s35, s35, 0
	s_cmp_ge_i32 s80, s58
	s_mov_b32 s36, s80
	s_cbranch_scc0 .LBB0_3032

.LBB0_3126:
	ds_read_b128 v[34:37], v196
	ds_read_b128 v[38:41], v196 offset:1024
	ds_read_b128 v[50:53], v196 offset:2048
	ds_read_b128 v[54:57], v196 offset:3072
	ds_read_b128 v[146:149], v197
	ds_read_b128 v[150:153], v197 offset:1024
	ds_read_b128 v[184:187], v197 offset:2048
	ds_read_b128 v[188:191], v197 offset:3072
	s_add_i32 s11, s6, 2
	s_add_u32 s12, s4, 0x80
	s_addc_u32 s7, s5, 0
	s_cmp_eq_u32 s84, s6
	s_cselect_b32 s6, s44, s12
	s_cselect_b32 s7, s45, s7
	s_cselect_b32 s13, s47, s9
	s_cselect_b32 s12, s46, s8
	v_lshl_add_u64 v[192:193], s[4:5], 0, v[174:175]
	s_add_i32 m0, s66, 0xc000
	ds_read_b128 v[200:203], v198
	ds_read_b128 v[204:207], v198 offset:1024
	ds_read_b128 v[208:211], v198 offset:2048
	ds_read_b128 v[212:215], v198 offset:3072
	ds_read_b128 v[216:219], v198 offset:4096
	ds_read_b128 v[220:223], v198 offset:5120
	ds_read_b128 v[224:227], v198 offset:6144
	ds_read_b128 v[228:231], v198 offset:7168
	global_load_lds_dwordx4 v[192:193], off
	v_lshl_add_u64 v[192:193], s[4:5], 0, v[176:177]
	s_add_i32 m0, s66, 0xe000
	s_nop 0
	global_load_lds_dwordx4 v[192:193], off
	s_waitcnt vmcnt(8)
	s_waitcnt lgkmcnt(0)
	s_setprio 1
	v_mfma_f32_16x16x32_bf16 v[142:145], v[34:37], v[200:203], v[142:145]
	v_mfma_f32_16x16x32_bf16 v[138:141], v[50:53], v[200:203], v[138:141]
	s_barrier
	v_mfma_f32_16x16x32_bf16 v[126:129], v[34:37], v[208:211], v[126:129]
	v_mfma_f32_16x16x32_bf16 v[122:125], v[50:53], v[208:211], v[122:125]
	v_mfma_f32_16x16x32_bf16 v[110:113], v[34:37], v[216:219], v[110:113]
	v_mfma_f32_16x16x32_bf16 v[106:109], v[50:53], v[216:219], v[106:109]
	v_mfma_f32_16x16x32_bf16 v[94:97], v[34:37], v[224:227], v[94:97]
	v_mfma_f32_16x16x32_bf16 v[90:93], v[50:53], v[224:227], v[90:93]
	v_mfma_f32_16x16x32_bf16 v[142:145], v[38:41], v[204:207], v[142:145]
	v_mfma_f32_16x16x32_bf16 v[138:141], v[54:57], v[204:207], v[138:141]
	v_mfma_f32_16x16x32_bf16 v[126:129], v[38:41], v[212:215], v[126:129]
	v_mfma_f32_16x16x32_bf16 v[122:125], v[54:57], v[212:215], v[122:125]
	v_mfma_f32_16x16x32_bf16 v[110:113], v[38:41], v[220:223], v[110:113]
	v_mfma_f32_16x16x32_bf16 v[106:109], v[54:57], v[220:223], v[106:109]
	v_mfma_f32_16x16x32_bf16 v[94:97], v[38:41], v[228:231], v[94:97]
	v_mfma_f32_16x16x32_bf16 v[90:93], v[54:57], v[228:231], v[90:93]
	v_mfma_f32_16x16x32_bf16 v[134:137], v[146:149], v[200:203], v[134:137]
	v_mfma_f32_16x16x32_bf16 v[130:133], v[184:187], v[200:203], v[130:133]
	v_mfma_f32_16x16x32_bf16 v[118:121], v[146:149], v[208:211], v[118:121]
	v_mfma_f32_16x16x32_bf16 v[114:117], v[184:187], v[208:211], v[114:117]
	v_mfma_f32_16x16x32_bf16 v[102:105], v[146:149], v[216:219], v[102:105]
	v_mfma_f32_16x16x32_bf16 v[98:101], v[184:187], v[216:219], v[98:101]
	v_mfma_f32_16x16x32_bf16 v[86:89], v[146:149], v[224:227], v[86:89]
	v_mfma_f32_16x16x32_bf16 v[82:85], v[184:187], v[224:227], v[82:85]
	v_mfma_f32_16x16x32_bf16 v[134:137], v[150:153], v[204:207], v[134:137]
	v_mfma_f32_16x16x32_bf16 v[130:133], v[188:191], v[204:207], v[130:133]
	v_mfma_f32_16x16x32_bf16 v[118:121], v[150:153], v[212:215], v[118:121]
	v_mfma_f32_16x16x32_bf16 v[114:117], v[188:191], v[212:215], v[114:117]
	v_mfma_f32_16x16x32_bf16 v[102:105], v[150:153], v[220:223], v[102:105]
	v_mfma_f32_16x16x32_bf16 v[98:101], v[188:191], v[220:223], v[98:101]
	v_mfma_f32_16x16x32_bf16 v[86:89], v[150:153], v[228:231], v[86:89]
	v_mfma_f32_16x16x32_bf16 v[82:85], v[188:191], v[228:231], v[82:85]
	s_setprio 0
	s_barrier
	s_add_i32 s20, s88, s61
	v_lshl_add_u64 v[192:193], s[12:13], 0, v[156:157]
	s_mov_b32 m0, s20
	ds_read_b128 v[200:203], v198 offset:16384
	ds_read_b128 v[204:207], v198 offset:17408
	ds_read_b128 v[208:211], v198 offset:18432
	ds_read_b128 v[212:215], v198 offset:19456
	ds_read_b128 v[216:219], v198 offset:20480
	ds_read_b128 v[220:223], v198 offset:21504
	ds_read_b128 v[224:227], v198 offset:22528
	ds_read_b128 v[228:231], v198 offset:23552
	global_load_lds_dwordx4 v[192:193], off
	s_add_i32 m0, s20, 0x2000
	v_lshl_add_u64 v[232:233], s[12:13], 0, v[160:161]
	s_add_u32 s12, s12, s16
	s_addc_u32 s13, s13, s17
	s_add_i32 s20, s89, s61
	global_load_lds_dwordx4 v[232:233], off
	v_lshl_add_u64 v[234:235], s[12:13], 0, v[156:157]
	s_mov_b32 m0, s20
	v_lshl_add_u64 v[236:237], s[12:13], 0, v[160:161]
	global_load_lds_dwordx4 v[234:235], off
	s_add_i32 m0, s20, 0x2000
	v_lshl_add_u64 v[238:239], s[6:7], 0, v[154:155]
	global_load_lds_dwordx4 v[236:237], off
	s_mov_b32 m0, s66
	v_lshl_add_u64 v[240:241], s[6:7], 0, v[158:159]
	global_load_lds_dwordx4 v[238:239], off
	s_mov_b32 m0, s68
	s_nop 0
	global_load_lds_dwordx4 v[240:241], off
	s_waitcnt vmcnt(8)
	s_waitcnt lgkmcnt(0)
	s_setprio 1
	v_mfma_f32_16x16x32_bf16 v[78:81], v[34:37], v[200:203], v[78:81]
	v_mfma_f32_16x16x32_bf16 v[74:77], v[50:53], v[200:203], v[74:77]
	s_barrier
	v_mfma_f32_16x16x32_bf16 v[62:65], v[34:37], v[208:211], v[62:65]
	v_mfma_f32_16x16x32_bf16 v[58:61], v[50:53], v[208:211], v[58:61]
	v_mfma_f32_16x16x32_bf16 v[30:33], v[34:37], v[216:219], v[30:33]
	v_mfma_f32_16x16x32_bf16 v[26:29], v[50:53], v[216:219], v[26:29]
	v_mfma_f32_16x16x32_bf16 v[14:17], v[34:37], v[224:227], v[14:17]
	v_mfma_f32_16x16x32_bf16 v[10:13], v[50:53], v[224:227], v[10:13]
	v_mfma_f32_16x16x32_bf16 v[78:81], v[38:41], v[204:207], v[78:81]
	v_mfma_f32_16x16x32_bf16 v[74:77], v[54:57], v[204:207], v[74:77]
	v_mfma_f32_16x16x32_bf16 v[62:65], v[38:41], v[212:215], v[62:65]
	v_mfma_f32_16x16x32_bf16 v[58:61], v[54:57], v[212:215], v[58:61]
	v_mfma_f32_16x16x32_bf16 v[30:33], v[38:41], v[220:223], v[30:33]
	v_mfma_f32_16x16x32_bf16 v[26:29], v[54:57], v[220:223], v[26:29]
	v_mfma_f32_16x16x32_bf16 v[14:17], v[38:41], v[228:231], v[14:17]
	v_mfma_f32_16x16x32_bf16 v[10:13], v[54:57], v[228:231], v[10:13]
	v_mfma_f32_16x16x32_bf16 v[46:49], v[146:149], v[208:211], v[46:49]
	v_mfma_f32_16x16x32_bf16 v[42:45], v[184:187], v[208:211], v[42:45]
	v_mfma_f32_16x16x32_bf16 v[22:25], v[146:149], v[216:219], v[22:25]
	v_mfma_f32_16x16x32_bf16 v[18:21], v[184:187], v[216:219], v[18:21]
	v_mfma_f32_16x16x32_bf16 v[6:9], v[146:149], v[224:227], v[6:9]
	v_mfma_f32_16x16x32_bf16 v[2:5], v[184:187], v[224:227], v[2:5]
	v_mfma_f32_16x16x32_bf16 v[34:37], v[146:149], v[200:203], v[70:73]
	v_mfma_f32_16x16x32_bf16 v[38:41], v[184:187], v[200:203], v[66:69]
	v_mfma_f32_16x16x32_bf16 v[46:49], v[150:153], v[212:215], v[46:49]
	v_mfma_f32_16x16x32_bf16 v[42:45], v[188:191], v[212:215], v[42:45]
	v_mfma_f32_16x16x32_bf16 v[22:25], v[150:153], v[220:223], v[22:25]
	v_mfma_f32_16x16x32_bf16 v[18:21], v[188:191], v[220:223], v[18:21]
	v_mfma_f32_16x16x32_bf16 v[6:9], v[150:153], v[228:231], v[6:9]
	v_mfma_f32_16x16x32_bf16 v[2:5], v[188:191], v[228:231], v[2:5]
	v_mfma_f32_16x16x32_bf16 v[34:37], v[150:153], v[204:207], v[34:37]
	v_mfma_f32_16x16x32_bf16 v[38:41], v[188:191], v[204:207], v[38:41]
	s_setprio 0
	s_barrier
	s_add_i32 s12, 0, 0x18000
	s_add_i32 s13, 0, 0x1c000
	v_add_u32_e32 v70, s12, v194
	v_add_u32_e32 v162, s13, v194
	ds_read_b128 v[50:53], v70
	ds_read_b128 v[54:57], v70 offset:1024
	ds_read_b128 v[66:69], v70 offset:2048
	ds_read_b128 v[70:73], v70 offset:3072
	ds_read_b128 v[146:149], v162
	ds_read_b128 v[150:153], v162 offset:1024
	ds_read_b128 v[184:187], v162 offset:2048
	ds_read_b128 v[188:191], v162 offset:3072
	s_add_u32 s6, s6, s16
	s_addc_u32 s7, s7, s17
	s_mov_b32 m0, s69
	v_lshl_add_u64 v[242:243], s[6:7], 0, v[154:155]
	ds_read_b128 v[200:203], v198 offset:32768
	ds_read_b128 v[204:207], v198 offset:33792
	ds_read_b128 v[208:211], v198 offset:34816
	ds_read_b128 v[212:215], v198 offset:35840
	ds_read_b128 v[216:219], v198 offset:36864
	ds_read_b128 v[220:223], v198 offset:37888
	ds_read_b128 v[224:227], v198 offset:38912
	ds_read_b128 v[228:231], v198 offset:39936
	global_load_lds_dwordx4 v[242:243], off
	v_lshl_add_u64 v[242:243], s[6:7], 0, v[158:159]
	s_mov_b32 m0, s70
	s_nop 0
	global_load_lds_dwordx4 v[242:243], off
	s_waitcnt vmcnt(8)
	s_waitcnt lgkmcnt(0)
	s_setprio 1
	v_mfma_f32_16x16x32_bf16 v[142:145], v[50:53], v[200:203], v[142:145]
	v_mfma_f32_16x16x32_bf16 v[138:141], v[66:69], v[200:203], v[138:141]
	s_barrier
	v_mfma_f32_16x16x32_bf16 v[126:129], v[50:53], v[208:211], v[126:129]
	v_mfma_f32_16x16x32_bf16 v[122:125], v[66:69], v[208:211], v[122:125]
	v_mfma_f32_16x16x32_bf16 v[110:113], v[50:53], v[216:219], v[110:113]
	v_mfma_f32_16x16x32_bf16 v[106:109], v[66:69], v[216:219], v[106:109]
	v_mfma_f32_16x16x32_bf16 v[94:97], v[50:53], v[224:227], v[94:97]
	v_mfma_f32_16x16x32_bf16 v[90:93], v[66:69], v[224:227], v[90:93]
	v_mfma_f32_16x16x32_bf16 v[142:145], v[54:57], v[204:207], v[142:145]
	v_mfma_f32_16x16x32_bf16 v[138:141], v[70:73], v[204:207], v[138:141]
	v_mfma_f32_16x16x32_bf16 v[126:129], v[54:57], v[212:215], v[126:129]
	v_mfma_f32_16x16x32_bf16 v[122:125], v[70:73], v[212:215], v[122:125]
	v_mfma_f32_16x16x32_bf16 v[110:113], v[54:57], v[220:223], v[110:113]
	v_mfma_f32_16x16x32_bf16 v[106:109], v[70:73], v[220:223], v[106:109]
	v_mfma_f32_16x16x32_bf16 v[94:97], v[54:57], v[228:231], v[94:97]
	v_mfma_f32_16x16x32_bf16 v[90:93], v[70:73], v[228:231], v[90:93]
	v_mfma_f32_16x16x32_bf16 v[134:137], v[146:149], v[200:203], v[134:137]
	v_mfma_f32_16x16x32_bf16 v[130:133], v[184:187], v[200:203], v[130:133]
	v_mfma_f32_16x16x32_bf16 v[118:121], v[146:149], v[208:211], v[118:121]
	v_mfma_f32_16x16x32_bf16 v[114:117], v[184:187], v[208:211], v[114:117]
	v_mfma_f32_16x16x32_bf16 v[102:105], v[146:149], v[216:219], v[102:105]
	v_mfma_f32_16x16x32_bf16 v[98:101], v[184:187], v[216:219], v[98:101]
	v_mfma_f32_16x16x32_bf16 v[86:89], v[146:149], v[224:227], v[86:89]
	v_mfma_f32_16x16x32_bf16 v[82:85], v[184:187], v[224:227], v[82:85]
	v_mfma_f32_16x16x32_bf16 v[134:137], v[150:153], v[204:207], v[134:137]
	v_mfma_f32_16x16x32_bf16 v[130:133], v[188:191], v[204:207], v[130:133]
	v_mfma_f32_16x16x32_bf16 v[118:121], v[150:153], v[212:215], v[118:121]
	v_mfma_f32_16x16x32_bf16 v[114:117], v[188:191], v[212:215], v[114:117]
	v_mfma_f32_16x16x32_bf16 v[102:105], v[150:153], v[220:223], v[102:105]
	v_mfma_f32_16x16x32_bf16 v[98:101], v[188:191], v[220:223], v[98:101]
	v_mfma_f32_16x16x32_bf16 v[86:89], v[150:153], v[228:231], v[86:89]
	v_mfma_f32_16x16x32_bf16 v[82:85], v[188:191], v[228:231], v[82:85]
	s_setprio 0
	s_barrier
	s_add_i32 s6, s12, s61
	v_lshl_add_u64 v[192:193], v[192:193], 0, s[38:39]
	s_mov_b32 m0, s6
	ds_read_b128 v[200:203], v198 offset:49152
	ds_read_b128 v[204:207], v198 offset:50176
	ds_read_b128 v[208:211], v198 offset:51200
	ds_read_b128 v[212:215], v198 offset:52224
	ds_read_b128 v[216:219], v198 offset:53248
	ds_read_b128 v[220:223], v198 offset:54272
	ds_read_b128 v[224:227], v198 offset:55296
	ds_read_b128 v[228:231], v198 offset:56320
	global_load_lds_dwordx4 v[192:193], off
	v_lshl_add_u64 v[192:193], v[232:233], 0, s[38:39]
	s_add_i32 m0, s6, 0x2000
	s_add_i32 s6, s13, s61
	global_load_lds_dwordx4 v[192:193], off
	v_lshl_add_u64 v[192:193], v[234:235], 0, s[38:39]
	s_mov_b32 m0, s6
	s_nop 0
	global_load_lds_dwordx4 v[192:193], off
	v_lshl_add_u64 v[192:193], v[236:237], 0, s[38:39]
	s_add_i32 m0, s6, 0x2000
	s_nop 0
	global_load_lds_dwordx4 v[192:193], off
	v_lshl_add_u64 v[192:193], v[238:239], 0, s[38:39]
	s_mov_b32 m0, s81
	s_nop 0
	global_load_lds_dwordx4 v[192:193], off
	v_lshl_add_u64 v[192:193], v[240:241], 0, s[38:39]
	s_mov_b32 m0, s82
	s_nop 0
	global_load_lds_dwordx4 v[192:193], off
	s_waitcnt vmcnt(8)
	s_waitcnt lgkmcnt(0)
	s_setprio 1
	v_mfma_f32_16x16x32_bf16 v[78:81], v[50:53], v[200:203], v[78:81]
	v_mfma_f32_16x16x32_bf16 v[74:77], v[66:69], v[200:203], v[74:77]
	s_barrier
	v_mfma_f32_16x16x32_bf16 v[62:65], v[50:53], v[208:211], v[62:65]
	v_mfma_f32_16x16x32_bf16 v[58:61], v[66:69], v[208:211], v[58:61]
	v_mfma_f32_16x16x32_bf16 v[30:33], v[50:53], v[216:219], v[30:33]
	v_mfma_f32_16x16x32_bf16 v[26:29], v[66:69], v[216:219], v[26:29]
	v_mfma_f32_16x16x32_bf16 v[14:17], v[50:53], v[224:227], v[14:17]
	v_mfma_f32_16x16x32_bf16 v[10:13], v[66:69], v[224:227], v[10:13]
	v_mfma_f32_16x16x32_bf16 v[78:81], v[54:57], v[204:207], v[78:81]
	v_mfma_f32_16x16x32_bf16 v[74:77], v[70:73], v[204:207], v[74:77]
	v_mfma_f32_16x16x32_bf16 v[62:65], v[54:57], v[212:215], v[62:65]
	v_mfma_f32_16x16x32_bf16 v[58:61], v[70:73], v[212:215], v[58:61]
	v_mfma_f32_16x16x32_bf16 v[30:33], v[54:57], v[220:223], v[30:33]
	v_mfma_f32_16x16x32_bf16 v[26:29], v[70:73], v[220:223], v[26:29]
	v_mfma_f32_16x16x32_bf16 v[14:17], v[54:57], v[228:231], v[14:17]
	v_mfma_f32_16x16x32_bf16 v[10:13], v[70:73], v[228:231], v[10:13]
	v_mfma_f32_16x16x32_bf16 v[34:37], v[146:149], v[200:203], v[34:37]
	v_mfma_f32_16x16x32_bf16 v[70:73], v[150:153], v[204:207], v[34:37]
	v_mfma_f32_16x16x32_bf16 v[34:37], v[184:187], v[200:203], v[38:41]
	v_mfma_f32_16x16x32_bf16 v[66:69], v[188:191], v[204:207], v[34:37]
	v_mfma_f32_16x16x32_bf16 v[34:37], v[146:149], v[208:211], v[46:49]
	v_mfma_f32_16x16x32_bf16 v[46:49], v[150:153], v[212:215], v[34:37]
	v_mfma_f32_16x16x32_bf16 v[34:37], v[184:187], v[208:211], v[42:45]
	v_mfma_f32_16x16x32_bf16 v[22:25], v[146:149], v[216:219], v[22:25]
	v_mfma_f32_16x16x32_bf16 v[18:21], v[184:187], v[216:219], v[18:21]
	v_mfma_f32_16x16x32_bf16 v[6:9], v[146:149], v[224:227], v[6:9]
	v_mfma_f32_16x16x32_bf16 v[2:5], v[184:187], v[224:227], v[2:5]
	v_mfma_f32_16x16x32_bf16 v[42:45], v[188:191], v[212:215], v[34:37]
	v_mfma_f32_16x16x32_bf16 v[22:25], v[150:153], v[220:223], v[22:25]
	v_mfma_f32_16x16x32_bf16 v[18:21], v[188:191], v[220:223], v[18:21]
	v_mfma_f32_16x16x32_bf16 v[6:9], v[150:153], v[228:231], v[6:9]
	v_mfma_f32_16x16x32_bf16 v[2:5], v[188:191], v[228:231], v[2:5]
	s_setprio 0
	s_barrier
	s_add_u32 s4, s4, 0x100
	s_addc_u32 s5, s5, 0
	s_add_u32 s8, s8, 0x100
	s_addc_u32 s9, s9, 0
	s_cmp_ge_i32 s11, s83
	s_mov_b32 s6, s11
	s_cbranch_scc0 .LBB0_3126

.LBB0_3613:
	v_add_u32_e32 v158, s64, v229
	v_add_u32_e32 v174, s65, v229
	ds_read_b128 v[146:149], v158
	ds_read_b128 v[150:153], v158 offset:1024
	ds_read_b128 v[154:157], v158 offset:2048
	ds_read_b128 v[158:161], v158 offset:3072
	ds_read_b128 v[162:165], v174
	ds_read_b128 v[166:169], v174 offset:1024
	ds_read_b128 v[170:173], v174 offset:2048
	ds_read_b128 v[174:177], v174 offset:3072
	s_add_i32 s80, s42, 2
	s_add_u32 s81, s40, 0x80
	s_addc_u32 s43, s41, 0
	s_cmp_eq_u32 s61, s42
	s_cselect_b32 s42, s4, s81
	s_cselect_b32 s43, s5, s43
	s_cselect_b32 s83, s39, s71
	s_cselect_b32 s82, s38, s70
	v_lshl_add_u64 v[210:211], s[40:41], 0, v[138:139]
	s_add_i32 m0, s51, 0xc000
	ds_read_b128 v[178:181], v231
	ds_read_b128 v[182:185], v231 offset:1024
	ds_read_b128 v[186:189], v231 offset:2048
	ds_read_b128 v[190:193], v231 offset:3072
	ds_read_b128 v[194:197], v231 offset:4096
	ds_read_b128 v[198:201], v231 offset:5120
	ds_read_b128 v[202:205], v231 offset:6144
	ds_read_b128 v[206:209], v231 offset:7168
	global_load_lds_dwordx4 v[210:211], off
	v_lshl_add_u64 v[210:211], s[40:41], 0, v[140:141]
	s_add_i32 m0, s51, 0xe000
	s_nop 0
	global_load_lds_dwordx4 v[210:211], off
	s_waitcnt vmcnt(8)
	s_waitcnt lgkmcnt(0)
	s_setprio 1
	v_mfma_i32_16x16x64_i8 v[126:129], v[146:149], v[178:181], v[126:129]
	v_mfma_i32_16x16x64_i8 v[122:125], v[154:157], v[178:181], v[122:125]
	s_barrier
	v_mfma_i32_16x16x64_i8 v[118:121], v[146:149], v[186:189], v[118:121]
	v_mfma_i32_16x16x64_i8 v[114:117], v[154:157], v[186:189], v[114:117]
	v_mfma_i32_16x16x64_i8 v[106:109], v[146:149], v[194:197], v[106:109]
	v_mfma_i32_16x16x64_i8 v[98:101], v[154:157], v[194:197], v[98:101]
	v_mfma_i32_16x16x64_i8 v[90:93], v[146:149], v[202:205], v[90:93]
	v_mfma_i32_16x16x64_i8 v[82:85], v[154:157], v[202:205], v[82:85]
	v_mfma_i32_16x16x64_i8 v[126:129], v[150:153], v[182:185], v[126:129]
	v_mfma_i32_16x16x64_i8 v[122:125], v[158:161], v[182:185], v[122:125]
	v_mfma_i32_16x16x64_i8 v[118:121], v[150:153], v[190:193], v[118:121]
	v_mfma_i32_16x16x64_i8 v[114:117], v[158:161], v[190:193], v[114:117]
	v_mfma_i32_16x16x64_i8 v[106:109], v[150:153], v[198:201], v[106:109]
	v_mfma_i32_16x16x64_i8 v[98:101], v[158:161], v[198:201], v[98:101]
	v_mfma_i32_16x16x64_i8 v[90:93], v[150:153], v[206:209], v[90:93]
	v_mfma_i32_16x16x64_i8 v[82:85], v[158:161], v[206:209], v[82:85]
	v_mfma_i32_16x16x64_i8 v[110:113], v[162:165], v[178:181], v[110:113]
	v_mfma_i32_16x16x64_i8 v[102:105], v[170:173], v[178:181], v[102:105]
	v_mfma_i32_16x16x64_i8 v[94:97], v[162:165], v[186:189], v[94:97]
	v_mfma_i32_16x16x64_i8 v[86:89], v[170:173], v[186:189], v[86:89]
	v_mfma_i32_16x16x64_i8 v[78:81], v[162:165], v[194:197], v[78:81]
	v_mfma_i32_16x16x64_i8 v[74:77], v[170:173], v[194:197], v[74:77]
	v_mfma_i32_16x16x64_i8 v[70:73], v[162:165], v[202:205], v[70:73]
	v_mfma_i32_16x16x64_i8 v[66:69], v[170:173], v[202:205], v[66:69]
	v_mfma_i32_16x16x64_i8 v[110:113], v[166:169], v[182:185], v[110:113]
	v_mfma_i32_16x16x64_i8 v[102:105], v[174:177], v[182:185], v[102:105]
	v_mfma_i32_16x16x64_i8 v[94:97], v[166:169], v[190:193], v[94:97]
	v_mfma_i32_16x16x64_i8 v[86:89], v[174:177], v[190:193], v[86:89]
	v_mfma_i32_16x16x64_i8 v[78:81], v[166:169], v[198:201], v[78:81]
	v_mfma_i32_16x16x64_i8 v[74:77], v[174:177], v[198:201], v[74:77]
	v_mfma_i32_16x16x64_i8 v[70:73], v[166:169], v[206:209], v[70:73]
	v_mfma_i32_16x16x64_i8 v[66:69], v[174:177], v[206:209], v[66:69]
	s_setprio 0
	s_barrier
	s_add_i32 s81, s64, s50
	v_lshl_add_u64 v[210:211], s[82:83], 0, v[132:133]
	s_mov_b32 m0, s81
	ds_read_b128 v[178:181], v231 offset:16384
	ds_read_b128 v[182:185], v231 offset:17408
	ds_read_b128 v[186:189], v231 offset:18432
	ds_read_b128 v[190:193], v231 offset:19456
	ds_read_b128 v[194:197], v231 offset:20480
	ds_read_b128 v[198:201], v231 offset:21504
	ds_read_b128 v[202:205], v231 offset:22528
	ds_read_b128 v[206:209], v231 offset:23552
	global_load_lds_dwordx4 v[210:211], off
	s_add_i32 m0, s81, 0x2000
	v_lshl_add_u64 v[212:213], s[82:83], 0, v[136:137]
	s_add_u32 s82, s82, s8
	s_addc_u32 s83, s83, s9
	s_add_i32 s81, s65, s50
	global_load_lds_dwordx4 v[212:213], off
	v_lshl_add_u64 v[214:215], s[82:83], 0, v[132:133]
	s_mov_b32 m0, s81
	v_lshl_add_u64 v[216:217], s[82:83], 0, v[136:137]
	global_load_lds_dwordx4 v[214:215], off
	s_add_i32 m0, s81, 0x2000
	v_lshl_add_u64 v[218:219], s[42:43], 0, v[130:131]
	global_load_lds_dwordx4 v[216:217], off
	s_mov_b32 m0, s51
	v_lshl_add_u64 v[220:221], s[42:43], 0, v[134:135]
	global_load_lds_dwordx4 v[218:219], off
	s_mov_b32 m0, s52
	s_nop 0
	global_load_lds_dwordx4 v[220:221], off
	s_waitcnt vmcnt(8)
	s_waitcnt lgkmcnt(0)
	s_setprio 1
	v_mfma_i32_16x16x64_i8 v[62:65], v[146:149], v[178:181], v[62:65]
	v_mfma_i32_16x16x64_i8 v[58:61], v[154:157], v[178:181], v[58:61]
	s_barrier
	v_mfma_i32_16x16x64_i8 v[54:57], v[146:149], v[186:189], v[54:57]
	v_mfma_i32_16x16x64_i8 v[50:53], v[154:157], v[186:189], v[50:53]
	v_mfma_i32_16x16x64_i8 v[42:45], v[146:149], v[194:197], v[42:45]
	v_mfma_i32_16x16x64_i8 v[34:37], v[154:157], v[194:197], v[34:37]
	v_mfma_i32_16x16x64_i8 v[26:29], v[146:149], v[202:205], v[26:29]
	v_mfma_i32_16x16x64_i8 v[18:21], v[154:157], v[202:205], v[18:21]
	v_mfma_i32_16x16x64_i8 v[62:65], v[150:153], v[182:185], v[62:65]
	v_mfma_i32_16x16x64_i8 v[58:61], v[158:161], v[182:185], v[58:61]
	v_mfma_i32_16x16x64_i8 v[54:57], v[150:153], v[190:193], v[54:57]
	v_mfma_i32_16x16x64_i8 v[50:53], v[158:161], v[190:193], v[50:53]
	v_mfma_i32_16x16x64_i8 v[42:45], v[150:153], v[198:201], v[42:45]
	v_mfma_i32_16x16x64_i8 v[34:37], v[158:161], v[198:201], v[34:37]
	v_mfma_i32_16x16x64_i8 v[26:29], v[150:153], v[206:209], v[26:29]
	v_mfma_i32_16x16x64_i8 v[18:21], v[158:161], v[206:209], v[18:21]
	v_mfma_i32_16x16x64_i8 v[46:49], v[162:165], v[178:181], v[46:49]
	v_mfma_i32_16x16x64_i8 v[38:41], v[170:173], v[178:181], v[38:41]
	v_mfma_i32_16x16x64_i8 v[30:33], v[162:165], v[186:189], v[30:33]
	v_mfma_i32_16x16x64_i8 v[22:25], v[170:173], v[186:189], v[22:25]
	v_mfma_i32_16x16x64_i8 v[14:17], v[162:165], v[194:197], v[14:17]
	v_mfma_i32_16x16x64_i8 v[10:13], v[170:173], v[194:197], v[10:13]
	v_mfma_i32_16x16x64_i8 v[6:9], v[162:165], v[202:205], v[6:9]
	v_mfma_i32_16x16x64_i8 v[2:5], v[170:173], v[202:205], v[2:5]
	v_mfma_i32_16x16x64_i8 v[46:49], v[166:169], v[182:185], v[46:49]
	v_mfma_i32_16x16x64_i8 v[38:41], v[174:177], v[182:185], v[38:41]
	v_mfma_i32_16x16x64_i8 v[30:33], v[166:169], v[190:193], v[30:33]
	v_mfma_i32_16x16x64_i8 v[22:25], v[174:177], v[190:193], v[22:25]
	v_mfma_i32_16x16x64_i8 v[14:17], v[166:169], v[198:201], v[14:17]
	v_mfma_i32_16x16x64_i8 v[10:13], v[174:177], v[198:201], v[10:13]
	v_mfma_i32_16x16x64_i8 v[6:9], v[166:169], v[206:209], v[6:9]
	v_mfma_i32_16x16x64_i8 v[2:5], v[174:177], v[206:209], v[2:5]
	s_setprio 0
	s_barrier
	s_add_i32 s81, 0, 0x18000
	s_add_i32 s82, 0, 0x1c000
	v_add_u32_e32 v158, s81, v229
	v_add_u32_e32 v174, s82, v229
	ds_read_b128 v[146:149], v158
	ds_read_b128 v[150:153], v158 offset:1024
	ds_read_b128 v[154:157], v158 offset:2048
	ds_read_b128 v[158:161], v158 offset:3072
	ds_read_b128 v[162:165], v174
	ds_read_b128 v[166:169], v174 offset:1024
	ds_read_b128 v[170:173], v174 offset:2048
	ds_read_b128 v[174:177], v174 offset:3072
	s_add_u32 s42, s42, s8
	s_addc_u32 s43, s43, s9
	s_mov_b32 m0, s53
	v_lshl_add_u64 v[222:223], s[42:43], 0, v[130:131]
	ds_read_b128 v[178:181], v231 offset:32768
	ds_read_b128 v[182:185], v231 offset:33792
	ds_read_b128 v[186:189], v231 offset:34816
	ds_read_b128 v[190:193], v231 offset:35840
	ds_read_b128 v[194:197], v231 offset:36864
	ds_read_b128 v[198:201], v231 offset:37888
	ds_read_b128 v[202:205], v231 offset:38912
	ds_read_b128 v[206:209], v231 offset:39936
	global_load_lds_dwordx4 v[222:223], off
	v_lshl_add_u64 v[222:223], s[42:43], 0, v[134:135]
	s_mov_b32 m0, s54
	s_nop 0
	global_load_lds_dwordx4 v[222:223], off
	s_waitcnt vmcnt(8)
	s_waitcnt lgkmcnt(0)
	s_setprio 1
	v_mfma_i32_16x16x64_i8 v[126:129], v[146:149], v[178:181], v[126:129]
	v_mfma_i32_16x16x64_i8 v[122:125], v[154:157], v[178:181], v[122:125]
	s_barrier
	v_mfma_i32_16x16x64_i8 v[118:121], v[146:149], v[186:189], v[118:121]
	v_mfma_i32_16x16x64_i8 v[114:117], v[154:157], v[186:189], v[114:117]
	v_mfma_i32_16x16x64_i8 v[106:109], v[146:149], v[194:197], v[106:109]
	v_mfma_i32_16x16x64_i8 v[98:101], v[154:157], v[194:197], v[98:101]
	v_mfma_i32_16x16x64_i8 v[90:93], v[146:149], v[202:205], v[90:93]
	v_mfma_i32_16x16x64_i8 v[82:85], v[154:157], v[202:205], v[82:85]
	v_mfma_i32_16x16x64_i8 v[126:129], v[150:153], v[182:185], v[126:129]
	v_mfma_i32_16x16x64_i8 v[122:125], v[158:161], v[182:185], v[122:125]
	v_mfma_i32_16x16x64_i8 v[118:121], v[150:153], v[190:193], v[118:121]
	v_mfma_i32_16x16x64_i8 v[114:117], v[158:161], v[190:193], v[114:117]
	v_mfma_i32_16x16x64_i8 v[106:109], v[150:153], v[198:201], v[106:109]
	v_mfma_i32_16x16x64_i8 v[98:101], v[158:161], v[198:201], v[98:101]
	v_mfma_i32_16x16x64_i8 v[90:93], v[150:153], v[206:209], v[90:93]
	v_mfma_i32_16x16x64_i8 v[82:85], v[158:161], v[206:209], v[82:85]
	v_mfma_i32_16x16x64_i8 v[110:113], v[162:165], v[178:181], v[110:113]
	v_mfma_i32_16x16x64_i8 v[102:105], v[170:173], v[178:181], v[102:105]
	v_mfma_i32_16x16x64_i8 v[94:97], v[162:165], v[186:189], v[94:97]
	v_mfma_i32_16x16x64_i8 v[86:89], v[170:173], v[186:189], v[86:89]
	v_mfma_i32_16x16x64_i8 v[78:81], v[162:165], v[194:197], v[78:81]
	v_mfma_i32_16x16x64_i8 v[74:77], v[170:173], v[194:197], v[74:77]
	v_mfma_i32_16x16x64_i8 v[70:73], v[162:165], v[202:205], v[70:73]
	v_mfma_i32_16x16x64_i8 v[66:69], v[170:173], v[202:205], v[66:69]
	v_mfma_i32_16x16x64_i8 v[110:113], v[166:169], v[182:185], v[110:113]
	v_mfma_i32_16x16x64_i8 v[102:105], v[174:177], v[182:185], v[102:105]
	v_mfma_i32_16x16x64_i8 v[94:97], v[166:169], v[190:193], v[94:97]
	v_mfma_i32_16x16x64_i8 v[86:89], v[174:177], v[190:193], v[86:89]
	v_mfma_i32_16x16x64_i8 v[78:81], v[166:169], v[198:201], v[78:81]
	v_mfma_i32_16x16x64_i8 v[74:77], v[174:177], v[198:201], v[74:77]
	v_mfma_i32_16x16x64_i8 v[70:73], v[166:169], v[206:209], v[70:73]
	v_mfma_i32_16x16x64_i8 v[66:69], v[174:177], v[206:209], v[66:69]
	s_setprio 0
	s_barrier
	s_add_i32 s42, s81, s50
	v_lshl_add_u64 v[210:211], v[210:211], 0, s[30:31]
	s_mov_b32 m0, s42
	ds_read_b128 v[178:181], v231 offset:49152
	ds_read_b128 v[182:185], v231 offset:50176
	ds_read_b128 v[186:189], v231 offset:51200
	ds_read_b128 v[190:193], v231 offset:52224
	ds_read_b128 v[194:197], v231 offset:53248
	ds_read_b128 v[198:201], v231 offset:54272
	ds_read_b128 v[202:205], v231 offset:55296
	ds_read_b128 v[206:209], v231 offset:56320
	global_load_lds_dwordx4 v[210:211], off
	v_lshl_add_u64 v[210:211], v[212:213], 0, s[30:31]
	s_add_i32 m0, s42, 0x2000
	s_add_i32 s42, s82, s50
	global_load_lds_dwordx4 v[210:211], off
	v_lshl_add_u64 v[210:211], v[214:215], 0, s[30:31]
	s_mov_b32 m0, s42
	s_nop 0
	global_load_lds_dwordx4 v[210:211], off
	v_lshl_add_u64 v[210:211], v[216:217], 0, s[30:31]
	s_add_i32 m0, s42, 0x2000
	s_nop 0
	global_load_lds_dwordx4 v[210:211], off
	v_lshl_add_u64 v[210:211], v[218:219], 0, s[30:31]
	s_mov_b32 m0, s57
	s_nop 0
	global_load_lds_dwordx4 v[210:211], off
	v_lshl_add_u64 v[210:211], v[220:221], 0, s[30:31]
	s_mov_b32 m0, s58
	s_nop 0
	global_load_lds_dwordx4 v[210:211], off
	s_waitcnt vmcnt(8)
	s_waitcnt lgkmcnt(0)
	s_setprio 1
	v_mfma_i32_16x16x64_i8 v[62:65], v[146:149], v[178:181], v[62:65]
	v_mfma_i32_16x16x64_i8 v[58:61], v[154:157], v[178:181], v[58:61]
	s_barrier
	v_mfma_i32_16x16x64_i8 v[54:57], v[146:149], v[186:189], v[54:57]
	v_mfma_i32_16x16x64_i8 v[50:53], v[154:157], v[186:189], v[50:53]
	v_mfma_i32_16x16x64_i8 v[42:45], v[146:149], v[194:197], v[42:45]
	v_mfma_i32_16x16x64_i8 v[34:37], v[154:157], v[194:197], v[34:37]
	v_mfma_i32_16x16x64_i8 v[26:29], v[146:149], v[202:205], v[26:29]
	v_mfma_i32_16x16x64_i8 v[18:21], v[154:157], v[202:205], v[18:21]
	v_mfma_i32_16x16x64_i8 v[62:65], v[150:153], v[182:185], v[62:65]
	v_mfma_i32_16x16x64_i8 v[58:61], v[158:161], v[182:185], v[58:61]
	v_mfma_i32_16x16x64_i8 v[54:57], v[150:153], v[190:193], v[54:57]
	v_mfma_i32_16x16x64_i8 v[50:53], v[158:161], v[190:193], v[50:53]
	v_mfma_i32_16x16x64_i8 v[42:45], v[150:153], v[198:201], v[42:45]
	v_mfma_i32_16x16x64_i8 v[34:37], v[158:161], v[198:201], v[34:37]
	v_mfma_i32_16x16x64_i8 v[26:29], v[150:153], v[206:209], v[26:29]
	v_mfma_i32_16x16x64_i8 v[18:21], v[158:161], v[206:209], v[18:21]
	v_mfma_i32_16x16x64_i8 v[46:49], v[162:165], v[178:181], v[46:49]
	v_mfma_i32_16x16x64_i8 v[38:41], v[170:173], v[178:181], v[38:41]
	v_mfma_i32_16x16x64_i8 v[30:33], v[162:165], v[186:189], v[30:33]
	v_mfma_i32_16x16x64_i8 v[22:25], v[170:173], v[186:189], v[22:25]
	v_mfma_i32_16x16x64_i8 v[14:17], v[162:165], v[194:197], v[14:17]
	v_mfma_i32_16x16x64_i8 v[10:13], v[170:173], v[194:197], v[10:13]
	v_mfma_i32_16x16x64_i8 v[6:9], v[162:165], v[202:205], v[6:9]
	v_mfma_i32_16x16x64_i8 v[2:5], v[170:173], v[202:205], v[2:5]
	v_mfma_i32_16x16x64_i8 v[46:49], v[166:169], v[182:185], v[46:49]
	v_mfma_i32_16x16x64_i8 v[38:41], v[174:177], v[182:185], v[38:41]
	v_mfma_i32_16x16x64_i8 v[30:33], v[166:169], v[190:193], v[30:33]
	v_mfma_i32_16x16x64_i8 v[22:25], v[174:177], v[190:193], v[22:25]
	v_mfma_i32_16x16x64_i8 v[14:17], v[166:169], v[198:201], v[14:17]
	v_mfma_i32_16x16x64_i8 v[10:13], v[174:177], v[198:201], v[10:13]
	v_mfma_i32_16x16x64_i8 v[6:9], v[166:169], v[206:209], v[6:9]
	v_mfma_i32_16x16x64_i8 v[2:5], v[174:177], v[206:209], v[2:5]
	s_setprio 0
	s_barrier
	s_add_u32 s40, s40, 0x100
	s_addc_u32 s41, s41, 0
	s_add_u32 s70, s70, 0x100
	s_addc_u32 s71, s71, 0
	s_cmp_ge_i32 s80, s60
	s_mov_b32 s42, s80
	s_cbranch_scc0 .LBB0_3613
	v_cvt_f32_i32_e32 v214, v126
	v_cvt_f32_i32_e32 v215, v127
	v_cvt_f32_i32_e32 v212, v128
	v_cvt_f32_i32_e32 v213, v129
	v_cvt_f32_i32_e32 v218, v122
	v_cvt_f32_i32_e32 v219, v123
	v_cvt_f32_i32_e32 v216, v124
	v_cvt_f32_i32_e32 v217, v125
	v_cvt_f32_i32_e32 v222, v110
	v_cvt_f32_i32_e32 v223, v111
	v_cvt_f32_i32_e32 v220, v112
	v_cvt_f32_i32_e32 v221, v113
	v_cvt_f32_i32_e32 v226, v102
	v_cvt_f32_i32_e32 v227, v103
	v_cvt_f32_i32_e32 v224, v104
	v_cvt_f32_i32_e32 v225, v105
	v_cvt_f32_i32_e32 v194, v118
	v_cvt_f32_i32_e32 v195, v119
	v_cvt_f32_i32_e32 v192, v120
	v_cvt_f32_i32_e32 v193, v121
	v_cvt_f32_i32_e32 v200, v114
	v_cvt_f32_i32_e32 v201, v115
	v_cvt_f32_i32_e32 v198, v116
	v_cvt_f32_i32_e32 v199, v117
	v_cvt_f32_i32_e32 v206, v94
	v_cvt_f32_i32_e32 v207, v95
	v_cvt_f32_i32_e32 v202, v96
	v_cvt_f32_i32_e32 v203, v97
	v_cvt_f32_i32_e32 v208, v86
	v_cvt_f32_i32_e32 v209, v87
	v_cvt_f32_i32_e32 v204, v88
	v_cvt_f32_i32_e32 v205, v89
	v_cvt_f32_i32_e32 v178, v106
	v_cvt_f32_i32_e32 v179, v107
	v_cvt_f32_i32_e32 v176, v108
	v_cvt_f32_i32_e32 v177, v109
	v_cvt_f32_i32_e32 v182, v98
	v_cvt_f32_i32_e32 v183, v99
	v_cvt_f32_i32_e32 v180, v100
	v_cvt_f32_i32_e32 v181, v101
	v_cvt_f32_i32_e32 v188, v78
	v_cvt_f32_i32_e32 v189, v79
	v_cvt_f32_i32_e32 v184, v80
	v_cvt_f32_i32_e32 v185, v81
	v_cvt_f32_i32_e32 v190, v74
	v_cvt_f32_i32_e32 v191, v75
	v_cvt_f32_i32_e32 v186, v76
	v_cvt_f32_i32_e32 v187, v77
	v_cvt_f32_i32_e32 v162, v90
	v_cvt_f32_i32_e32 v163, v91
	v_cvt_f32_i32_e32 v160, v92
	v_cvt_f32_i32_e32 v161, v93
	v_cvt_f32_i32_e32 v166, v82
	v_cvt_f32_i32_e32 v167, v83
	v_cvt_f32_i32_e32 v164, v84
	v_cvt_f32_i32_e32 v165, v85
	v_cvt_f32_i32_e32 v172, v70
	v_cvt_f32_i32_e32 v173, v71
	v_cvt_f32_i32_e32 v168, v72
	v_cvt_f32_i32_e32 v169, v73
	v_cvt_f32_i32_e32 v174, v66
	v_cvt_f32_i32_e32 v175, v67
	v_cvt_f32_i32_e32 v170, v68
	v_cvt_f32_i32_e32 v171, v69
	v_cvt_f32_i32_e32 v146, v62
	v_cvt_f32_i32_e32 v147, v63
	v_cvt_f32_i32_e32 v128, v64
	v_cvt_f32_i32_e32 v129, v65
	v_cvt_f32_i32_e32 v150, v58
	v_cvt_f32_i32_e32 v151, v59
	v_cvt_f32_i32_e32 v148, v60
	v_cvt_f32_i32_e32 v149, v61
	v_cvt_f32_i32_e32 v156, v46
	v_cvt_f32_i32_e32 v157, v47
	v_cvt_f32_i32_e32 v152, v48
	v_cvt_f32_i32_e32 v153, v49
	v_cvt_f32_i32_e32 v158, v38
	v_cvt_f32_i32_e32 v159, v39
	v_cvt_f32_i32_e32 v154, v40
	v_cvt_f32_i32_e32 v155, v41
	v_cvt_f32_i32_e32 v114, v54
	v_cvt_f32_i32_e32 v115, v55
	v_cvt_f32_i32_e32 v112, v56
	v_cvt_f32_i32_e32 v113, v57
	v_cvt_f32_i32_e32 v118, v50
	v_cvt_f32_i32_e32 v119, v51
	v_cvt_f32_i32_e32 v116, v52
	v_cvt_f32_i32_e32 v117, v53
	v_cvt_f32_i32_e32 v124, v30
	v_cvt_f32_i32_e32 v125, v31
	v_cvt_f32_i32_e32 v120, v32
	v_cvt_f32_i32_e32 v121, v33
	v_cvt_f32_i32_e32 v126, v22
	v_cvt_f32_i32_e32 v127, v23
	v_cvt_f32_i32_e32 v122, v24
	v_cvt_f32_i32_e32 v123, v25
	v_cvt_f32_i32_e32 v64, v42
	v_cvt_f32_i32_e32 v65, v43
	v_cvt_f32_i32_e32 v62, v44
	v_cvt_f32_i32_e32 v63, v45
	v_cvt_f32_i32_e32 v68, v34
	v_cvt_f32_i32_e32 v69, v35
	v_cvt_f32_i32_e32 v66, v36
	v_cvt_f32_i32_e32 v67, v37
	v_cvt_f32_i32_e32 v74, v14
	v_cvt_f32_i32_e32 v75, v15
	v_cvt_f32_i32_e32 v70, v16
	v_cvt_f32_i32_e32 v71, v17
	v_cvt_f32_i32_e32 v76, v10
	v_cvt_f32_i32_e32 v77, v11
	v_cvt_f32_i32_e32 v72, v12
	v_cvt_f32_i32_e32 v73, v13
	v_cvt_f32_i32_e32 v48, v26
	v_cvt_f32_i32_e32 v49, v27
	v_cvt_f32_i32_e32 v46, v28
	v_cvt_f32_i32_e32 v47, v29
	v_cvt_f32_i32_e32 v52, v18
	v_cvt_f32_i32_e32 v53, v19
	v_cvt_f32_i32_e32 v50, v20
	v_cvt_f32_i32_e32 v51, v21
	v_cvt_f32_i32_e32 v58, v6
	v_cvt_f32_i32_e32 v59, v7
	v_cvt_f32_i32_e32 v54, v8
	v_cvt_f32_i32_e32 v55, v9
	v_cvt_f32_i32_e32 v60, v2
	v_cvt_f32_i32_e32 v61, v3
	v_cvt_f32_i32_e32 v56, v4
	v_cvt_f32_i32_e32 v57, v5

.LBB0_3798:
	v_add_u32_e32 v138, s56, v188
	ds_read_b128 v[148:151], v138
	ds_read_b128 v[152:155], v138 offset:1024
	ds_read_b128 v[156:159], v138 offset:2048
	ds_read_b128 v[160:163], v138 offset:3072
	v_add_u32_e32 v138, s57, v188
	ds_read_b128 v[164:167], v138
	ds_read_b128 v[168:171], v138 offset:1024
	ds_read_b128 v[172:175], v138 offset:2048
	ds_read_b128 v[176:179], v138 offset:3072
	s_add_i32 s60, s28, 2
	s_add_u32 s61, s26, 0x80
	s_addc_u32 s29, s27, 0
	s_cmp_eq_u32 s54, s28
	s_cselect_b32 s28, s2, s61
	s_cselect_b32 s29, s3, s29
	s_cselect_b32 s63, s25, s35
	s_cselect_b32 s62, s24, s34
	v_lshl_add_u64 v[184:185], s[26:27], 0, v[140:141]
	s_add_i32 m0, s42, 0xc000
	ds_read_b128 v[180:183], v189
	ds_read_b128 v[190:193], v189 offset:1024
	ds_read_b128 v[194:197], v189 offset:2048
	ds_read_b128 v[198:201], v189 offset:3072
	ds_read_b128 v[202:205], v189 offset:4096
	ds_read_b128 v[206:209], v189 offset:5120
	ds_read_b128 v[210:213], v189 offset:6144
	ds_read_b128 v[214:217], v189 offset:7168
	global_load_lds_dwordx4 v[184:185], off
	v_lshl_add_u64 v[184:185], s[26:27], 0, v[142:143]
	s_add_i32 m0, s42, 0xe000
	s_nop 0
	global_load_lds_dwordx4 v[184:185], off
	s_waitcnt vmcnt(8)
	s_waitcnt lgkmcnt(0)
	s_setprio 1
	v_mfma_i32_16x16x64_i8 v[126:129], v[148:151], v[180:183], v[126:129]
	v_mfma_i32_16x16x64_i8 v[122:125], v[156:159], v[180:183], v[122:125]
	s_barrier
	v_mfma_i32_16x16x64_i8 v[118:121], v[148:151], v[194:197], v[118:121]
	v_mfma_i32_16x16x64_i8 v[114:117], v[156:159], v[194:197], v[114:117]
	v_mfma_i32_16x16x64_i8 v[106:109], v[148:151], v[202:205], v[106:109]
	v_mfma_i32_16x16x64_i8 v[98:101], v[156:159], v[202:205], v[98:101]
	v_mfma_i32_16x16x64_i8 v[90:93], v[148:151], v[210:213], v[90:93]
	v_mfma_i32_16x16x64_i8 v[82:85], v[156:159], v[210:213], v[82:85]
	v_mfma_i32_16x16x64_i8 v[126:129], v[152:155], v[190:193], v[126:129]
	v_mfma_i32_16x16x64_i8 v[122:125], v[160:163], v[190:193], v[122:125]
	v_mfma_i32_16x16x64_i8 v[118:121], v[152:155], v[198:201], v[118:121]
	v_mfma_i32_16x16x64_i8 v[114:117], v[160:163], v[198:201], v[114:117]
	v_mfma_i32_16x16x64_i8 v[106:109], v[152:155], v[206:209], v[106:109]
	v_mfma_i32_16x16x64_i8 v[98:101], v[160:163], v[206:209], v[98:101]
	v_mfma_i32_16x16x64_i8 v[90:93], v[152:155], v[214:217], v[90:93]
	v_mfma_i32_16x16x64_i8 v[82:85], v[160:163], v[214:217], v[82:85]
	v_mfma_i32_16x16x64_i8 v[110:113], v[164:167], v[180:183], v[110:113]
	v_mfma_i32_16x16x64_i8 v[102:105], v[172:175], v[180:183], v[102:105]
	v_mfma_i32_16x16x64_i8 v[94:97], v[164:167], v[194:197], v[94:97]
	v_mfma_i32_16x16x64_i8 v[86:89], v[172:175], v[194:197], v[86:89]
	v_mfma_i32_16x16x64_i8 v[78:81], v[164:167], v[202:205], v[78:81]
	v_mfma_i32_16x16x64_i8 v[74:77], v[172:175], v[202:205], v[74:77]
	v_mfma_i32_16x16x64_i8 v[70:73], v[164:167], v[210:213], v[70:73]
	v_mfma_i32_16x16x64_i8 v[66:69], v[172:175], v[210:213], v[66:69]
	v_mfma_i32_16x16x64_i8 v[110:113], v[168:171], v[190:193], v[110:113]
	v_mfma_i32_16x16x64_i8 v[102:105], v[176:179], v[190:193], v[102:105]
	v_mfma_i32_16x16x64_i8 v[94:97], v[168:171], v[198:201], v[94:97]
	v_mfma_i32_16x16x64_i8 v[86:89], v[176:179], v[198:201], v[86:89]
	v_mfma_i32_16x16x64_i8 v[78:81], v[168:171], v[206:209], v[78:81]
	v_mfma_i32_16x16x64_i8 v[74:77], v[176:179], v[206:209], v[74:77]
	v_mfma_i32_16x16x64_i8 v[70:73], v[168:171], v[214:217], v[70:73]
	v_mfma_i32_16x16x64_i8 v[66:69], v[176:179], v[214:217], v[66:69]
	s_setprio 0
	s_barrier
	s_add_i32 s61, s56, s41
	v_lshl_add_u64 v[184:185], s[62:63], 0, v[132:133]
	s_mov_b32 m0, s61
	ds_read_b128 v[180:183], v189 offset:16384
	ds_read_b128 v[190:193], v189 offset:17408
	ds_read_b128 v[194:197], v189 offset:18432
	ds_read_b128 v[198:201], v189 offset:19456
	ds_read_b128 v[202:205], v189 offset:20480
	ds_read_b128 v[206:209], v189 offset:21504
	ds_read_b128 v[210:213], v189 offset:22528
	ds_read_b128 v[214:217], v189 offset:23552
	global_load_lds_dwordx4 v[184:185], off
	s_add_i32 m0, s61, 0x2000
	v_lshl_add_u64 v[218:219], s[62:63], 0, v[136:137]
	s_add_u32 s62, s62, s6
	s_addc_u32 s63, s63, s7
	s_add_i32 s61, s57, s41
	global_load_lds_dwordx4 v[218:219], off
	v_lshl_add_u64 v[220:221], s[62:63], 0, v[132:133]
	s_mov_b32 m0, s61
	v_lshl_add_u64 v[222:223], s[62:63], 0, v[136:137]
	global_load_lds_dwordx4 v[220:221], off
	s_add_i32 m0, s61, 0x2000
	v_lshl_add_u64 v[224:225], s[28:29], 0, v[130:131]
	global_load_lds_dwordx4 v[222:223], off
	s_mov_b32 m0, s42
	v_lshl_add_u64 v[226:227], s[28:29], 0, v[134:135]
	global_load_lds_dwordx4 v[224:225], off
	s_mov_b32 m0, s43
	s_nop 0
	global_load_lds_dwordx4 v[226:227], off
	s_waitcnt vmcnt(8)
	s_waitcnt lgkmcnt(0)
	s_setprio 1
	v_mfma_i32_16x16x64_i8 v[62:65], v[148:151], v[180:183], v[62:65]
	v_mfma_i32_16x16x64_i8 v[58:61], v[156:159], v[180:183], v[58:61]
	s_barrier
	v_mfma_i32_16x16x64_i8 v[54:57], v[148:151], v[194:197], v[54:57]
	v_mfma_i32_16x16x64_i8 v[50:53], v[156:159], v[194:197], v[50:53]
	v_mfma_i32_16x16x64_i8 v[42:45], v[148:151], v[202:205], v[42:45]
	v_mfma_i32_16x16x64_i8 v[34:37], v[156:159], v[202:205], v[34:37]
	v_mfma_i32_16x16x64_i8 v[26:29], v[148:151], v[210:213], v[26:29]
	v_mfma_i32_16x16x64_i8 v[18:21], v[156:159], v[210:213], v[18:21]
	v_mfma_i32_16x16x64_i8 v[62:65], v[152:155], v[190:193], v[62:65]
	v_mfma_i32_16x16x64_i8 v[58:61], v[160:163], v[190:193], v[58:61]
	v_mfma_i32_16x16x64_i8 v[54:57], v[152:155], v[198:201], v[54:57]
	v_mfma_i32_16x16x64_i8 v[50:53], v[160:163], v[198:201], v[50:53]
	v_mfma_i32_16x16x64_i8 v[42:45], v[152:155], v[206:209], v[42:45]
	v_mfma_i32_16x16x64_i8 v[34:37], v[160:163], v[206:209], v[34:37]
	v_mfma_i32_16x16x64_i8 v[26:29], v[152:155], v[214:217], v[26:29]
	v_mfma_i32_16x16x64_i8 v[18:21], v[160:163], v[214:217], v[18:21]
	v_mfma_i32_16x16x64_i8 v[46:49], v[164:167], v[180:183], v[46:49]
	v_mfma_i32_16x16x64_i8 v[38:41], v[172:175], v[180:183], v[38:41]
	v_mfma_i32_16x16x64_i8 v[30:33], v[164:167], v[194:197], v[30:33]
	v_mfma_i32_16x16x64_i8 v[22:25], v[172:175], v[194:197], v[22:25]
	v_mfma_i32_16x16x64_i8 v[14:17], v[164:167], v[202:205], v[14:17]
	v_mfma_i32_16x16x64_i8 v[10:13], v[172:175], v[202:205], v[10:13]
	v_mfma_i32_16x16x64_i8 v[6:9], v[164:167], v[210:213], v[6:9]
	v_mfma_i32_16x16x64_i8 v[2:5], v[172:175], v[210:213], v[2:5]
	v_mfma_i32_16x16x64_i8 v[46:49], v[168:171], v[190:193], v[46:49]
	v_mfma_i32_16x16x64_i8 v[38:41], v[176:179], v[190:193], v[38:41]
	v_mfma_i32_16x16x64_i8 v[30:33], v[168:171], v[198:201], v[30:33]
	v_mfma_i32_16x16x64_i8 v[22:25], v[176:179], v[198:201], v[22:25]
	v_mfma_i32_16x16x64_i8 v[14:17], v[168:171], v[206:209], v[14:17]
	v_mfma_i32_16x16x64_i8 v[10:13], v[176:179], v[206:209], v[10:13]
	v_mfma_i32_16x16x64_i8 v[6:9], v[168:171], v[214:217], v[6:9]
	v_mfma_i32_16x16x64_i8 v[2:5], v[176:179], v[214:217], v[2:5]
	s_setprio 0
	s_barrier
	s_add_i32 s61, 0, 0x18000
	v_add_u32_e32 v138, s61, v188
	s_add_i32 s62, 0, 0x1c000
	ds_read_b128 v[148:151], v138
	ds_read_b128 v[152:155], v138 offset:1024
	ds_read_b128 v[156:159], v138 offset:2048
	ds_read_b128 v[160:163], v138 offset:3072
	v_add_u32_e32 v138, s62, v188
	ds_read_b128 v[164:167], v138
	ds_read_b128 v[168:171], v138 offset:1024
	ds_read_b128 v[172:175], v138 offset:2048
	ds_read_b128 v[176:179], v138 offset:3072
	s_add_u32 s28, s28, s6
	s_addc_u32 s29, s29, s7
	s_mov_b32 m0, s44
	v_lshl_add_u64 v[228:229], s[28:29], 0, v[130:131]
	ds_read_b128 v[180:183], v189 offset:32768
	ds_read_b128 v[190:193], v189 offset:33792
	ds_read_b128 v[194:197], v189 offset:34816
	ds_read_b128 v[198:201], v189 offset:35840
	ds_read_b128 v[202:205], v189 offset:36864
	ds_read_b128 v[206:209], v189 offset:37888
	ds_read_b128 v[210:213], v189 offset:38912
	ds_read_b128 v[214:217], v189 offset:39936
	global_load_lds_dwordx4 v[228:229], off
	v_lshl_add_u64 v[228:229], s[28:29], 0, v[134:135]
	s_mov_b32 m0, s45
	s_nop 0
	global_load_lds_dwordx4 v[228:229], off
	s_waitcnt vmcnt(8)
	s_waitcnt lgkmcnt(0)
	s_setprio 1
	v_mfma_i32_16x16x64_i8 v[126:129], v[148:151], v[180:183], v[126:129]
	v_mfma_i32_16x16x64_i8 v[122:125], v[156:159], v[180:183], v[122:125]
	s_barrier
	v_mfma_i32_16x16x64_i8 v[118:121], v[148:151], v[194:197], v[118:121]
	v_mfma_i32_16x16x64_i8 v[114:117], v[156:159], v[194:197], v[114:117]
	v_mfma_i32_16x16x64_i8 v[106:109], v[148:151], v[202:205], v[106:109]
	v_mfma_i32_16x16x64_i8 v[98:101], v[156:159], v[202:205], v[98:101]
	v_mfma_i32_16x16x64_i8 v[90:93], v[148:151], v[210:213], v[90:93]
	v_mfma_i32_16x16x64_i8 v[82:85], v[156:159], v[210:213], v[82:85]
	v_mfma_i32_16x16x64_i8 v[126:129], v[152:155], v[190:193], v[126:129]
	v_mfma_i32_16x16x64_i8 v[122:125], v[160:163], v[190:193], v[122:125]
	v_mfma_i32_16x16x64_i8 v[118:121], v[152:155], v[198:201], v[118:121]
	v_mfma_i32_16x16x64_i8 v[114:117], v[160:163], v[198:201], v[114:117]
	v_mfma_i32_16x16x64_i8 v[106:109], v[152:155], v[206:209], v[106:109]
	v_mfma_i32_16x16x64_i8 v[98:101], v[160:163], v[206:209], v[98:101]
	v_mfma_i32_16x16x64_i8 v[90:93], v[152:155], v[214:217], v[90:93]
	v_mfma_i32_16x16x64_i8 v[82:85], v[160:163], v[214:217], v[82:85]
	v_mfma_i32_16x16x64_i8 v[110:113], v[164:167], v[180:183], v[110:113]
	v_mfma_i32_16x16x64_i8 v[102:105], v[172:175], v[180:183], v[102:105]
	v_mfma_i32_16x16x64_i8 v[94:97], v[164:167], v[194:197], v[94:97]
	v_mfma_i32_16x16x64_i8 v[86:89], v[172:175], v[194:197], v[86:89]
	v_mfma_i32_16x16x64_i8 v[78:81], v[164:167], v[202:205], v[78:81]
	v_mfma_i32_16x16x64_i8 v[74:77], v[172:175], v[202:205], v[74:77]
	v_mfma_i32_16x16x64_i8 v[70:73], v[164:167], v[210:213], v[70:73]
	v_mfma_i32_16x16x64_i8 v[66:69], v[172:175], v[210:213], v[66:69]
	v_mfma_i32_16x16x64_i8 v[110:113], v[168:171], v[190:193], v[110:113]
	v_mfma_i32_16x16x64_i8 v[102:105], v[176:179], v[190:193], v[102:105]
	v_mfma_i32_16x16x64_i8 v[94:97], v[168:171], v[198:201], v[94:97]
	v_mfma_i32_16x16x64_i8 v[86:89], v[176:179], v[198:201], v[86:89]
	v_mfma_i32_16x16x64_i8 v[78:81], v[168:171], v[206:209], v[78:81]
	v_mfma_i32_16x16x64_i8 v[74:77], v[176:179], v[206:209], v[74:77]
	v_mfma_i32_16x16x64_i8 v[70:73], v[168:171], v[214:217], v[70:73]
	v_mfma_i32_16x16x64_i8 v[66:69], v[176:179], v[214:217], v[66:69]
	s_setprio 0
	s_barrier
	s_add_i32 s28, s61, s41
	v_lshl_add_u64 v[184:185], v[184:185], 0, s[18:19]
	s_mov_b32 m0, s28
	ds_read_b128 v[180:183], v189 offset:49152
	ds_read_b128 v[190:193], v189 offset:50176
	ds_read_b128 v[194:197], v189 offset:51200
	ds_read_b128 v[198:201], v189 offset:52224
	ds_read_b128 v[202:205], v189 offset:53248
	ds_read_b128 v[206:209], v189 offset:54272
	ds_read_b128 v[210:213], v189 offset:55296
	ds_read_b128 v[214:217], v189 offset:56320
	global_load_lds_dwordx4 v[184:185], off
	v_lshl_add_u64 v[184:185], v[218:219], 0, s[18:19]
	s_add_i32 m0, s28, 0x2000
	s_add_i32 s28, s62, s41
	global_load_lds_dwordx4 v[184:185], off
	v_lshl_add_u64 v[184:185], v[220:221], 0, s[18:19]
	s_mov_b32 m0, s28
	s_nop 0
	global_load_lds_dwordx4 v[184:185], off
	v_lshl_add_u64 v[184:185], v[222:223], 0, s[18:19]
	s_add_i32 m0, s28, 0x2000
	s_nop 0
	global_load_lds_dwordx4 v[184:185], off
	v_lshl_add_u64 v[184:185], v[224:225], 0, s[18:19]
	s_mov_b32 m0, s49
	s_nop 0
	global_load_lds_dwordx4 v[184:185], off
	v_lshl_add_u64 v[184:185], v[226:227], 0, s[18:19]
	s_mov_b32 m0, s50
	s_nop 0
	global_load_lds_dwordx4 v[184:185], off
	s_waitcnt vmcnt(8)
	s_waitcnt lgkmcnt(0)
	s_setprio 1
	v_mfma_i32_16x16x64_i8 v[62:65], v[148:151], v[180:183], v[62:65]
	v_mfma_i32_16x16x64_i8 v[58:61], v[156:159], v[180:183], v[58:61]
	s_barrier
	v_mfma_i32_16x16x64_i8 v[54:57], v[148:151], v[194:197], v[54:57]
	v_mfma_i32_16x16x64_i8 v[50:53], v[156:159], v[194:197], v[50:53]
	v_mfma_i32_16x16x64_i8 v[42:45], v[148:151], v[202:205], v[42:45]
	v_mfma_i32_16x16x64_i8 v[34:37], v[156:159], v[202:205], v[34:37]
	v_mfma_i32_16x16x64_i8 v[26:29], v[148:151], v[210:213], v[26:29]
	v_mfma_i32_16x16x64_i8 v[18:21], v[156:159], v[210:213], v[18:21]
	v_mfma_i32_16x16x64_i8 v[62:65], v[152:155], v[190:193], v[62:65]
	v_mfma_i32_16x16x64_i8 v[58:61], v[160:163], v[190:193], v[58:61]
	v_mfma_i32_16x16x64_i8 v[54:57], v[152:155], v[198:201], v[54:57]
	v_mfma_i32_16x16x64_i8 v[50:53], v[160:163], v[198:201], v[50:53]
	v_mfma_i32_16x16x64_i8 v[42:45], v[152:155], v[206:209], v[42:45]
	v_mfma_i32_16x16x64_i8 v[34:37], v[160:163], v[206:209], v[34:37]
	v_mfma_i32_16x16x64_i8 v[26:29], v[152:155], v[214:217], v[26:29]
	v_mfma_i32_16x16x64_i8 v[18:21], v[160:163], v[214:217], v[18:21]
	v_mfma_i32_16x16x64_i8 v[46:49], v[164:167], v[180:183], v[46:49]
	v_mfma_i32_16x16x64_i8 v[38:41], v[172:175], v[180:183], v[38:41]
	v_mfma_i32_16x16x64_i8 v[30:33], v[164:167], v[194:197], v[30:33]
	v_mfma_i32_16x16x64_i8 v[22:25], v[172:175], v[194:197], v[22:25]
	v_mfma_i32_16x16x64_i8 v[14:17], v[164:167], v[202:205], v[14:17]
	v_mfma_i32_16x16x64_i8 v[10:13], v[172:175], v[202:205], v[10:13]
	v_mfma_i32_16x16x64_i8 v[6:9], v[164:167], v[210:213], v[6:9]
	v_mfma_i32_16x16x64_i8 v[2:5], v[172:175], v[210:213], v[2:5]
	v_mfma_i32_16x16x64_i8 v[46:49], v[168:171], v[190:193], v[46:49]
	v_mfma_i32_16x16x64_i8 v[38:41], v[176:179], v[190:193], v[38:41]
	v_mfma_i32_16x16x64_i8 v[30:33], v[168:171], v[198:201], v[30:33]
	v_mfma_i32_16x16x64_i8 v[22:25], v[176:179], v[198:201], v[22:25]
	v_mfma_i32_16x16x64_i8 v[14:17], v[168:171], v[206:209], v[14:17]
	v_mfma_i32_16x16x64_i8 v[10:13], v[176:179], v[206:209], v[10:13]
	v_mfma_i32_16x16x64_i8 v[6:9], v[168:171], v[214:217], v[6:9]
	v_mfma_i32_16x16x64_i8 v[2:5], v[176:179], v[214:217], v[2:5]
	s_setprio 0
	s_barrier
	s_add_u32 s26, s26, 0x100
	s_addc_u32 s27, s27, 0
	s_add_u32 s34, s34, 0x100
	s_addc_u32 s35, s35, 0
	s_cmp_ge_i32 s60, s51
	s_mov_b32 s28, s60
	s_cbranch_scc0 .LBB0_3798
	v_cvt_f32_i32_e32 v172, v126
	v_cvt_f32_i32_e32 v173, v127
	v_cvt_f32_i32_e32 v170, v128
	v_cvt_f32_i32_e32 v171, v129
	v_cvt_f32_i32_e32 v174, v122
	v_cvt_f32_i32_e32 v175, v123
	v_cvt_f32_i32_e32 v176, v124
	v_cvt_f32_i32_e32 v177, v125
	v_cvt_f32_i32_e32 v180, v110
	v_cvt_f32_i32_e32 v181, v111
	v_cvt_f32_i32_e32 v182, v112
	v_cvt_f32_i32_e32 v183, v113
	v_cvt_f32_i32_e32 v178, v102
	v_cvt_f32_i32_e32 v179, v103
	v_cvt_f32_i32_e32 v184, v104
	v_cvt_f32_i32_e32 v185, v105
	v_cvt_f32_i32_e32 v152, v118
	v_cvt_f32_i32_e32 v153, v119
	v_cvt_f32_i32_e32 v154, v120
	v_cvt_f32_i32_e32 v155, v121
	v_cvt_f32_i32_e32 v156, v114
	v_cvt_f32_i32_e32 v157, v115
	v_cvt_f32_i32_e32 v158, v116
	v_cvt_f32_i32_e32 v159, v117
	v_cvt_f32_i32_e32 v160, v94
	v_cvt_f32_i32_e32 v161, v95
	v_cvt_f32_i32_e32 v162, v96
	v_cvt_f32_i32_e32 v163, v97
	v_cvt_f32_i32_e32 v164, v86
	v_cvt_f32_i32_e32 v165, v87
	v_cvt_f32_i32_e32 v166, v88
	v_cvt_f32_i32_e32 v167, v89
	v_cvt_f32_i32_e32 v118, v106
	v_cvt_f32_i32_e32 v119, v107
	v_cvt_f32_i32_e32 v120, v108
	v_cvt_f32_i32_e32 v121, v109
	v_cvt_f32_i32_e32 v122, v98
	v_cvt_f32_i32_e32 v123, v99
	v_cvt_f32_i32_e32 v124, v100
	v_cvt_f32_i32_e32 v125, v101
	v_cvt_f32_i32_e32 v126, v78
	v_cvt_f32_i32_e32 v127, v79
	v_cvt_f32_i32_e32 v128, v80
	v_cvt_f32_i32_e32 v129, v81
	v_cvt_f32_i32_e32 v148, v74
	v_cvt_f32_i32_e32 v149, v75
	v_cvt_f32_i32_e32 v150, v76
	v_cvt_f32_i32_e32 v151, v77
	v_cvt_f32_i32_e32 v102, v90
	v_cvt_f32_i32_e32 v103, v91
	v_cvt_f32_i32_e32 v104, v92
	v_cvt_f32_i32_e32 v105, v93
	v_cvt_f32_i32_e32 v106, v82
	v_cvt_f32_i32_e32 v107, v83
	v_cvt_f32_i32_e32 v108, v84
	v_cvt_f32_i32_e32 v109, v85
	v_cvt_f32_i32_e32 v110, v70
	v_cvt_f32_i32_e32 v111, v71
	v_cvt_f32_i32_e32 v112, v72
	v_cvt_f32_i32_e32 v113, v73
	v_cvt_f32_i32_e32 v114, v66
	v_cvt_f32_i32_e32 v115, v67
	v_cvt_f32_i32_e32 v116, v68
	v_cvt_f32_i32_e32 v117, v69
	v_cvt_f32_i32_e32 v82, v62
	v_cvt_f32_i32_e32 v83, v63
	v_cvt_f32_i32_e32 v84, v64
	v_cvt_f32_i32_e32 v85, v65
	v_cvt_f32_i32_e32 v86, v58
	v_cvt_f32_i32_e32 v87, v59
	v_cvt_f32_i32_e32 v88, v60
	v_cvt_f32_i32_e32 v89, v61
	v_cvt_f32_i32_e32 v92, v46
	v_cvt_f32_i32_e32 v93, v47
	v_cvt_f32_i32_e32 v94, v48
	v_cvt_f32_i32_e32 v95, v49
	v_cvt_f32_i32_e32 v96, v38
	v_cvt_f32_i32_e32 v97, v39
	v_cvt_f32_i32_e32 v98, v40
	v_cvt_f32_i32_e32 v99, v41
	v_cvt_f32_i32_e32 v66, v54
	v_cvt_f32_i32_e32 v67, v55
	v_cvt_f32_i32_e32 v68, v56
	v_cvt_f32_i32_e32 v69, v57
	v_cvt_f32_i32_e32 v70, v50
	v_cvt_f32_i32_e32 v71, v51
	v_cvt_f32_i32_e32 v72, v52
	v_cvt_f32_i32_e32 v73, v53
	v_cvt_f32_i32_e32 v74, v30
	v_cvt_f32_i32_e32 v75, v31
	v_cvt_f32_i32_e32 v76, v32
	v_cvt_f32_i32_e32 v77, v33
	v_cvt_f32_i32_e32 v78, v22
	v_cvt_f32_i32_e32 v79, v23
	v_cvt_f32_i32_e32 v80, v24
	v_cvt_f32_i32_e32 v81, v25
	v_cvt_f32_i32_e32 v50, v42
	v_cvt_f32_i32_e32 v51, v43
	v_cvt_f32_i32_e32 v52, v44
	v_cvt_f32_i32_e32 v53, v45
	v_cvt_f32_i32_e32 v54, v34
	v_cvt_f32_i32_e32 v55, v35
	v_cvt_f32_i32_e32 v56, v36
	v_cvt_f32_i32_e32 v57, v37
	v_cvt_f32_i32_e32 v58, v14
	v_cvt_f32_i32_e32 v59, v15
	v_cvt_f32_i32_e32 v60, v16
	v_cvt_f32_i32_e32 v61, v17
	v_cvt_f32_i32_e32 v62, v10
	v_cvt_f32_i32_e32 v63, v11
	v_cvt_f32_i32_e32 v64, v12
	v_cvt_f32_i32_e32 v65, v13
	v_cvt_f32_i32_e32 v34, v26
	v_cvt_f32_i32_e32 v35, v27
	v_cvt_f32_i32_e32 v36, v28
	v_cvt_f32_i32_e32 v37, v29
	v_cvt_f32_i32_e32 v38, v18
	v_cvt_f32_i32_e32 v39, v19
	v_cvt_f32_i32_e32 v40, v20
	v_cvt_f32_i32_e32 v41, v21
	v_cvt_f32_i32_e32 v42, v6
	v_cvt_f32_i32_e32 v43, v7
	v_cvt_f32_i32_e32 v44, v8
	v_cvt_f32_i32_e32 v45, v9
	v_cvt_f32_i32_e32 v46, v2
	v_cvt_f32_i32_e32 v47, v3
	v_cvt_f32_i32_e32 v48, v4
	v_cvt_f32_i32_e32 v49, v5

.LBB0_3879:
	ds_read_b128 v[130:133], v169
	ds_read_b128 v[134:137], v169 offset:1024
	ds_read_b128 v[138:141], v169 offset:2048
	ds_read_b128 v[142:145], v169 offset:3072
	ds_read_b128 v[162:165], v170
	ds_read_b128 v[172:175], v170 offset:1024
	ds_read_b128 v[176:179], v170 offset:2048
	ds_read_b128 v[180:183], v170 offset:3072
	s_add_i32 s59, s26, 2
	s_add_u32 s27, s24, 0x4000
	s_addc_u32 s28, s25, 0
	s_cmp_eq_u32 s48, s26
	s_cselect_b32 s29, s3, s28
	s_cselect_b32 s28, s2, s27
	s_cselect_b32 s60, s22, s57
	s_cselect_b32 s61, s23, s58
	s_add_u32 s26, s28, 0x8000
	s_addc_u32 s27, s29, 0
	v_lshl_add_u64 v[216:217], s[24:25], 0, v[154:155]
	s_add_i32 m0, s38, 0xc000
	ds_read_b128 v[184:187], v171
	ds_read_b128 v[188:191], v171 offset:1024
	ds_read_b128 v[192:195], v171 offset:2048
	ds_read_b128 v[196:199], v171 offset:3072
	ds_read_b128 v[200:203], v171 offset:4096
	ds_read_b128 v[204:207], v171 offset:5120
	ds_read_b128 v[208:211], v171 offset:6144
	ds_read_b128 v[212:215], v171 offset:7168
	global_load_lds_dwordx4 v[216:217], off
	v_lshl_add_u64 v[216:217], s[24:25], 0, v[156:157]
	s_add_i32 m0, s38, 0xe000
	s_nop 0
	global_load_lds_dwordx4 v[216:217], off
	s_waitcnt vmcnt(8)
	s_waitcnt lgkmcnt(0)
	s_setprio 1
	v_mfma_f32_16x16x32_bf16 v[126:129], v[130:133], v[184:187], v[126:129]
	v_mfma_f32_16x16x32_bf16 v[122:125], v[138:141], v[184:187], v[122:125]
	s_barrier
	v_mfma_f32_16x16x32_bf16 v[110:113], v[130:133], v[192:195], v[110:113]
	v_mfma_f32_16x16x32_bf16 v[106:109], v[138:141], v[192:195], v[106:109]
	v_mfma_f32_16x16x32_bf16 v[94:97], v[130:133], v[200:203], v[94:97]
	v_mfma_f32_16x16x32_bf16 v[90:93], v[138:141], v[200:203], v[90:93]
	v_mfma_f32_16x16x32_bf16 v[78:81], v[130:133], v[208:211], v[78:81]
	v_mfma_f32_16x16x32_bf16 v[74:77], v[138:141], v[208:211], v[74:77]
	v_mfma_f32_16x16x32_bf16 v[126:129], v[134:137], v[188:191], v[126:129]
	v_mfma_f32_16x16x32_bf16 v[122:125], v[142:145], v[188:191], v[122:125]
	v_mfma_f32_16x16x32_bf16 v[110:113], v[134:137], v[196:199], v[110:113]
	v_mfma_f32_16x16x32_bf16 v[106:109], v[142:145], v[196:199], v[106:109]
	v_mfma_f32_16x16x32_bf16 v[94:97], v[134:137], v[204:207], v[94:97]
	v_mfma_f32_16x16x32_bf16 v[90:93], v[142:145], v[204:207], v[90:93]
	v_mfma_f32_16x16x32_bf16 v[78:81], v[134:137], v[212:215], v[78:81]
	v_mfma_f32_16x16x32_bf16 v[74:77], v[142:145], v[212:215], v[74:77]
	v_mfma_f32_16x16x32_bf16 v[118:121], v[162:165], v[184:187], v[118:121]
	v_mfma_f32_16x16x32_bf16 v[114:117], v[176:179], v[184:187], v[114:117]
	v_mfma_f32_16x16x32_bf16 v[102:105], v[162:165], v[192:195], v[102:105]
	v_mfma_f32_16x16x32_bf16 v[98:101], v[176:179], v[192:195], v[98:101]
	v_mfma_f32_16x16x32_bf16 v[86:89], v[162:165], v[200:203], v[86:89]
	v_mfma_f32_16x16x32_bf16 v[82:85], v[176:179], v[200:203], v[82:85]
	v_mfma_f32_16x16x32_bf16 v[70:73], v[162:165], v[208:211], v[70:73]
	v_mfma_f32_16x16x32_bf16 v[66:69], v[176:179], v[208:211], v[66:69]
	v_mfma_f32_16x16x32_bf16 v[118:121], v[172:175], v[188:191], v[118:121]
	v_mfma_f32_16x16x32_bf16 v[114:117], v[180:183], v[188:191], v[114:117]
	v_mfma_f32_16x16x32_bf16 v[102:105], v[172:175], v[196:199], v[102:105]
	v_mfma_f32_16x16x32_bf16 v[98:101], v[180:183], v[196:199], v[98:101]
	v_mfma_f32_16x16x32_bf16 v[86:89], v[172:175], v[204:207], v[86:89]
	v_mfma_f32_16x16x32_bf16 v[82:85], v[180:183], v[204:207], v[82:85]
	v_mfma_f32_16x16x32_bf16 v[70:73], v[172:175], v[212:215], v[70:73]
	v_mfma_f32_16x16x32_bf16 v[66:69], v[180:183], v[212:215], v[66:69]
	s_setprio 0
	s_barrier
	s_add_i32 s62, s50, s37
	v_lshl_add_u64 v[216:217], s[60:61], 0, v[148:149]
	s_mov_b32 m0, s62
	ds_read_b128 v[184:187], v171 offset:16384
	ds_read_b128 v[188:191], v171 offset:17408
	ds_read_b128 v[192:195], v171 offset:18432
	ds_read_b128 v[196:199], v171 offset:19456
	ds_read_b128 v[200:203], v171 offset:20480
	ds_read_b128 v[204:207], v171 offset:21504
	ds_read_b128 v[208:211], v171 offset:22528
	ds_read_b128 v[212:215], v171 offset:23552
	global_load_lds_dwordx4 v[216:217], off
	s_add_i32 m0, s62, 0x2000
	v_lshl_add_u64 v[218:219], s[60:61], 0, v[152:153]
	s_add_u32 s60, s60, s6
	s_addc_u32 s61, s61, s7
	s_add_i32 s62, s51, s37
	global_load_lds_dwordx4 v[218:219], off
	v_lshl_add_u64 v[220:221], s[60:61], 0, v[148:149]
	s_mov_b32 m0, s62
	v_lshl_add_u64 v[222:223], s[60:61], 0, v[152:153]
	global_load_lds_dwordx4 v[220:221], off
	s_add_i32 m0, s62, 0x2000
	v_lshl_add_u64 v[224:225], s[28:29], 0, v[146:147]
	global_load_lds_dwordx4 v[222:223], off
	s_mov_b32 m0, s38
	s_nop 0
	global_load_lds_dwordx4 v[224:225], off
	v_lshl_add_u64 v[224:225], s[28:29], 0, v[150:151]
	s_mov_b32 m0, s39
	s_nop 0
	global_load_lds_dwordx4 v[224:225], off
	s_waitcnt vmcnt(8)
	s_waitcnt lgkmcnt(0)
	s_setprio 1
	v_mfma_f32_16x16x32_bf16 v[62:65], v[130:133], v[184:187], v[62:65]
	v_mfma_f32_16x16x32_bf16 v[58:61], v[138:141], v[184:187], v[58:61]
	s_barrier
	v_mfma_f32_16x16x32_bf16 v[46:49], v[130:133], v[192:195], v[46:49]
	v_mfma_f32_16x16x32_bf16 v[42:45], v[138:141], v[192:195], v[42:45]
	v_mfma_f32_16x16x32_bf16 v[30:33], v[130:133], v[200:203], v[30:33]
	v_mfma_f32_16x16x32_bf16 v[26:29], v[138:141], v[200:203], v[26:29]
	v_mfma_f32_16x16x32_bf16 v[14:17], v[130:133], v[208:211], v[14:17]
	v_mfma_f32_16x16x32_bf16 v[10:13], v[138:141], v[208:211], v[10:13]
	v_mfma_f32_16x16x32_bf16 v[62:65], v[134:137], v[188:191], v[62:65]
	v_mfma_f32_16x16x32_bf16 v[58:61], v[142:145], v[188:191], v[58:61]
	v_mfma_f32_16x16x32_bf16 v[46:49], v[134:137], v[196:199], v[46:49]
	v_mfma_f32_16x16x32_bf16 v[42:45], v[142:145], v[196:199], v[42:45]
	v_mfma_f32_16x16x32_bf16 v[30:33], v[134:137], v[204:207], v[30:33]
	v_mfma_f32_16x16x32_bf16 v[26:29], v[142:145], v[204:207], v[26:29]
	v_mfma_f32_16x16x32_bf16 v[14:17], v[134:137], v[212:215], v[14:17]
	v_mfma_f32_16x16x32_bf16 v[10:13], v[142:145], v[212:215], v[10:13]
	v_mfma_f32_16x16x32_bf16 v[54:57], v[162:165], v[184:187], v[54:57]
	v_mfma_f32_16x16x32_bf16 v[50:53], v[176:179], v[184:187], v[50:53]
	v_mfma_f32_16x16x32_bf16 v[38:41], v[162:165], v[192:195], v[38:41]
	v_mfma_f32_16x16x32_bf16 v[34:37], v[176:179], v[192:195], v[34:37]
	v_mfma_f32_16x16x32_bf16 v[22:25], v[162:165], v[200:203], v[22:25]
	v_mfma_f32_16x16x32_bf16 v[18:21], v[176:179], v[200:203], v[18:21]
	v_mfma_f32_16x16x32_bf16 v[6:9], v[162:165], v[208:211], v[6:9]
	v_mfma_f32_16x16x32_bf16 v[2:5], v[176:179], v[208:211], v[2:5]
	v_mfma_f32_16x16x32_bf16 v[54:57], v[172:175], v[188:191], v[54:57]
	v_mfma_f32_16x16x32_bf16 v[50:53], v[180:183], v[188:191], v[50:53]
	v_mfma_f32_16x16x32_bf16 v[38:41], v[172:175], v[196:199], v[38:41]
	v_mfma_f32_16x16x32_bf16 v[34:37], v[180:183], v[196:199], v[34:37]
	v_mfma_f32_16x16x32_bf16 v[22:25], v[172:175], v[204:207], v[22:25]
	v_mfma_f32_16x16x32_bf16 v[18:21], v[180:183], v[204:207], v[18:21]
	v_mfma_f32_16x16x32_bf16 v[6:9], v[172:175], v[212:215], v[6:9]
	v_mfma_f32_16x16x32_bf16 v[2:5], v[180:183], v[212:215], v[2:5]
	s_setprio 0
	s_barrier
	s_add_i32 s60, 0, 0x18000
	s_add_i32 s61, 0, 0x1c000
	v_add_u32_e32 v142, s60, v167
	v_add_u32_e32 v180, s61, v167
	ds_read_b128 v[130:133], v142
	ds_read_b128 v[134:137], v142 offset:1024
	ds_read_b128 v[138:141], v142 offset:2048
	ds_read_b128 v[142:145], v142 offset:3072
	ds_read_b128 v[162:165], v180
	ds_read_b128 v[172:175], v180 offset:1024
	ds_read_b128 v[176:179], v180 offset:2048
	ds_read_b128 v[180:183], v180 offset:3072
	s_add_u32 s28, s28, 0x4000
	s_addc_u32 s29, s29, 0
	s_mov_b32 m0, s40
	v_lshl_add_u64 v[224:225], s[28:29], 0, v[146:147]
	ds_read_b128 v[184:187], v171 offset:32768
	ds_read_b128 v[188:191], v171 offset:33792
	ds_read_b128 v[192:195], v171 offset:34816
	ds_read_b128 v[196:199], v171 offset:35840
	ds_read_b128 v[200:203], v171 offset:36864
	ds_read_b128 v[204:207], v171 offset:37888
	ds_read_b128 v[208:211], v171 offset:38912
	ds_read_b128 v[212:215], v171 offset:39936
	global_load_lds_dwordx4 v[224:225], off
	v_lshl_add_u64 v[224:225], s[28:29], 0, v[150:151]
	s_mov_b32 m0, s41
	s_nop 0
	global_load_lds_dwordx4 v[224:225], off
	s_waitcnt vmcnt(8)
	s_waitcnt lgkmcnt(0)
	s_setprio 1
	v_mfma_f32_16x16x32_bf16 v[126:129], v[130:133], v[184:187], v[126:129]
	v_mfma_f32_16x16x32_bf16 v[122:125], v[138:141], v[184:187], v[122:125]
	s_barrier
	v_mfma_f32_16x16x32_bf16 v[110:113], v[130:133], v[192:195], v[110:113]
	v_mfma_f32_16x16x32_bf16 v[106:109], v[138:141], v[192:195], v[106:109]
	v_mfma_f32_16x16x32_bf16 v[94:97], v[130:133], v[200:203], v[94:97]
	v_mfma_f32_16x16x32_bf16 v[90:93], v[138:141], v[200:203], v[90:93]
	v_mfma_f32_16x16x32_bf16 v[78:81], v[130:133], v[208:211], v[78:81]
	v_mfma_f32_16x16x32_bf16 v[74:77], v[138:141], v[208:211], v[74:77]
	v_mfma_f32_16x16x32_bf16 v[126:129], v[134:137], v[188:191], v[126:129]
	v_mfma_f32_16x16x32_bf16 v[122:125], v[142:145], v[188:191], v[122:125]
	v_mfma_f32_16x16x32_bf16 v[110:113], v[134:137], v[196:199], v[110:113]
	v_mfma_f32_16x16x32_bf16 v[106:109], v[142:145], v[196:199], v[106:109]
	v_mfma_f32_16x16x32_bf16 v[94:97], v[134:137], v[204:207], v[94:97]
	v_mfma_f32_16x16x32_bf16 v[90:93], v[142:145], v[204:207], v[90:93]
	v_mfma_f32_16x16x32_bf16 v[78:81], v[134:137], v[212:215], v[78:81]
	v_mfma_f32_16x16x32_bf16 v[74:77], v[142:145], v[212:215], v[74:77]
	v_mfma_f32_16x16x32_bf16 v[118:121], v[162:165], v[184:187], v[118:121]
	v_mfma_f32_16x16x32_bf16 v[114:117], v[176:179], v[184:187], v[114:117]
	v_mfma_f32_16x16x32_bf16 v[102:105], v[162:165], v[192:195], v[102:105]
	v_mfma_f32_16x16x32_bf16 v[98:101], v[176:179], v[192:195], v[98:101]
	v_mfma_f32_16x16x32_bf16 v[86:89], v[162:165], v[200:203], v[86:89]
	v_mfma_f32_16x16x32_bf16 v[82:85], v[176:179], v[200:203], v[82:85]
	v_mfma_f32_16x16x32_bf16 v[70:73], v[162:165], v[208:211], v[70:73]
	v_mfma_f32_16x16x32_bf16 v[66:69], v[176:179], v[208:211], v[66:69]
	v_mfma_f32_16x16x32_bf16 v[118:121], v[172:175], v[188:191], v[118:121]
	v_mfma_f32_16x16x32_bf16 v[114:117], v[180:183], v[188:191], v[114:117]
	v_mfma_f32_16x16x32_bf16 v[102:105], v[172:175], v[196:199], v[102:105]
	v_mfma_f32_16x16x32_bf16 v[98:101], v[180:183], v[196:199], v[98:101]
	v_mfma_f32_16x16x32_bf16 v[86:89], v[172:175], v[204:207], v[86:89]
	v_mfma_f32_16x16x32_bf16 v[82:85], v[180:183], v[204:207], v[82:85]
	v_mfma_f32_16x16x32_bf16 v[70:73], v[172:175], v[212:215], v[70:73]
	v_mfma_f32_16x16x32_bf16 v[66:69], v[180:183], v[212:215], v[66:69]
	s_setprio 0
	s_barrier
	s_add_i32 s28, s60, s37
	v_lshl_add_u64 v[216:217], v[216:217], 0, s[14:15]
	s_mov_b32 m0, s28
	ds_read_b128 v[184:187], v171 offset:49152
	ds_read_b128 v[188:191], v171 offset:50176
	ds_read_b128 v[192:195], v171 offset:51200
	ds_read_b128 v[196:199], v171 offset:52224
	ds_read_b128 v[200:203], v171 offset:53248
	ds_read_b128 v[204:207], v171 offset:54272
	ds_read_b128 v[208:211], v171 offset:55296
	ds_read_b128 v[212:215], v171 offset:56320
	global_load_lds_dwordx4 v[216:217], off
	v_lshl_add_u64 v[216:217], v[218:219], 0, s[14:15]
	s_add_i32 m0, s28, 0x2000
	s_add_i32 s28, s61, s37
	global_load_lds_dwordx4 v[216:217], off
	v_lshl_add_u64 v[216:217], v[220:221], 0, s[14:15]
	s_mov_b32 m0, s28
	s_nop 0
	global_load_lds_dwordx4 v[216:217], off
	v_lshl_add_u64 v[216:217], v[222:223], 0, s[14:15]
	s_add_i32 m0, s28, 0x2000
	s_nop 0
	global_load_lds_dwordx4 v[216:217], off
	v_lshl_add_u64 v[216:217], s[26:27], 0, v[146:147]
	s_mov_b32 m0, s46
	s_nop 0
	global_load_lds_dwordx4 v[216:217], off
	v_lshl_add_u64 v[216:217], s[26:27], 0, v[150:151]
	s_mov_b32 m0, s47
	s_nop 0
	global_load_lds_dwordx4 v[216:217], off
	s_waitcnt vmcnt(8)
	s_waitcnt lgkmcnt(0)
	s_setprio 1
	v_mfma_f32_16x16x32_bf16 v[62:65], v[130:133], v[184:187], v[62:65]
	v_mfma_f32_16x16x32_bf16 v[58:61], v[138:141], v[184:187], v[58:61]
	s_barrier
	v_mfma_f32_16x16x32_bf16 v[46:49], v[130:133], v[192:195], v[46:49]
	v_mfma_f32_16x16x32_bf16 v[42:45], v[138:141], v[192:195], v[42:45]
	v_mfma_f32_16x16x32_bf16 v[30:33], v[130:133], v[200:203], v[30:33]
	v_mfma_f32_16x16x32_bf16 v[26:29], v[138:141], v[200:203], v[26:29]
	v_mfma_f32_16x16x32_bf16 v[14:17], v[130:133], v[208:211], v[14:17]
	v_mfma_f32_16x16x32_bf16 v[10:13], v[138:141], v[208:211], v[10:13]
	v_mfma_f32_16x16x32_bf16 v[62:65], v[134:137], v[188:191], v[62:65]
	v_mfma_f32_16x16x32_bf16 v[58:61], v[142:145], v[188:191], v[58:61]
	v_mfma_f32_16x16x32_bf16 v[46:49], v[134:137], v[196:199], v[46:49]
	v_mfma_f32_16x16x32_bf16 v[42:45], v[142:145], v[196:199], v[42:45]
	v_mfma_f32_16x16x32_bf16 v[30:33], v[134:137], v[204:207], v[30:33]
	v_mfma_f32_16x16x32_bf16 v[26:29], v[142:145], v[204:207], v[26:29]
	v_mfma_f32_16x16x32_bf16 v[14:17], v[134:137], v[212:215], v[14:17]
	v_mfma_f32_16x16x32_bf16 v[10:13], v[142:145], v[212:215], v[10:13]
	v_mfma_f32_16x16x32_bf16 v[54:57], v[162:165], v[184:187], v[54:57]
	v_mfma_f32_16x16x32_bf16 v[50:53], v[176:179], v[184:187], v[50:53]
	v_mfma_f32_16x16x32_bf16 v[38:41], v[162:165], v[192:195], v[38:41]
	v_mfma_f32_16x16x32_bf16 v[34:37], v[176:179], v[192:195], v[34:37]
	v_mfma_f32_16x16x32_bf16 v[22:25], v[162:165], v[200:203], v[22:25]
	v_mfma_f32_16x16x32_bf16 v[18:21], v[176:179], v[200:203], v[18:21]
	v_mfma_f32_16x16x32_bf16 v[6:9], v[162:165], v[208:211], v[6:9]
	v_mfma_f32_16x16x32_bf16 v[2:5], v[176:179], v[208:211], v[2:5]
	v_mfma_f32_16x16x32_bf16 v[54:57], v[172:175], v[188:191], v[54:57]
	v_mfma_f32_16x16x32_bf16 v[50:53], v[180:183], v[188:191], v[50:53]
	v_mfma_f32_16x16x32_bf16 v[38:41], v[172:175], v[196:199], v[38:41]
	v_mfma_f32_16x16x32_bf16 v[34:37], v[180:183], v[196:199], v[34:37]
	v_mfma_f32_16x16x32_bf16 v[22:25], v[172:175], v[204:207], v[22:25]
	v_mfma_f32_16x16x32_bf16 v[18:21], v[180:183], v[204:207], v[18:21]
	v_mfma_f32_16x16x32_bf16 v[6:9], v[172:175], v[212:215], v[6:9]
	v_mfma_f32_16x16x32_bf16 v[2:5], v[180:183], v[212:215], v[2:5]
	s_setprio 0
	s_barrier
	s_add_u32 s57, s57, 0x100
	s_addc_u32 s58, s58, 0
	s_add_u32 s24, s24, 0x10000
	s_addc_u32 s25, s25, 0
	s_cmp_ge_i32 s59, s45
	s_mov_b32 s26, s59
	s_cbranch_scc0 .LBB0_3879
